# speedup vs baseline: 1.0076x; 1.0076x over previous
; #define STAGE(P, BASE, br, kt) do { const char* _gb = (const char*)(BASE) + ((size_t)(br) * K + (size_t)(kt) * BK) * 2; \
;     __builtin_amdgcn_global_load_lds((const unsigned*)(_gb + loff0), (unsigned*)((char*)(P) + tid * 16), 16, 0, 0); \
;     __builtin_amdgcn_global_load_lds((const unsigned*)(_gb + (size_t)K * 128 + loff0), (unsigned*)((char*)(P) + tid * 16 + 8192), 16, 0, 0); } while (0)
; #define BAR __builtin_amdgcn_s_barrier()
; template <int EPI> ...
;     ...
;   f32x4 acc[2][2][4][2] = {};
;   bf16x8 At[4][2], B0[2][2], B1[2][2];
;   int nt = K / BK;
;   const int aoff0 = lds_byte(wr * 64 + fr, fq * 8), aoff1 = lds_byte(wr * 64 + fr, 32 + fq * 8);
;   const int brw = wc * 32 + (fr >> 2) * 8 + (fr & 3);
;   const int boff0 = lds_byte(brw, fq * 8), boff1 = lds_byte(brw, 32 + fq * 8);
;   unsigned loff0;
;   { int _r, _c; stage_rc(tid * 16, _r, _c); loff0 = (unsigned)(_r * K + _c) * 2u; }
;   STAGE(SB(0, 0), Bt, bcol, 0); STAGE(SA(0, 0), A, brow, 0);
;   STAGE(SB(0, 1), Bt, bcol + HALF, 0); STAGE(SA(0, 1), A, brow + HALF, 0);
;   if (wr == 1) BAR;
; template <int EPI>
; __device__ __forceinline__ void gemm_phase(const u16* A, const u16* Bt, int M, int N, int K, u16* out, int ldo,
;                                            const float* aux, int bid, int nblk, int wv) {
;     ...
;   for (int base = 0; base < ntile; base += nblk) {
;     int wgid;
;     if (base + nblk <= ntile && (nblk & 7) == 0) wgid = base + (bid & 7) * (nblk >> 3) + (bid >> 3);
;     else wgid = base + bid;
;     if (wgid >= ntile) break;
;     int nig = WGM * nN, gid = wgid / nig, fm = gid * WGM, gsz = min(nM - fm, WGM);
;     int pm = fm + ((wgid % nig) % gsz), pn = (wgid % nig) / gsz;
;     int brow = pm * BM, bcol = pn * BM;
;     gemm_tile<EPI>(A, Bt, K, brow, bcol, out, ldo, EPI == 1 ? pn * HALF : bcol, aux, tid);
.LBB0_273:
	s_mov_b32 s68, s74
	s_add_i32 s74, s74, s33
	s_cmpk_lt_i32 s74, 0x1601
	s_cselect_b64 s[66:67], -1, 0
	s_and_b64 s[66:67], s[44:45], s[66:67]
	s_and_b64 s[66:67], s[66:67], exec
	s_cselect_b32 s66, s86, s91
	s_add_i32 s68, s66, s68
	s_cmpk_gt_i32 s68, 0x15ff
	s_mov_b64 s[66:67], -1
	s_cbranch_scc1 .LBB0_272
	s_mul_hi_i32 s66, s68, 0x2e8ba2e9
	s_lshr_b32 s67, s66, 31
	s_ashr_i32 s66, s66, 6
	s_add_i32 s66, s66, s67
	s_mul_i32 s67, s66, 0x160
	s_sub_i32 s67, s68, s67
	s_sext_i32_i16 s68, s67
	s_bfe_u32 s68, s68, 0x3001c
	s_add_i32 s68, s67, s68
	s_sext_i32_i16 s69, s68
	s_and_b32 s68, s68, 0xfff8
	s_sub_i32 s67, s67, s68
	s_ashr_i32 s76, s69, 3
	s_sext_i32_i16 s67, s67
	s_lshl_b32 s72, s76, 8
	s_lshl_b32 s66, s66, 11
	s_lshl_b32 s67, s67, 8
	s_ashr_i32 s73, s72, 31
	s_add_i32 s66, s67, s66
	s_lshl_b64 s[68:69], s[72:73], 12
	s_add_u32 s68, s6, s68
	s_addc_u32 s69, s7, s69
	v_readfirstlane_b32 s67, v136
	v_lshl_add_u64 v[0:1], s[68:69], 0, v[128:129]
	s_mov_b32 m0, s67
	v_readfirstlane_b32 s67, v137
	global_load_lds_dwordx4 v[0:1], off
	s_mov_b32 m0, s67
	s_ashr_i32 s67, s66, 31
	s_lshl_b64 s[70:71], s[66:67], 12
	s_add_u32 s78, s14, s70
	s_addc_u32 s79, s43, s71
	s_bitset1_b32 s72, 7
	s_ashr_i32 s73, s72, 31
	v_lshl_add_u64 v[2:3], v[0:1], 0, s[10:11]
	v_readfirstlane_b32 s67, v138
	s_lshl_b64 s[72:73], s[72:73], 12
	global_load_lds_dwordx4 v[2:3], off
	v_lshl_add_u64 v[2:3], s[78:79], 0, v[128:129]
	s_mov_b32 m0, s67
	v_readfirstlane_b32 s67, v139
	s_add_u32 s72, s6, s72
	global_load_lds_dwordx4 v[2:3], off
	v_lshl_add_u64 v[4:5], v[2:3], 0, s[10:11]
	s_mov_b32 m0, s67
	s_addc_u32 s73, s7, s73
	global_load_lds_dwordx4 v[4:5], off
	v_lshl_add_u64 v[4:5], s[72:73], 0, v[128:129]
	s_or_b32 s72, s66, 0x80
	s_ashr_i32 s73, s72, 31
	v_readfirstlane_b32 s67, v140
	s_lshl_b64 s[72:73], s[72:73], 12
	s_mov_b32 m0, s67
	v_readfirstlane_b32 s67, v141
	s_add_u32 s72, s14, s72
	global_load_lds_dwordx4 v[4:5], off
	v_lshl_add_u64 v[6:7], v[4:5], 0, s[10:11]
	s_mov_b32 m0, s67
	s_addc_u32 s73, s43, s73
	v_readfirstlane_b32 s67, v142
	global_load_lds_dwordx4 v[6:7], off
	v_lshl_add_u64 v[132:133], s[72:73], 0, v[128:129]
	s_mov_b32 m0, s67
	v_readfirstlane_b32 s67, v143
	global_load_lds_dwordx4 v[132:133], off
	v_lshl_add_u64 v[6:7], v[132:133], 0, s[10:11]
	s_mov_b32 m0, s67
	s_nop 0
	global_load_lds_dwordx4 v[6:7], off
	v_mov_b32_e32 v8, 0
	v_mov_b32_e32 v9, 0
	v_mov_b32_e32 v10, 0
	v_mov_b32_e32 v11, 0
	v_mov_b32_e32 v12, 0
	v_mov_b32_e32 v13, 0
	v_mov_b32_e32 v14, 0
	v_mov_b32_e32 v15, 0
	v_mov_b32_e32 v16, 0
	v_mov_b32_e32 v17, 0
	v_mov_b32_e32 v18, 0
	v_mov_b32_e32 v19, 0
	v_mov_b32_e32 v20, 0
	v_mov_b32_e32 v21, 0
	v_mov_b32_e32 v22, 0
	v_mov_b32_e32 v23, 0
	v_mov_b32_e32 v24, 0
	v_mov_b32_e32 v25, 0
	v_mov_b32_e32 v26, 0
	v_mov_b32_e32 v27, 0
	v_mov_b32_e32 v28, 0
	v_mov_b32_e32 v29, 0
	v_mov_b32_e32 v30, 0
	v_mov_b32_e32 v31, 0
	v_mov_b32_e32 v32, 0
	v_mov_b32_e32 v33, 0
	v_mov_b32_e32 v34, 0
	v_mov_b32_e32 v35, 0
	v_mov_b32_e32 v36, 0
	v_mov_b32_e32 v37, 0
	v_mov_b32_e32 v38, 0
	v_mov_b32_e32 v39, 0
	v_mov_b32_e32 v40, 0
	v_mov_b32_e32 v41, 0
	v_mov_b32_e32 v42, 0
	v_mov_b32_e32 v43, 0
	v_mov_b32_e32 v44, 0
	v_mov_b32_e32 v45, 0
	v_mov_b32_e32 v46, 0
	v_mov_b32_e32 v47, 0
	v_mov_b32_e32 v48, 0
	v_mov_b32_e32 v49, 0
	v_mov_b32_e32 v50, 0
	v_mov_b32_e32 v51, 0
	v_mov_b32_e32 v52, 0
	v_mov_b32_e32 v53, 0
	v_mov_b32_e32 v54, 0
	v_mov_b32_e32 v55, 0
	v_mov_b32_e32 v56, 0
	v_mov_b32_e32 v57, 0
	v_mov_b32_e32 v58, 0
	v_mov_b32_e32 v59, 0
	v_mov_b32_e32 v60, 0
	v_mov_b32_e32 v61, 0
	v_mov_b32_e32 v62, 0
	v_mov_b32_e32 v63, 0
	v_mov_b32_e32 v64, 0
	v_mov_b32_e32 v65, 0
	v_mov_b32_e32 v66, 0
	v_mov_b32_e32 v67, 0
	v_mov_b32_e32 v68, 0
	v_mov_b32_e32 v69, 0
	v_mov_b32_e32 v70, 0
	v_mov_b32_e32 v71, 0
	v_mov_b32_e32 v72, 0
	v_mov_b32_e32 v73, 0
	v_mov_b32_e32 v74, 0
	v_mov_b32_e32 v75, 0
	v_mov_b32_e32 v76, 0
	v_mov_b32_e32 v77, 0
	v_mov_b32_e32 v78, 0
	v_mov_b32_e32 v79, 0
	v_mov_b32_e32 v80, 0
	v_mov_b32_e32 v81, 0
	v_mov_b32_e32 v82, 0
	v_mov_b32_e32 v83, 0
	v_mov_b32_e32 v84, 0
	v_mov_b32_e32 v85, 0
	v_mov_b32_e32 v86, 0
	v_mov_b32_e32 v87, 0
	v_mov_b32_e32 v88, 0
	v_mov_b32_e32 v89, 0
	v_mov_b32_e32 v90, 0
	v_mov_b32_e32 v91, 0
	v_mov_b32_e32 v92, 0
	v_mov_b32_e32 v93, 0
	v_mov_b32_e32 v94, 0
	v_mov_b32_e32 v95, 0
	v_mov_b32_e32 v96, 0
	v_mov_b32_e32 v97, 0
	v_mov_b32_e32 v98, 0
	v_mov_b32_e32 v99, 0
	v_mov_b32_e32 v100, 0
	v_mov_b32_e32 v101, 0
	v_mov_b32_e32 v102, 0
	v_mov_b32_e32 v103, 0
	v_mov_b32_e32 v104, 0
	v_mov_b32_e32 v105, 0
	v_mov_b32_e32 v106, 0
	v_mov_b32_e32 v107, 0
	v_mov_b32_e32 v108, 0
	v_mov_b32_e32 v109, 0
	v_mov_b32_e32 v110, 0
	v_mov_b32_e32 v111, 0
	v_mov_b32_e32 v112, 0
	v_mov_b32_e32 v113, 0
	v_mov_b32_e32 v114, 0
	v_mov_b32_e32 v115, 0
	v_mov_b32_e32 v116, 0
	v_mov_b32_e32 v117, 0
	v_mov_b32_e32 v118, 0
	v_mov_b32_e32 v119, 0
	v_mov_b32_e32 v120, 0
	v_mov_b32_e32 v121, 0
	v_mov_b32_e32 v122, 0
	v_mov_b32_e32 v123, 0
	v_mov_b32_e32 v124, 0
	v_mov_b32_e32 v125, 0
	v_mov_b32_e32 v126, 0
	v_mov_b32_e32 v127, 0
	s_and_saveexec_b64 s[72:73], s[4:5]
	s_cbranch_execz .LBB0_276
	s_setprio 1
	s_barrier

; #define STAGE(P, BASE, br, kt) do { const char* _gb = (const char*)(BASE) + ((size_t)(br) * K + (size_t)(kt) * BK) * 2; \
;     __builtin_amdgcn_global_load_lds((const unsigned*)(_gb + loff0), (unsigned*)((char*)(P) + tid * 16), 16, 0, 0); \
;     __builtin_amdgcn_global_load_lds((const unsigned*)(_gb + (size_t)K * 128 + loff0), (unsigned*)((char*)(P) + tid * 16 + 8192), 16, 0, 0); } while (0)
; #define LDA(dst, b, h) for (int m = 0; m < 4; ++m) { \
;     dst[m][0] = *reinterpret_cast<const bf16x8*>((char*)SA(b, h) + aoff0 + m * 2048); \
;     dst[m][1] = *reinterpret_cast<const bf16x8*>((char*)SA(b, h) + aoff1 + m * 2048); }
; #define LDB(dst, b, h) for (int n = 0; n < 2; ++n) { \
;     dst[n][0] = *reinterpret_cast<const bf16x8*>((char*)SB(b, h) + boff0 + n * 256); \
;     dst[n][1] = *reinterpret_cast<const bf16x8*>((char*)SB(b, h) + boff1 + n * 256); }
; #define MMA(ai, bj, At, Btf) do { __builtin_amdgcn_s_setprio(1); \
;     for (int m = 0; m < 4; ++m) for (int n = 0; n < 2; ++n) for (int k = 0; k < 2; ++k) \
;       acc[ai][bj][m][n] = __builtin_amdgcn_mfma_f32_16x16x32_bf16(Btf[n][k], At[m][k], acc[ai][bj][m][n], 0, 0, 0); \
;     __builtin_amdgcn_s_setprio(0); } while (0)
; #define WAIT_L(n) asm volatile("s_waitcnt lgkmcnt(" #n ")" ::: "memory")
; #define BAR __builtin_amdgcn_s_barrier()
; #define SCHED __builtin_amdgcn_sched_barrier(0)
; template <int EPI> ...
;     ...
;     LDB(B0, 0, 0); SCHED; LDA(At, 0, 0); STAGE(SA(1, 1), A, brow + HALF, t + 1);
;     WAIT_L(8); BAR; WAIT_L(0); MMA(0, 0, At, B0); BAR; SCHED;
;     LDB(B1, 0, 1); STAGE(SB(0, 0), Bt, bcol, t + 2);
.LBB0_277:
	ds_read_b128 v[162:165], v153
	ds_read_b128 v[166:169], v153 offset:256
	ds_read_b128 v[170:173], v154
	ds_read_b128 v[174:177], v154 offset:256
	v_lshl_add_u64 v[226:227], s[70:71], 0, v[130:131]
	v_readfirstlane_b32 s72, v151
	v_lshl_add_u64 v[210:211], v[226:227], 0, s[18:19]
	s_mov_b32 m0, s72
	v_readfirstlane_b32 s72, v152
	ds_read_b128 v[178:181], v150
	ds_read_b128 v[182:185], v150 offset:1024
	ds_read_b128 v[186:189], v150 offset:2048
	ds_read_b128 v[190:193], v150 offset:3072
	ds_read_b128 v[194:197], v150 offset:4096
	ds_read_b128 v[198:201], v150 offset:5120
	ds_read_b128 v[202:205], v150 offset:6144
	ds_read_b128 v[206:209], v150 offset:7168
	global_load_lds_dwordx4 v[210:211], off
	v_lshl_add_u64 v[210:211], v[226:227], 0, s[20:21]
	s_mov_b32 m0, s72
	s_nop 0
	global_load_lds_dwordx4 v[210:211], off
	s_waitcnt lgkmcnt(8)
	v_readfirstlane_b32 s72, v149
	v_lshl_add_u64 v[246:247], v[228:229], 0, s[60:61]
	s_mov_b32 m0, s72
	s_nop 0
	global_load_lds_dwordx4 v[246:247], off
	ds_read_b128 v[210:213], v155
	ds_read_b128 v[214:217], v155 offset:256
	ds_read_b128 v[218:221], v156
	ds_read_b128 v[222:225], v156 offset:256
	s_waitcnt lgkmcnt(0)

; #define STAGE(P, BASE, br, kt) do { const char* _gb = (const char*)(BASE) + ((size_t)(br) * K + (size_t)(kt) * BK) * 2; \
;     __builtin_amdgcn_global_load_lds((const unsigned*)(_gb + loff0), (unsigned*)((char*)(P) + tid * 16), 16, 0, 0); \
;     __builtin_amdgcn_global_load_lds((const unsigned*)(_gb + (size_t)K * 128 + loff0), (unsigned*)((char*)(P) + tid * 16 + 8192), 16, 0, 0); } while (0)
; #define LDB(dst, b, h) for (int n = 0; n < 2; ++n) { \
;     dst[n][0] = *reinterpret_cast<const bf16x8*>((char*)SB(b, h) + boff0 + n * 256); \
;     dst[n][1] = *reinterpret_cast<const bf16x8*>((char*)SB(b, h) + boff1 + n * 256); }
; #define MMA(ai, bj, At, Btf) do { __builtin_amdgcn_s_setprio(1); \
;     for (int m = 0; m < 4; ++m) for (int n = 0; n < 2; ++n) for (int k = 0; k < 2; ++k) \
;       acc[ai][bj][m][n] = __builtin_amdgcn_mfma_f32_16x16x32_bf16(Btf[n][k], At[m][k], acc[ai][bj][m][n], 0, 0, 0); \
;     __builtin_amdgcn_s_setprio(0); } while (0)
; #define WAIT_L(n) asm volatile("s_waitcnt lgkmcnt(" #n ")" ::: "memory")
; #define BAR __builtin_amdgcn_s_barrier()
; #define SCHED __builtin_amdgcn_sched_barrier(0)
; template <int EPI> ...
;     ...
;     WAIT_L(8); BAR; WAIT_L(0); MMA(0, 0, At, B0); BAR; SCHED;
;     LDB(B1, 0, 1); STAGE(SB(0, 0), Bt, bcol, t + 2);
;     BAR; WAIT_L(0); MMA(0, 1, At, B1); BAR;
	s_barrier
	v_mfma_f32_16x16x32_bf16 v[124:127], v[162:165], v[178:181], v[124:127]
	v_mfma_f32_16x16x32_bf16 v[120:123], v[166:169], v[178:181], v[120:123]
	v_mfma_f32_16x16x32_bf16 v[116:119], v[162:165], v[186:189], v[116:119]
	v_mfma_f32_16x16x32_bf16 v[112:115], v[166:169], v[186:189], v[112:115]
	v_mfma_f32_16x16x32_bf16 v[108:111], v[162:165], v[194:197], v[108:111]
	v_mfma_f32_16x16x32_bf16 v[104:107], v[166:169], v[194:197], v[104:107]
	v_mfma_f32_16x16x32_bf16 v[100:103], v[162:165], v[202:205], v[100:103]
	v_mfma_f32_16x16x32_bf16 v[96:99], v[166:169], v[202:205], v[96:99]
	v_mfma_f32_16x16x32_bf16 v[124:127], v[170:173], v[182:185], v[124:127]
	v_mfma_f32_16x16x32_bf16 v[120:123], v[174:177], v[182:185], v[120:123]
	v_mfma_f32_16x16x32_bf16 v[116:119], v[170:173], v[190:193], v[116:119]
	v_mfma_f32_16x16x32_bf16 v[112:115], v[174:177], v[190:193], v[112:115]
	v_mfma_f32_16x16x32_bf16 v[108:111], v[170:173], v[198:201], v[108:111]
	v_mfma_f32_16x16x32_bf16 v[104:107], v[174:177], v[198:201], v[104:107]
	v_mfma_f32_16x16x32_bf16 v[100:103], v[170:173], v[206:209], v[100:103]
	v_mfma_f32_16x16x32_bf16 v[96:99], v[174:177], v[206:209], v[96:99]
	v_mfma_f32_16x16x32_bf16 v[92:95], v[210:213], v[178:181], v[92:95]
	v_mfma_f32_16x16x32_bf16 v[88:91], v[214:217], v[178:181], v[88:91]
	v_mfma_f32_16x16x32_bf16 v[84:87], v[210:213], v[186:189], v[84:87]
	v_mfma_f32_16x16x32_bf16 v[80:83], v[214:217], v[186:189], v[80:83]
	v_mfma_f32_16x16x32_bf16 v[76:79], v[210:213], v[194:197], v[76:79]
	v_mfma_f32_16x16x32_bf16 v[72:75], v[214:217], v[194:197], v[72:75]
	v_mfma_f32_16x16x32_bf16 v[68:71], v[210:213], v[202:205], v[68:71]
	v_mfma_f32_16x16x32_bf16 v[64:67], v[214:217], v[202:205], v[64:67]
	v_mfma_f32_16x16x32_bf16 v[92:95], v[218:221], v[182:185], v[92:95]
	v_mfma_f32_16x16x32_bf16 v[88:91], v[222:225], v[182:185], v[88:91]
	v_mfma_f32_16x16x32_bf16 v[84:87], v[218:221], v[190:193], v[84:87]
	v_mfma_f32_16x16x32_bf16 v[80:83], v[222:225], v[190:193], v[80:83]
	v_mfma_f32_16x16x32_bf16 v[76:79], v[218:221], v[198:201], v[76:79]
	v_mfma_f32_16x16x32_bf16 v[72:75], v[222:225], v[198:201], v[72:75]
	v_mfma_f32_16x16x32_bf16 v[68:71], v[218:221], v[206:209], v[68:71]
	v_mfma_f32_16x16x32_bf16 v[64:67], v[222:225], v[206:209], v[64:67]
	s_barrier

; #define STAGE(P, BASE, br, kt) do { const char* _gb = (const char*)(BASE) + ((size_t)(br) * K + (size_t)(kt) * BK) * 2; \
;     __builtin_amdgcn_global_load_lds((const unsigned*)(_gb + loff0), (unsigned*)((char*)(P) + tid * 16), 16, 0, 0); \
;     __builtin_amdgcn_global_load_lds((const unsigned*)(_gb + (size_t)K * 128 + loff0), (unsigned*)((char*)(P) + tid * 16 + 8192), 16, 0, 0); } while (0)
; #define LDA(dst, b, h) for (int m = 0; m < 4; ++m) { \
;     dst[m][0] = *reinterpret_cast<const bf16x8*>((char*)SA(b, h) + aoff0 + m * 2048); \
;     dst[m][1] = *reinterpret_cast<const bf16x8*>((char*)SA(b, h) + aoff1 + m * 2048); }
; #define MMA(ai, bj, At, Btf) do { __builtin_amdgcn_s_setprio(1); \
;     for (int m = 0; m < 4; ++m) for (int n = 0; n < 2; ++n) for (int k = 0; k < 2; ++k) \
;       acc[ai][bj][m][n] = __builtin_amdgcn_mfma_f32_16x16x32_bf16(Btf[n][k], At[m][k], acc[ai][bj][m][n], 0, 0, 0); \
;     __builtin_amdgcn_s_setprio(0); } while (0)
; #define WAIT_V(n) asm volatile("s_waitcnt vmcnt(" #n ")" ::: "memory")
; #define WAIT_L(n) asm volatile("s_waitcnt lgkmcnt(" #n ")" ::: "memory")
; #define BAR __builtin_amdgcn_s_barrier()
; #define SCHED __builtin_amdgcn_sched_barrier(0)
; template <int EPI> ...
;     ...
;     LDA(At, 0, 1); STAGE(SA(0, 0), A, brow, t + 2);
;     BAR; WAIT_L(0); MMA(1, 0, At, B0); BAR; SCHED;
;     STAGE(SB(0, 1), Bt, bcol + HALF, t + 2);
;     WAIT_V(6); BAR; MMA(1, 1, At, B1); BAR;
	v_lshl_add_u64 v[228:229], s[68:69], 0, v[130:131]
	v_readfirstlane_b32 s72, v136
	v_lshl_add_u64 v[230:231], v[228:229], 0, s[22:23]
	s_mov_b32 m0, s72
	v_readfirstlane_b32 s72, v137
	global_load_lds_dwordx4 v[230:231], off
	v_lshl_add_u64 v[230:231], v[228:229], 0, s[26:27]
	s_mov_b32 m0, s72
	s_nop 0
	global_load_lds_dwordx4 v[230:231], off
	v_readfirstlane_b32 s72, v138
	v_lshl_add_u64 v[230:231], v[226:227], 0, s[28:29]
	s_mov_b32 m0, s72
	v_readfirstlane_b32 s72, v139
	ds_read_b128 v[178:181], v150 offset:16384
	ds_read_b128 v[182:185], v150 offset:17408
	ds_read_b128 v[186:189], v150 offset:18432
	ds_read_b128 v[190:193], v150 offset:19456
	ds_read_b128 v[194:197], v150 offset:20480
	ds_read_b128 v[198:201], v150 offset:21504
	ds_read_b128 v[202:205], v150 offset:22528
	ds_read_b128 v[206:209], v150 offset:23552
	global_load_lds_dwordx4 v[230:231], off
	v_lshl_add_u64 v[230:231], v[226:227], 0, s[30:31]
	s_mov_b32 m0, s72
	s_nop 0
	global_load_lds_dwordx4 v[230:231], off
	v_readfirstlane_b32 s72, v140
	v_lshl_add_u64 v[246:247], v[228:229], 0, s[36:37]
	s_mov_b32 m0, s72
	v_readfirstlane_b32 s72, v141
	global_load_lds_dwordx4 v[246:247], off
	s_waitcnt vmcnt(5)
	s_waitcnt lgkmcnt(0)

; #define STAGE(P, BASE, br, kt) do { const char* _gb = (const char*)(BASE) + ((size_t)(br) * K + (size_t)(kt) * BK) * 2; \
;     __builtin_amdgcn_global_load_lds((const unsigned*)(_gb + loff0), (unsigned*)((char*)(P) + tid * 16), 16, 0, 0); \
;     __builtin_amdgcn_global_load_lds((const unsigned*)(_gb + (size_t)K * 128 + loff0), (unsigned*)((char*)(P) + tid * 16 + 8192), 16, 0, 0); } while (0)
; #define MMA(ai, bj, At, Btf) do { __builtin_amdgcn_s_setprio(1); \
;     for (int m = 0; m < 4; ++m) for (int n = 0; n < 2; ++n) for (int k = 0; k < 2; ++k) \
;       acc[ai][bj][m][n] = __builtin_amdgcn_mfma_f32_16x16x32_bf16(Btf[n][k], At[m][k], acc[ai][bj][m][n], 0, 0, 0); \
;     __builtin_amdgcn_s_setprio(0); } while (0)
; #define WAIT_V(n) asm volatile("s_waitcnt vmcnt(" #n ")" ::: "memory")
; #define WAIT_L(n) asm volatile("s_waitcnt lgkmcnt(" #n ")" ::: "memory")
; #define BAR __builtin_amdgcn_s_barrier()
; #define SCHED __builtin_amdgcn_sched_barrier(0)
; template <int EPI> ...
;     ...
;     BAR; WAIT_L(0); MMA(1, 0, At, B0); BAR; SCHED;
;     STAGE(SB(0, 1), Bt, bcol + HALF, t + 2);
;     WAIT_V(6); BAR; MMA(1, 1, At, B1); BAR;
	s_barrier
	v_mfma_f32_16x16x32_bf16 v[60:63], v[162:165], v[178:181], v[60:63]
	v_mfma_f32_16x16x32_bf16 v[56:59], v[166:169], v[178:181], v[56:59]
	v_mfma_f32_16x16x32_bf16 v[52:55], v[162:165], v[186:189], v[52:55]
	v_mfma_f32_16x16x32_bf16 v[48:51], v[166:169], v[186:189], v[48:51]
	v_mfma_f32_16x16x32_bf16 v[44:47], v[162:165], v[194:197], v[44:47]
	v_mfma_f32_16x16x32_bf16 v[40:43], v[166:169], v[194:197], v[40:43]
	v_mfma_f32_16x16x32_bf16 v[36:39], v[162:165], v[202:205], v[36:39]
	v_mfma_f32_16x16x32_bf16 v[32:35], v[166:169], v[202:205], v[32:35]
	v_mfma_f32_16x16x32_bf16 v[60:63], v[170:173], v[182:185], v[60:63]
	v_mfma_f32_16x16x32_bf16 v[56:59], v[174:177], v[182:185], v[56:59]
	v_mfma_f32_16x16x32_bf16 v[52:55], v[170:173], v[190:193], v[52:55]
	v_mfma_f32_16x16x32_bf16 v[48:51], v[174:177], v[190:193], v[48:51]
	v_mfma_f32_16x16x32_bf16 v[44:47], v[170:173], v[198:201], v[44:47]
	v_mfma_f32_16x16x32_bf16 v[40:43], v[174:177], v[198:201], v[40:43]
	v_mfma_f32_16x16x32_bf16 v[36:39], v[170:173], v[206:209], v[36:39]
	v_mfma_f32_16x16x32_bf16 v[32:35], v[174:177], v[206:209], v[32:35]
	v_mfma_f32_16x16x32_bf16 v[28:31], v[210:213], v[178:181], v[28:31]
	v_mfma_f32_16x16x32_bf16 v[24:27], v[214:217], v[178:181], v[24:27]
	v_mfma_f32_16x16x32_bf16 v[20:23], v[210:213], v[186:189], v[20:23]
	v_mfma_f32_16x16x32_bf16 v[16:19], v[214:217], v[186:189], v[16:19]
	v_mfma_f32_16x16x32_bf16 v[12:15], v[210:213], v[194:197], v[12:15]
	v_mfma_f32_16x16x32_bf16 v[8:11], v[214:217], v[194:197], v[8:11]
	v_mfma_f32_16x16x32_bf16 v[4:7], v[210:213], v[202:205], v[4:7]
	v_mfma_f32_16x16x32_bf16 v[0:3], v[214:217], v[202:205], v[0:3]
	v_mfma_f32_16x16x32_bf16 v[28:31], v[218:221], v[182:185], v[28:31]
	v_mfma_f32_16x16x32_bf16 v[24:27], v[222:225], v[182:185], v[24:27]
	v_mfma_f32_16x16x32_bf16 v[20:23], v[218:221], v[190:193], v[20:23]
	v_mfma_f32_16x16x32_bf16 v[16:19], v[222:225], v[190:193], v[16:19]
	v_mfma_f32_16x16x32_bf16 v[12:15], v[218:221], v[198:201], v[12:15]
	v_mfma_f32_16x16x32_bf16 v[8:11], v[222:225], v[198:201], v[8:11]
	v_mfma_f32_16x16x32_bf16 v[4:7], v[218:221], v[206:209], v[4:7]
	v_mfma_f32_16x16x32_bf16 v[0:3], v[222:225], v[206:209], v[0:3]
	s_barrier

; #define STAGE(P, BASE, br, kt) do { const char* _gb = (const char*)(BASE) + ((size_t)(br) * K + (size_t)(kt) * BK) * 2; \
;     __builtin_amdgcn_global_load_lds((const unsigned*)(_gb + loff0), (unsigned*)((char*)(P) + tid * 16), 16, 0, 0); \
;     __builtin_amdgcn_global_load_lds((const unsigned*)(_gb + (size_t)K * 128 + loff0), (unsigned*)((char*)(P) + tid * 16 + 8192), 16, 0, 0); } while (0)
; #define LDA(dst, b, h) for (int m = 0; m < 4; ++m) { \
;     dst[m][0] = *reinterpret_cast<const bf16x8*>((char*)SA(b, h) + aoff0 + m * 2048); \
;     dst[m][1] = *reinterpret_cast<const bf16x8*>((char*)SA(b, h) + aoff1 + m * 2048); }
; #define LDB(dst, b, h) for (int n = 0; n < 2; ++n) { \
;     dst[n][0] = *reinterpret_cast<const bf16x8*>((char*)SB(b, h) + boff0 + n * 256); \
;     dst[n][1] = *reinterpret_cast<const bf16x8*>((char*)SB(b, h) + boff1 + n * 256); }
; #define MMA(ai, bj, At, Btf) do { __builtin_amdgcn_s_setprio(1); \
;     for (int m = 0; m < 4; ++m) for (int n = 0; n < 2; ++n) for (int k = 0; k < 2; ++k) \
;       acc[ai][bj][m][n] = __builtin_amdgcn_mfma_f32_16x16x32_bf16(Btf[n][k], At[m][k], acc[ai][bj][m][n], 0, 0, 0); \
;     __builtin_amdgcn_s_setprio(0); } while (0)
; #define WAIT_L(n) asm volatile("s_waitcnt lgkmcnt(" #n ")" ::: "memory")
; #define BAR __builtin_amdgcn_s_barrier()
; #define SCHED __builtin_amdgcn_sched_barrier(0)
; template <int EPI> ...
;     ...
;     LDB(B0, 1, 0); SCHED; LDA(At, 1, 0); STAGE(SA(0, 1), A, brow + HALF, t + 2);
;     WAIT_L(8); BAR; WAIT_L(0); MMA(0, 0, At, B0); BAR; SCHED;
;     LDB(B1, 1, 1); STAGE(SB(1, 0), Bt, bcol, t + 3);
	ds_read_b128 v[162:165], v157
	ds_read_b128 v[166:169], v157 offset:256
	ds_read_b128 v[170:173], v158
	ds_read_b128 v[174:177], v158 offset:256
	v_readfirstlane_b32 s72, v142
	v_lshl_add_u64 v[210:211], v[226:227], 0, s[46:47]
	s_mov_b32 m0, s72
	v_readfirstlane_b32 s72, v143
	ds_read_b128 v[178:181], v150 offset:32768
	ds_read_b128 v[182:185], v150 offset:33792
	ds_read_b128 v[186:189], v150 offset:34816
	ds_read_b128 v[190:193], v150 offset:35840
	ds_read_b128 v[194:197], v150 offset:36864
	ds_read_b128 v[198:201], v150 offset:37888
	ds_read_b128 v[202:205], v150 offset:38912
	ds_read_b128 v[206:209], v150 offset:39936
	global_load_lds_dwordx4 v[210:211], off
	v_lshl_add_u64 v[210:211], v[226:227], 0, s[48:49]
	s_mov_b32 m0, s72
	s_nop 0
	global_load_lds_dwordx4 v[210:211], off
	s_waitcnt lgkmcnt(8)
	v_readfirstlane_b32 s72, v141
	v_lshl_add_u64 v[246:247], v[228:229], 0, s[38:39]
	s_mov_b32 m0, s72
	s_nop 0
	global_load_lds_dwordx4 v[246:247], off
	ds_read_b128 v[210:213], v159
	ds_read_b128 v[214:217], v159 offset:256
	ds_read_b128 v[218:221], v160
	ds_read_b128 v[222:225], v160 offset:256
	s_waitcnt lgkmcnt(0)

; #define STAGE(P, BASE, br, kt) do { const char* _gb = (const char*)(BASE) + ((size_t)(br) * K + (size_t)(kt) * BK) * 2; \
;     __builtin_amdgcn_global_load_lds((const unsigned*)(_gb + loff0), (unsigned*)((char*)(P) + tid * 16), 16, 0, 0); \
;     __builtin_amdgcn_global_load_lds((const unsigned*)(_gb + (size_t)K * 128 + loff0), (unsigned*)((char*)(P) + tid * 16 + 8192), 16, 0, 0); } while (0)
; #define LDB(dst, b, h) for (int n = 0; n < 2; ++n) { \
;     dst[n][0] = *reinterpret_cast<const bf16x8*>((char*)SB(b, h) + boff0 + n * 256); \
;     dst[n][1] = *reinterpret_cast<const bf16x8*>((char*)SB(b, h) + boff1 + n * 256); }
; #define MMA(ai, bj, At, Btf) do { __builtin_amdgcn_s_setprio(1); \
;     for (int m = 0; m < 4; ++m) for (int n = 0; n < 2; ++n) for (int k = 0; k < 2; ++k) \
;       acc[ai][bj][m][n] = __builtin_amdgcn_mfma_f32_16x16x32_bf16(Btf[n][k], At[m][k], acc[ai][bj][m][n], 0, 0, 0); \
;     __builtin_amdgcn_s_setprio(0); } while (0)
; #define WAIT_L(n) asm volatile("s_waitcnt lgkmcnt(" #n ")" ::: "memory")
; #define BAR __builtin_amdgcn_s_barrier()
; #define SCHED __builtin_amdgcn_sched_barrier(0)
; template <int EPI> ...
;     ...
;     WAIT_L(8); BAR; WAIT_L(0); MMA(0, 0, At, B0); BAR; SCHED;
;     LDB(B1, 1, 1); STAGE(SB(1, 0), Bt, bcol, t + 3);
;     BAR; WAIT_L(0); MMA(0, 1, At, B1); BAR;
	s_barrier
	v_mfma_f32_16x16x32_bf16 v[124:127], v[162:165], v[178:181], v[124:127]
	v_mfma_f32_16x16x32_bf16 v[120:123], v[166:169], v[178:181], v[120:123]
	v_mfma_f32_16x16x32_bf16 v[116:119], v[162:165], v[186:189], v[116:119]
	v_mfma_f32_16x16x32_bf16 v[112:115], v[166:169], v[186:189], v[112:115]
	v_mfma_f32_16x16x32_bf16 v[108:111], v[162:165], v[194:197], v[108:111]
	v_mfma_f32_16x16x32_bf16 v[104:107], v[166:169], v[194:197], v[104:107]
	v_mfma_f32_16x16x32_bf16 v[100:103], v[162:165], v[202:205], v[100:103]
	v_mfma_f32_16x16x32_bf16 v[96:99], v[166:169], v[202:205], v[96:99]
	v_mfma_f32_16x16x32_bf16 v[124:127], v[170:173], v[182:185], v[124:127]
	v_mfma_f32_16x16x32_bf16 v[120:123], v[174:177], v[182:185], v[120:123]
	v_mfma_f32_16x16x32_bf16 v[116:119], v[170:173], v[190:193], v[116:119]
	v_mfma_f32_16x16x32_bf16 v[112:115], v[174:177], v[190:193], v[112:115]
	v_mfma_f32_16x16x32_bf16 v[108:111], v[170:173], v[198:201], v[108:111]
	v_mfma_f32_16x16x32_bf16 v[104:107], v[174:177], v[198:201], v[104:107]
	v_mfma_f32_16x16x32_bf16 v[100:103], v[170:173], v[206:209], v[100:103]
	v_mfma_f32_16x16x32_bf16 v[96:99], v[174:177], v[206:209], v[96:99]
	v_mfma_f32_16x16x32_bf16 v[92:95], v[210:213], v[178:181], v[92:95]
	v_mfma_f32_16x16x32_bf16 v[88:91], v[214:217], v[178:181], v[88:91]
	v_mfma_f32_16x16x32_bf16 v[84:87], v[210:213], v[186:189], v[84:87]
	v_mfma_f32_16x16x32_bf16 v[80:83], v[214:217], v[186:189], v[80:83]
	v_mfma_f32_16x16x32_bf16 v[76:79], v[210:213], v[194:197], v[76:79]
	v_mfma_f32_16x16x32_bf16 v[72:75], v[214:217], v[194:197], v[72:75]
	v_mfma_f32_16x16x32_bf16 v[68:71], v[210:213], v[202:205], v[68:71]
	v_mfma_f32_16x16x32_bf16 v[64:67], v[214:217], v[202:205], v[64:67]
	v_mfma_f32_16x16x32_bf16 v[92:95], v[218:221], v[182:185], v[92:95]
	v_mfma_f32_16x16x32_bf16 v[88:91], v[222:225], v[182:185], v[88:91]
	v_mfma_f32_16x16x32_bf16 v[84:87], v[218:221], v[190:193], v[84:87]
	v_mfma_f32_16x16x32_bf16 v[80:83], v[222:225], v[190:193], v[80:83]
	v_mfma_f32_16x16x32_bf16 v[76:79], v[218:221], v[198:201], v[76:79]
	v_mfma_f32_16x16x32_bf16 v[72:75], v[222:225], v[198:201], v[72:75]
	v_mfma_f32_16x16x32_bf16 v[68:71], v[218:221], v[206:209], v[68:71]
	v_mfma_f32_16x16x32_bf16 v[64:67], v[222:225], v[206:209], v[64:67]
	s_barrier

; #define STAGE(P, BASE, br, kt) do { const char* _gb = (const char*)(BASE) + ((size_t)(br) * K + (size_t)(kt) * BK) * 2; \
;     __builtin_amdgcn_global_load_lds((const unsigned*)(_gb + loff0), (unsigned*)((char*)(P) + tid * 16), 16, 0, 0); \
;     __builtin_amdgcn_global_load_lds((const unsigned*)(_gb + (size_t)K * 128 + loff0), (unsigned*)((char*)(P) + tid * 16 + 8192), 16, 0, 0); } while (0)
; #define LDA(dst, b, h) for (int m = 0; m < 4; ++m) { \
;     dst[m][0] = *reinterpret_cast<const bf16x8*>((char*)SA(b, h) + aoff0 + m * 2048); \
;     dst[m][1] = *reinterpret_cast<const bf16x8*>((char*)SA(b, h) + aoff1 + m * 2048); }
; #define MMA(ai, bj, At, Btf) do { __builtin_amdgcn_s_setprio(1); \
;     for (int m = 0; m < 4; ++m) for (int n = 0; n < 2; ++n) for (int k = 0; k < 2; ++k) \
;       acc[ai][bj][m][n] = __builtin_amdgcn_mfma_f32_16x16x32_bf16(Btf[n][k], At[m][k], acc[ai][bj][m][n], 0, 0, 0); \
;     __builtin_amdgcn_s_setprio(0); } while (0)
; #define WAIT_V(n) asm volatile("s_waitcnt vmcnt(" #n ")" ::: "memory")
; #define WAIT_L(n) asm volatile("s_waitcnt lgkmcnt(" #n ")" ::: "memory")
; #define BAR __builtin_amdgcn_s_barrier()
; #define SCHED __builtin_amdgcn_sched_barrier(0)
; template <int EPI> ...
;     ...
;     LDA(At, 1, 1); STAGE(SA(1, 0), A, brow, t + 3);
;     BAR; WAIT_L(0); MMA(1, 0, At, B0); BAR; SCHED;
;     STAGE(SB(1, 1), Bt, bcol + HALF, t + 3);
;     WAIT_V(6); BAR; MMA(1, 1, At, B1); BAR;
	v_readfirstlane_b32 s72, v144
	v_lshl_add_u64 v[230:231], v[228:229], 0, s[50:51]
	s_mov_b32 m0, s72
	v_readfirstlane_b32 s72, v145
	global_load_lds_dwordx4 v[230:231], off
	v_lshl_add_u64 v[230:231], v[228:229], 0, s[52:53]
	s_mov_b32 m0, s72
	s_nop 0
	global_load_lds_dwordx4 v[230:231], off
	v_readfirstlane_b32 s72, v146
	v_lshl_add_u64 v[230:231], v[226:227], 0, s[54:55]
	s_mov_b32 m0, s72
	v_readfirstlane_b32 s72, v147
	ds_read_b128 v[178:181], v150 offset:49152
	ds_read_b128 v[182:185], v150 offset:50176
	ds_read_b128 v[186:189], v150 offset:51200
	ds_read_b128 v[190:193], v150 offset:52224
	ds_read_b128 v[194:197], v150 offset:53248
	ds_read_b128 v[198:201], v150 offset:54272
	ds_read_b128 v[202:205], v150 offset:55296
	ds_read_b128 v[206:209], v150 offset:56320
	global_load_lds_dwordx4 v[230:231], off
	v_lshl_add_u64 v[226:227], v[226:227], 0, s[56:57]
	s_mov_b32 m0, s72
	s_nop 0
	global_load_lds_dwordx4 v[226:227], off
	v_readfirstlane_b32 s72, v148
	v_lshl_add_u64 v[246:247], v[228:229], 0, s[58:59]
	s_mov_b32 m0, s72
	v_readfirstlane_b32 s72, v149
	global_load_lds_dwordx4 v[246:247], off
	s_waitcnt vmcnt(5)
	s_barrier
	s_waitcnt lgkmcnt(0)

; #define MMA(ai, bj, At, Btf) do { __builtin_amdgcn_s_setprio(1); \
;     for (int m = 0; m < 4; ++m) for (int n = 0; n < 2; ++n) for (int k = 0; k < 2; ++k) \
;       acc[ai][bj][m][n] = __builtin_amdgcn_mfma_f32_16x16x32_bf16(Btf[n][k], At[m][k], acc[ai][bj][m][n], 0, 0, 0); \
;     __builtin_amdgcn_s_setprio(0); } while (0)
; #define WAIT_L(n) asm volatile("s_waitcnt lgkmcnt(" #n ")" ::: "memory")
; #define BAR __builtin_amdgcn_s_barrier()
; #define SCHED __builtin_amdgcn_sched_barrier(0)
; template <int EPI> ...
;     ...
;     BAR; WAIT_L(0); MMA(1, 0, At, B0); BAR; SCHED;
	s_waitcnt lgkmcnt(0)
	v_mfma_f32_16x16x32_bf16 v[60:63], v[162:165], v[178:181], v[60:63]
	v_mfma_f32_16x16x32_bf16 v[56:59], v[166:169], v[178:181], v[56:59]
	v_mfma_f32_16x16x32_bf16 v[52:55], v[162:165], v[186:189], v[52:55]
	v_mfma_f32_16x16x32_bf16 v[48:51], v[166:169], v[186:189], v[48:51]
	v_mfma_f32_16x16x32_bf16 v[44:47], v[162:165], v[194:197], v[44:47]
	v_mfma_f32_16x16x32_bf16 v[40:43], v[166:169], v[194:197], v[40:43]
	v_mfma_f32_16x16x32_bf16 v[36:39], v[162:165], v[202:205], v[36:39]
	v_mfma_f32_16x16x32_bf16 v[32:35], v[166:169], v[202:205], v[32:35]
	v_mfma_f32_16x16x32_bf16 v[60:63], v[170:173], v[182:185], v[60:63]
	v_mfma_f32_16x16x32_bf16 v[56:59], v[174:177], v[182:185], v[56:59]
	v_mfma_f32_16x16x32_bf16 v[52:55], v[170:173], v[190:193], v[52:55]
	v_mfma_f32_16x16x32_bf16 v[48:51], v[174:177], v[190:193], v[48:51]
	v_mfma_f32_16x16x32_bf16 v[44:47], v[170:173], v[198:201], v[44:47]
	v_mfma_f32_16x16x32_bf16 v[40:43], v[174:177], v[198:201], v[40:43]
	v_mfma_f32_16x16x32_bf16 v[36:39], v[170:173], v[206:209], v[36:39]
	v_mfma_f32_16x16x32_bf16 v[32:35], v[174:177], v[206:209], v[32:35]


; #define MMA(ai, bj, At, Btf) do { __builtin_amdgcn_s_setprio(1); \
;     for (int m = 0; m < 4; ++m) for (int n = 0; n < 2; ++n) for (int k = 0; k < 2; ++k) \
;       acc[ai][bj][m][n] = __builtin_amdgcn_mfma_f32_16x16x32_bf16(Btf[n][k], At[m][k], acc[ai][bj][m][n], 0, 0, 0); \
;     __builtin_amdgcn_s_setprio(0); } while (0)
; #define WAIT_V(n) asm volatile("s_waitcnt vmcnt(" #n ")" ::: "memory")
; #define BAR __builtin_amdgcn_s_barrier()
; template <int EPI> ...
;     ...
;     WAIT_V(6); BAR; MMA(1, 1, At, B1); BAR;
	v_mfma_f32_16x16x32_bf16 v[28:31], v[210:213], v[178:181], v[28:31]
	v_mfma_f32_16x16x32_bf16 v[24:27], v[214:217], v[178:181], v[24:27]
	v_mfma_f32_16x16x32_bf16 v[20:23], v[210:213], v[186:189], v[20:23]
	v_mfma_f32_16x16x32_bf16 v[16:19], v[214:217], v[186:189], v[16:19]
	v_mfma_f32_16x16x32_bf16 v[12:15], v[210:213], v[194:197], v[12:15]
	v_mfma_f32_16x16x32_bf16 v[8:11], v[214:217], v[194:197], v[8:11]
	v_mfma_f32_16x16x32_bf16 v[4:7], v[210:213], v[202:205], v[4:7]
	v_mfma_f32_16x16x32_bf16 v[0:3], v[214:217], v[202:205], v[0:3]
	v_mfma_f32_16x16x32_bf16 v[28:31], v[218:221], v[182:185], v[28:31]
	v_mfma_f32_16x16x32_bf16 v[24:27], v[222:225], v[182:185], v[24:27]
	v_mfma_f32_16x16x32_bf16 v[20:23], v[218:221], v[190:193], v[20:23]
	v_mfma_f32_16x16x32_bf16 v[16:19], v[222:225], v[190:193], v[16:19]
	v_mfma_f32_16x16x32_bf16 v[12:15], v[218:221], v[198:201], v[12:15]
	v_mfma_f32_16x16x32_bf16 v[8:11], v[222:225], v[198:201], v[8:11]
	v_mfma_f32_16x16x32_bf16 v[4:7], v[218:221], v[206:209], v[4:7]
	v_mfma_f32_16x16x32_bf16 v[0:3], v[222:225], v[206:209], v[0:3]

; #define STAGE(P, BASE, br, kt) do { const char* _gb = (const char*)(BASE) + ((size_t)(br) * K + (size_t)(kt) * BK) * 2; \
;     __builtin_amdgcn_global_load_lds((const unsigned*)(_gb + loff0), (unsigned*)((char*)(P) + tid * 16), 16, 0, 0); \
;     __builtin_amdgcn_global_load_lds((const unsigned*)(_gb + (size_t)K * 128 + loff0), (unsigned*)((char*)(P) + tid * 16 + 8192), 16, 0, 0); } while (0)
; #define LDA(dst, b, h) for (int m = 0; m < 4; ++m) { \
;     dst[m][0] = *reinterpret_cast<const bf16x8*>((char*)SA(b, h) + aoff0 + m * 2048); \
;     dst[m][1] = *reinterpret_cast<const bf16x8*>((char*)SA(b, h) + aoff1 + m * 2048); }
; #define LDB(dst, b, h) for (int n = 0; n < 2; ++n) { \
;     dst[n][0] = *reinterpret_cast<const bf16x8*>((char*)SB(b, h) + boff0 + n * 256); \
;     dst[n][1] = *reinterpret_cast<const bf16x8*>((char*)SB(b, h) + boff1 + n * 256); }
; #define MMA(ai, bj, At, Btf) do { __builtin_amdgcn_s_setprio(1); \
;     for (int m = 0; m < 4; ++m) for (int n = 0; n < 2; ++n) for (int k = 0; k < 2; ++k) \
;       acc[ai][bj][m][n] = __builtin_amdgcn_mfma_f32_16x16x32_bf16(Btf[n][k], At[m][k], acc[ai][bj][m][n], 0, 0, 0); \
;     __builtin_amdgcn_s_setprio(0); } while (0)
; #define WAIT_V(n) asm volatile("s_waitcnt vmcnt(" #n ")" ::: "memory")
; #define BAR __builtin_amdgcn_s_barrier()
; template <int EPI> ...
;     ...
;   for (int t = 0; t < nt - 2; t += 2) {
;     ...
;     WAIT_V(6); BAR; MMA(1, 1, At, B1); BAR;
;   }
;   { LDB(B0, 0, 0); LDA(At, 0, 0); STAGE(SA(1, 1), A, brow + HALF, nt - 1);
	s_add_i32 s67, s67, 2
	s_add_u32 s70, s70, 0x100
	s_addc_u32 s71, s71, 0
	s_add_u32 s68, s68, 0x100
	s_addc_u32 s69, s69, 0
	s_cmp_lt_u32 s67, 28
	s_barrier
	s_cbranch_scc1 .LBB0_277
	v_readfirstlane_b32 s72, v149
	v_lshl_add_u64 v[246:247], v[228:229], 0, s[60:61]
	s_mov_b32 m0, s72
	s_nop 0
	global_load_lds_dwordx4 v[246:247], off
	v_readfirstlane_b32 s67, v151
	v_lshl_add_u64 v[210:211], v[132:133], 0, s[62:63]
	s_mov_b32 m0, s67
	v_readfirstlane_b32 s67, v152
	ds_read_b128 v[162:165], v153
	ds_read_b128 v[166:169], v153 offset:256
	ds_read_b128 v[170:173], v154
	ds_read_b128 v[174:177], v154 offset:256
	ds_read_b128 v[178:181], v150
	ds_read_b128 v[182:185], v150 offset:1024
	ds_read_b128 v[186:189], v150 offset:2048
	ds_read_b128 v[190:193], v150 offset:3072
	ds_read_b128 v[194:197], v150 offset:4096
	ds_read_b128 v[198:201], v150 offset:5120
	ds_read_b128 v[202:205], v150 offset:6144
	ds_read_b128 v[206:209], v150 offset:7168
	global_load_lds_dwordx4 v[210:211], off
	v_lshl_add_u64 v[132:133], v[132:133], 0, s[64:65]
	s_mov_b32 m0, s67
	s_nop 0
	global_load_lds_dwordx4 v[132:133], off
	s_waitcnt lgkmcnt(0)

; #define STAGE(P, BASE, br, kt) do { const char* _gb = (const char*)(BASE) + ((size_t)(br) * K + (size_t)(kt) * BK) * 2; \
;     __builtin_amdgcn_global_load_lds((const unsigned*)(_gb + loff0), (unsigned*)((char*)(P) + tid * 16), 16, 0, 0); \
;     __builtin_amdgcn_global_load_lds((const unsigned*)(_gb + (size_t)K * 128 + loff0), (unsigned*)((char*)(P) + tid * 16 + 8192), 16, 0, 0); } while (0)
; #define LDA(dst, b, h) for (int m = 0; m < 4; ++m) { \
;     dst[m][0] = *reinterpret_cast<const bf16x8*>((char*)SA(b, h) + aoff0 + m * 2048); \
;     dst[m][1] = *reinterpret_cast<const bf16x8*>((char*)SA(b, h) + aoff1 + m * 2048); }
; #define LDB(dst, b, h) for (int n = 0; n < 2; ++n) { \
;     dst[n][0] = *reinterpret_cast<const bf16x8*>((char*)SB(b, h) + boff0 + n * 256); \
;     dst[n][1] = *reinterpret_cast<const bf16x8*>((char*)SB(b, h) + boff1 + n * 256); }
; #define MMA(ai, bj, At, Btf) do { __builtin_amdgcn_s_setprio(1); \
;     for (int m = 0; m < 4; ++m) for (int n = 0; n < 2; ++n) for (int k = 0; k < 2; ++k) \
;       acc[ai][bj][m][n] = __builtin_amdgcn_mfma_f32_16x16x32_bf16(Btf[n][k], At[m][k], acc[ai][bj][m][n], 0, 0, 0); \
;     __builtin_amdgcn_s_setprio(0); } while (0)
; #define WAIT_L(n) asm volatile("s_waitcnt lgkmcnt(" #n ")" ::: "memory")
; #define BAR __builtin_amdgcn_s_barrier()
; template <int EPI> ...
;     ...
;   { LDB(B0, 0, 0); LDA(At, 0, 0); STAGE(SA(1, 1), A, brow + HALF, nt - 1);
;     BAR; WAIT_L(0); MMA(0, 0, At, B0); BAR;
	s_barrier
	v_mfma_f32_16x16x32_bf16 v[124:127], v[162:165], v[178:181], v[124:127]
	v_mfma_f32_16x16x32_bf16 v[116:119], v[162:165], v[186:189], v[116:119]
	v_mfma_f32_16x16x32_bf16 v[108:111], v[162:165], v[194:197], v[108:111]
	v_mfma_f32_16x16x32_bf16 v[100:103], v[162:165], v[202:205], v[100:103]
	v_mfma_f32_16x16x32_bf16 v[124:127], v[170:173], v[182:185], v[124:127]
	v_mfma_f32_16x16x32_bf16 v[120:123], v[166:169], v[178:181], v[120:123]
	v_mfma_f32_16x16x32_bf16 v[116:119], v[170:173], v[190:193], v[116:119]
	v_mfma_f32_16x16x32_bf16 v[112:115], v[166:169], v[186:189], v[112:115]
	v_mfma_f32_16x16x32_bf16 v[108:111], v[170:173], v[198:201], v[108:111]
	v_mfma_f32_16x16x32_bf16 v[104:107], v[166:169], v[194:197], v[104:107]
	v_mfma_f32_16x16x32_bf16 v[100:103], v[170:173], v[206:209], v[100:103]
	v_mfma_f32_16x16x32_bf16 v[96:99], v[166:169], v[202:205], v[96:99]
	v_mfma_f32_16x16x32_bf16 v[210:213], v[174:177], v[182:185], v[120:123]
	v_mfma_f32_16x16x32_bf16 v[214:217], v[174:177], v[190:193], v[112:115]
	v_mfma_f32_16x16x32_bf16 v[218:221], v[174:177], v[198:201], v[104:107]
	v_mfma_f32_16x16x32_bf16 v[222:225], v[174:177], v[206:209], v[96:99]
	s_barrier

; #define LDB(dst, b, h) for (int n = 0; n < 2; ++n) { \
;     dst[n][0] = *reinterpret_cast<const bf16x8*>((char*)SB(b, h) + boff0 + n * 256); \
;     dst[n][1] = *reinterpret_cast<const bf16x8*>((char*)SB(b, h) + boff1 + n * 256); }
; #define MMA(ai, bj, At, Btf) do { __builtin_amdgcn_s_setprio(1); \
;     for (int m = 0; m < 4; ++m) for (int n = 0; n < 2; ++n) for (int k = 0; k < 2; ++k) \
;       acc[ai][bj][m][n] = __builtin_amdgcn_mfma_f32_16x16x32_bf16(Btf[n][k], At[m][k], acc[ai][bj][m][n], 0, 0, 0); \
;     __builtin_amdgcn_s_setprio(0); } while (0)
; #define WAIT_L(n) asm volatile("s_waitcnt lgkmcnt(" #n ")" ::: "memory")
; #define BAR __builtin_amdgcn_s_barrier()
; template <int EPI> ...
;     ...
;     LDB(B1, 0, 1); BAR; WAIT_L(0); MMA(0, 1, At, B1); BAR;
	s_nop 1
	ds_read_b128 v[96:99], v155
	ds_read_b128 v[104:107], v155 offset:256
	ds_read_b128 v[112:115], v156
	ds_read_b128 v[120:123], v156 offset:256
	s_waitcnt lgkmcnt(0)

; #define LDB(dst, b, h) for (int n = 0; n < 2; ++n) { \
;     dst[n][0] = *reinterpret_cast<const bf16x8*>((char*)SB(b, h) + boff0 + n * 256); \
;     dst[n][1] = *reinterpret_cast<const bf16x8*>((char*)SB(b, h) + boff1 + n * 256); }
; #define MMA(ai, bj, At, Btf) do { __builtin_amdgcn_s_setprio(1); \
;     for (int m = 0; m < 4; ++m) for (int n = 0; n < 2; ++n) for (int k = 0; k < 2; ++k) \
;       acc[ai][bj][m][n] = __builtin_amdgcn_mfma_f32_16x16x32_bf16(Btf[n][k], At[m][k], acc[ai][bj][m][n], 0, 0, 0); \
;     __builtin_amdgcn_s_setprio(0); } while (0)
; #define WAIT_L(n) asm volatile("s_waitcnt lgkmcnt(" #n ")" ::: "memory")
; #define BAR __builtin_amdgcn_s_barrier()
; template <int EPI> ...
;     ...
;     LDB(B1, 0, 1); BAR; WAIT_L(0); MMA(0, 1, At, B1); BAR;
	s_barrier
	v_mfma_f32_16x16x32_bf16 v[92:95], v[96:99], v[178:181], v[92:95]
	v_mfma_f32_16x16x32_bf16 v[84:87], v[96:99], v[186:189], v[84:87]
	v_mfma_f32_16x16x32_bf16 v[76:79], v[96:99], v[194:197], v[76:79]
	v_mfma_f32_16x16x32_bf16 v[68:71], v[96:99], v[202:205], v[68:71]
	v_mfma_f32_16x16x32_bf16 v[92:95], v[112:115], v[182:185], v[92:95]
	v_mfma_f32_16x16x32_bf16 v[88:91], v[104:107], v[178:181], v[88:91]
	v_mfma_f32_16x16x32_bf16 v[84:87], v[112:115], v[190:193], v[84:87]
	v_mfma_f32_16x16x32_bf16 v[80:83], v[104:107], v[186:189], v[80:83]
	v_mfma_f32_16x16x32_bf16 v[76:79], v[112:115], v[198:201], v[76:79]
	v_mfma_f32_16x16x32_bf16 v[72:75], v[104:107], v[194:197], v[72:75]
	v_mfma_f32_16x16x32_bf16 v[68:71], v[112:115], v[206:209], v[68:71]
	v_mfma_f32_16x16x32_bf16 v[64:67], v[104:107], v[202:205], v[64:67]
	v_mfma_f32_16x16x32_bf16 v[178:181], v[120:123], v[182:185], v[88:91]
	v_mfma_f32_16x16x32_bf16 v[182:185], v[120:123], v[190:193], v[80:83]
	v_mfma_f32_16x16x32_bf16 v[186:189], v[120:123], v[198:201], v[72:75]
	v_mfma_f32_16x16x32_bf16 v[190:193], v[120:123], v[206:209], v[64:67]
	s_barrier

; #define LDA(dst, b, h) for (int m = 0; m < 4; ++m) { \
;     dst[m][0] = *reinterpret_cast<const bf16x8*>((char*)SA(b, h) + aoff0 + m * 2048); \
;     dst[m][1] = *reinterpret_cast<const bf16x8*>((char*)SA(b, h) + aoff1 + m * 2048); }
; #define MMA(ai, bj, At, Btf) do { __builtin_amdgcn_s_setprio(1); \
;     for (int m = 0; m < 4; ++m) for (int n = 0; n < 2; ++n) for (int k = 0; k < 2; ++k) \
;       acc[ai][bj][m][n] = __builtin_amdgcn_mfma_f32_16x16x32_bf16(Btf[n][k], At[m][k], acc[ai][bj][m][n], 0, 0, 0); \
;     __builtin_amdgcn_s_setprio(0); } while (0)
; #define WAIT_V(n) asm volatile("s_waitcnt vmcnt(" #n ")" ::: "memory")
; #define WAIT_L(n) asm volatile("s_waitcnt lgkmcnt(" #n ")" ::: "memory")
; #define BAR __builtin_amdgcn_s_barrier()
; template <int EPI> ...
;     ...
;     LDA(At, 0, 1); WAIT_V(4); BAR; WAIT_L(0); MMA(1, 0, At, B0); MMA(1, 1, At, B1); BAR; }
	s_nop 1
	ds_read_b128 v[64:67], v150 offset:16384
	ds_read_b128 v[72:75], v150 offset:17408
	ds_read_b128 v[80:83], v150 offset:18432
	ds_read_b128 v[88:91], v150 offset:19456
	ds_read_b128 v[194:197], v150 offset:20480
	ds_read_b128 v[198:201], v150 offset:21504
	ds_read_b128 v[202:205], v150 offset:22528
	ds_read_b128 v[206:209], v150 offset:23552
	s_waitcnt vmcnt(4)
	s_waitcnt lgkmcnt(0)

; #define LDA(dst, b, h) for (int m = 0; m < 4; ++m) { \
;     dst[m][0] = *reinterpret_cast<const bf16x8*>((char*)SA(b, h) + aoff0 + m * 2048); \
;     dst[m][1] = *reinterpret_cast<const bf16x8*>((char*)SA(b, h) + aoff1 + m * 2048); }
; #define MMA(ai, bj, At, Btf) do { __builtin_amdgcn_s_setprio(1); \
;     for (int m = 0; m < 4; ++m) for (int n = 0; n < 2; ++n) for (int k = 0; k < 2; ++k) \
;       acc[ai][bj][m][n] = __builtin_amdgcn_mfma_f32_16x16x32_bf16(Btf[n][k], At[m][k], acc[ai][bj][m][n], 0, 0, 0); \
;     __builtin_amdgcn_s_setprio(0); } while (0)
; #define WAIT_V(n) asm volatile("s_waitcnt vmcnt(" #n ")" ::: "memory")
; #define WAIT_L(n) asm volatile("s_waitcnt lgkmcnt(" #n ")" ::: "memory")
; #define BAR __builtin_amdgcn_s_barrier()
; template <int EPI> ...
;     ...
;     LDA(At, 0, 1); WAIT_V(4); BAR; WAIT_L(0); MMA(1, 0, At, B0); MMA(1, 1, At, B1); BAR; }
	s_barrier
	v_mfma_f32_16x16x32_bf16 v[60:63], v[162:165], v[64:67], v[60:63]
	v_mfma_f32_16x16x32_bf16 v[56:59], v[166:169], v[64:67], v[56:59]
	v_mfma_f32_16x16x32_bf16 v[52:55], v[162:165], v[80:83], v[52:55]
	v_mfma_f32_16x16x32_bf16 v[40:43], v[166:169], v[194:197], v[40:43]
	v_mfma_f32_16x16x32_bf16 v[36:39], v[162:165], v[202:205], v[36:39]
	v_mfma_f32_16x16x32_bf16 v[60:63], v[170:173], v[72:75], v[60:63]
	v_mfma_f32_16x16x32_bf16 v[56:59], v[174:177], v[72:75], v[56:59]
	v_mfma_f32_16x16x32_bf16 v[52:55], v[170:173], v[88:91], v[52:55]
	v_mfma_f32_16x16x32_bf16 v[48:51], v[166:169], v[80:83], v[48:51]
	v_mfma_f32_16x16x32_bf16 v[44:47], v[162:165], v[194:197], v[44:47]
	v_mfma_f32_16x16x32_bf16 v[40:43], v[174:177], v[198:201], v[40:43]
	v_mfma_f32_16x16x32_bf16 v[36:39], v[170:173], v[206:209], v[36:39]
	v_mfma_f32_16x16x32_bf16 v[32:35], v[166:169], v[202:205], v[32:35]
	v_mfma_f32_16x16x32_bf16 v[226:229], v[174:177], v[88:91], v[48:51]
	v_mfma_f32_16x16x32_bf16 v[230:233], v[170:173], v[198:201], v[44:47]
	v_mfma_f32_16x16x32_bf16 v[162:165], v[174:177], v[206:209], v[32:35]
	v_mfma_f32_16x16x32_bf16 v[24:27], v[104:107], v[64:67], v[24:27]
	v_mfma_f32_16x16x32_bf16 v[20:23], v[96:99], v[80:83], v[20:23]
	v_mfma_f32_16x16x32_bf16 v[8:11], v[104:107], v[194:197], v[8:11]
	v_mfma_f32_16x16x32_bf16 v[4:7], v[96:99], v[202:205], v[4:7]
	v_mfma_f32_16x16x32_bf16 v[28:31], v[96:99], v[64:67], v[28:31]
	v_mfma_f32_16x16x32_bf16 v[24:27], v[120:123], v[72:75], v[24:27]
	v_mfma_f32_16x16x32_bf16 v[20:23], v[112:115], v[88:91], v[20:23]
	v_mfma_f32_16x16x32_bf16 v[16:19], v[104:107], v[80:83], v[16:19]
	v_mfma_f32_16x16x32_bf16 v[12:15], v[96:99], v[194:197], v[12:15]
	v_mfma_f32_16x16x32_bf16 v[8:11], v[120:123], v[198:201], v[8:11]
	v_mfma_f32_16x16x32_bf16 v[4:7], v[112:115], v[206:209], v[4:7]
	v_mfma_f32_16x16x32_bf16 v[0:3], v[104:107], v[202:205], v[0:3]
	v_mfma_f32_16x16x32_bf16 v[166:169], v[112:115], v[72:75], v[28:31]
	v_mfma_f32_16x16x32_bf16 v[170:173], v[120:123], v[88:91], v[16:19]
	v_mfma_f32_16x16x32_bf16 v[174:177], v[112:115], v[198:201], v[12:15]
	v_mfma_f32_16x16x32_bf16 v[194:197], v[120:123], v[206:209], v[0:3]
	s_barrier

; #define LDA(dst, b, h) for (int m = 0; m < 4; ++m) { \
;     dst[m][0] = *reinterpret_cast<const bf16x8*>((char*)SA(b, h) + aoff0 + m * 2048); \
;     dst[m][1] = *reinterpret_cast<const bf16x8*>((char*)SA(b, h) + aoff1 + m * 2048); }
; #define LDB(dst, b, h) for (int n = 0; n < 2; ++n) { \
;     dst[n][0] = *reinterpret_cast<const bf16x8*>((char*)SB(b, h) + boff0 + n * 256); \
;     dst[n][1] = *reinterpret_cast<const bf16x8*>((char*)SB(b, h) + boff1 + n * 256); }
; #define MMA(ai, bj, At, Btf) do { __builtin_amdgcn_s_setprio(1); \
;     for (int m = 0; m < 4; ++m) for (int n = 0; n < 2; ++n) for (int k = 0; k < 2; ++k) \
;       acc[ai][bj][m][n] = __builtin_amdgcn_mfma_f32_16x16x32_bf16(Btf[n][k], At[m][k], acc[ai][bj][m][n], 0, 0, 0); \
;     __builtin_amdgcn_s_setprio(0); } while (0)
; #define WAIT_V(n) asm volatile("s_waitcnt vmcnt(" #n ")" ::: "memory")
; #define WAIT_L(n) asm volatile("s_waitcnt lgkmcnt(" #n ")" ::: "memory")
; #define BAR __builtin_amdgcn_s_barrier()
; template <int EPI> ...
;     ...
;   { LDB(B0, 1, 0); LDA(At, 1, 0); WAIT_V(2); BAR; WAIT_L(0); MMA(0, 0, At, B0); BAR;
	s_nop 1
	ds_read_b128 v[0:3], v157
	ds_read_b128 v[198:201], v157 offset:256
	ds_read_b128 v[12:15], v158
	ds_read_b128 v[202:205], v158 offset:256
	ds_read_b128 v[16:19], v150 offset:32768
	ds_read_b128 v[28:31], v150 offset:33792
	ds_read_b128 v[32:35], v150 offset:34816
	ds_read_b128 v[44:47], v150 offset:35840
	ds_read_b128 v[48:51], v150 offset:36864
	ds_read_b128 v[206:209], v150 offset:37888
	ds_read_b128 v[234:237], v150 offset:38912
	ds_read_b128 v[238:241], v150 offset:39936
	s_waitcnt vmcnt(2)
	s_waitcnt lgkmcnt(0)

; #define LDA(dst, b, h) for (int m = 0; m < 4; ++m) { \
;     dst[m][0] = *reinterpret_cast<const bf16x8*>((char*)SA(b, h) + aoff0 + m * 2048); \
;     dst[m][1] = *reinterpret_cast<const bf16x8*>((char*)SA(b, h) + aoff1 + m * 2048); }
; #define LDB(dst, b, h) for (int n = 0; n < 2; ++n) { \
;     dst[n][0] = *reinterpret_cast<const bf16x8*>((char*)SB(b, h) + boff0 + n * 256); \
;     dst[n][1] = *reinterpret_cast<const bf16x8*>((char*)SB(b, h) + boff1 + n * 256); }
; #define MMA(ai, bj, At, Btf) do { __builtin_amdgcn_s_setprio(1); \
;     for (int m = 0; m < 4; ++m) for (int n = 0; n < 2; ++n) for (int k = 0; k < 2; ++k) \
;       acc[ai][bj][m][n] = __builtin_amdgcn_mfma_f32_16x16x32_bf16(Btf[n][k], At[m][k], acc[ai][bj][m][n], 0, 0, 0); \
;     __builtin_amdgcn_s_setprio(0); } while (0)
; #define WAIT_V(n) asm volatile("s_waitcnt vmcnt(" #n ")" ::: "memory")
; #define WAIT_L(n) asm volatile("s_waitcnt lgkmcnt(" #n ")" ::: "memory")
; #define BAR __builtin_amdgcn_s_barrier()
; template <int EPI> ...
;     ...
;   { LDB(B0, 1, 0); LDA(At, 1, 0); WAIT_V(2); BAR; WAIT_L(0); MMA(0, 0, At, B0); BAR;
	s_barrier
	v_mfma_f32_16x16x32_bf16 v[64:67], v[0:3], v[16:19], v[124:127]
	v_mfma_f32_16x16x32_bf16 v[120:123], v[12:15], v[28:31], v[64:67]
	v_mfma_f32_16x16x32_bf16 v[64:67], v[198:201], v[16:19], v[210:213]
	v_mfma_f32_16x16x32_bf16 v[112:115], v[202:205], v[28:31], v[64:67]
	v_mfma_f32_16x16x32_bf16 v[64:67], v[0:3], v[32:35], v[116:119]
	v_mfma_f32_16x16x32_bf16 v[104:107], v[12:15], v[44:47], v[64:67]
	v_mfma_f32_16x16x32_bf16 v[64:67], v[198:201], v[32:35], v[214:217]
	v_mfma_f32_16x16x32_bf16 v[96:99], v[202:205], v[44:47], v[64:67]
	v_mfma_f32_16x16x32_bf16 v[64:67], v[0:3], v[48:51], v[108:111]
	v_mfma_f32_16x16x32_bf16 v[88:91], v[12:15], v[206:209], v[64:67]
	v_mfma_f32_16x16x32_bf16 v[64:67], v[198:201], v[48:51], v[218:221]
	v_mfma_f32_16x16x32_bf16 v[80:83], v[202:205], v[206:209], v[64:67]
	v_mfma_f32_16x16x32_bf16 v[64:67], v[0:3], v[234:237], v[100:103]
	v_mfma_f32_16x16x32_bf16 v[72:75], v[12:15], v[238:241], v[64:67]
	v_mfma_f32_16x16x32_bf16 v[64:67], v[198:201], v[234:237], v[222:225]
	v_mfma_f32_16x16x32_bf16 v[64:67], v[202:205], v[238:241], v[64:67]
	s_barrier

; #define LDB(dst, b, h) for (int n = 0; n < 2; ++n) { \
;     dst[n][0] = *reinterpret_cast<const bf16x8*>((char*)SB(b, h) + boff0 + n * 256); \
;     dst[n][1] = *reinterpret_cast<const bf16x8*>((char*)SB(b, h) + boff1 + n * 256); }
; #define MMA(ai, bj, At, Btf) do { __builtin_amdgcn_s_setprio(1); \
;     for (int m = 0; m < 4; ++m) for (int n = 0; n < 2; ++n) for (int k = 0; k < 2; ++k) \
;       acc[ai][bj][m][n] = __builtin_amdgcn_mfma_f32_16x16x32_bf16(Btf[n][k], At[m][k], acc[ai][bj][m][n], 0, 0, 0); \
;     __builtin_amdgcn_s_setprio(0); } while (0)
; #define WAIT_V(n) asm volatile("s_waitcnt vmcnt(" #n ")" ::: "memory")
; #define WAIT_L(n) asm volatile("s_waitcnt lgkmcnt(" #n ")" ::: "memory")
; #define BAR __builtin_amdgcn_s_barrier()
; template <int EPI> ...
;     ...
;     LDB(B1, 1, 1); WAIT_V(0); BAR; WAIT_L(0); MMA(0, 1, At, B1); BAR;
	ds_read_b128 v[210:213], v159
	ds_read_b128 v[214:217], v159 offset:256
	ds_read_b128 v[218:221], v160
	ds_read_b128 v[222:225], v160 offset:256
	s_waitcnt vmcnt(0)
	s_waitcnt lgkmcnt(0)

; #define LDB(dst, b, h) for (int n = 0; n < 2; ++n) { \
;     dst[n][0] = *reinterpret_cast<const bf16x8*>((char*)SB(b, h) + boff0 + n * 256); \
;     dst[n][1] = *reinterpret_cast<const bf16x8*>((char*)SB(b, h) + boff1 + n * 256); }
; #define MMA(ai, bj, At, Btf) do { __builtin_amdgcn_s_setprio(1); \
;     for (int m = 0; m < 4; ++m) for (int n = 0; n < 2; ++n) for (int k = 0; k < 2; ++k) \
;       acc[ai][bj][m][n] = __builtin_amdgcn_mfma_f32_16x16x32_bf16(Btf[n][k], At[m][k], acc[ai][bj][m][n], 0, 0, 0); \
;     __builtin_amdgcn_s_setprio(0); } while (0)
; #define WAIT_V(n) asm volatile("s_waitcnt vmcnt(" #n ")" ::: "memory")
; #define WAIT_L(n) asm volatile("s_waitcnt lgkmcnt(" #n ")" ::: "memory")
; #define BAR __builtin_amdgcn_s_barrier()
; template <int EPI> ...
;     ...
;     LDB(B1, 1, 1); WAIT_V(0); BAR; WAIT_L(0); MMA(0, 1, At, B1); BAR;
	s_barrier
	v_mfma_f32_16x16x32_bf16 v[92:95], v[210:213], v[16:19], v[92:95]
	v_mfma_f32_16x16x32_bf16 v[16:19], v[214:217], v[16:19], v[178:181]
	v_mfma_f32_16x16x32_bf16 v[116:119], v[222:225], v[28:31], v[16:19]
	v_mfma_f32_16x16x32_bf16 v[16:19], v[210:213], v[32:35], v[84:87]
	v_mfma_f32_16x16x32_bf16 v[108:111], v[218:221], v[44:47], v[16:19]
	v_mfma_f32_16x16x32_bf16 v[16:19], v[214:217], v[32:35], v[182:185]
	v_mfma_f32_16x16x32_bf16 v[100:103], v[222:225], v[44:47], v[16:19]
	v_mfma_f32_16x16x32_bf16 v[16:19], v[210:213], v[48:51], v[76:79]
	v_mfma_f32_16x16x32_bf16 v[124:127], v[218:221], v[28:31], v[92:95]
	v_mfma_f32_16x16x32_bf16 v[92:95], v[218:221], v[206:209], v[16:19]
	v_mfma_f32_16x16x32_bf16 v[16:19], v[214:217], v[48:51], v[186:189]
	v_mfma_f32_16x16x32_bf16 v[84:87], v[222:225], v[206:209], v[16:19]
	v_mfma_f32_16x16x32_bf16 v[16:19], v[210:213], v[234:237], v[68:71]
	v_mfma_f32_16x16x32_bf16 v[76:79], v[218:221], v[238:241], v[16:19]
	v_mfma_f32_16x16x32_bf16 v[16:19], v[214:217], v[234:237], v[190:193]
	v_mfma_f32_16x16x32_bf16 v[68:71], v[222:225], v[238:241], v[16:19]
	s_barrier

; #define LDA(dst, b, h) for (int m = 0; m < 4; ++m) { \
;     dst[m][0] = *reinterpret_cast<const bf16x8*>((char*)SA(b, h) + aoff0 + m * 2048); \
;     dst[m][1] = *reinterpret_cast<const bf16x8*>((char*)SA(b, h) + aoff1 + m * 2048); }
; #define MMA(ai, bj, At, Btf) do { __builtin_amdgcn_s_setprio(1); \
;     for (int m = 0; m < 4; ++m) for (int n = 0; n < 2; ++n) for (int k = 0; k < 2; ++k) \
;       acc[ai][bj][m][n] = __builtin_amdgcn_mfma_f32_16x16x32_bf16(Btf[n][k], At[m][k], acc[ai][bj][m][n], 0, 0, 0); \
;     __builtin_amdgcn_s_setprio(0); } while (0)
; #define WAIT_L(n) asm volatile("s_waitcnt lgkmcnt(" #n ")" ::: "memory")
; #define BAR __builtin_amdgcn_s_barrier()
; template <int EPI> ...
;     ...
;     LDA(At, 1, 1); BAR; WAIT_L(0); MMA(1, 0, At, B0); MMA(1, 1, At, B1); BAR; }
	ds_read_b128 v[178:181], v150 offset:49152
	ds_read_b128 v[182:185], v150 offset:50176
	ds_read_b128 v[186:189], v150 offset:51200
	ds_read_b128 v[190:193], v150 offset:52224
	ds_read_b128 v[206:209], v150 offset:53248
	ds_read_b128 v[234:237], v150 offset:54272
	ds_read_b128 v[238:241], v150 offset:55296
	ds_read_b128 v[242:245], v150 offset:56320
	s_waitcnt lgkmcnt(0)

; #define LDA(dst, b, h) for (int m = 0; m < 4; ++m) { \
;     dst[m][0] = *reinterpret_cast<const bf16x8*>((char*)SA(b, h) + aoff0 + m * 2048); \
;     dst[m][1] = *reinterpret_cast<const bf16x8*>((char*)SA(b, h) + aoff1 + m * 2048); }
; #define MMA(ai, bj, At, Btf) do { __builtin_amdgcn_s_setprio(1); \
;     for (int m = 0; m < 4; ++m) for (int n = 0; n < 2; ++n) for (int k = 0; k < 2; ++k) \
;       acc[ai][bj][m][n] = __builtin_amdgcn_mfma_f32_16x16x32_bf16(Btf[n][k], At[m][k], acc[ai][bj][m][n], 0, 0, 0); \
;     __builtin_amdgcn_s_setprio(0); } while (0)
; #define WAIT_L(n) asm volatile("s_waitcnt lgkmcnt(" #n ")" ::: "memory")
; #define BAR __builtin_amdgcn_s_barrier()
; template <int EPI> ...
;     ...
;     LDA(At, 1, 1); BAR; WAIT_L(0); MMA(1, 0, At, B0); MMA(1, 1, At, B1); BAR; }
	s_barrier
	v_mfma_f32_16x16x32_bf16 v[16:19], v[0:3], v[178:181], v[60:63]
	v_mfma_f32_16x16x32_bf16 v[60:63], v[12:15], v[182:185], v[16:19]
	v_mfma_f32_16x16x32_bf16 v[16:19], v[198:201], v[178:181], v[56:59]
	v_mfma_f32_16x16x32_bf16 v[48:51], v[202:205], v[182:185], v[16:19]
	v_mfma_f32_16x16x32_bf16 v[16:19], v[0:3], v[186:189], v[52:55]
	v_mfma_f32_16x16x32_bf16 v[44:47], v[12:15], v[190:193], v[16:19]
	v_mfma_f32_16x16x32_bf16 v[16:19], v[198:201], v[186:189], v[226:229]
	v_mfma_f32_16x16x32_bf16 v[32:35], v[202:205], v[190:193], v[16:19]
	v_mfma_f32_16x16x32_bf16 v[16:19], v[0:3], v[206:209], v[230:233]
	v_mfma_f32_16x16x32_bf16 v[0:3], v[0:3], v[238:241], v[36:39]
	v_mfma_f32_16x16x32_bf16 v[28:31], v[12:15], v[234:237], v[16:19]
	v_mfma_f32_16x16x32_bf16 v[16:19], v[198:201], v[206:209], v[40:43]
	v_mfma_f32_16x16x32_bf16 v[12:15], v[12:15], v[242:245], v[0:3]
	v_mfma_f32_16x16x32_bf16 v[0:3], v[198:201], v[238:241], v[162:165]
	v_mfma_f32_16x16x32_bf16 v[16:19], v[202:205], v[234:237], v[16:19]
	v_mfma_f32_16x16x32_bf16 v[0:3], v[202:205], v[242:245], v[0:3]
	v_mfma_f32_16x16x32_bf16 v[20:23], v[210:213], v[186:189], v[20:23]
	v_mfma_f32_16x16x32_bf16 v[36:39], v[210:213], v[178:181], v[166:169]
	v_mfma_f32_16x16x32_bf16 v[40:43], v[218:221], v[190:193], v[20:23]
	v_mfma_f32_16x16x32_bf16 v[20:23], v[214:217], v[186:189], v[170:173]
	v_mfma_f32_16x16x32_bf16 v[56:59], v[218:221], v[182:185], v[36:39]
	v_mfma_f32_16x16x32_bf16 v[24:27], v[214:217], v[178:181], v[24:27]
	v_mfma_f32_16x16x32_bf16 v[36:39], v[222:225], v[190:193], v[20:23]
	v_mfma_f32_16x16x32_bf16 v[20:23], v[210:213], v[206:209], v[174:177]
	v_mfma_f32_16x16x32_bf16 v[8:11], v[214:217], v[206:209], v[8:11]
	v_mfma_f32_16x16x32_bf16 v[4:7], v[210:213], v[238:241], v[4:7]
	v_mfma_f32_16x16x32_bf16 v[52:55], v[222:225], v[182:185], v[24:27]
	v_mfma_f32_16x16x32_bf16 v[24:27], v[218:221], v[234:237], v[20:23]
	v_mfma_f32_16x16x32_bf16 v[20:23], v[222:225], v[234:237], v[8:11]
	v_mfma_f32_16x16x32_bf16 v[8:11], v[218:221], v[242:245], v[4:7]
	v_mfma_f32_16x16x32_bf16 v[4:7], v[214:217], v[238:241], v[194:197]
	v_mfma_f32_16x16x32_bf16 v[4:7], v[222:225], v[242:245], v[4:7]
	s_barrier

; #define LDA(dst, b, h) for (int m = 0; m < 4; ++m) { \
;     dst[m][0] = *reinterpret_cast<const bf16x8*>((char*)SA(b, h) + aoff0 + m * 2048); \
;     dst[m][1] = *reinterpret_cast<const bf16x8*>((char*)SA(b, h) + aoff1 + m * 2048); }
; #define MMA(ai, bj, At, Btf) do { __builtin_amdgcn_s_setprio(1); \
;     for (int m = 0; m < 4; ++m) for (int n = 0; n < 2; ++n) for (int k = 0; k < 2; ++k) \
;       acc[ai][bj][m][n] = __builtin_amdgcn_mfma_f32_16x16x32_bf16(Btf[n][k], At[m][k], acc[ai][bj][m][n], 0, 0, 0); \
;     __builtin_amdgcn_s_setprio(0); } while (0)
; #define WAIT_L(n) asm volatile("s_waitcnt lgkmcnt(" #n ")" ::: "memory")
; #define BAR __builtin_amdgcn_s_barrier()
; template <int EPI> ...
;     ...
;     LDA(At, 1, 1); BAR; WAIT_L(0); MMA(1, 0, At, B0); MMA(1, 1, At, B1); BAR; }
;   if (wr == 0) BAR;
	s_setprio 0
	s_and_saveexec_b64 s[68:69], s[2:3]
	s_cbranch_execz .LBB0_271
	s_barrier
	s_branch .LBB0_271

; #define STAGE(P, BASE, br, kt) do { const char* _gb = (const char*)(BASE) + ((size_t)(br) * K + (size_t)(kt) * BK) * 2; \
;     __builtin_amdgcn_global_load_lds((const unsigned*)(_gb + loff0), (unsigned*)((char*)(P) + tid * 16), 16, 0, 0); \
;     __builtin_amdgcn_global_load_lds((const unsigned*)(_gb + (size_t)K * 128 + loff0), (unsigned*)((char*)(P) + tid * 16 + 8192), 16, 0, 0); } while (0)
; #define BAR __builtin_amdgcn_s_barrier()
; template <int EPI> ...
;     ...
;   f32x4 acc[2][2][4][2] = {};
;   bf16x8 At[4][2], B0[2][2], B1[2][2];
;   int nt = K / BK;
;   const int aoff0 = lds_byte(wr * 64 + fr, fq * 8), aoff1 = lds_byte(wr * 64 + fr, 32 + fq * 8);
;   const int brw = wc * 32 + (fr >> 2) * 8 + (fr & 3);
;   const int boff0 = lds_byte(brw, fq * 8), boff1 = lds_byte(brw, 32 + fq * 8);
;   unsigned loff0;
;   { int _r, _c; stage_rc(tid * 16, _r, _c); loff0 = (unsigned)(_r * K + _c) * 2u; }
;   STAGE(SB(0, 0), Bt, bcol, 0); STAGE(SA(0, 0), A, brow, 0);
;   STAGE(SB(0, 1), Bt, bcol + HALF, 0); STAGE(SA(0, 1), A, brow + HALF, 0);
;   if (wr == 1) BAR;
; template <int EPI>
; __device__ __forceinline__ void gemm_phase(const u16* A, const u16* Bt, int M, int N, int K, u16* out, int ldo,
;                                            const float* aux, int bid, int nblk, int wv) {
;     ...
;   for (int base = 0; base < ntile; base += nblk) {
;     int wgid;
;     if (base + nblk <= ntile && (nblk & 7) == 0) wgid = base + (bid & 7) * (nblk >> 3) + (bid >> 3);
;     else wgid = base + bid;
;     if (wgid >= ntile) break;
;     int nig = WGM * nN, gid = wgid / nig, fm = gid * WGM, gsz = min(nM - fm, WGM);
;     int pm = fm + ((wgid % nig) % gsz), pn = (wgid % nig) / gsz;
;     int brow = pm * BM, bcol = pn * BM;
;     gemm_tile<EPI>(A, Bt, K, brow, bcol, out, ldo, EPI == 1 ? pn * HALF : bcol, aux, tid);
.LBB0_320:
	s_mov_b32 s62, s72
	s_add_i32 s72, s72, s33
	s_cmpk_lt_i32 s72, 0x401
	s_cselect_b64 s[60:61], -1, 0
	s_and_b64 s[60:61], s[44:45], s[60:61]
	s_and_b64 s[60:61], s[60:61], exec
	s_cselect_b32 s60, s86, s91
	s_add_i32 s62, s60, s62
	s_cmpk_gt_i32 s62, 0x3ff
	s_mov_b64 s[60:61], -1
	s_cbranch_scc1 .LBB0_319
	s_sub_i32 s62, 0x3ff, s62
	s_ashr_i32 s60, s62, 31
	s_lshr_b32 s60, s60, 26
	s_add_i32 s60, s62, s60
	s_and_b32 s61, s60, 0xffc0
	s_sub_i32 s61, s62, s61
	s_bfe_i32 s62, s61, 0x80000
	s_bfe_u32 s62, s62, 0x3000c
	s_add_i32 s62, s61, s62
	s_bfe_i32 s63, s62, 0x80000
	s_and_b32 s62, s62, 0xf8
	s_sub_i32 s61, s61, s62
	s_sext_i32_i16 s63, s63
	s_sext_i32_i8 s61, s61
	s_lshl_b32 s60, s60, 5
	s_ashr_i32 s64, s63, 3
	s_and_b32 s60, s60, 0xfffff800
	s_lshl_b32 s73, s61, 8
	s_add_i32 s73, s73, s60
	s_lshl_b32 s60, s64, 8
	s_mul_i32 s66, s64, 0x2c0000
	s_mul_hi_i32 s67, s60, 0x2c00
	s_add_u32 s62, s68, s66
	s_addc_u32 s63, s69, s67
	v_readfirstlane_b32 s61, v135
	s_mul_i32 s77, s73, 0x2c00
	v_lshl_add_u64 v[0:1], s[62:63], 0, v[128:129]
	s_mov_b32 m0, s61
	v_readfirstlane_b32 s61, v136
	s_mul_hi_i32 s76, s73, 0x2c00
	s_add_u32 s62, s14, s77
	global_load_lds_dwordx4 v[0:1], off
	v_lshl_add_u64 v[2:3], v[0:1], 0, s[8:9]
	s_mov_b32 m0, s61
	s_addc_u32 s63, s43, s76
	global_load_lds_dwordx4 v[2:3], off
	v_lshl_add_u64 v[2:3], s[62:63], 0, v[128:129]
	s_mul_i32 s62, s64, 0x160000
	v_readfirstlane_b32 s61, v137
	s_ashr_i32 s63, s62, 31
	s_mov_b32 m0, s61
	v_readfirstlane_b32 s61, v138
	s_lshl_b64 s[62:63], s[62:63], 1
	global_load_lds_dwordx4 v[2:3], off
	s_mov_b32 m0, s61
	s_add_u32 s61, s68, s62
	s_addc_u32 s65, s69, s63
	s_add_u32 s64, s61, 0x160000
	v_lshl_add_u64 v[4:5], v[2:3], 0, s[8:9]
	s_addc_u32 s65, s65, 0
	v_readfirstlane_b32 s61, v139
	global_load_lds_dwordx4 v[4:5], off
	v_lshl_add_u64 v[4:5], s[64:65], 0, v[128:129]
	s_mov_b32 m0, s61
	v_readfirstlane_b32 s61, v140
	global_load_lds_dwordx4 v[4:5], off
	s_mov_b32 m0, s61
	s_or_b32 s61, s73, 0x80
	s_mul_i32 s75, s61, 0x2c00
	s_mul_hi_i32 s74, s61, 0x2c00
	s_add_u32 s64, s14, s75
	v_lshl_add_u64 v[6:7], v[4:5], 0, s[8:9]
	s_addc_u32 s65, s43, s74
	v_readfirstlane_b32 s61, v141
	global_load_lds_dwordx4 v[6:7], off
	v_lshl_add_u64 v[6:7], s[64:65], 0, v[128:129]
	s_mov_b32 m0, s61
	v_readfirstlane_b32 s61, v142
	global_load_lds_dwordx4 v[6:7], off
	v_lshl_add_u64 v[6:7], v[6:7], 0, s[8:9]
	s_mov_b32 m0, s61
	s_nop 0
	global_load_lds_dwordx4 v[6:7], off
	v_mov_b32_e32 v8, 0
	v_mov_b32_e32 v9, 0
	v_mov_b32_e32 v10, 0
	v_mov_b32_e32 v11, 0
	v_mov_b32_e32 v12, 0
	v_mov_b32_e32 v13, 0
	v_mov_b32_e32 v14, 0
	v_mov_b32_e32 v15, 0
	v_mov_b32_e32 v16, 0
	v_mov_b32_e32 v17, 0
	v_mov_b32_e32 v18, 0
	v_mov_b32_e32 v19, 0
	v_mov_b32_e32 v20, 0
	v_mov_b32_e32 v21, 0
	v_mov_b32_e32 v22, 0
	v_mov_b32_e32 v23, 0
	v_mov_b32_e32 v24, 0
	v_mov_b32_e32 v25, 0
	v_mov_b32_e32 v26, 0
	v_mov_b32_e32 v27, 0
	v_mov_b32_e32 v28, 0
	v_mov_b32_e32 v29, 0
	v_mov_b32_e32 v30, 0
	v_mov_b32_e32 v31, 0
	v_mov_b32_e32 v32, 0
	v_mov_b32_e32 v33, 0
	v_mov_b32_e32 v34, 0
	v_mov_b32_e32 v35, 0
	v_mov_b32_e32 v36, 0
	v_mov_b32_e32 v37, 0
	v_mov_b32_e32 v38, 0
	v_mov_b32_e32 v39, 0
	v_mov_b32_e32 v40, 0
	v_mov_b32_e32 v41, 0
	v_mov_b32_e32 v42, 0
	v_mov_b32_e32 v43, 0
	v_mov_b32_e32 v44, 0
	v_mov_b32_e32 v45, 0
	v_mov_b32_e32 v46, 0
	v_mov_b32_e32 v47, 0
	v_mov_b32_e32 v48, 0
	v_mov_b32_e32 v49, 0
	v_mov_b32_e32 v50, 0
	v_mov_b32_e32 v51, 0
	v_mov_b32_e32 v52, 0
	v_mov_b32_e32 v53, 0
	v_mov_b32_e32 v54, 0
	v_mov_b32_e32 v55, 0
	v_mov_b32_e32 v56, 0
	v_mov_b32_e32 v57, 0
	v_mov_b32_e32 v58, 0
	v_mov_b32_e32 v59, 0
	v_mov_b32_e32 v60, 0
	v_mov_b32_e32 v61, 0
	v_mov_b32_e32 v62, 0
	v_mov_b32_e32 v63, 0
	v_mov_b32_e32 v64, 0
	v_mov_b32_e32 v65, 0
	v_mov_b32_e32 v66, 0
	v_mov_b32_e32 v67, 0
	v_mov_b32_e32 v68, 0
	v_mov_b32_e32 v69, 0
	v_mov_b32_e32 v70, 0
	v_mov_b32_e32 v71, 0
	v_mov_b32_e32 v72, 0
	v_mov_b32_e32 v73, 0
	v_mov_b32_e32 v74, 0
	v_mov_b32_e32 v75, 0
	v_mov_b32_e32 v76, 0
	v_mov_b32_e32 v77, 0
	v_mov_b32_e32 v78, 0
	v_mov_b32_e32 v79, 0
	v_mov_b32_e32 v80, 0
	v_mov_b32_e32 v81, 0
	v_mov_b32_e32 v82, 0
	v_mov_b32_e32 v83, 0
	v_mov_b32_e32 v84, 0
	v_mov_b32_e32 v85, 0
	v_mov_b32_e32 v86, 0
	v_mov_b32_e32 v87, 0
	v_mov_b32_e32 v88, 0
	v_mov_b32_e32 v89, 0
	v_mov_b32_e32 v90, 0
	v_mov_b32_e32 v91, 0
	v_mov_b32_e32 v92, 0
	v_mov_b32_e32 v93, 0
	v_mov_b32_e32 v94, 0
	v_mov_b32_e32 v95, 0
	v_mov_b32_e32 v96, 0
	v_mov_b32_e32 v97, 0
	v_mov_b32_e32 v98, 0
	v_mov_b32_e32 v99, 0
	v_mov_b32_e32 v100, 0
	v_mov_b32_e32 v101, 0
	v_mov_b32_e32 v102, 0
	v_mov_b32_e32 v103, 0
	v_mov_b32_e32 v104, 0
	v_mov_b32_e32 v105, 0
	v_mov_b32_e32 v106, 0
	v_mov_b32_e32 v107, 0
	v_mov_b32_e32 v108, 0
	v_mov_b32_e32 v109, 0
	v_mov_b32_e32 v110, 0
	v_mov_b32_e32 v111, 0
	v_mov_b32_e32 v112, 0
	v_mov_b32_e32 v113, 0
	v_mov_b32_e32 v114, 0
	v_mov_b32_e32 v115, 0
	v_mov_b32_e32 v116, 0
	v_mov_b32_e32 v117, 0
	v_mov_b32_e32 v118, 0
	v_mov_b32_e32 v119, 0
	v_mov_b32_e32 v120, 0
	v_mov_b32_e32 v121, 0
	v_mov_b32_e32 v122, 0
	v_mov_b32_e32 v123, 0
	v_mov_b32_e32 v124, 0
	v_mov_b32_e32 v125, 0
	v_mov_b32_e32 v126, 0
	v_mov_b32_e32 v127, 0
	s_and_saveexec_b64 s[64:65], s[4:5]
	s_cbranch_execz .LBB0_323
	s_setprio 1
	s_barrier

; #define STAGE(P, BASE, br, kt) do { const char* _gb = (const char*)(BASE) + ((size_t)(br) * K + (size_t)(kt) * BK) * 2; \
;     __builtin_amdgcn_global_load_lds((const unsigned*)(_gb + loff0), (unsigned*)((char*)(P) + tid * 16), 16, 0, 0); \
;     __builtin_amdgcn_global_load_lds((const unsigned*)(_gb + (size_t)K * 128 + loff0), (unsigned*)((char*)(P) + tid * 16 + 8192), 16, 0, 0); } while (0)
; #define LDA(dst, b, h) for (int m = 0; m < 4; ++m) { \
;     dst[m][0] = *reinterpret_cast<const bf16x8*>((char*)SA(b, h) + aoff0 + m * 2048); \
;     dst[m][1] = *reinterpret_cast<const bf16x8*>((char*)SA(b, h) + aoff1 + m * 2048); }
; #define LDB(dst, b, h) for (int n = 0; n < 2; ++n) { \
;     dst[n][0] = *reinterpret_cast<const bf16x8*>((char*)SB(b, h) + boff0 + n * 256); \
;     dst[n][1] = *reinterpret_cast<const bf16x8*>((char*)SB(b, h) + boff1 + n * 256); }
; #define MMA(ai, bj, At, Btf) do { __builtin_amdgcn_s_setprio(1); \
;     for (int m = 0; m < 4; ++m) for (int n = 0; n < 2; ++n) for (int k = 0; k < 2; ++k) \
;       acc[ai][bj][m][n] = __builtin_amdgcn_mfma_f32_16x16x32_bf16(Btf[n][k], At[m][k], acc[ai][bj][m][n], 0, 0, 0); \
;     __builtin_amdgcn_s_setprio(0); } while (0)
; #define WAIT_L(n) asm volatile("s_waitcnt lgkmcnt(" #n ")" ::: "memory")
; #define BAR __builtin_amdgcn_s_barrier()
; #define SCHED __builtin_amdgcn_sched_barrier(0)
; template <int EPI> ...
;     ...
;     LDB(B0, 0, 0); SCHED; LDA(At, 0, 0); STAGE(SA(1, 1), A, brow + HALF, t + 1);
;     WAIT_L(8); BAR; WAIT_L(0); MMA(0, 0, At, B0); BAR; SCHED;
;     LDB(B1, 0, 1); STAGE(SB(0, 0), Bt, bcol, t + 2);
.LBB0_324:
	ds_read_b128 v[160:163], v152
	ds_read_b128 v[164:167], v152 offset:256
	ds_read_b128 v[168:171], v153
	ds_read_b128 v[172:175], v153 offset:256
	v_lshl_add_u64 v[224:225], s[64:65], 0, v[132:133]
	v_readfirstlane_b32 s77, v150
	v_lshl_add_u64 v[208:209], v[224:225], 0, s[16:17]
	s_mov_b32 m0, s77
	v_readfirstlane_b32 s77, v151
	ds_read_b128 v[176:179], v149
	ds_read_b128 v[180:183], v149 offset:1024
	ds_read_b128 v[184:187], v149 offset:2048
	ds_read_b128 v[188:191], v149 offset:3072
	ds_read_b128 v[192:195], v149 offset:4096
	ds_read_b128 v[196:199], v149 offset:5120
	ds_read_b128 v[200:203], v149 offset:6144
	ds_read_b128 v[204:207], v149 offset:7168
	global_load_lds_dwordx4 v[208:209], off
	v_lshl_add_u64 v[208:209], v[224:225], 0, s[18:19]
	s_mov_b32 m0, s77
	s_nop 0
	global_load_lds_dwordx4 v[208:209], off
	s_waitcnt lgkmcnt(8)
	v_readfirstlane_b32 s77, v148
	v_lshl_add_u64 v[246:247], v[228:229], 0, s[58:59]
	s_mov_b32 m0, s77
	s_nop 0
	global_load_lds_dwordx4 v[246:247], off
	ds_read_b128 v[208:211], v154
	ds_read_b128 v[212:215], v154 offset:256
	ds_read_b128 v[216:219], v155
	ds_read_b128 v[220:223], v155 offset:256
	s_waitcnt lgkmcnt(0)

; #define STAGE(P, BASE, br, kt) do { const char* _gb = (const char*)(BASE) + ((size_t)(br) * K + (size_t)(kt) * BK) * 2; \
;     __builtin_amdgcn_global_load_lds((const unsigned*)(_gb + loff0), (unsigned*)((char*)(P) + tid * 16), 16, 0, 0); \
;     __builtin_amdgcn_global_load_lds((const unsigned*)(_gb + (size_t)K * 128 + loff0), (unsigned*)((char*)(P) + tid * 16 + 8192), 16, 0, 0); } while (0)
; #define LDB(dst, b, h) for (int n = 0; n < 2; ++n) { \
;     dst[n][0] = *reinterpret_cast<const bf16x8*>((char*)SB(b, h) + boff0 + n * 256); \
;     dst[n][1] = *reinterpret_cast<const bf16x8*>((char*)SB(b, h) + boff1 + n * 256); }
; #define MMA(ai, bj, At, Btf) do { __builtin_amdgcn_s_setprio(1); \
;     for (int m = 0; m < 4; ++m) for (int n = 0; n < 2; ++n) for (int k = 0; k < 2; ++k) \
;       acc[ai][bj][m][n] = __builtin_amdgcn_mfma_f32_16x16x32_bf16(Btf[n][k], At[m][k], acc[ai][bj][m][n], 0, 0, 0); \
;     __builtin_amdgcn_s_setprio(0); } while (0)
; #define WAIT_L(n) asm volatile("s_waitcnt lgkmcnt(" #n ")" ::: "memory")
; #define BAR __builtin_amdgcn_s_barrier()
; #define SCHED __builtin_amdgcn_sched_barrier(0)
; template <int EPI> ...
;     ...
;     WAIT_L(8); BAR; WAIT_L(0); MMA(0, 0, At, B0); BAR; SCHED;
;     LDB(B1, 0, 1); STAGE(SB(0, 0), Bt, bcol, t + 2);
;     BAR; WAIT_L(0); MMA(0, 1, At, B1); BAR;
	s_barrier
	v_mfma_f32_16x16x32_bf16 v[124:127], v[160:163], v[176:179], v[124:127]
	v_mfma_f32_16x16x32_bf16 v[120:123], v[164:167], v[176:179], v[120:123]
	v_mfma_f32_16x16x32_bf16 v[116:119], v[160:163], v[184:187], v[116:119]
	v_mfma_f32_16x16x32_bf16 v[112:115], v[164:167], v[184:187], v[112:115]
	v_mfma_f32_16x16x32_bf16 v[108:111], v[160:163], v[192:195], v[108:111]
	v_mfma_f32_16x16x32_bf16 v[104:107], v[164:167], v[192:195], v[104:107]
	v_mfma_f32_16x16x32_bf16 v[100:103], v[160:163], v[200:203], v[100:103]
	v_mfma_f32_16x16x32_bf16 v[96:99], v[164:167], v[200:203], v[96:99]
	v_mfma_f32_16x16x32_bf16 v[124:127], v[168:171], v[180:183], v[124:127]
	v_mfma_f32_16x16x32_bf16 v[120:123], v[172:175], v[180:183], v[120:123]
	v_mfma_f32_16x16x32_bf16 v[116:119], v[168:171], v[188:191], v[116:119]
	v_mfma_f32_16x16x32_bf16 v[112:115], v[172:175], v[188:191], v[112:115]
	v_mfma_f32_16x16x32_bf16 v[108:111], v[168:171], v[196:199], v[108:111]
	v_mfma_f32_16x16x32_bf16 v[104:107], v[172:175], v[196:199], v[104:107]
	v_mfma_f32_16x16x32_bf16 v[100:103], v[168:171], v[204:207], v[100:103]
	v_mfma_f32_16x16x32_bf16 v[96:99], v[172:175], v[204:207], v[96:99]
	v_mfma_f32_16x16x32_bf16 v[92:95], v[208:211], v[176:179], v[92:95]
	v_mfma_f32_16x16x32_bf16 v[88:91], v[212:215], v[176:179], v[88:91]
	v_mfma_f32_16x16x32_bf16 v[84:87], v[208:211], v[184:187], v[84:87]
	v_mfma_f32_16x16x32_bf16 v[80:83], v[212:215], v[184:187], v[80:83]
	v_mfma_f32_16x16x32_bf16 v[76:79], v[208:211], v[192:195], v[76:79]
	v_mfma_f32_16x16x32_bf16 v[72:75], v[212:215], v[192:195], v[72:75]
	v_mfma_f32_16x16x32_bf16 v[68:71], v[208:211], v[200:203], v[68:71]
	v_mfma_f32_16x16x32_bf16 v[64:67], v[212:215], v[200:203], v[64:67]
	v_mfma_f32_16x16x32_bf16 v[92:95], v[216:219], v[180:183], v[92:95]
	v_mfma_f32_16x16x32_bf16 v[88:91], v[220:223], v[180:183], v[88:91]
	v_mfma_f32_16x16x32_bf16 v[84:87], v[216:219], v[188:191], v[84:87]
	v_mfma_f32_16x16x32_bf16 v[80:83], v[220:223], v[188:191], v[80:83]
	v_mfma_f32_16x16x32_bf16 v[76:79], v[216:219], v[196:199], v[76:79]
	v_mfma_f32_16x16x32_bf16 v[72:75], v[220:223], v[196:199], v[72:75]
	v_mfma_f32_16x16x32_bf16 v[68:71], v[216:219], v[204:207], v[68:71]
	v_mfma_f32_16x16x32_bf16 v[64:67], v[220:223], v[204:207], v[64:67]
	s_barrier

; #define STAGE(P, BASE, br, kt) do { const char* _gb = (const char*)(BASE) + ((size_t)(br) * K + (size_t)(kt) * BK) * 2; \
;     __builtin_amdgcn_global_load_lds((const unsigned*)(_gb + loff0), (unsigned*)((char*)(P) + tid * 16), 16, 0, 0); \
;     __builtin_amdgcn_global_load_lds((const unsigned*)(_gb + (size_t)K * 128 + loff0), (unsigned*)((char*)(P) + tid * 16 + 8192), 16, 0, 0); } while (0)
; #define LDA(dst, b, h) for (int m = 0; m < 4; ++m) { \
;     dst[m][0] = *reinterpret_cast<const bf16x8*>((char*)SA(b, h) + aoff0 + m * 2048); \
;     dst[m][1] = *reinterpret_cast<const bf16x8*>((char*)SA(b, h) + aoff1 + m * 2048); }
; #define MMA(ai, bj, At, Btf) do { __builtin_amdgcn_s_setprio(1); \
;     for (int m = 0; m < 4; ++m) for (int n = 0; n < 2; ++n) for (int k = 0; k < 2; ++k) \
;       acc[ai][bj][m][n] = __builtin_amdgcn_mfma_f32_16x16x32_bf16(Btf[n][k], At[m][k], acc[ai][bj][m][n], 0, 0, 0); \
;     __builtin_amdgcn_s_setprio(0); } while (0)
; #define WAIT_V(n) asm volatile("s_waitcnt vmcnt(" #n ")" ::: "memory")
; #define WAIT_L(n) asm volatile("s_waitcnt lgkmcnt(" #n ")" ::: "memory")
; #define BAR __builtin_amdgcn_s_barrier()
; #define SCHED __builtin_amdgcn_sched_barrier(0)
; template <int EPI> ...
;     ...
;     LDA(At, 0, 1); STAGE(SA(0, 0), A, brow, t + 2);
;     BAR; WAIT_L(0); MMA(1, 0, At, B0); BAR; SCHED;
;     STAGE(SB(0, 1), Bt, bcol + HALF, t + 2);
;     WAIT_V(6); BAR; MMA(1, 1, At, B1); BAR;
	v_lshl_add_u64 v[226:227], s[66:67], 0, v[132:133]
	v_readfirstlane_b32 s77, v135
	v_lshl_add_u64 v[228:229], v[226:227], 0, s[20:21]
	s_mov_b32 m0, s77
	v_readfirstlane_b32 s77, v136
	global_load_lds_dwordx4 v[228:229], off
	v_lshl_add_u64 v[228:229], v[226:227], 0, s[22:23]
	s_mov_b32 m0, s77
	s_nop 0
	global_load_lds_dwordx4 v[228:229], off
	v_readfirstlane_b32 s77, v137
	v_lshl_add_u64 v[228:229], v[224:225], 0, s[26:27]
	s_mov_b32 m0, s77
	v_readfirstlane_b32 s77, v138
	ds_read_b128 v[176:179], v149 offset:16384
	ds_read_b128 v[180:183], v149 offset:17408
	ds_read_b128 v[184:187], v149 offset:18432
	ds_read_b128 v[188:191], v149 offset:19456
	ds_read_b128 v[192:195], v149 offset:20480
	ds_read_b128 v[196:199], v149 offset:21504
	ds_read_b128 v[200:203], v149 offset:22528
	ds_read_b128 v[204:207], v149 offset:23552
	global_load_lds_dwordx4 v[228:229], off
	v_lshl_add_u64 v[228:229], v[224:225], 0, s[28:29]
	s_mov_b32 m0, s77
	s_nop 0
	global_load_lds_dwordx4 v[228:229], off
	v_lshl_add_u64 v[228:229], s[62:63], 0, v[132:133]
	v_readfirstlane_b32 s77, v139
	v_lshl_add_u64 v[246:247], v[228:229], 0, s[30:31]
	s_mov_b32 m0, s77
	v_readfirstlane_b32 s77, v140
	global_load_lds_dwordx4 v[246:247], off
	s_waitcnt vmcnt(5)
	s_waitcnt lgkmcnt(0)

; #define STAGE(P, BASE, br, kt) do { const char* _gb = (const char*)(BASE) + ((size_t)(br) * K + (size_t)(kt) * BK) * 2; \
;     __builtin_amdgcn_global_load_lds((const unsigned*)(_gb + loff0), (unsigned*)((char*)(P) + tid * 16), 16, 0, 0); \
;     __builtin_amdgcn_global_load_lds((const unsigned*)(_gb + (size_t)K * 128 + loff0), (unsigned*)((char*)(P) + tid * 16 + 8192), 16, 0, 0); } while (0)
; #define MMA(ai, bj, At, Btf) do { __builtin_amdgcn_s_setprio(1); \
;     for (int m = 0; m < 4; ++m) for (int n = 0; n < 2; ++n) for (int k = 0; k < 2; ++k) \
;       acc[ai][bj][m][n] = __builtin_amdgcn_mfma_f32_16x16x32_bf16(Btf[n][k], At[m][k], acc[ai][bj][m][n], 0, 0, 0); \
;     __builtin_amdgcn_s_setprio(0); } while (0)
; #define WAIT_V(n) asm volatile("s_waitcnt vmcnt(" #n ")" ::: "memory")
; #define WAIT_L(n) asm volatile("s_waitcnt lgkmcnt(" #n ")" ::: "memory")
; #define BAR __builtin_amdgcn_s_barrier()
; #define SCHED __builtin_amdgcn_sched_barrier(0)
; template <int EPI> ...
;     ...
;     BAR; WAIT_L(0); MMA(1, 0, At, B0); BAR; SCHED;
;     STAGE(SB(0, 1), Bt, bcol + HALF, t + 2);
;     WAIT_V(6); BAR; MMA(1, 1, At, B1); BAR;
	s_barrier
	v_mfma_f32_16x16x32_bf16 v[60:63], v[160:163], v[176:179], v[60:63]
	v_mfma_f32_16x16x32_bf16 v[56:59], v[164:167], v[176:179], v[56:59]
	v_mfma_f32_16x16x32_bf16 v[52:55], v[160:163], v[184:187], v[52:55]
	v_mfma_f32_16x16x32_bf16 v[48:51], v[164:167], v[184:187], v[48:51]
	v_mfma_f32_16x16x32_bf16 v[44:47], v[160:163], v[192:195], v[44:47]
	v_mfma_f32_16x16x32_bf16 v[40:43], v[164:167], v[192:195], v[40:43]
	v_mfma_f32_16x16x32_bf16 v[36:39], v[160:163], v[200:203], v[36:39]
	v_mfma_f32_16x16x32_bf16 v[32:35], v[164:167], v[200:203], v[32:35]
	v_mfma_f32_16x16x32_bf16 v[60:63], v[168:171], v[180:183], v[60:63]
	v_mfma_f32_16x16x32_bf16 v[56:59], v[172:175], v[180:183], v[56:59]
	v_mfma_f32_16x16x32_bf16 v[52:55], v[168:171], v[188:191], v[52:55]
	v_mfma_f32_16x16x32_bf16 v[48:51], v[172:175], v[188:191], v[48:51]
	v_mfma_f32_16x16x32_bf16 v[44:47], v[168:171], v[196:199], v[44:47]
	v_mfma_f32_16x16x32_bf16 v[40:43], v[172:175], v[196:199], v[40:43]
	v_mfma_f32_16x16x32_bf16 v[36:39], v[168:171], v[204:207], v[36:39]
	v_mfma_f32_16x16x32_bf16 v[32:35], v[172:175], v[204:207], v[32:35]
	v_mfma_f32_16x16x32_bf16 v[28:31], v[208:211], v[176:179], v[28:31]
	v_mfma_f32_16x16x32_bf16 v[24:27], v[212:215], v[176:179], v[24:27]
	v_mfma_f32_16x16x32_bf16 v[20:23], v[208:211], v[184:187], v[20:23]
	v_mfma_f32_16x16x32_bf16 v[16:19], v[212:215], v[184:187], v[16:19]
	v_mfma_f32_16x16x32_bf16 v[12:15], v[208:211], v[192:195], v[12:15]
	v_mfma_f32_16x16x32_bf16 v[8:11], v[212:215], v[192:195], v[8:11]
	v_mfma_f32_16x16x32_bf16 v[4:7], v[208:211], v[200:203], v[4:7]
	v_mfma_f32_16x16x32_bf16 v[0:3], v[212:215], v[200:203], v[0:3]
	v_mfma_f32_16x16x32_bf16 v[28:31], v[216:219], v[180:183], v[28:31]
	v_mfma_f32_16x16x32_bf16 v[24:27], v[220:223], v[180:183], v[24:27]
	v_mfma_f32_16x16x32_bf16 v[20:23], v[216:219], v[188:191], v[20:23]
	v_mfma_f32_16x16x32_bf16 v[16:19], v[220:223], v[188:191], v[16:19]
	v_mfma_f32_16x16x32_bf16 v[12:15], v[216:219], v[196:199], v[12:15]
	v_mfma_f32_16x16x32_bf16 v[8:11], v[220:223], v[196:199], v[8:11]
	v_mfma_f32_16x16x32_bf16 v[4:7], v[216:219], v[204:207], v[4:7]
	v_mfma_f32_16x16x32_bf16 v[0:3], v[220:223], v[204:207], v[0:3]
	s_barrier

; #define STAGE(P, BASE, br, kt) do { const char* _gb = (const char*)(BASE) + ((size_t)(br) * K + (size_t)(kt) * BK) * 2; \
;     __builtin_amdgcn_global_load_lds((const unsigned*)(_gb + loff0), (unsigned*)((char*)(P) + tid * 16), 16, 0, 0); \
;     __builtin_amdgcn_global_load_lds((const unsigned*)(_gb + (size_t)K * 128 + loff0), (unsigned*)((char*)(P) + tid * 16 + 8192), 16, 0, 0); } while (0)
; #define LDA(dst, b, h) for (int m = 0; m < 4; ++m) { \
;     dst[m][0] = *reinterpret_cast<const bf16x8*>((char*)SA(b, h) + aoff0 + m * 2048); \
;     dst[m][1] = *reinterpret_cast<const bf16x8*>((char*)SA(b, h) + aoff1 + m * 2048); }
; #define LDB(dst, b, h) for (int n = 0; n < 2; ++n) { \
;     dst[n][0] = *reinterpret_cast<const bf16x8*>((char*)SB(b, h) + boff0 + n * 256); \
;     dst[n][1] = *reinterpret_cast<const bf16x8*>((char*)SB(b, h) + boff1 + n * 256); }
; #define MMA(ai, bj, At, Btf) do { __builtin_amdgcn_s_setprio(1); \
;     for (int m = 0; m < 4; ++m) for (int n = 0; n < 2; ++n) for (int k = 0; k < 2; ++k) \
;       acc[ai][bj][m][n] = __builtin_amdgcn_mfma_f32_16x16x32_bf16(Btf[n][k], At[m][k], acc[ai][bj][m][n], 0, 0, 0); \
;     __builtin_amdgcn_s_setprio(0); } while (0)
; #define WAIT_L(n) asm volatile("s_waitcnt lgkmcnt(" #n ")" ::: "memory")
; #define BAR __builtin_amdgcn_s_barrier()
; #define SCHED __builtin_amdgcn_sched_barrier(0)
; template <int EPI> ...
;     ...
;     LDB(B0, 1, 0); SCHED; LDA(At, 1, 0); STAGE(SA(0, 1), A, brow + HALF, t + 2);
;     WAIT_L(8); BAR; WAIT_L(0); MMA(0, 0, At, B0); BAR; SCHED;
;     LDB(B1, 1, 1); STAGE(SB(1, 0), Bt, bcol, t + 3);
	ds_read_b128 v[160:163], v156
	ds_read_b128 v[164:167], v156 offset:256
	ds_read_b128 v[168:171], v157
	ds_read_b128 v[172:175], v157 offset:256
	v_readfirstlane_b32 s77, v141
	v_lshl_add_u64 v[208:209], v[224:225], 0, s[38:39]
	s_mov_b32 m0, s77
	v_readfirstlane_b32 s77, v142
	ds_read_b128 v[176:179], v149 offset:32768
	ds_read_b128 v[180:183], v149 offset:33792
	ds_read_b128 v[184:187], v149 offset:34816
	ds_read_b128 v[188:191], v149 offset:35840
	ds_read_b128 v[192:195], v149 offset:36864
	ds_read_b128 v[196:199], v149 offset:37888
	ds_read_b128 v[200:203], v149 offset:38912
	ds_read_b128 v[204:207], v149 offset:39936
	global_load_lds_dwordx4 v[208:209], off
	v_lshl_add_u64 v[208:209], v[224:225], 0, s[46:47]
	s_mov_b32 m0, s77
	s_nop 0
	global_load_lds_dwordx4 v[208:209], off
	s_waitcnt lgkmcnt(8)
	v_readfirstlane_b32 s77, v140
	v_lshl_add_u64 v[246:247], v[228:229], 0, s[36:37]
	s_mov_b32 m0, s77
	s_nop 0
	global_load_lds_dwordx4 v[246:247], off
	ds_read_b128 v[208:211], v158
	ds_read_b128 v[212:215], v158 offset:256
	ds_read_b128 v[216:219], v159
	ds_read_b128 v[220:223], v159 offset:256
	s_waitcnt lgkmcnt(0)

; #define STAGE(P, BASE, br, kt) do { const char* _gb = (const char*)(BASE) + ((size_t)(br) * K + (size_t)(kt) * BK) * 2; \
;     __builtin_amdgcn_global_load_lds((const unsigned*)(_gb + loff0), (unsigned*)((char*)(P) + tid * 16), 16, 0, 0); \
;     __builtin_amdgcn_global_load_lds((const unsigned*)(_gb + (size_t)K * 128 + loff0), (unsigned*)((char*)(P) + tid * 16 + 8192), 16, 0, 0); } while (0)
; #define LDB(dst, b, h) for (int n = 0; n < 2; ++n) { \
;     dst[n][0] = *reinterpret_cast<const bf16x8*>((char*)SB(b, h) + boff0 + n * 256); \
;     dst[n][1] = *reinterpret_cast<const bf16x8*>((char*)SB(b, h) + boff1 + n * 256); }
; #define MMA(ai, bj, At, Btf) do { __builtin_amdgcn_s_setprio(1); \
;     for (int m = 0; m < 4; ++m) for (int n = 0; n < 2; ++n) for (int k = 0; k < 2; ++k) \
;       acc[ai][bj][m][n] = __builtin_amdgcn_mfma_f32_16x16x32_bf16(Btf[n][k], At[m][k], acc[ai][bj][m][n], 0, 0, 0); \
;     __builtin_amdgcn_s_setprio(0); } while (0)
; #define WAIT_L(n) asm volatile("s_waitcnt lgkmcnt(" #n ")" ::: "memory")
; #define BAR __builtin_amdgcn_s_barrier()
; #define SCHED __builtin_amdgcn_sched_barrier(0)
; template <int EPI> ...
;     ...
;     WAIT_L(8); BAR; WAIT_L(0); MMA(0, 0, At, B0); BAR; SCHED;
;     LDB(B1, 1, 1); STAGE(SB(1, 0), Bt, bcol, t + 3);
;     BAR; WAIT_L(0); MMA(0, 1, At, B1); BAR;
	s_barrier
	v_mfma_f32_16x16x32_bf16 v[124:127], v[160:163], v[176:179], v[124:127]
	v_mfma_f32_16x16x32_bf16 v[120:123], v[164:167], v[176:179], v[120:123]
	v_mfma_f32_16x16x32_bf16 v[116:119], v[160:163], v[184:187], v[116:119]
	v_mfma_f32_16x16x32_bf16 v[112:115], v[164:167], v[184:187], v[112:115]
	v_mfma_f32_16x16x32_bf16 v[108:111], v[160:163], v[192:195], v[108:111]
	v_mfma_f32_16x16x32_bf16 v[104:107], v[164:167], v[192:195], v[104:107]
	v_mfma_f32_16x16x32_bf16 v[100:103], v[160:163], v[200:203], v[100:103]
	v_mfma_f32_16x16x32_bf16 v[96:99], v[164:167], v[200:203], v[96:99]
	v_mfma_f32_16x16x32_bf16 v[124:127], v[168:171], v[180:183], v[124:127]
	v_mfma_f32_16x16x32_bf16 v[120:123], v[172:175], v[180:183], v[120:123]
	v_mfma_f32_16x16x32_bf16 v[116:119], v[168:171], v[188:191], v[116:119]
	v_mfma_f32_16x16x32_bf16 v[112:115], v[172:175], v[188:191], v[112:115]
	v_mfma_f32_16x16x32_bf16 v[108:111], v[168:171], v[196:199], v[108:111]
	v_mfma_f32_16x16x32_bf16 v[104:107], v[172:175], v[196:199], v[104:107]
	v_mfma_f32_16x16x32_bf16 v[100:103], v[168:171], v[204:207], v[100:103]
	v_mfma_f32_16x16x32_bf16 v[96:99], v[172:175], v[204:207], v[96:99]
	v_mfma_f32_16x16x32_bf16 v[92:95], v[208:211], v[176:179], v[92:95]
	v_mfma_f32_16x16x32_bf16 v[88:91], v[212:215], v[176:179], v[88:91]
	v_mfma_f32_16x16x32_bf16 v[84:87], v[208:211], v[184:187], v[84:87]
	v_mfma_f32_16x16x32_bf16 v[80:83], v[212:215], v[184:187], v[80:83]
	v_mfma_f32_16x16x32_bf16 v[76:79], v[208:211], v[192:195], v[76:79]
	v_mfma_f32_16x16x32_bf16 v[72:75], v[212:215], v[192:195], v[72:75]
	v_mfma_f32_16x16x32_bf16 v[68:71], v[208:211], v[200:203], v[68:71]
	v_mfma_f32_16x16x32_bf16 v[64:67], v[212:215], v[200:203], v[64:67]
	v_mfma_f32_16x16x32_bf16 v[92:95], v[216:219], v[180:183], v[92:95]
	v_mfma_f32_16x16x32_bf16 v[88:91], v[220:223], v[180:183], v[88:91]
	v_mfma_f32_16x16x32_bf16 v[84:87], v[216:219], v[188:191], v[84:87]
	v_mfma_f32_16x16x32_bf16 v[80:83], v[220:223], v[188:191], v[80:83]
	v_mfma_f32_16x16x32_bf16 v[76:79], v[216:219], v[196:199], v[76:79]
	v_mfma_f32_16x16x32_bf16 v[72:75], v[220:223], v[196:199], v[72:75]
	v_mfma_f32_16x16x32_bf16 v[68:71], v[216:219], v[204:207], v[68:71]
	v_mfma_f32_16x16x32_bf16 v[64:67], v[220:223], v[204:207], v[64:67]
	s_barrier

; #define STAGE(P, BASE, br, kt) do { const char* _gb = (const char*)(BASE) + ((size_t)(br) * K + (size_t)(kt) * BK) * 2; \
;     __builtin_amdgcn_global_load_lds((const unsigned*)(_gb + loff0), (unsigned*)((char*)(P) + tid * 16), 16, 0, 0); \
;     __builtin_amdgcn_global_load_lds((const unsigned*)(_gb + (size_t)K * 128 + loff0), (unsigned*)((char*)(P) + tid * 16 + 8192), 16, 0, 0); } while (0)
; #define LDA(dst, b, h) for (int m = 0; m < 4; ++m) { \
;     dst[m][0] = *reinterpret_cast<const bf16x8*>((char*)SA(b, h) + aoff0 + m * 2048); \
;     dst[m][1] = *reinterpret_cast<const bf16x8*>((char*)SA(b, h) + aoff1 + m * 2048); }
; #define MMA(ai, bj, At, Btf) do { __builtin_amdgcn_s_setprio(1); \
;     for (int m = 0; m < 4; ++m) for (int n = 0; n < 2; ++n) for (int k = 0; k < 2; ++k) \
;       acc[ai][bj][m][n] = __builtin_amdgcn_mfma_f32_16x16x32_bf16(Btf[n][k], At[m][k], acc[ai][bj][m][n], 0, 0, 0); \
;     __builtin_amdgcn_s_setprio(0); } while (0)
; #define WAIT_V(n) asm volatile("s_waitcnt vmcnt(" #n ")" ::: "memory")
; #define WAIT_L(n) asm volatile("s_waitcnt lgkmcnt(" #n ")" ::: "memory")
; #define BAR __builtin_amdgcn_s_barrier()
; #define SCHED __builtin_amdgcn_sched_barrier(0)
; template <int EPI> ...
;     ...
;     LDA(At, 1, 1); STAGE(SA(1, 0), A, brow, t + 3);
;     BAR; WAIT_L(0); MMA(1, 0, At, B0); BAR; SCHED;
;     STAGE(SB(1, 1), Bt, bcol + HALF, t + 3);
;     WAIT_V(6); BAR; MMA(1, 1, At, B1); BAR;
	v_readfirstlane_b32 s77, v143
	v_lshl_add_u64 v[230:231], v[226:227], 0, s[48:49]
	s_mov_b32 m0, s77
	v_readfirstlane_b32 s77, v144
	global_load_lds_dwordx4 v[230:231], off
	v_lshl_add_u64 v[226:227], v[226:227], 0, s[50:51]
	s_mov_b32 m0, s77
	s_nop 0
	global_load_lds_dwordx4 v[226:227], off
	v_readfirstlane_b32 s77, v145
	v_lshl_add_u64 v[226:227], v[224:225], 0, s[52:53]
	s_mov_b32 m0, s77
	v_readfirstlane_b32 s77, v146
	ds_read_b128 v[176:179], v149 offset:49152
	ds_read_b128 v[180:183], v149 offset:50176
	ds_read_b128 v[184:187], v149 offset:51200
	ds_read_b128 v[188:191], v149 offset:52224
	ds_read_b128 v[192:195], v149 offset:53248
	ds_read_b128 v[196:199], v149 offset:54272
	ds_read_b128 v[200:203], v149 offset:55296
	ds_read_b128 v[204:207], v149 offset:56320
	global_load_lds_dwordx4 v[226:227], off
	v_lshl_add_u64 v[224:225], v[224:225], 0, s[54:55]
	s_mov_b32 m0, s77
	s_nop 0
	global_load_lds_dwordx4 v[224:225], off
	v_readfirstlane_b32 s77, v147
	v_lshl_add_u64 v[246:247], v[228:229], 0, s[56:57]
	s_mov_b32 m0, s77
	v_readfirstlane_b32 s77, v148
	global_load_lds_dwordx4 v[246:247], off
	s_waitcnt vmcnt(5)
	s_barrier
	s_waitcnt lgkmcnt(0)

; #define MMA(ai, bj, At, Btf) do { __builtin_amdgcn_s_setprio(1); \
;     for (int m = 0; m < 4; ++m) for (int n = 0; n < 2; ++n) for (int k = 0; k < 2; ++k) \
;       acc[ai][bj][m][n] = __builtin_amdgcn_mfma_f32_16x16x32_bf16(Btf[n][k], At[m][k], acc[ai][bj][m][n], 0, 0, 0); \
;     __builtin_amdgcn_s_setprio(0); } while (0)
; #define WAIT_L(n) asm volatile("s_waitcnt lgkmcnt(" #n ")" ::: "memory")
; #define BAR __builtin_amdgcn_s_barrier()
; #define SCHED __builtin_amdgcn_sched_barrier(0)
; template <int EPI> ...
;     ...
;     BAR; WAIT_L(0); MMA(1, 0, At, B0); BAR; SCHED;
	s_waitcnt lgkmcnt(0)
	v_mfma_f32_16x16x32_bf16 v[60:63], v[160:163], v[176:179], v[60:63]
	v_mfma_f32_16x16x32_bf16 v[56:59], v[164:167], v[176:179], v[56:59]
	v_mfma_f32_16x16x32_bf16 v[52:55], v[160:163], v[184:187], v[52:55]
	v_mfma_f32_16x16x32_bf16 v[48:51], v[164:167], v[184:187], v[48:51]
	v_mfma_f32_16x16x32_bf16 v[44:47], v[160:163], v[192:195], v[44:47]
	v_mfma_f32_16x16x32_bf16 v[40:43], v[164:167], v[192:195], v[40:43]
	v_mfma_f32_16x16x32_bf16 v[36:39], v[160:163], v[200:203], v[36:39]
	v_mfma_f32_16x16x32_bf16 v[32:35], v[164:167], v[200:203], v[32:35]
	v_mfma_f32_16x16x32_bf16 v[60:63], v[168:171], v[180:183], v[60:63]
	v_mfma_f32_16x16x32_bf16 v[56:59], v[172:175], v[180:183], v[56:59]
	v_mfma_f32_16x16x32_bf16 v[52:55], v[168:171], v[188:191], v[52:55]
	v_mfma_f32_16x16x32_bf16 v[48:51], v[172:175], v[188:191], v[48:51]
	v_mfma_f32_16x16x32_bf16 v[44:47], v[168:171], v[196:199], v[44:47]
	v_mfma_f32_16x16x32_bf16 v[40:43], v[172:175], v[196:199], v[40:43]
	v_mfma_f32_16x16x32_bf16 v[36:39], v[168:171], v[204:207], v[36:39]
	v_mfma_f32_16x16x32_bf16 v[32:35], v[172:175], v[204:207], v[32:35]


; #define MMA(ai, bj, At, Btf) do { __builtin_amdgcn_s_setprio(1); \
;     for (int m = 0; m < 4; ++m) for (int n = 0; n < 2; ++n) for (int k = 0; k < 2; ++k) \
;       acc[ai][bj][m][n] = __builtin_amdgcn_mfma_f32_16x16x32_bf16(Btf[n][k], At[m][k], acc[ai][bj][m][n], 0, 0, 0); \
;     __builtin_amdgcn_s_setprio(0); } while (0)
; #define WAIT_V(n) asm volatile("s_waitcnt vmcnt(" #n ")" ::: "memory")
; #define BAR __builtin_amdgcn_s_barrier()
; template <int EPI> ...
;     ...
;     WAIT_V(6); BAR; MMA(1, 1, At, B1); BAR;
	v_mfma_f32_16x16x32_bf16 v[28:31], v[208:211], v[176:179], v[28:31]
	v_mfma_f32_16x16x32_bf16 v[24:27], v[212:215], v[176:179], v[24:27]
	v_mfma_f32_16x16x32_bf16 v[20:23], v[208:211], v[184:187], v[20:23]
	v_mfma_f32_16x16x32_bf16 v[16:19], v[212:215], v[184:187], v[16:19]
	v_mfma_f32_16x16x32_bf16 v[12:15], v[208:211], v[192:195], v[12:15]
	v_mfma_f32_16x16x32_bf16 v[8:11], v[212:215], v[192:195], v[8:11]
	v_mfma_f32_16x16x32_bf16 v[4:7], v[208:211], v[200:203], v[4:7]
	v_mfma_f32_16x16x32_bf16 v[0:3], v[212:215], v[200:203], v[0:3]
	v_mfma_f32_16x16x32_bf16 v[28:31], v[216:219], v[180:183], v[28:31]
	v_mfma_f32_16x16x32_bf16 v[24:27], v[220:223], v[180:183], v[24:27]
	v_mfma_f32_16x16x32_bf16 v[20:23], v[216:219], v[188:191], v[20:23]
	v_mfma_f32_16x16x32_bf16 v[16:19], v[220:223], v[188:191], v[16:19]
	v_mfma_f32_16x16x32_bf16 v[12:15], v[216:219], v[196:199], v[12:15]
	v_mfma_f32_16x16x32_bf16 v[8:11], v[220:223], v[196:199], v[8:11]
	v_mfma_f32_16x16x32_bf16 v[4:7], v[216:219], v[204:207], v[4:7]
	v_mfma_f32_16x16x32_bf16 v[0:3], v[220:223], v[204:207], v[0:3]

; #define STAGE(P, BASE, br, kt) do { const char* _gb = (const char*)(BASE) + ((size_t)(br) * K + (size_t)(kt) * BK) * 2; \
;     __builtin_amdgcn_global_load_lds((const unsigned*)(_gb + loff0), (unsigned*)((char*)(P) + tid * 16), 16, 0, 0); \
;     __builtin_amdgcn_global_load_lds((const unsigned*)(_gb + (size_t)K * 128 + loff0), (unsigned*)((char*)(P) + tid * 16 + 8192), 16, 0, 0); } while (0)
; #define LDA(dst, b, h) for (int m = 0; m < 4; ++m) { \
;     dst[m][0] = *reinterpret_cast<const bf16x8*>((char*)SA(b, h) + aoff0 + m * 2048); \
;     dst[m][1] = *reinterpret_cast<const bf16x8*>((char*)SA(b, h) + aoff1 + m * 2048); }
; #define LDB(dst, b, h) for (int n = 0; n < 2; ++n) { \
;     dst[n][0] = *reinterpret_cast<const bf16x8*>((char*)SB(b, h) + boff0 + n * 256); \
;     dst[n][1] = *reinterpret_cast<const bf16x8*>((char*)SB(b, h) + boff1 + n * 256); }
; #define MMA(ai, bj, At, Btf) do { __builtin_amdgcn_s_setprio(1); \
;     for (int m = 0; m < 4; ++m) for (int n = 0; n < 2; ++n) for (int k = 0; k < 2; ++k) \
;       acc[ai][bj][m][n] = __builtin_amdgcn_mfma_f32_16x16x32_bf16(Btf[n][k], At[m][k], acc[ai][bj][m][n], 0, 0, 0); \
;     __builtin_amdgcn_s_setprio(0); } while (0)
; #define WAIT_V(n) asm volatile("s_waitcnt vmcnt(" #n ")" ::: "memory")
; #define BAR __builtin_amdgcn_s_barrier()
; template <int EPI> ...
;     ...
;   for (int t = 0; t < nt - 2; t += 2) {
;     ...
;     WAIT_V(6); BAR; MMA(1, 1, At, B1); BAR;
;   }
;   { LDB(B0, 0, 0); LDA(At, 0, 0); STAGE(SA(1, 1), A, brow + HALF, nt - 1);
	s_add_i32 s76, s76, 2
	s_add_u32 s62, s62, 0x100
	s_addc_u32 s63, s63, 0
	s_add_u32 s64, s64, 0x100
	s_addc_u32 s65, s65, 0
	s_add_u32 s66, s66, 0x100
	s_addc_u32 s67, s67, 0
	s_cmpk_lt_u32 s76, 0x54
	s_barrier
	s_cbranch_scc1 .LBB0_324
	v_readfirstlane_b32 s77, v148
	v_lshl_add_u64 v[246:247], v[228:229], 0, s[58:59]
	s_mov_b32 m0, s77
	s_nop 0
	global_load_lds_dwordx4 v[246:247], off
	s_add_u32 s62, s70, s75
	s_addc_u32 s63, s71, s74
	v_lshl_add_u64 v[208:209], s[62:63], 0, v[128:129]
	v_readfirstlane_b32 s62, v150
	s_mov_b32 m0, s62
	v_readfirstlane_b32 s62, v151
	ds_read_b128 v[160:163], v152
	ds_read_b128 v[164:167], v152 offset:256
	ds_read_b128 v[168:171], v153
	ds_read_b128 v[172:175], v153 offset:256
	ds_read_b128 v[176:179], v149
	ds_read_b128 v[180:183], v149 offset:1024
	ds_read_b128 v[184:187], v149 offset:2048
	ds_read_b128 v[188:191], v149 offset:3072
	ds_read_b128 v[192:195], v149 offset:4096
	ds_read_b128 v[196:199], v149 offset:5120
	ds_read_b128 v[200:203], v149 offset:6144
	ds_read_b128 v[204:207], v149 offset:7168
	global_load_lds_dwordx4 v[208:209], off
	v_lshl_add_u64 v[208:209], v[208:209], 0, s[8:9]
	s_mov_b32 m0, s62
	s_nop 0
	global_load_lds_dwordx4 v[208:209], off
	s_waitcnt lgkmcnt(0)

; #define STAGE(P, BASE, br, kt) do { const char* _gb = (const char*)(BASE) + ((size_t)(br) * K + (size_t)(kt) * BK) * 2; \
;     __builtin_amdgcn_global_load_lds((const unsigned*)(_gb + loff0), (unsigned*)((char*)(P) + tid * 16), 16, 0, 0); \
;     __builtin_amdgcn_global_load_lds((const unsigned*)(_gb + (size_t)K * 128 + loff0), (unsigned*)((char*)(P) + tid * 16 + 8192), 16, 0, 0); } while (0)
; #define LDA(dst, b, h) for (int m = 0; m < 4; ++m) { \
;     dst[m][0] = *reinterpret_cast<const bf16x8*>((char*)SA(b, h) + aoff0 + m * 2048); \
;     dst[m][1] = *reinterpret_cast<const bf16x8*>((char*)SA(b, h) + aoff1 + m * 2048); }
; #define LDB(dst, b, h) for (int n = 0; n < 2; ++n) { \
;     dst[n][0] = *reinterpret_cast<const bf16x8*>((char*)SB(b, h) + boff0 + n * 256); \
;     dst[n][1] = *reinterpret_cast<const bf16x8*>((char*)SB(b, h) + boff1 + n * 256); }
; #define MMA(ai, bj, At, Btf) do { __builtin_amdgcn_s_setprio(1); \
;     for (int m = 0; m < 4; ++m) for (int n = 0; n < 2; ++n) for (int k = 0; k < 2; ++k) \
;       acc[ai][bj][m][n] = __builtin_amdgcn_mfma_f32_16x16x32_bf16(Btf[n][k], At[m][k], acc[ai][bj][m][n], 0, 0, 0); \
;     __builtin_amdgcn_s_setprio(0); } while (0)
; #define WAIT_L(n) asm volatile("s_waitcnt lgkmcnt(" #n ")" ::: "memory")
; #define BAR __builtin_amdgcn_s_barrier()
; template <int EPI> ...
;     ...
;   { LDB(B0, 0, 0); LDA(At, 0, 0); STAGE(SA(1, 1), A, brow + HALF, nt - 1);
;     BAR; WAIT_L(0); MMA(0, 0, At, B0); BAR;
	s_barrier
	v_mfma_f32_16x16x32_bf16 v[124:127], v[160:163], v[176:179], v[124:127]
	v_mfma_f32_16x16x32_bf16 v[116:119], v[160:163], v[184:187], v[116:119]
	v_mfma_f32_16x16x32_bf16 v[108:111], v[160:163], v[192:195], v[108:111]
	v_mfma_f32_16x16x32_bf16 v[100:103], v[160:163], v[200:203], v[100:103]
	v_mfma_f32_16x16x32_bf16 v[96:99], v[164:167], v[200:203], v[96:99]
	v_mfma_f32_16x16x32_bf16 v[124:127], v[168:171], v[180:183], v[124:127]
	v_mfma_f32_16x16x32_bf16 v[120:123], v[164:167], v[176:179], v[120:123]
	v_mfma_f32_16x16x32_bf16 v[116:119], v[168:171], v[188:191], v[116:119]
	v_mfma_f32_16x16x32_bf16 v[112:115], v[164:167], v[184:187], v[112:115]
	v_mfma_f32_16x16x32_bf16 v[108:111], v[168:171], v[196:199], v[108:111]
	v_mfma_f32_16x16x32_bf16 v[104:107], v[164:167], v[192:195], v[104:107]
	v_mfma_f32_16x16x32_bf16 v[100:103], v[168:171], v[204:207], v[100:103]
	v_mfma_f32_16x16x32_bf16 v[96:99], v[172:175], v[204:207], v[96:99]
	v_mfma_f32_16x16x32_bf16 v[208:211], v[172:175], v[180:183], v[120:123]
	v_mfma_f32_16x16x32_bf16 v[212:215], v[172:175], v[188:191], v[112:115]
	v_mfma_f32_16x16x32_bf16 v[216:219], v[172:175], v[196:199], v[104:107]
	s_barrier

; #define LDB(dst, b, h) for (int n = 0; n < 2; ++n) { \
;     dst[n][0] = *reinterpret_cast<const bf16x8*>((char*)SB(b, h) + boff0 + n * 256); \
;     dst[n][1] = *reinterpret_cast<const bf16x8*>((char*)SB(b, h) + boff1 + n * 256); }
; #define MMA(ai, bj, At, Btf) do { __builtin_amdgcn_s_setprio(1); \
;     for (int m = 0; m < 4; ++m) for (int n = 0; n < 2; ++n) for (int k = 0; k < 2; ++k) \
;       acc[ai][bj][m][n] = __builtin_amdgcn_mfma_f32_16x16x32_bf16(Btf[n][k], At[m][k], acc[ai][bj][m][n], 0, 0, 0); \
;     __builtin_amdgcn_s_setprio(0); } while (0)
; #define WAIT_L(n) asm volatile("s_waitcnt lgkmcnt(" #n ")" ::: "memory")
; #define BAR __builtin_amdgcn_s_barrier()
; template <int EPI> ...
;     ...
;     LDB(B1, 0, 1); BAR; WAIT_L(0); MMA(0, 1, At, B1); BAR;
	s_nop 0
	ds_read_b128 v[104:107], v154
	ds_read_b128 v[112:115], v154 offset:256
	ds_read_b128 v[120:123], v155
	ds_read_b128 v[220:223], v155 offset:256
	s_waitcnt lgkmcnt(0)

; #define LDB(dst, b, h) for (int n = 0; n < 2; ++n) { \
;     dst[n][0] = *reinterpret_cast<const bf16x8*>((char*)SB(b, h) + boff0 + n * 256); \
;     dst[n][1] = *reinterpret_cast<const bf16x8*>((char*)SB(b, h) + boff1 + n * 256); }
; #define MMA(ai, bj, At, Btf) do { __builtin_amdgcn_s_setprio(1); \
;     for (int m = 0; m < 4; ++m) for (int n = 0; n < 2; ++n) for (int k = 0; k < 2; ++k) \
;       acc[ai][bj][m][n] = __builtin_amdgcn_mfma_f32_16x16x32_bf16(Btf[n][k], At[m][k], acc[ai][bj][m][n], 0, 0, 0); \
;     __builtin_amdgcn_s_setprio(0); } while (0)
; #define WAIT_L(n) asm volatile("s_waitcnt lgkmcnt(" #n ")" ::: "memory")
; #define BAR __builtin_amdgcn_s_barrier()
; template <int EPI> ...
;     ...
;     LDB(B1, 0, 1); BAR; WAIT_L(0); MMA(0, 1, At, B1); BAR;
	s_barrier
	v_mfma_f32_16x16x32_bf16 v[84:87], v[104:107], v[184:187], v[84:87]
	v_mfma_f32_16x16x32_bf16 v[76:79], v[104:107], v[192:195], v[76:79]
	v_mfma_f32_16x16x32_bf16 v[72:75], v[112:115], v[192:195], v[72:75]
	v_mfma_f32_16x16x32_bf16 v[92:95], v[104:107], v[176:179], v[92:95]
	v_mfma_f32_16x16x32_bf16 v[88:91], v[112:115], v[176:179], v[88:91]
	v_mfma_f32_16x16x32_bf16 v[84:87], v[120:123], v[188:191], v[84:87]
	v_mfma_f32_16x16x32_bf16 v[80:83], v[112:115], v[184:187], v[80:83]
	v_mfma_f32_16x16x32_bf16 v[76:79], v[120:123], v[196:199], v[76:79]
	v_mfma_f32_16x16x32_bf16 v[72:75], v[220:223], v[196:199], v[72:75]
	v_mfma_f32_16x16x32_bf16 v[68:71], v[104:107], v[200:203], v[68:71]
	v_mfma_f32_16x16x32_bf16 v[64:67], v[112:115], v[200:203], v[64:67]
	v_mfma_f32_16x16x32_bf16 v[224:227], v[120:123], v[180:183], v[92:95]
	v_mfma_f32_16x16x32_bf16 v[176:179], v[220:223], v[180:183], v[88:91]
	v_mfma_f32_16x16x32_bf16 v[180:183], v[220:223], v[188:191], v[80:83]
	v_mfma_f32_16x16x32_bf16 v[184:187], v[120:123], v[204:207], v[68:71]
	v_mfma_f32_16x16x32_bf16 v[188:191], v[220:223], v[204:207], v[64:67]
	s_barrier

; #define LDA(dst, b, h) for (int m = 0; m < 4; ++m) { \
;     dst[m][0] = *reinterpret_cast<const bf16x8*>((char*)SA(b, h) + aoff0 + m * 2048); \
;     dst[m][1] = *reinterpret_cast<const bf16x8*>((char*)SA(b, h) + aoff1 + m * 2048); }
; #define MMA(ai, bj, At, Btf) do { __builtin_amdgcn_s_setprio(1); \
;     for (int m = 0; m < 4; ++m) for (int n = 0; n < 2; ++n) for (int k = 0; k < 2; ++k) \
;       acc[ai][bj][m][n] = __builtin_amdgcn_mfma_f32_16x16x32_bf16(Btf[n][k], At[m][k], acc[ai][bj][m][n], 0, 0, 0); \
;     __builtin_amdgcn_s_setprio(0); } while (0)
; #define WAIT_V(n) asm volatile("s_waitcnt vmcnt(" #n ")" ::: "memory")
; #define WAIT_L(n) asm volatile("s_waitcnt lgkmcnt(" #n ")" ::: "memory")
; #define BAR __builtin_amdgcn_s_barrier()
; template <int EPI> ...
;     ...
;     LDA(At, 0, 1); WAIT_V(4); BAR; WAIT_L(0); MMA(1, 0, At, B0); MMA(1, 1, At, B1); BAR; }
	s_nop 0
	ds_read_b128 v[64:67], v149 offset:16384
	ds_read_b128 v[68:71], v149 offset:17408
	ds_read_b128 v[80:83], v149 offset:18432
	ds_read_b128 v[88:91], v149 offset:19456
	ds_read_b128 v[92:95], v149 offset:20480
	ds_read_b128 v[192:195], v149 offset:21504
	ds_read_b128 v[196:199], v149 offset:22528
	ds_read_b128 v[200:203], v149 offset:23552
	s_waitcnt vmcnt(4)
	s_waitcnt lgkmcnt(0)

; #define LDA(dst, b, h) for (int m = 0; m < 4; ++m) { \
;     dst[m][0] = *reinterpret_cast<const bf16x8*>((char*)SA(b, h) + aoff0 + m * 2048); \
;     dst[m][1] = *reinterpret_cast<const bf16x8*>((char*)SA(b, h) + aoff1 + m * 2048); }
; #define MMA(ai, bj, At, Btf) do { __builtin_amdgcn_s_setprio(1); \
;     for (int m = 0; m < 4; ++m) for (int n = 0; n < 2; ++n) for (int k = 0; k < 2; ++k) \
;       acc[ai][bj][m][n] = __builtin_amdgcn_mfma_f32_16x16x32_bf16(Btf[n][k], At[m][k], acc[ai][bj][m][n], 0, 0, 0); \
;     __builtin_amdgcn_s_setprio(0); } while (0)
; #define WAIT_V(n) asm volatile("s_waitcnt vmcnt(" #n ")" ::: "memory")
; #define WAIT_L(n) asm volatile("s_waitcnt lgkmcnt(" #n ")" ::: "memory")
; #define BAR __builtin_amdgcn_s_barrier()
; template <int EPI> ...
;     ...
;     LDA(At, 0, 1); WAIT_V(4); BAR; WAIT_L(0); MMA(1, 0, At, B0); MMA(1, 1, At, B1); BAR; }
	s_barrier
	v_mfma_f32_16x16x32_bf16 v[52:55], v[160:163], v[80:83], v[52:55]
	v_mfma_f32_16x16x32_bf16 v[44:47], v[160:163], v[92:95], v[44:47]
	v_mfma_f32_16x16x32_bf16 v[36:39], v[160:163], v[196:199], v[36:39]
	v_mfma_f32_16x16x32_bf16 v[60:63], v[160:163], v[64:67], v[60:63]
	v_mfma_f32_16x16x32_bf16 v[56:59], v[164:167], v[64:67], v[56:59]
	v_mfma_f32_16x16x32_bf16 v[52:55], v[168:171], v[88:91], v[52:55]
	v_mfma_f32_16x16x32_bf16 v[48:51], v[164:167], v[80:83], v[48:51]
	v_mfma_f32_16x16x32_bf16 v[44:47], v[168:171], v[192:195], v[44:47]
	v_mfma_f32_16x16x32_bf16 v[40:43], v[164:167], v[92:95], v[40:43]
	v_mfma_f32_16x16x32_bf16 v[36:39], v[168:171], v[200:203], v[36:39]
	v_mfma_f32_16x16x32_bf16 v[32:35], v[164:167], v[196:199], v[32:35]
	v_mfma_f32_16x16x32_bf16 v[204:207], v[168:171], v[68:71], v[60:63]
	v_mfma_f32_16x16x32_bf16 v[228:231], v[172:175], v[68:71], v[56:59]
	v_mfma_f32_16x16x32_bf16 v[232:235], v[172:175], v[88:91], v[48:51]
	v_mfma_f32_16x16x32_bf16 v[236:239], v[172:175], v[192:195], v[40:43]
	v_mfma_f32_16x16x32_bf16 v[160:163], v[172:175], v[200:203], v[32:35]
	v_mfma_f32_16x16x32_bf16 v[28:31], v[104:107], v[64:67], v[28:31]
	v_mfma_f32_16x16x32_bf16 v[20:23], v[104:107], v[80:83], v[20:23]
	v_mfma_f32_16x16x32_bf16 v[12:15], v[104:107], v[92:95], v[12:15]
	v_mfma_f32_16x16x32_bf16 v[4:7], v[104:107], v[196:199], v[4:7]
	v_mfma_f32_16x16x32_bf16 v[28:31], v[120:123], v[68:71], v[28:31]
	v_mfma_f32_16x16x32_bf16 v[24:27], v[112:115], v[64:67], v[24:27]
	v_mfma_f32_16x16x32_bf16 v[20:23], v[120:123], v[88:91], v[20:23]
	v_mfma_f32_16x16x32_bf16 v[16:19], v[112:115], v[80:83], v[16:19]
	v_mfma_f32_16x16x32_bf16 v[12:15], v[120:123], v[192:195], v[12:15]
	v_mfma_f32_16x16x32_bf16 v[8:11], v[112:115], v[92:95], v[8:11]
	v_mfma_f32_16x16x32_bf16 v[4:7], v[120:123], v[200:203], v[4:7]
	v_mfma_f32_16x16x32_bf16 v[0:3], v[112:115], v[196:199], v[0:3]
	v_mfma_f32_16x16x32_bf16 v[164:167], v[220:223], v[68:71], v[24:27]
	v_mfma_f32_16x16x32_bf16 v[168:171], v[220:223], v[88:91], v[16:19]
	v_mfma_f32_16x16x32_bf16 v[172:175], v[220:223], v[192:195], v[8:11]
	v_mfma_f32_16x16x32_bf16 v[192:195], v[220:223], v[200:203], v[0:3]
	s_barrier

; #define LDA(dst, b, h) for (int m = 0; m < 4; ++m) { \
;     dst[m][0] = *reinterpret_cast<const bf16x8*>((char*)SA(b, h) + aoff0 + m * 2048); \
;     dst[m][1] = *reinterpret_cast<const bf16x8*>((char*)SA(b, h) + aoff1 + m * 2048); }
; #define LDB(dst, b, h) for (int n = 0; n < 2; ++n) { \
;     dst[n][0] = *reinterpret_cast<const bf16x8*>((char*)SB(b, h) + boff0 + n * 256); \
;     dst[n][1] = *reinterpret_cast<const bf16x8*>((char*)SB(b, h) + boff1 + n * 256); }
; #define MMA(ai, bj, At, Btf) do { __builtin_amdgcn_s_setprio(1); \
;     for (int m = 0; m < 4; ++m) for (int n = 0; n < 2; ++n) for (int k = 0; k < 2; ++k) \
;       acc[ai][bj][m][n] = __builtin_amdgcn_mfma_f32_16x16x32_bf16(Btf[n][k], At[m][k], acc[ai][bj][m][n], 0, 0, 0); \
;     __builtin_amdgcn_s_setprio(0); } while (0)
; #define WAIT_V(n) asm volatile("s_waitcnt vmcnt(" #n ")" ::: "memory")
; #define WAIT_L(n) asm volatile("s_waitcnt lgkmcnt(" #n ")" ::: "memory")
; #define BAR __builtin_amdgcn_s_barrier()
; template <int EPI> ...
;     ...
;   { LDB(B0, 1, 0); LDA(At, 1, 0); WAIT_V(2); BAR; WAIT_L(0); MMA(0, 0, At, B0); BAR;
	s_nop 1
	ds_read_b128 v[0:3], v156
	ds_read_b128 v[8:11], v156 offset:256
	ds_read_b128 v[16:19], v157
	ds_read_b128 v[24:27], v157 offset:256
	ds_read_b128 v[32:35], v149 offset:32768
	ds_read_b128 v[40:43], v149 offset:33792
	ds_read_b128 v[48:51], v149 offset:34816
	ds_read_b128 v[56:59], v149 offset:35840
	ds_read_b128 v[60:63], v149 offset:36864
	ds_read_b128 v[68:71], v149 offset:37888
	ds_read_b128 v[196:199], v149 offset:38912
	ds_read_b128 v[200:203], v149 offset:39936
	s_waitcnt vmcnt(2)
	s_waitcnt lgkmcnt(0)

; #define LDA(dst, b, h) for (int m = 0; m < 4; ++m) { \
;     dst[m][0] = *reinterpret_cast<const bf16x8*>((char*)SA(b, h) + aoff0 + m * 2048); \
;     dst[m][1] = *reinterpret_cast<const bf16x8*>((char*)SA(b, h) + aoff1 + m * 2048); }
; #define LDB(dst, b, h) for (int n = 0; n < 2; ++n) { \
;     dst[n][0] = *reinterpret_cast<const bf16x8*>((char*)SB(b, h) + boff0 + n * 256); \
;     dst[n][1] = *reinterpret_cast<const bf16x8*>((char*)SB(b, h) + boff1 + n * 256); }
; #define MMA(ai, bj, At, Btf) do { __builtin_amdgcn_s_setprio(1); \
;     for (int m = 0; m < 4; ++m) for (int n = 0; n < 2; ++n) for (int k = 0; k < 2; ++k) \
;       acc[ai][bj][m][n] = __builtin_amdgcn_mfma_f32_16x16x32_bf16(Btf[n][k], At[m][k], acc[ai][bj][m][n], 0, 0, 0); \
;     __builtin_amdgcn_s_setprio(0); } while (0)
; #define WAIT_V(n) asm volatile("s_waitcnt vmcnt(" #n ")" ::: "memory")
; #define WAIT_L(n) asm volatile("s_waitcnt lgkmcnt(" #n ")" ::: "memory")
; #define BAR __builtin_amdgcn_s_barrier()
; template <int EPI> ...
;     ...
;   { LDB(B0, 1, 0); LDA(At, 1, 0); WAIT_V(2); BAR; WAIT_L(0); MMA(0, 0, At, B0); BAR;
	s_barrier
	v_mfma_f32_16x16x32_bf16 v[64:67], v[0:3], v[32:35], v[124:127]
	v_mfma_f32_16x16x32_bf16 v[120:123], v[16:19], v[40:43], v[64:67]
	v_mfma_f32_16x16x32_bf16 v[64:67], v[8:11], v[32:35], v[208:211]
	v_mfma_f32_16x16x32_bf16 v[124:127], v[24:27], v[40:43], v[64:67]
	v_mfma_f32_16x16x32_bf16 v[64:67], v[0:3], v[48:51], v[116:119]
	v_mfma_f32_16x16x32_bf16 v[112:115], v[16:19], v[56:59], v[64:67]
	v_mfma_f32_16x16x32_bf16 v[64:67], v[8:11], v[48:51], v[212:215]
	v_mfma_f32_16x16x32_bf16 v[116:119], v[24:27], v[56:59], v[64:67]
	v_mfma_f32_16x16x32_bf16 v[64:67], v[0:3], v[60:63], v[108:111]
	v_mfma_f32_16x16x32_bf16 v[104:107], v[16:19], v[68:71], v[64:67]
	v_mfma_f32_16x16x32_bf16 v[64:67], v[8:11], v[60:63], v[216:219]
	v_mfma_f32_16x16x32_bf16 v[108:111], v[24:27], v[68:71], v[64:67]
	v_mfma_f32_16x16x32_bf16 v[64:67], v[0:3], v[196:199], v[100:103]
	v_mfma_f32_16x16x32_bf16 v[88:91], v[16:19], v[200:203], v[64:67]
	v_mfma_f32_16x16x32_bf16 v[64:67], v[8:11], v[196:199], v[96:99]
	v_mfma_f32_16x16x32_bf16 v[92:95], v[24:27], v[200:203], v[64:67]
	s_barrier

; #define LDB(dst, b, h) for (int n = 0; n < 2; ++n) { \
;     dst[n][0] = *reinterpret_cast<const bf16x8*>((char*)SB(b, h) + boff0 + n * 256); \
;     dst[n][1] = *reinterpret_cast<const bf16x8*>((char*)SB(b, h) + boff1 + n * 256); }
; #define MMA(ai, bj, At, Btf) do { __builtin_amdgcn_s_setprio(1); \
;     for (int m = 0; m < 4; ++m) for (int n = 0; n < 2; ++n) for (int k = 0; k < 2; ++k) \
;       acc[ai][bj][m][n] = __builtin_amdgcn_mfma_f32_16x16x32_bf16(Btf[n][k], At[m][k], acc[ai][bj][m][n], 0, 0, 0); \
;     __builtin_amdgcn_s_setprio(0); } while (0)
; #define WAIT_V(n) asm volatile("s_waitcnt vmcnt(" #n ")" ::: "memory")
; #define WAIT_L(n) asm volatile("s_waitcnt lgkmcnt(" #n ")" ::: "memory")
; #define BAR __builtin_amdgcn_s_barrier()
; template <int EPI> ...
;     ...
;     LDB(B1, 1, 1); WAIT_V(0); BAR; WAIT_L(0); MMA(0, 1, At, B1); BAR;
	ds_read_b128 v[208:211], v158
	ds_read_b128 v[212:215], v158 offset:256
	ds_read_b128 v[216:219], v159
	ds_read_b128 v[220:223], v159 offset:256
	s_waitcnt vmcnt(0)
	s_waitcnt lgkmcnt(0)

; #define LDB(dst, b, h) for (int n = 0; n < 2; ++n) { \
;     dst[n][0] = *reinterpret_cast<const bf16x8*>((char*)SB(b, h) + boff0 + n * 256); \
;     dst[n][1] = *reinterpret_cast<const bf16x8*>((char*)SB(b, h) + boff1 + n * 256); }
; #define MMA(ai, bj, At, Btf) do { __builtin_amdgcn_s_setprio(1); \
;     for (int m = 0; m < 4; ++m) for (int n = 0; n < 2; ++n) for (int k = 0; k < 2; ++k) \
;       acc[ai][bj][m][n] = __builtin_amdgcn_mfma_f32_16x16x32_bf16(Btf[n][k], At[m][k], acc[ai][bj][m][n], 0, 0, 0); \
;     __builtin_amdgcn_s_setprio(0); } while (0)
; #define WAIT_V(n) asm volatile("s_waitcnt vmcnt(" #n ")" ::: "memory")
; #define WAIT_L(n) asm volatile("s_waitcnt lgkmcnt(" #n ")" ::: "memory")
; #define BAR __builtin_amdgcn_s_barrier()
; template <int EPI> ...
;     ...
;     LDB(B1, 1, 1); WAIT_V(0); BAR; WAIT_L(0); MMA(0, 1, At, B1); BAR;
	s_barrier
	v_mfma_f32_16x16x32_bf16 v[64:67], v[208:211], v[32:35], v[224:227]
	v_mfma_f32_16x16x32_bf16 v[32:35], v[212:215], v[32:35], v[176:179]
	v_mfma_f32_16x16x32_bf16 v[100:103], v[220:223], v[40:43], v[32:35]
	v_mfma_f32_16x16x32_bf16 v[32:35], v[208:211], v[48:51], v[84:87]
	v_mfma_f32_16x16x32_bf16 v[80:83], v[216:219], v[56:59], v[32:35]
	v_mfma_f32_16x16x32_bf16 v[32:35], v[212:215], v[48:51], v[180:183]
	v_mfma_f32_16x16x32_bf16 v[84:87], v[220:223], v[56:59], v[32:35]
	v_mfma_f32_16x16x32_bf16 v[32:35], v[208:211], v[60:63], v[76:79]
	v_mfma_f32_16x16x32_bf16 v[96:99], v[216:219], v[40:43], v[64:67]
	v_mfma_f32_16x16x32_bf16 v[64:67], v[216:219], v[68:71], v[32:35]
	v_mfma_f32_16x16x32_bf16 v[32:35], v[212:215], v[60:63], v[72:75]
	v_mfma_f32_16x16x32_bf16 v[68:71], v[220:223], v[68:71], v[32:35]
	v_mfma_f32_16x16x32_bf16 v[32:35], v[208:211], v[196:199], v[184:187]
	v_mfma_f32_16x16x32_bf16 v[56:59], v[216:219], v[200:203], v[32:35]
	v_mfma_f32_16x16x32_bf16 v[32:35], v[212:215], v[196:199], v[188:191]
	v_mfma_f32_16x16x32_bf16 v[60:63], v[220:223], v[200:203], v[32:35]
	s_barrier

; #define LDA(dst, b, h) for (int m = 0; m < 4; ++m) { \
;     dst[m][0] = *reinterpret_cast<const bf16x8*>((char*)SA(b, h) + aoff0 + m * 2048); \
;     dst[m][1] = *reinterpret_cast<const bf16x8*>((char*)SA(b, h) + aoff1 + m * 2048); }
; #define MMA(ai, bj, At, Btf) do { __builtin_amdgcn_s_setprio(1); \
;     for (int m = 0; m < 4; ++m) for (int n = 0; n < 2; ++n) for (int k = 0; k < 2; ++k) \
;       acc[ai][bj][m][n] = __builtin_amdgcn_mfma_f32_16x16x32_bf16(Btf[n][k], At[m][k], acc[ai][bj][m][n], 0, 0, 0); \
;     __builtin_amdgcn_s_setprio(0); } while (0)
; #define WAIT_L(n) asm volatile("s_waitcnt lgkmcnt(" #n ")" ::: "memory")
; #define BAR __builtin_amdgcn_s_barrier()
; template <int EPI> ...
;     ...
;     LDA(At, 1, 1); BAR; WAIT_L(0); MMA(1, 0, At, B0); MMA(1, 1, At, B1); BAR; }
	ds_read_b128 v[176:179], v149 offset:49152
	ds_read_b128 v[180:183], v149 offset:50176
	ds_read_b128 v[184:187], v149 offset:51200
	ds_read_b128 v[188:191], v149 offset:52224
	ds_read_b128 v[196:199], v149 offset:53248
	ds_read_b128 v[200:203], v149 offset:54272
	ds_read_b128 v[224:227], v149 offset:55296
	ds_read_b128 v[240:243], v149 offset:56320
	s_waitcnt lgkmcnt(0)

; #define LDA(dst, b, h) for (int m = 0; m < 4; ++m) { \
;     dst[m][0] = *reinterpret_cast<const bf16x8*>((char*)SA(b, h) + aoff0 + m * 2048); \
;     dst[m][1] = *reinterpret_cast<const bf16x8*>((char*)SA(b, h) + aoff1 + m * 2048); }
; #define MMA(ai, bj, At, Btf) do { __builtin_amdgcn_s_setprio(1); \
;     for (int m = 0; m < 4; ++m) for (int n = 0; n < 2; ++n) for (int k = 0; k < 2; ++k) \
;       acc[ai][bj][m][n] = __builtin_amdgcn_mfma_f32_16x16x32_bf16(Btf[n][k], At[m][k], acc[ai][bj][m][n], 0, 0, 0); \
;     __builtin_amdgcn_s_setprio(0); } while (0)
; #define WAIT_L(n) asm volatile("s_waitcnt lgkmcnt(" #n ")" ::: "memory")
; #define BAR __builtin_amdgcn_s_barrier()
; template <int EPI> ...
;     ...
;     LDA(At, 1, 1); BAR; WAIT_L(0); MMA(1, 0, At, B0); MMA(1, 1, At, B1); BAR; }
	s_barrier
	v_mfma_f32_16x16x32_bf16 v[32:35], v[0:3], v[176:179], v[204:207]
	v_mfma_f32_16x16x32_bf16 v[72:75], v[16:19], v[180:183], v[32:35]
	v_mfma_f32_16x16x32_bf16 v[32:35], v[8:11], v[176:179], v[228:231]
	v_mfma_f32_16x16x32_bf16 v[76:79], v[24:27], v[180:183], v[32:35]
	v_mfma_f32_16x16x32_bf16 v[32:35], v[0:3], v[184:187], v[52:55]
	v_mfma_f32_16x16x32_bf16 v[48:51], v[16:19], v[188:191], v[32:35]
	v_mfma_f32_16x16x32_bf16 v[32:35], v[8:11], v[184:187], v[232:235]
	v_mfma_f32_16x16x32_bf16 v[52:55], v[24:27], v[188:191], v[32:35]
	v_mfma_f32_16x16x32_bf16 v[32:35], v[0:3], v[196:199], v[44:47]
	v_mfma_f32_16x16x32_bf16 v[40:43], v[16:19], v[200:203], v[32:35]
	v_mfma_f32_16x16x32_bf16 v[32:35], v[8:11], v[196:199], v[236:239]
	v_mfma_f32_16x16x32_bf16 v[0:3], v[0:3], v[224:227], v[36:39]
	v_mfma_f32_16x16x32_bf16 v[44:47], v[24:27], v[200:203], v[32:35]
	v_mfma_f32_16x16x32_bf16 v[32:35], v[16:19], v[240:243], v[0:3]
	v_mfma_f32_16x16x32_bf16 v[0:3], v[8:11], v[224:227], v[160:163]
	v_mfma_f32_16x16x32_bf16 v[36:39], v[24:27], v[240:243], v[0:3]
	v_mfma_f32_16x16x32_bf16 v[0:3], v[208:211], v[176:179], v[28:31]
	v_mfma_f32_16x16x32_bf16 v[24:27], v[216:219], v[180:183], v[0:3]
	v_mfma_f32_16x16x32_bf16 v[0:3], v[212:215], v[176:179], v[164:167]
	v_mfma_f32_16x16x32_bf16 v[28:31], v[220:223], v[180:183], v[0:3]
	v_mfma_f32_16x16x32_bf16 v[0:3], v[208:211], v[184:187], v[20:23]
	v_mfma_f32_16x16x32_bf16 v[16:19], v[216:219], v[188:191], v[0:3]
	v_mfma_f32_16x16x32_bf16 v[0:3], v[212:215], v[184:187], v[168:171]
	v_mfma_f32_16x16x32_bf16 v[20:23], v[220:223], v[188:191], v[0:3]
	v_mfma_f32_16x16x32_bf16 v[0:3], v[208:211], v[196:199], v[12:15]
	v_mfma_f32_16x16x32_bf16 v[8:11], v[216:219], v[200:203], v[0:3]
	v_mfma_f32_16x16x32_bf16 v[0:3], v[212:215], v[196:199], v[172:175]
	v_mfma_f32_16x16x32_bf16 v[12:15], v[220:223], v[200:203], v[0:3]
	v_mfma_f32_16x16x32_bf16 v[0:3], v[208:211], v[224:227], v[4:7]
	v_mfma_f32_16x16x32_bf16 v[4:7], v[212:215], v[224:227], v[192:195]
	v_mfma_f32_16x16x32_bf16 v[0:3], v[216:219], v[240:243], v[0:3]
	v_mfma_f32_16x16x32_bf16 v[4:7], v[220:223], v[240:243], v[4:7]
	s_barrier

; #define LDA(dst, b, h) for (int m = 0; m < 4; ++m) { \
;     dst[m][0] = *reinterpret_cast<const bf16x8*>((char*)SA(b, h) + aoff0 + m * 2048); \
;     dst[m][1] = *reinterpret_cast<const bf16x8*>((char*)SA(b, h) + aoff1 + m * 2048); }
; #define MMA(ai, bj, At, Btf) do { __builtin_amdgcn_s_setprio(1); \
;     for (int m = 0; m < 4; ++m) for (int n = 0; n < 2; ++n) for (int k = 0; k < 2; ++k) \
;       acc[ai][bj][m][n] = __builtin_amdgcn_mfma_f32_16x16x32_bf16(Btf[n][k], At[m][k], acc[ai][bj][m][n], 0, 0, 0); \
;     __builtin_amdgcn_s_setprio(0); } while (0)
; #define WAIT_L(n) asm volatile("s_waitcnt lgkmcnt(" #n ")" ::: "memory")
; #define BAR __builtin_amdgcn_s_barrier()
; template <int EPI> ...
;     ...
;     LDA(At, 1, 1); BAR; WAIT_L(0); MMA(1, 0, At, B0); MMA(1, 1, At, B1); BAR; }
;   if (wr == 0) BAR;
	s_setprio 0
	s_and_saveexec_b64 s[62:63], s[2:3]
	s_cbranch_execz .LBB0_318
	s_barrier
	s_branch .LBB0_318

; #define STAGE(P, BASE, br, kt) do { const char* _gb = (const char*)(BASE) + ((size_t)(br) * K + (size_t)(kt) * BK) * 2; \
;     __builtin_amdgcn_global_load_lds((const unsigned*)(_gb + loff0), (unsigned*)((char*)(P) + tid * 16), 16, 0, 0); \
;     __builtin_amdgcn_global_load_lds((const unsigned*)(_gb + (size_t)K * 128 + loff0), (unsigned*)((char*)(P) + tid * 16 + 8192), 16, 0, 0); } while (0)
; #define BAR __builtin_amdgcn_s_barrier()
; template <int EPI> ...
;     ...
;   f32x4 acc[2][2][4][2] = {};
;   bf16x8 At[4][2], B0[2][2], B1[2][2];
;   int nt = K / BK;
;   const int aoff0 = lds_byte(wr * 64 + fr, fq * 8), aoff1 = lds_byte(wr * 64 + fr, 32 + fq * 8);
;   const int brw = wc * 32 + (fr >> 2) * 8 + (fr & 3);
;   const int boff0 = lds_byte(brw, fq * 8), boff1 = lds_byte(brw, 32 + fq * 8);
;   unsigned loff0;
;   { int _r, _c; stage_rc(tid * 16, _r, _c); loff0 = (unsigned)(_r * K + _c) * 2u; }
;   STAGE(SB(0, 0), Bt, bcol, 0); STAGE(SA(0, 0), A, brow, 0);
;   STAGE(SB(0, 1), Bt, bcol + HALF, 0); STAGE(SA(0, 1), A, brow + HALF, 0);
;   if (wr == 1) BAR;
; template <int EPI>
; __device__ __forceinline__ void gemm_phase(const u16* A, const u16* Bt, int M, int N, int K, u16* out, int ldo,
;                                            const float* aux, int bid, int nblk, int wv) {
;     ...
;   for (int base = 0; base < ntile; base += nblk) {
;     int wgid;
;     if (base + nblk <= ntile && (nblk & 7) == 0) wgid = base + (bid & 7) * (nblk >> 3) + (bid >> 3);
;     else wgid = base + bid;
;     if (wgid >= ntile) break;
;     int nig = WGM * nN, gid = wgid / nig, fm = gid * WGM, gsz = min(nM - fm, WGM);
;     int pm = fm + ((wgid % nig) % gsz), pn = (wgid % nig) / gsz;
;     int brow = pm * BM, bcol = pn * BM;
;     gemm_tile<EPI>(A, Bt, K, brow, bcol, out, ldo, EPI == 1 ? pn * HALF : bcol, aux, tid);
.LBB0_407:
	s_mov_b32 s62, s76
	s_add_i32 s76, s76, s33
	s_cmpk_lt_i32 s76, 0xb01
	s_cselect_b64 s[60:61], -1, 0
	s_and_b64 s[60:61], s[44:45], s[60:61]
	s_and_b64 s[60:61], s[60:61], exec
	s_cselect_b32 s60, s86, s91
	s_add_i32 s62, s60, s62
	s_cmpk_gt_i32 s62, 0xaff
	s_mov_b64 s[60:61], -1
	s_cbranch_scc1 .LBB0_406
	s_mul_hi_i32 s60, s62, 0x2e8ba2e9
	s_lshr_b32 s61, s60, 31
	s_ashr_i32 s60, s60, 5
	s_add_i32 s60, s60, s61
	s_mul_i32 s61, s60, 0xb0
	s_sub_i32 s61, s62, s61
	s_sext_i32_i16 s62, s61
	s_bfe_u32 s62, s62, 0x3001c
	s_add_i32 s62, s61, s62
	s_sext_i32_i16 s63, s62
	s_and_b32 s62, s62, 0xfff8
	s_sub_i32 s61, s61, s62
	s_sext_i32_i16 s61, s61
	s_lshl_b32 s60, s60, 11
	s_lshl_b32 s61, s61, 8
	s_add_i32 s60, s61, s60
	s_lshl_b32 s61, s63, 5
	s_and_b32 s62, s61, 0xffffff00
	s_ashr_i32 s63, s62, 31
	s_lshl_b64 s[66:67], s[62:63], 12
	s_add_u32 s64, s72, s66
	s_addc_u32 s65, s73, s67
	v_readfirstlane_b32 s61, v135
	v_lshl_add_u64 v[0:1], s[64:65], 0, v[128:129]
	s_mov_b32 m0, s61
	v_readfirstlane_b32 s61, v136
	global_load_lds_dwordx4 v[0:1], off
	s_mov_b32 m0, s61
	s_ashr_i32 s61, s60, 31
	s_lshl_b64 s[68:69], s[60:61], 12
	s_add_u32 s64, s14, s68
	v_lshl_add_u64 v[2:3], v[0:1], 0, s[8:9]
	s_addc_u32 s65, s43, s69
	global_load_lds_dwordx4 v[2:3], off
	v_lshl_add_u64 v[2:3], s[64:65], 0, v[128:129]
	s_or_b32 s64, s62, 0x80
	s_ashr_i32 s65, s64, 31
	v_readfirstlane_b32 s61, v137
	s_lshl_b64 s[64:65], s[64:65], 12
	s_mov_b32 m0, s61
	v_readfirstlane_b32 s61, v138
	s_add_u32 s64, s72, s64
	global_load_lds_dwordx4 v[2:3], off
	v_lshl_add_u64 v[4:5], v[2:3], 0, s[8:9]
	s_mov_b32 m0, s61
	s_addc_u32 s65, s73, s65
	global_load_lds_dwordx4 v[4:5], off
	v_lshl_add_u64 v[4:5], s[64:65], 0, v[128:129]
	s_or_b32 s64, s60, 0x80
	s_ashr_i32 s65, s64, 31
	v_readfirstlane_b32 s61, v139
	s_lshl_b64 s[64:65], s[64:65], 12
	s_mov_b32 m0, s61
	v_readfirstlane_b32 s61, v140
	s_add_u32 s70, s14, s64
	global_load_lds_dwordx4 v[4:5], off
	v_lshl_add_u64 v[6:7], v[4:5], 0, s[8:9]
	s_mov_b32 m0, s61
	s_addc_u32 s71, s43, s65
	v_readfirstlane_b32 s61, v141
	global_load_lds_dwordx4 v[6:7], off
	v_lshl_add_u64 v[6:7], s[70:71], 0, v[128:129]
	s_mov_b32 m0, s61
	v_readfirstlane_b32 s61, v142
	global_load_lds_dwordx4 v[6:7], off
	v_lshl_add_u64 v[6:7], v[6:7], 0, s[8:9]
	s_mov_b32 m0, s61
	s_nop 0
	global_load_lds_dwordx4 v[6:7], off
	v_mov_b32_e32 v8, 0
	v_mov_b32_e32 v9, 0
	v_mov_b32_e32 v10, 0
	v_mov_b32_e32 v11, 0
	v_mov_b32_e32 v12, 0
	v_mov_b32_e32 v13, 0
	v_mov_b32_e32 v14, 0
	v_mov_b32_e32 v15, 0
	v_mov_b32_e32 v16, 0
	v_mov_b32_e32 v17, 0
	v_mov_b32_e32 v18, 0
	v_mov_b32_e32 v19, 0
	v_mov_b32_e32 v20, 0
	v_mov_b32_e32 v21, 0
	v_mov_b32_e32 v22, 0
	v_mov_b32_e32 v23, 0
	v_mov_b32_e32 v24, 0
	v_mov_b32_e32 v25, 0
	v_mov_b32_e32 v26, 0
	v_mov_b32_e32 v27, 0
	v_mov_b32_e32 v28, 0
	v_mov_b32_e32 v29, 0
	v_mov_b32_e32 v30, 0
	v_mov_b32_e32 v31, 0
	v_mov_b32_e32 v32, 0
	v_mov_b32_e32 v33, 0
	v_mov_b32_e32 v34, 0
	v_mov_b32_e32 v35, 0
	v_mov_b32_e32 v36, 0
	v_mov_b32_e32 v37, 0
	v_mov_b32_e32 v38, 0
	v_mov_b32_e32 v39, 0
	v_mov_b32_e32 v40, 0
	v_mov_b32_e32 v41, 0
	v_mov_b32_e32 v42, 0
	v_mov_b32_e32 v43, 0
	v_mov_b32_e32 v44, 0
	v_mov_b32_e32 v45, 0
	v_mov_b32_e32 v46, 0
	v_mov_b32_e32 v47, 0
	v_mov_b32_e32 v48, 0
	v_mov_b32_e32 v49, 0
	v_mov_b32_e32 v50, 0
	v_mov_b32_e32 v51, 0
	v_mov_b32_e32 v52, 0
	v_mov_b32_e32 v53, 0
	v_mov_b32_e32 v54, 0
	v_mov_b32_e32 v55, 0
	v_mov_b32_e32 v56, 0
	v_mov_b32_e32 v57, 0
	v_mov_b32_e32 v58, 0
	v_mov_b32_e32 v59, 0
	v_mov_b32_e32 v60, 0
	v_mov_b32_e32 v61, 0
	v_mov_b32_e32 v62, 0
	v_mov_b32_e32 v63, 0
	v_mov_b32_e32 v64, 0
	v_mov_b32_e32 v65, 0
	v_mov_b32_e32 v66, 0
	v_mov_b32_e32 v67, 0
	v_mov_b32_e32 v68, 0
	v_mov_b32_e32 v69, 0
	v_mov_b32_e32 v70, 0
	v_mov_b32_e32 v71, 0
	v_mov_b32_e32 v72, 0
	v_mov_b32_e32 v73, 0
	v_mov_b32_e32 v74, 0
	v_mov_b32_e32 v75, 0
	v_mov_b32_e32 v76, 0
	v_mov_b32_e32 v77, 0
	v_mov_b32_e32 v78, 0
	v_mov_b32_e32 v79, 0
	v_mov_b32_e32 v80, 0
	v_mov_b32_e32 v81, 0
	v_mov_b32_e32 v82, 0
	v_mov_b32_e32 v83, 0
	v_mov_b32_e32 v84, 0
	v_mov_b32_e32 v85, 0
	v_mov_b32_e32 v86, 0
	v_mov_b32_e32 v87, 0
	v_mov_b32_e32 v88, 0
	v_mov_b32_e32 v89, 0
	v_mov_b32_e32 v90, 0
	v_mov_b32_e32 v91, 0
	v_mov_b32_e32 v92, 0
	v_mov_b32_e32 v93, 0
	v_mov_b32_e32 v94, 0
	v_mov_b32_e32 v95, 0
	v_mov_b32_e32 v96, 0
	v_mov_b32_e32 v97, 0
	v_mov_b32_e32 v98, 0
	v_mov_b32_e32 v99, 0
	v_mov_b32_e32 v100, 0
	v_mov_b32_e32 v101, 0
	v_mov_b32_e32 v102, 0
	v_mov_b32_e32 v103, 0
	v_mov_b32_e32 v104, 0
	v_mov_b32_e32 v105, 0
	v_mov_b32_e32 v106, 0
	v_mov_b32_e32 v107, 0
	v_mov_b32_e32 v108, 0
	v_mov_b32_e32 v109, 0
	v_mov_b32_e32 v110, 0
	v_mov_b32_e32 v111, 0
	v_mov_b32_e32 v112, 0
	v_mov_b32_e32 v113, 0
	v_mov_b32_e32 v114, 0
	v_mov_b32_e32 v115, 0
	v_mov_b32_e32 v116, 0
	v_mov_b32_e32 v117, 0
	v_mov_b32_e32 v118, 0
	v_mov_b32_e32 v119, 0
	v_mov_b32_e32 v120, 0
	v_mov_b32_e32 v121, 0
	v_mov_b32_e32 v122, 0
	v_mov_b32_e32 v123, 0
	v_mov_b32_e32 v124, 0
	v_mov_b32_e32 v125, 0
	v_mov_b32_e32 v126, 0
	v_mov_b32_e32 v127, 0
	s_and_saveexec_b64 s[70:71], s[4:5]
	s_cbranch_execz .LBB0_410
	s_setprio 1
	s_barrier

; #define STAGE(P, BASE, br, kt) do { const char* _gb = (const char*)(BASE) + ((size_t)(br) * K + (size_t)(kt) * BK) * 2; \
;     __builtin_amdgcn_global_load_lds((const unsigned*)(_gb + loff0), (unsigned*)((char*)(P) + tid * 16), 16, 0, 0); \
;     __builtin_amdgcn_global_load_lds((const unsigned*)(_gb + (size_t)K * 128 + loff0), (unsigned*)((char*)(P) + tid * 16 + 8192), 16, 0, 0); } while (0)
; #define LDA(dst, b, h) for (int m = 0; m < 4; ++m) { \
;     dst[m][0] = *reinterpret_cast<const bf16x8*>((char*)SA(b, h) + aoff0 + m * 2048); \
;     dst[m][1] = *reinterpret_cast<const bf16x8*>((char*)SA(b, h) + aoff1 + m * 2048); }
; #define LDB(dst, b, h) for (int n = 0; n < 2; ++n) { \
;     dst[n][0] = *reinterpret_cast<const bf16x8*>((char*)SB(b, h) + boff0 + n * 256); \
;     dst[n][1] = *reinterpret_cast<const bf16x8*>((char*)SB(b, h) + boff1 + n * 256); }
; #define MMA(ai, bj, At, Btf) do { __builtin_amdgcn_s_setprio(1); \
;     for (int m = 0; m < 4; ++m) for (int n = 0; n < 2; ++n) for (int k = 0; k < 2; ++k) \
;       acc[ai][bj][m][n] = __builtin_amdgcn_mfma_f32_16x16x32_bf16(Btf[n][k], At[m][k], acc[ai][bj][m][n], 0, 0, 0); \
;     __builtin_amdgcn_s_setprio(0); } while (0)
; #define WAIT_L(n) asm volatile("s_waitcnt lgkmcnt(" #n ")" ::: "memory")
; #define BAR __builtin_amdgcn_s_barrier()
; #define SCHED __builtin_amdgcn_sched_barrier(0)
; template <int EPI> ...
;     ...
;     LDB(B0, 0, 0); SCHED; LDA(At, 0, 0); STAGE(SA(1, 1), A, brow + HALF, t + 1);
;     WAIT_L(8); BAR; WAIT_L(0); MMA(0, 0, At, B0); BAR; SCHED;
;     LDB(B1, 0, 1); STAGE(SB(0, 0), Bt, bcol, t + 2);
.LBB0_411:
	ds_read_b128 v[160:163], v152
	ds_read_b128 v[164:167], v152 offset:256
	ds_read_b128 v[168:171], v153
	ds_read_b128 v[172:175], v153 offset:256
	v_lshl_add_u64 v[224:225], s[68:69], 0, v[132:133]
	v_readfirstlane_b32 s70, v150
	v_lshl_add_u64 v[208:209], v[224:225], 0, s[16:17]
	s_mov_b32 m0, s70
	v_readfirstlane_b32 s70, v151
	ds_read_b128 v[176:179], v149
	ds_read_b128 v[180:183], v149 offset:1024
	ds_read_b128 v[184:187], v149 offset:2048
	ds_read_b128 v[188:191], v149 offset:3072
	ds_read_b128 v[192:195], v149 offset:4096
	ds_read_b128 v[196:199], v149 offset:5120
	ds_read_b128 v[200:203], v149 offset:6144
	ds_read_b128 v[204:207], v149 offset:7168
	global_load_lds_dwordx4 v[208:209], off
	v_lshl_add_u64 v[208:209], v[224:225], 0, s[18:19]
	s_mov_b32 m0, s70
	s_nop 0
	global_load_lds_dwordx4 v[208:209], off
	s_waitcnt lgkmcnt(8)
	v_readfirstlane_b32 s70, v148
	v_lshl_add_u64 v[246:247], v[226:227], 0, s[58:59]
	s_mov_b32 m0, s70
	s_nop 0
	global_load_lds_dwordx4 v[246:247], off
	ds_read_b128 v[208:211], v154
	ds_read_b128 v[212:215], v154 offset:256
	ds_read_b128 v[216:219], v155
	ds_read_b128 v[220:223], v155 offset:256
	s_waitcnt lgkmcnt(0)

; #define STAGE(P, BASE, br, kt) do { const char* _gb = (const char*)(BASE) + ((size_t)(br) * K + (size_t)(kt) * BK) * 2; \
;     __builtin_amdgcn_global_load_lds((const unsigned*)(_gb + loff0), (unsigned*)((char*)(P) + tid * 16), 16, 0, 0); \
;     __builtin_amdgcn_global_load_lds((const unsigned*)(_gb + (size_t)K * 128 + loff0), (unsigned*)((char*)(P) + tid * 16 + 8192), 16, 0, 0); } while (0)
; #define LDB(dst, b, h) for (int n = 0; n < 2; ++n) { \
;     dst[n][0] = *reinterpret_cast<const bf16x8*>((char*)SB(b, h) + boff0 + n * 256); \
;     dst[n][1] = *reinterpret_cast<const bf16x8*>((char*)SB(b, h) + boff1 + n * 256); }
; #define MMA(ai, bj, At, Btf) do { __builtin_amdgcn_s_setprio(1); \
;     for (int m = 0; m < 4; ++m) for (int n = 0; n < 2; ++n) for (int k = 0; k < 2; ++k) \
;       acc[ai][bj][m][n] = __builtin_amdgcn_mfma_f32_16x16x32_bf16(Btf[n][k], At[m][k], acc[ai][bj][m][n], 0, 0, 0); \
;     __builtin_amdgcn_s_setprio(0); } while (0)
; #define WAIT_L(n) asm volatile("s_waitcnt lgkmcnt(" #n ")" ::: "memory")
; #define BAR __builtin_amdgcn_s_barrier()
; #define SCHED __builtin_amdgcn_sched_barrier(0)
; template <int EPI> ...
;     ...
;     WAIT_L(8); BAR; WAIT_L(0); MMA(0, 0, At, B0); BAR; SCHED;
;     LDB(B1, 0, 1); STAGE(SB(0, 0), Bt, bcol, t + 2);
;     BAR; WAIT_L(0); MMA(0, 1, At, B1); BAR;
	s_barrier
	v_mfma_f32_16x16x32_bf16 v[124:127], v[160:163], v[176:179], v[124:127]
	v_mfma_f32_16x16x32_bf16 v[120:123], v[164:167], v[176:179], v[120:123]
	v_mfma_f32_16x16x32_bf16 v[116:119], v[160:163], v[184:187], v[116:119]
	v_mfma_f32_16x16x32_bf16 v[112:115], v[164:167], v[184:187], v[112:115]
	v_mfma_f32_16x16x32_bf16 v[108:111], v[160:163], v[192:195], v[108:111]
	v_mfma_f32_16x16x32_bf16 v[104:107], v[164:167], v[192:195], v[104:107]
	v_mfma_f32_16x16x32_bf16 v[100:103], v[160:163], v[200:203], v[100:103]
	v_mfma_f32_16x16x32_bf16 v[96:99], v[164:167], v[200:203], v[96:99]
	v_mfma_f32_16x16x32_bf16 v[124:127], v[168:171], v[180:183], v[124:127]
	v_mfma_f32_16x16x32_bf16 v[120:123], v[172:175], v[180:183], v[120:123]
	v_mfma_f32_16x16x32_bf16 v[116:119], v[168:171], v[188:191], v[116:119]
	v_mfma_f32_16x16x32_bf16 v[112:115], v[172:175], v[188:191], v[112:115]
	v_mfma_f32_16x16x32_bf16 v[108:111], v[168:171], v[196:199], v[108:111]
	v_mfma_f32_16x16x32_bf16 v[104:107], v[172:175], v[196:199], v[104:107]
	v_mfma_f32_16x16x32_bf16 v[100:103], v[168:171], v[204:207], v[100:103]
	v_mfma_f32_16x16x32_bf16 v[96:99], v[172:175], v[204:207], v[96:99]
	v_mfma_f32_16x16x32_bf16 v[92:95], v[208:211], v[176:179], v[92:95]
	v_mfma_f32_16x16x32_bf16 v[88:91], v[212:215], v[176:179], v[88:91]
	v_mfma_f32_16x16x32_bf16 v[84:87], v[208:211], v[184:187], v[84:87]
	v_mfma_f32_16x16x32_bf16 v[80:83], v[212:215], v[184:187], v[80:83]
	v_mfma_f32_16x16x32_bf16 v[76:79], v[208:211], v[192:195], v[76:79]
	v_mfma_f32_16x16x32_bf16 v[72:75], v[212:215], v[192:195], v[72:75]
	v_mfma_f32_16x16x32_bf16 v[68:71], v[208:211], v[200:203], v[68:71]
	v_mfma_f32_16x16x32_bf16 v[64:67], v[212:215], v[200:203], v[64:67]
	v_mfma_f32_16x16x32_bf16 v[92:95], v[216:219], v[180:183], v[92:95]
	v_mfma_f32_16x16x32_bf16 v[88:91], v[220:223], v[180:183], v[88:91]
	v_mfma_f32_16x16x32_bf16 v[84:87], v[216:219], v[188:191], v[84:87]
	v_mfma_f32_16x16x32_bf16 v[80:83], v[220:223], v[188:191], v[80:83]
	v_mfma_f32_16x16x32_bf16 v[76:79], v[216:219], v[196:199], v[76:79]
	v_mfma_f32_16x16x32_bf16 v[72:75], v[220:223], v[196:199], v[72:75]
	v_mfma_f32_16x16x32_bf16 v[68:71], v[216:219], v[204:207], v[68:71]
	v_mfma_f32_16x16x32_bf16 v[64:67], v[220:223], v[204:207], v[64:67]
	s_barrier

; #define STAGE(P, BASE, br, kt) do { const char* _gb = (const char*)(BASE) + ((size_t)(br) * K + (size_t)(kt) * BK) * 2; \
;     __builtin_amdgcn_global_load_lds((const unsigned*)(_gb + loff0), (unsigned*)((char*)(P) + tid * 16), 16, 0, 0); \
;     __builtin_amdgcn_global_load_lds((const unsigned*)(_gb + (size_t)K * 128 + loff0), (unsigned*)((char*)(P) + tid * 16 + 8192), 16, 0, 0); } while (0)
; #define LDA(dst, b, h) for (int m = 0; m < 4; ++m) { \
;     dst[m][0] = *reinterpret_cast<const bf16x8*>((char*)SA(b, h) + aoff0 + m * 2048); \
;     dst[m][1] = *reinterpret_cast<const bf16x8*>((char*)SA(b, h) + aoff1 + m * 2048); }
; #define MMA(ai, bj, At, Btf) do { __builtin_amdgcn_s_setprio(1); \
;     for (int m = 0; m < 4; ++m) for (int n = 0; n < 2; ++n) for (int k = 0; k < 2; ++k) \
;       acc[ai][bj][m][n] = __builtin_amdgcn_mfma_f32_16x16x32_bf16(Btf[n][k], At[m][k], acc[ai][bj][m][n], 0, 0, 0); \
;     __builtin_amdgcn_s_setprio(0); } while (0)
; #define WAIT_V(n) asm volatile("s_waitcnt vmcnt(" #n ")" ::: "memory")
; #define WAIT_L(n) asm volatile("s_waitcnt lgkmcnt(" #n ")" ::: "memory")
; #define BAR __builtin_amdgcn_s_barrier()
; #define SCHED __builtin_amdgcn_sched_barrier(0)
; template <int EPI> ...
;     ...
;     LDA(At, 0, 1); STAGE(SA(0, 0), A, brow, t + 2);
;     BAR; WAIT_L(0); MMA(1, 0, At, B0); BAR; SCHED;
;     STAGE(SB(0, 1), Bt, bcol + HALF, t + 2);
;     WAIT_V(6); BAR; MMA(1, 1, At, B1); BAR;
	v_lshl_add_u64 v[226:227], s[66:67], 0, v[132:133]
	v_readfirstlane_b32 s70, v135
	v_lshl_add_u64 v[228:229], v[226:227], 0, s[20:21]
	s_mov_b32 m0, s70
	v_readfirstlane_b32 s70, v136
	global_load_lds_dwordx4 v[228:229], off
	v_lshl_add_u64 v[228:229], v[226:227], 0, s[22:23]
	s_mov_b32 m0, s70
	s_nop 0
	global_load_lds_dwordx4 v[228:229], off
	v_readfirstlane_b32 s70, v137
	v_lshl_add_u64 v[228:229], v[224:225], 0, s[26:27]
	s_mov_b32 m0, s70
	v_readfirstlane_b32 s70, v138
	ds_read_b128 v[176:179], v149 offset:16384
	ds_read_b128 v[180:183], v149 offset:17408
	ds_read_b128 v[184:187], v149 offset:18432
	ds_read_b128 v[188:191], v149 offset:19456
	ds_read_b128 v[192:195], v149 offset:20480
	ds_read_b128 v[196:199], v149 offset:21504
	ds_read_b128 v[200:203], v149 offset:22528
	ds_read_b128 v[204:207], v149 offset:23552
	global_load_lds_dwordx4 v[228:229], off
	v_lshl_add_u64 v[228:229], v[224:225], 0, s[28:29]
	s_mov_b32 m0, s70
	s_nop 0
	global_load_lds_dwordx4 v[228:229], off
	v_readfirstlane_b32 s70, v139
	v_lshl_add_u64 v[246:247], v[226:227], 0, s[30:31]
	s_mov_b32 m0, s70
	v_readfirstlane_b32 s70, v140
	global_load_lds_dwordx4 v[246:247], off
	s_waitcnt vmcnt(5)
	s_waitcnt lgkmcnt(0)

; #define STAGE(P, BASE, br, kt) do { const char* _gb = (const char*)(BASE) + ((size_t)(br) * K + (size_t)(kt) * BK) * 2; \
;     __builtin_amdgcn_global_load_lds((const unsigned*)(_gb + loff0), (unsigned*)((char*)(P) + tid * 16), 16, 0, 0); \
;     __builtin_amdgcn_global_load_lds((const unsigned*)(_gb + (size_t)K * 128 + loff0), (unsigned*)((char*)(P) + tid * 16 + 8192), 16, 0, 0); } while (0)
; #define MMA(ai, bj, At, Btf) do { __builtin_amdgcn_s_setprio(1); \
;     for (int m = 0; m < 4; ++m) for (int n = 0; n < 2; ++n) for (int k = 0; k < 2; ++k) \
;       acc[ai][bj][m][n] = __builtin_amdgcn_mfma_f32_16x16x32_bf16(Btf[n][k], At[m][k], acc[ai][bj][m][n], 0, 0, 0); \
;     __builtin_amdgcn_s_setprio(0); } while (0)
; #define WAIT_V(n) asm volatile("s_waitcnt vmcnt(" #n ")" ::: "memory")
; #define WAIT_L(n) asm volatile("s_waitcnt lgkmcnt(" #n ")" ::: "memory")
; #define BAR __builtin_amdgcn_s_barrier()
; #define SCHED __builtin_amdgcn_sched_barrier(0)
; template <int EPI> ...
;     ...
;     BAR; WAIT_L(0); MMA(1, 0, At, B0); BAR; SCHED;
;     STAGE(SB(0, 1), Bt, bcol + HALF, t + 2);
;     WAIT_V(6); BAR; MMA(1, 1, At, B1); BAR;
	s_barrier
	v_mfma_f32_16x16x32_bf16 v[60:63], v[160:163], v[176:179], v[60:63]
	v_mfma_f32_16x16x32_bf16 v[56:59], v[164:167], v[176:179], v[56:59]
	v_mfma_f32_16x16x32_bf16 v[52:55], v[160:163], v[184:187], v[52:55]
	v_mfma_f32_16x16x32_bf16 v[48:51], v[164:167], v[184:187], v[48:51]
	v_mfma_f32_16x16x32_bf16 v[44:47], v[160:163], v[192:195], v[44:47]
	v_mfma_f32_16x16x32_bf16 v[40:43], v[164:167], v[192:195], v[40:43]
	v_mfma_f32_16x16x32_bf16 v[36:39], v[160:163], v[200:203], v[36:39]
	v_mfma_f32_16x16x32_bf16 v[32:35], v[164:167], v[200:203], v[32:35]
	v_mfma_f32_16x16x32_bf16 v[60:63], v[168:171], v[180:183], v[60:63]
	v_mfma_f32_16x16x32_bf16 v[56:59], v[172:175], v[180:183], v[56:59]
	v_mfma_f32_16x16x32_bf16 v[52:55], v[168:171], v[188:191], v[52:55]
	v_mfma_f32_16x16x32_bf16 v[48:51], v[172:175], v[188:191], v[48:51]
	v_mfma_f32_16x16x32_bf16 v[44:47], v[168:171], v[196:199], v[44:47]
	v_mfma_f32_16x16x32_bf16 v[40:43], v[172:175], v[196:199], v[40:43]
	v_mfma_f32_16x16x32_bf16 v[36:39], v[168:171], v[204:207], v[36:39]
	v_mfma_f32_16x16x32_bf16 v[32:35], v[172:175], v[204:207], v[32:35]
	v_mfma_f32_16x16x32_bf16 v[28:31], v[208:211], v[176:179], v[28:31]
	v_mfma_f32_16x16x32_bf16 v[24:27], v[212:215], v[176:179], v[24:27]
	v_mfma_f32_16x16x32_bf16 v[20:23], v[208:211], v[184:187], v[20:23]
	v_mfma_f32_16x16x32_bf16 v[16:19], v[212:215], v[184:187], v[16:19]
	v_mfma_f32_16x16x32_bf16 v[12:15], v[208:211], v[192:195], v[12:15]
	v_mfma_f32_16x16x32_bf16 v[8:11], v[212:215], v[192:195], v[8:11]
	v_mfma_f32_16x16x32_bf16 v[4:7], v[208:211], v[200:203], v[4:7]
	v_mfma_f32_16x16x32_bf16 v[0:3], v[212:215], v[200:203], v[0:3]
	v_mfma_f32_16x16x32_bf16 v[28:31], v[216:219], v[180:183], v[28:31]
	v_mfma_f32_16x16x32_bf16 v[24:27], v[220:223], v[180:183], v[24:27]
	v_mfma_f32_16x16x32_bf16 v[20:23], v[216:219], v[188:191], v[20:23]
	v_mfma_f32_16x16x32_bf16 v[16:19], v[220:223], v[188:191], v[16:19]
	v_mfma_f32_16x16x32_bf16 v[12:15], v[216:219], v[196:199], v[12:15]
	v_mfma_f32_16x16x32_bf16 v[8:11], v[220:223], v[196:199], v[8:11]
	v_mfma_f32_16x16x32_bf16 v[4:7], v[216:219], v[204:207], v[4:7]
	v_mfma_f32_16x16x32_bf16 v[0:3], v[220:223], v[204:207], v[0:3]
	s_barrier

; #define STAGE(P, BASE, br, kt) do { const char* _gb = (const char*)(BASE) + ((size_t)(br) * K + (size_t)(kt) * BK) * 2; \
;     __builtin_amdgcn_global_load_lds((const unsigned*)(_gb + loff0), (unsigned*)((char*)(P) + tid * 16), 16, 0, 0); \
;     __builtin_amdgcn_global_load_lds((const unsigned*)(_gb + (size_t)K * 128 + loff0), (unsigned*)((char*)(P) + tid * 16 + 8192), 16, 0, 0); } while (0)
; #define LDA(dst, b, h) for (int m = 0; m < 4; ++m) { \
;     dst[m][0] = *reinterpret_cast<const bf16x8*>((char*)SA(b, h) + aoff0 + m * 2048); \
;     dst[m][1] = *reinterpret_cast<const bf16x8*>((char*)SA(b, h) + aoff1 + m * 2048); }
; #define LDB(dst, b, h) for (int n = 0; n < 2; ++n) { \
;     dst[n][0] = *reinterpret_cast<const bf16x8*>((char*)SB(b, h) + boff0 + n * 256); \
;     dst[n][1] = *reinterpret_cast<const bf16x8*>((char*)SB(b, h) + boff1 + n * 256); }
; #define MMA(ai, bj, At, Btf) do { __builtin_amdgcn_s_setprio(1); \
;     for (int m = 0; m < 4; ++m) for (int n = 0; n < 2; ++n) for (int k = 0; k < 2; ++k) \
;       acc[ai][bj][m][n] = __builtin_amdgcn_mfma_f32_16x16x32_bf16(Btf[n][k], At[m][k], acc[ai][bj][m][n], 0, 0, 0); \
;     __builtin_amdgcn_s_setprio(0); } while (0)
; #define WAIT_L(n) asm volatile("s_waitcnt lgkmcnt(" #n ")" ::: "memory")
; #define BAR __builtin_amdgcn_s_barrier()
; #define SCHED __builtin_amdgcn_sched_barrier(0)
; template <int EPI> ...
;     ...
;     LDB(B0, 1, 0); SCHED; LDA(At, 1, 0); STAGE(SA(0, 1), A, brow + HALF, t + 2);
;     WAIT_L(8); BAR; WAIT_L(0); MMA(0, 0, At, B0); BAR; SCHED;
;     LDB(B1, 1, 1); STAGE(SB(1, 0), Bt, bcol, t + 3);
	ds_read_b128 v[160:163], v156
	ds_read_b128 v[164:167], v156 offset:256
	ds_read_b128 v[168:171], v157
	ds_read_b128 v[172:175], v157 offset:256
	v_readfirstlane_b32 s70, v141
	v_lshl_add_u64 v[208:209], v[224:225], 0, s[38:39]
	s_mov_b32 m0, s70
	v_readfirstlane_b32 s70, v142
	ds_read_b128 v[176:179], v149 offset:32768
	ds_read_b128 v[180:183], v149 offset:33792
	ds_read_b128 v[184:187], v149 offset:34816
	ds_read_b128 v[188:191], v149 offset:35840
	ds_read_b128 v[192:195], v149 offset:36864
	ds_read_b128 v[196:199], v149 offset:37888
	ds_read_b128 v[200:203], v149 offset:38912
	ds_read_b128 v[204:207], v149 offset:39936
	global_load_lds_dwordx4 v[208:209], off
	v_lshl_add_u64 v[208:209], v[224:225], 0, s[46:47]
	s_mov_b32 m0, s70
	s_nop 0
	global_load_lds_dwordx4 v[208:209], off
	s_waitcnt lgkmcnt(8)
	v_readfirstlane_b32 s70, v140
	v_lshl_add_u64 v[246:247], v[226:227], 0, s[36:37]
	s_mov_b32 m0, s70
	s_nop 0
	global_load_lds_dwordx4 v[246:247], off
	ds_read_b128 v[208:211], v158
	ds_read_b128 v[212:215], v158 offset:256
	ds_read_b128 v[216:219], v159
	ds_read_b128 v[220:223], v159 offset:256
	s_waitcnt lgkmcnt(0)

; #define STAGE(P, BASE, br, kt) do { const char* _gb = (const char*)(BASE) + ((size_t)(br) * K + (size_t)(kt) * BK) * 2; \
;     __builtin_amdgcn_global_load_lds((const unsigned*)(_gb + loff0), (unsigned*)((char*)(P) + tid * 16), 16, 0, 0); \
;     __builtin_amdgcn_global_load_lds((const unsigned*)(_gb + (size_t)K * 128 + loff0), (unsigned*)((char*)(P) + tid * 16 + 8192), 16, 0, 0); } while (0)
; #define LDB(dst, b, h) for (int n = 0; n < 2; ++n) { \
;     dst[n][0] = *reinterpret_cast<const bf16x8*>((char*)SB(b, h) + boff0 + n * 256); \
;     dst[n][1] = *reinterpret_cast<const bf16x8*>((char*)SB(b, h) + boff1 + n * 256); }
; #define MMA(ai, bj, At, Btf) do { __builtin_amdgcn_s_setprio(1); \
;     for (int m = 0; m < 4; ++m) for (int n = 0; n < 2; ++n) for (int k = 0; k < 2; ++k) \
;       acc[ai][bj][m][n] = __builtin_amdgcn_mfma_f32_16x16x32_bf16(Btf[n][k], At[m][k], acc[ai][bj][m][n], 0, 0, 0); \
;     __builtin_amdgcn_s_setprio(0); } while (0)
; #define WAIT_L(n) asm volatile("s_waitcnt lgkmcnt(" #n ")" ::: "memory")
; #define BAR __builtin_amdgcn_s_barrier()
; #define SCHED __builtin_amdgcn_sched_barrier(0)
; template <int EPI> ...
;     ...
;     WAIT_L(8); BAR; WAIT_L(0); MMA(0, 0, At, B0); BAR; SCHED;
;     LDB(B1, 1, 1); STAGE(SB(1, 0), Bt, bcol, t + 3);
;     BAR; WAIT_L(0); MMA(0, 1, At, B1); BAR;
	s_barrier
	v_mfma_f32_16x16x32_bf16 v[124:127], v[160:163], v[176:179], v[124:127]
	v_mfma_f32_16x16x32_bf16 v[120:123], v[164:167], v[176:179], v[120:123]
	v_mfma_f32_16x16x32_bf16 v[116:119], v[160:163], v[184:187], v[116:119]
	v_mfma_f32_16x16x32_bf16 v[112:115], v[164:167], v[184:187], v[112:115]
	v_mfma_f32_16x16x32_bf16 v[108:111], v[160:163], v[192:195], v[108:111]
	v_mfma_f32_16x16x32_bf16 v[104:107], v[164:167], v[192:195], v[104:107]
	v_mfma_f32_16x16x32_bf16 v[100:103], v[160:163], v[200:203], v[100:103]
	v_mfma_f32_16x16x32_bf16 v[96:99], v[164:167], v[200:203], v[96:99]
	v_mfma_f32_16x16x32_bf16 v[124:127], v[168:171], v[180:183], v[124:127]
	v_mfma_f32_16x16x32_bf16 v[120:123], v[172:175], v[180:183], v[120:123]
	v_mfma_f32_16x16x32_bf16 v[116:119], v[168:171], v[188:191], v[116:119]
	v_mfma_f32_16x16x32_bf16 v[112:115], v[172:175], v[188:191], v[112:115]
	v_mfma_f32_16x16x32_bf16 v[108:111], v[168:171], v[196:199], v[108:111]
	v_mfma_f32_16x16x32_bf16 v[104:107], v[172:175], v[196:199], v[104:107]
	v_mfma_f32_16x16x32_bf16 v[100:103], v[168:171], v[204:207], v[100:103]
	v_mfma_f32_16x16x32_bf16 v[96:99], v[172:175], v[204:207], v[96:99]
	v_mfma_f32_16x16x32_bf16 v[92:95], v[208:211], v[176:179], v[92:95]
	v_mfma_f32_16x16x32_bf16 v[88:91], v[212:215], v[176:179], v[88:91]
	v_mfma_f32_16x16x32_bf16 v[84:87], v[208:211], v[184:187], v[84:87]
	v_mfma_f32_16x16x32_bf16 v[80:83], v[212:215], v[184:187], v[80:83]
	v_mfma_f32_16x16x32_bf16 v[76:79], v[208:211], v[192:195], v[76:79]
	v_mfma_f32_16x16x32_bf16 v[72:75], v[212:215], v[192:195], v[72:75]
	v_mfma_f32_16x16x32_bf16 v[68:71], v[208:211], v[200:203], v[68:71]
	v_mfma_f32_16x16x32_bf16 v[64:67], v[212:215], v[200:203], v[64:67]
	v_mfma_f32_16x16x32_bf16 v[92:95], v[216:219], v[180:183], v[92:95]
	v_mfma_f32_16x16x32_bf16 v[88:91], v[220:223], v[180:183], v[88:91]
	v_mfma_f32_16x16x32_bf16 v[84:87], v[216:219], v[188:191], v[84:87]
	v_mfma_f32_16x16x32_bf16 v[80:83], v[220:223], v[188:191], v[80:83]
	v_mfma_f32_16x16x32_bf16 v[76:79], v[216:219], v[196:199], v[76:79]
	v_mfma_f32_16x16x32_bf16 v[72:75], v[220:223], v[196:199], v[72:75]
	v_mfma_f32_16x16x32_bf16 v[68:71], v[216:219], v[204:207], v[68:71]
	v_mfma_f32_16x16x32_bf16 v[64:67], v[220:223], v[204:207], v[64:67]
	s_barrier

; #define STAGE(P, BASE, br, kt) do { const char* _gb = (const char*)(BASE) + ((size_t)(br) * K + (size_t)(kt) * BK) * 2; \
;     __builtin_amdgcn_global_load_lds((const unsigned*)(_gb + loff0), (unsigned*)((char*)(P) + tid * 16), 16, 0, 0); \
;     __builtin_amdgcn_global_load_lds((const unsigned*)(_gb + (size_t)K * 128 + loff0), (unsigned*)((char*)(P) + tid * 16 + 8192), 16, 0, 0); } while (0)
; #define LDA(dst, b, h) for (int m = 0; m < 4; ++m) { \
;     dst[m][0] = *reinterpret_cast<const bf16x8*>((char*)SA(b, h) + aoff0 + m * 2048); \
;     dst[m][1] = *reinterpret_cast<const bf16x8*>((char*)SA(b, h) + aoff1 + m * 2048); }
; #define MMA(ai, bj, At, Btf) do { __builtin_amdgcn_s_setprio(1); \
;     for (int m = 0; m < 4; ++m) for (int n = 0; n < 2; ++n) for (int k = 0; k < 2; ++k) \
;       acc[ai][bj][m][n] = __builtin_amdgcn_mfma_f32_16x16x32_bf16(Btf[n][k], At[m][k], acc[ai][bj][m][n], 0, 0, 0); \
;     __builtin_amdgcn_s_setprio(0); } while (0)
; #define WAIT_V(n) asm volatile("s_waitcnt vmcnt(" #n ")" ::: "memory")
; #define WAIT_L(n) asm volatile("s_waitcnt lgkmcnt(" #n ")" ::: "memory")
; #define BAR __builtin_amdgcn_s_barrier()
; #define SCHED __builtin_amdgcn_sched_barrier(0)
; template <int EPI> ...
;     ...
;     LDA(At, 1, 1); STAGE(SA(1, 0), A, brow, t + 3);
;     BAR; WAIT_L(0); MMA(1, 0, At, B0); BAR; SCHED;
;     STAGE(SB(1, 1), Bt, bcol + HALF, t + 3);
;     WAIT_V(6); BAR; MMA(1, 1, At, B1); BAR;
	v_readfirstlane_b32 s70, v143
	v_lshl_add_u64 v[228:229], v[226:227], 0, s[48:49]
	s_mov_b32 m0, s70
	v_readfirstlane_b32 s70, v144
	global_load_lds_dwordx4 v[228:229], off
	v_lshl_add_u64 v[228:229], v[226:227], 0, s[50:51]
	s_mov_b32 m0, s70
	s_nop 0
	global_load_lds_dwordx4 v[228:229], off
	v_readfirstlane_b32 s70, v145
	v_lshl_add_u64 v[228:229], v[224:225], 0, s[52:53]
	s_mov_b32 m0, s70
	v_readfirstlane_b32 s70, v146
	ds_read_b128 v[176:179], v149 offset:49152
	ds_read_b128 v[180:183], v149 offset:50176
	ds_read_b128 v[184:187], v149 offset:51200
	ds_read_b128 v[188:191], v149 offset:52224
	ds_read_b128 v[192:195], v149 offset:53248
	ds_read_b128 v[196:199], v149 offset:54272
	ds_read_b128 v[200:203], v149 offset:55296
	ds_read_b128 v[204:207], v149 offset:56320
	global_load_lds_dwordx4 v[228:229], off
	v_lshl_add_u64 v[224:225], v[224:225], 0, s[54:55]
	s_mov_b32 m0, s70
	s_nop 0
	global_load_lds_dwordx4 v[224:225], off
	v_readfirstlane_b32 s70, v147
	v_lshl_add_u64 v[246:247], v[226:227], 0, s[56:57]
	s_mov_b32 m0, s70
	v_readfirstlane_b32 s70, v148
	global_load_lds_dwordx4 v[246:247], off
	s_waitcnt vmcnt(5)
	s_barrier
	s_waitcnt lgkmcnt(0)

; #define MMA(ai, bj, At, Btf) do { __builtin_amdgcn_s_setprio(1); \
;     for (int m = 0; m < 4; ++m) for (int n = 0; n < 2; ++n) for (int k = 0; k < 2; ++k) \
;       acc[ai][bj][m][n] = __builtin_amdgcn_mfma_f32_16x16x32_bf16(Btf[n][k], At[m][k], acc[ai][bj][m][n], 0, 0, 0); \
;     __builtin_amdgcn_s_setprio(0); } while (0)
; #define WAIT_L(n) asm volatile("s_waitcnt lgkmcnt(" #n ")" ::: "memory")
; #define BAR __builtin_amdgcn_s_barrier()
; #define SCHED __builtin_amdgcn_sched_barrier(0)
; template <int EPI> ...
;     ...
;     BAR; WAIT_L(0); MMA(1, 0, At, B0); BAR; SCHED;
	s_waitcnt lgkmcnt(0)
	v_mfma_f32_16x16x32_bf16 v[60:63], v[160:163], v[176:179], v[60:63]
	v_mfma_f32_16x16x32_bf16 v[56:59], v[164:167], v[176:179], v[56:59]
	v_mfma_f32_16x16x32_bf16 v[52:55], v[160:163], v[184:187], v[52:55]
	v_mfma_f32_16x16x32_bf16 v[48:51], v[164:167], v[184:187], v[48:51]
	v_mfma_f32_16x16x32_bf16 v[44:47], v[160:163], v[192:195], v[44:47]
	v_mfma_f32_16x16x32_bf16 v[40:43], v[164:167], v[192:195], v[40:43]
	v_mfma_f32_16x16x32_bf16 v[36:39], v[160:163], v[200:203], v[36:39]
	v_mfma_f32_16x16x32_bf16 v[32:35], v[164:167], v[200:203], v[32:35]
	v_mfma_f32_16x16x32_bf16 v[60:63], v[168:171], v[180:183], v[60:63]
	v_mfma_f32_16x16x32_bf16 v[56:59], v[172:175], v[180:183], v[56:59]
	v_mfma_f32_16x16x32_bf16 v[52:55], v[168:171], v[188:191], v[52:55]
	v_mfma_f32_16x16x32_bf16 v[48:51], v[172:175], v[188:191], v[48:51]
	v_mfma_f32_16x16x32_bf16 v[44:47], v[168:171], v[196:199], v[44:47]
	v_mfma_f32_16x16x32_bf16 v[40:43], v[172:175], v[196:199], v[40:43]
	v_mfma_f32_16x16x32_bf16 v[36:39], v[168:171], v[204:207], v[36:39]
	v_mfma_f32_16x16x32_bf16 v[32:35], v[172:175], v[204:207], v[32:35]


; #define MMA(ai, bj, At, Btf) do { __builtin_amdgcn_s_setprio(1); \
;     for (int m = 0; m < 4; ++m) for (int n = 0; n < 2; ++n) for (int k = 0; k < 2; ++k) \
;       acc[ai][bj][m][n] = __builtin_amdgcn_mfma_f32_16x16x32_bf16(Btf[n][k], At[m][k], acc[ai][bj][m][n], 0, 0, 0); \
;     __builtin_amdgcn_s_setprio(0); } while (0)
; #define WAIT_V(n) asm volatile("s_waitcnt vmcnt(" #n ")" ::: "memory")
; #define BAR __builtin_amdgcn_s_barrier()
; template <int EPI> ...
;     ...
;     WAIT_V(6); BAR; MMA(1, 1, At, B1); BAR;
	v_mfma_f32_16x16x32_bf16 v[28:31], v[208:211], v[176:179], v[28:31]
	v_mfma_f32_16x16x32_bf16 v[24:27], v[212:215], v[176:179], v[24:27]
	v_mfma_f32_16x16x32_bf16 v[20:23], v[208:211], v[184:187], v[20:23]
	v_mfma_f32_16x16x32_bf16 v[16:19], v[212:215], v[184:187], v[16:19]
	v_mfma_f32_16x16x32_bf16 v[12:15], v[208:211], v[192:195], v[12:15]
	v_mfma_f32_16x16x32_bf16 v[8:11], v[212:215], v[192:195], v[8:11]
	v_mfma_f32_16x16x32_bf16 v[4:7], v[208:211], v[200:203], v[4:7]
	v_mfma_f32_16x16x32_bf16 v[0:3], v[212:215], v[200:203], v[0:3]
	v_mfma_f32_16x16x32_bf16 v[28:31], v[216:219], v[180:183], v[28:31]
	v_mfma_f32_16x16x32_bf16 v[24:27], v[220:223], v[180:183], v[24:27]
	v_mfma_f32_16x16x32_bf16 v[20:23], v[216:219], v[188:191], v[20:23]
	v_mfma_f32_16x16x32_bf16 v[16:19], v[220:223], v[188:191], v[16:19]
	v_mfma_f32_16x16x32_bf16 v[12:15], v[216:219], v[196:199], v[12:15]
	v_mfma_f32_16x16x32_bf16 v[8:11], v[220:223], v[196:199], v[8:11]
	v_mfma_f32_16x16x32_bf16 v[4:7], v[216:219], v[204:207], v[4:7]
	v_mfma_f32_16x16x32_bf16 v[0:3], v[220:223], v[204:207], v[0:3]

; #define STAGE(P, BASE, br, kt) do { const char* _gb = (const char*)(BASE) + ((size_t)(br) * K + (size_t)(kt) * BK) * 2; \
;     __builtin_amdgcn_global_load_lds((const unsigned*)(_gb + loff0), (unsigned*)((char*)(P) + tid * 16), 16, 0, 0); \
;     __builtin_amdgcn_global_load_lds((const unsigned*)(_gb + (size_t)K * 128 + loff0), (unsigned*)((char*)(P) + tid * 16 + 8192), 16, 0, 0); } while (0)
; #define LDA(dst, b, h) for (int m = 0; m < 4; ++m) { \
;     dst[m][0] = *reinterpret_cast<const bf16x8*>((char*)SA(b, h) + aoff0 + m * 2048); \
;     dst[m][1] = *reinterpret_cast<const bf16x8*>((char*)SA(b, h) + aoff1 + m * 2048); }
; #define LDB(dst, b, h) for (int n = 0; n < 2; ++n) { \
;     dst[n][0] = *reinterpret_cast<const bf16x8*>((char*)SB(b, h) + boff0 + n * 256); \
;     dst[n][1] = *reinterpret_cast<const bf16x8*>((char*)SB(b, h) + boff1 + n * 256); }
; #define MMA(ai, bj, At, Btf) do { __builtin_amdgcn_s_setprio(1); \
;     for (int m = 0; m < 4; ++m) for (int n = 0; n < 2; ++n) for (int k = 0; k < 2; ++k) \
;       acc[ai][bj][m][n] = __builtin_amdgcn_mfma_f32_16x16x32_bf16(Btf[n][k], At[m][k], acc[ai][bj][m][n], 0, 0, 0); \
;     __builtin_amdgcn_s_setprio(0); } while (0)
; #define WAIT_V(n) asm volatile("s_waitcnt vmcnt(" #n ")" ::: "memory")
; #define WAIT_L(n) asm volatile("s_waitcnt lgkmcnt(" #n ")" ::: "memory")
; template <int EPI> ...
;     ...
;   for (int t = 0; t < nt - 2; t += 2) {
;     LDB(B0, 0, 0); SCHED; LDA(At, 0, 0); STAGE(SA(1, 1), A, brow + HALF, t + 1);
;     WAIT_L(8); BAR; WAIT_L(0); MMA(0, 0, At, B0); BAR; SCHED;
;     LDB(B1, 0, 1); STAGE(SB(0, 0), Bt, bcol, t + 2);
;     BAR; WAIT_L(0); MMA(0, 1, At, B1); BAR;
;     LDA(At, 0, 1); STAGE(SA(0, 0), A, brow, t + 2);
;     BAR; WAIT_L(0); MMA(1, 0, At, B0); BAR; SCHED;
;     STAGE(SB(0, 1), Bt, bcol + HALF, t + 2);
;     WAIT_V(6); BAR; MMA(1, 1, At, B1); BAR;
;     LDB(B0, 1, 0); SCHED; LDA(At, 1, 0); STAGE(SA(0, 1), A, brow + HALF, t + 2);
;     WAIT_L(8); BAR; WAIT_L(0); MMA(0, 0, At, B0); BAR; SCHED;
;     LDB(B1, 1, 1); STAGE(SB(1, 0), Bt, bcol, t + 3);
;     BAR; WAIT_L(0); MMA(0, 1, At, B1); BAR;
;     LDA(At, 1, 1); STAGE(SA(1, 0), A, brow, t + 3);
;     BAR; WAIT_L(0); MMA(1, 0, At, B0); BAR; SCHED;
;     STAGE(SB(1, 1), Bt, bcol + HALF, t + 3);
;     WAIT_V(6); BAR; MMA(1, 1, At, B1); BAR;
;   }
;   { LDB(B0, 0, 0); LDA(At, 0, 0); STAGE(SA(1, 1), A, brow + HALF, nt - 1);
	s_add_i32 s61, s61, 2
	s_add_u32 s66, s66, 0x100
	s_addc_u32 s67, s67, 0
	s_add_u32 s68, s68, 0x100
	s_addc_u32 s69, s69, 0
	s_cmp_lt_u32 s61, 28
	s_barrier
	s_cbranch_scc1 .LBB0_411
	v_readfirstlane_b32 s70, v148
	v_lshl_add_u64 v[246:247], v[226:227], 0, s[58:59]
	s_mov_b32 m0, s70
	s_nop 0
	global_load_lds_dwordx4 v[246:247], off
	s_add_u32 s64, s74, s64
	s_addc_u32 s65, s75, s65
	v_readfirstlane_b32 s61, v150
	v_lshl_add_u64 v[208:209], s[64:65], 0, v[128:129]
	s_mov_b32 m0, s61
	v_readfirstlane_b32 s61, v151
	ds_read_b128 v[160:163], v152
	ds_read_b128 v[164:167], v152 offset:256
	ds_read_b128 v[168:171], v153
	ds_read_b128 v[172:175], v153 offset:256
	ds_read_b128 v[176:179], v149
	ds_read_b128 v[180:183], v149 offset:1024
	ds_read_b128 v[184:187], v149 offset:2048
	ds_read_b128 v[188:191], v149 offset:3072
	ds_read_b128 v[192:195], v149 offset:4096
	ds_read_b128 v[196:199], v149 offset:5120
	ds_read_b128 v[200:203], v149 offset:6144
	ds_read_b128 v[204:207], v149 offset:7168
	global_load_lds_dwordx4 v[208:209], off
	v_lshl_add_u64 v[208:209], v[208:209], 0, s[8:9]
	s_mov_b32 m0, s61
	s_nop 0
	global_load_lds_dwordx4 v[208:209], off
	s_waitcnt lgkmcnt(0)

; #define MMA(ai, bj, At, Btf) do { __builtin_amdgcn_s_setprio(1); \
;     for (int m = 0; m < 4; ++m) for (int n = 0; n < 2; ++n) for (int k = 0; k < 2; ++k) \
;       acc[ai][bj][m][n] = __builtin_amdgcn_mfma_f32_16x16x32_bf16(Btf[n][k], At[m][k], acc[ai][bj][m][n], 0, 0, 0); \
;     __builtin_amdgcn_s_setprio(0); } while (0)
; #define WAIT_L(n) asm volatile("s_waitcnt lgkmcnt(" #n ")" ::: "memory")
; #define BAR __builtin_amdgcn_s_barrier()
; template <int EPI> ...
;     ...
;     BAR; WAIT_L(0); MMA(0, 0, At, B0); BAR;
	s_barrier
	v_mfma_f32_16x16x32_bf16 v[124:127], v[160:163], v[176:179], v[124:127]
	v_mfma_f32_16x16x32_bf16 v[116:119], v[160:163], v[184:187], v[116:119]
	v_mfma_f32_16x16x32_bf16 v[108:111], v[160:163], v[192:195], v[108:111]
	v_mfma_f32_16x16x32_bf16 v[100:103], v[160:163], v[200:203], v[100:103]
	v_mfma_f32_16x16x32_bf16 v[96:99], v[164:167], v[200:203], v[96:99]
	v_mfma_f32_16x16x32_bf16 v[124:127], v[168:171], v[180:183], v[124:127]
	v_mfma_f32_16x16x32_bf16 v[120:123], v[164:167], v[176:179], v[120:123]
	v_mfma_f32_16x16x32_bf16 v[116:119], v[168:171], v[188:191], v[116:119]
	v_mfma_f32_16x16x32_bf16 v[112:115], v[164:167], v[184:187], v[112:115]
	v_mfma_f32_16x16x32_bf16 v[108:111], v[168:171], v[196:199], v[108:111]
	v_mfma_f32_16x16x32_bf16 v[104:107], v[164:167], v[192:195], v[104:107]
	v_mfma_f32_16x16x32_bf16 v[100:103], v[168:171], v[204:207], v[100:103]
	v_mfma_f32_16x16x32_bf16 v[96:99], v[172:175], v[204:207], v[96:99]
	v_mfma_f32_16x16x32_bf16 v[208:211], v[172:175], v[180:183], v[120:123]
	v_mfma_f32_16x16x32_bf16 v[212:215], v[172:175], v[188:191], v[112:115]
	v_mfma_f32_16x16x32_bf16 v[216:219], v[172:175], v[196:199], v[104:107]
	s_barrier

; #define LDB(dst, b, h) for (int n = 0; n < 2; ++n) { \
;     dst[n][0] = *reinterpret_cast<const bf16x8*>((char*)SB(b, h) + boff0 + n * 256); \
;     dst[n][1] = *reinterpret_cast<const bf16x8*>((char*)SB(b, h) + boff1 + n * 256); }
; #define MMA(ai, bj, At, Btf) do { __builtin_amdgcn_s_setprio(1); \
;     for (int m = 0; m < 4; ++m) for (int n = 0; n < 2; ++n) for (int k = 0; k < 2; ++k) \
;       acc[ai][bj][m][n] = __builtin_amdgcn_mfma_f32_16x16x32_bf16(Btf[n][k], At[m][k], acc[ai][bj][m][n], 0, 0, 0); \
;     __builtin_amdgcn_s_setprio(0); } while (0)
; #define WAIT_L(n) asm volatile("s_waitcnt lgkmcnt(" #n ")" ::: "memory")
; #define BAR __builtin_amdgcn_s_barrier()
; template <int EPI> ...
;     ...
;     LDB(B1, 0, 1); BAR; WAIT_L(0); MMA(0, 1, At, B1); BAR;
	s_nop 0
	ds_read_b128 v[104:107], v154
	ds_read_b128 v[112:115], v154 offset:256
	ds_read_b128 v[120:123], v155
	ds_read_b128 v[220:223], v155 offset:256
	s_waitcnt lgkmcnt(0)

; #define LDB(dst, b, h) for (int n = 0; n < 2; ++n) { \
;     dst[n][0] = *reinterpret_cast<const bf16x8*>((char*)SB(b, h) + boff0 + n * 256); \
;     dst[n][1] = *reinterpret_cast<const bf16x8*>((char*)SB(b, h) + boff1 + n * 256); }
; #define MMA(ai, bj, At, Btf) do { __builtin_amdgcn_s_setprio(1); \
;     for (int m = 0; m < 4; ++m) for (int n = 0; n < 2; ++n) for (int k = 0; k < 2; ++k) \
;       acc[ai][bj][m][n] = __builtin_amdgcn_mfma_f32_16x16x32_bf16(Btf[n][k], At[m][k], acc[ai][bj][m][n], 0, 0, 0); \
;     __builtin_amdgcn_s_setprio(0); } while (0)
; #define WAIT_L(n) asm volatile("s_waitcnt lgkmcnt(" #n ")" ::: "memory")
; #define BAR __builtin_amdgcn_s_barrier()
; template <int EPI> ...
;     ...
;     LDB(B1, 0, 1); BAR; WAIT_L(0); MMA(0, 1, At, B1); BAR;
	s_barrier
	v_mfma_f32_16x16x32_bf16 v[92:95], v[104:107], v[176:179], v[92:95]
	v_mfma_f32_16x16x32_bf16 v[88:91], v[112:115], v[176:179], v[88:91]
	v_mfma_f32_16x16x32_bf16 v[76:79], v[104:107], v[192:195], v[76:79]
	v_mfma_f32_16x16x32_bf16 v[72:75], v[112:115], v[192:195], v[72:75]
	v_mfma_f32_16x16x32_bf16 v[92:95], v[120:123], v[180:183], v[92:95]
	v_mfma_f32_16x16x32_bf16 v[88:91], v[220:223], v[180:183], v[88:91]
	v_mfma_f32_16x16x32_bf16 v[84:87], v[104:107], v[184:187], v[84:87]
	v_mfma_f32_16x16x32_bf16 v[80:83], v[112:115], v[184:187], v[80:83]
	v_mfma_f32_16x16x32_bf16 v[76:79], v[120:123], v[196:199], v[76:79]
	v_mfma_f32_16x16x32_bf16 v[72:75], v[220:223], v[196:199], v[72:75]
	v_mfma_f32_16x16x32_bf16 v[68:71], v[104:107], v[200:203], v[68:71]
	v_mfma_f32_16x16x32_bf16 v[64:67], v[112:115], v[200:203], v[64:67]
	v_mfma_f32_16x16x32_bf16 v[176:179], v[120:123], v[188:191], v[84:87]
	v_mfma_f32_16x16x32_bf16 v[180:183], v[220:223], v[188:191], v[80:83]
	v_mfma_f32_16x16x32_bf16 v[184:187], v[120:123], v[204:207], v[68:71]
	v_mfma_f32_16x16x32_bf16 v[188:191], v[220:223], v[204:207], v[64:67]
	s_barrier

; #define LDA(dst, b, h) for (int m = 0; m < 4; ++m) { \
;     dst[m][0] = *reinterpret_cast<const bf16x8*>((char*)SA(b, h) + aoff0 + m * 2048); \
;     dst[m][1] = *reinterpret_cast<const bf16x8*>((char*)SA(b, h) + aoff1 + m * 2048); }
; #define MMA(ai, bj, At, Btf) do { __builtin_amdgcn_s_setprio(1); \
;     for (int m = 0; m < 4; ++m) for (int n = 0; n < 2; ++n) for (int k = 0; k < 2; ++k) \
;       acc[ai][bj][m][n] = __builtin_amdgcn_mfma_f32_16x16x32_bf16(Btf[n][k], At[m][k], acc[ai][bj][m][n], 0, 0, 0); \
;     __builtin_amdgcn_s_setprio(0); } while (0)
; #define WAIT_V(n) asm volatile("s_waitcnt vmcnt(" #n ")" ::: "memory")
; #define WAIT_L(n) asm volatile("s_waitcnt lgkmcnt(" #n ")" ::: "memory")
; #define BAR __builtin_amdgcn_s_barrier()
; template <int EPI> ...
;     ...
;     LDA(At, 0, 1); WAIT_V(4); BAR; WAIT_L(0); MMA(1, 0, At, B0); MMA(1, 1, At, B1); BAR; }
	s_nop 1
	ds_read_b128 v[64:67], v149 offset:16384
	ds_read_b128 v[68:71], v149 offset:17408
	ds_read_b128 v[80:83], v149 offset:18432
	ds_read_b128 v[84:87], v149 offset:19456
	ds_read_b128 v[192:195], v149 offset:20480
	ds_read_b128 v[196:199], v149 offset:21504
	ds_read_b128 v[200:203], v149 offset:22528
	ds_read_b128 v[204:207], v149 offset:23552
	s_waitcnt vmcnt(4)
	s_waitcnt lgkmcnt(0)

; #define LDA(dst, b, h) for (int m = 0; m < 4; ++m) { \
;     dst[m][0] = *reinterpret_cast<const bf16x8*>((char*)SA(b, h) + aoff0 + m * 2048); \
;     dst[m][1] = *reinterpret_cast<const bf16x8*>((char*)SA(b, h) + aoff1 + m * 2048); }
; #define MMA(ai, bj, At, Btf) do { __builtin_amdgcn_s_setprio(1); \
;     for (int m = 0; m < 4; ++m) for (int n = 0; n < 2; ++n) for (int k = 0; k < 2; ++k) \
;       acc[ai][bj][m][n] = __builtin_amdgcn_mfma_f32_16x16x32_bf16(Btf[n][k], At[m][k], acc[ai][bj][m][n], 0, 0, 0); \
;     __builtin_amdgcn_s_setprio(0); } while (0)
; #define WAIT_V(n) asm volatile("s_waitcnt vmcnt(" #n ")" ::: "memory")
; #define WAIT_L(n) asm volatile("s_waitcnt lgkmcnt(" #n ")" ::: "memory")
; #define BAR __builtin_amdgcn_s_barrier()
; template <int EPI> ...
;     ...
;     LDA(At, 0, 1); WAIT_V(4); BAR; WAIT_L(0); MMA(1, 0, At, B0); MMA(1, 1, At, B1); BAR; }
	s_barrier
	v_mfma_f32_16x16x32_bf16 v[60:63], v[160:163], v[64:67], v[60:63]
	v_mfma_f32_16x16x32_bf16 v[56:59], v[164:167], v[64:67], v[56:59]
	v_mfma_f32_16x16x32_bf16 v[44:47], v[160:163], v[192:195], v[44:47]
	v_mfma_f32_16x16x32_bf16 v[36:39], v[160:163], v[200:203], v[36:39]
	v_mfma_f32_16x16x32_bf16 v[60:63], v[168:171], v[68:71], v[60:63]
	v_mfma_f32_16x16x32_bf16 v[56:59], v[172:175], v[68:71], v[56:59]
	v_mfma_f32_16x16x32_bf16 v[52:55], v[160:163], v[80:83], v[52:55]
	v_mfma_f32_16x16x32_bf16 v[48:51], v[164:167], v[80:83], v[48:51]
	v_mfma_f32_16x16x32_bf16 v[44:47], v[168:171], v[196:199], v[44:47]
	v_mfma_f32_16x16x32_bf16 v[40:43], v[164:167], v[192:195], v[40:43]
	v_mfma_f32_16x16x32_bf16 v[36:39], v[168:171], v[204:207], v[36:39]
	v_mfma_f32_16x16x32_bf16 v[32:35], v[164:167], v[200:203], v[32:35]
	v_mfma_f32_16x16x32_bf16 v[224:227], v[168:171], v[84:87], v[52:55]
	v_mfma_f32_16x16x32_bf16 v[228:231], v[172:175], v[84:87], v[48:51]
	v_mfma_f32_16x16x32_bf16 v[232:235], v[172:175], v[196:199], v[40:43]
	v_mfma_f32_16x16x32_bf16 v[160:163], v[172:175], v[204:207], v[32:35]
	v_mfma_f32_16x16x32_bf16 v[28:31], v[104:107], v[64:67], v[28:31]
	v_mfma_f32_16x16x32_bf16 v[20:23], v[104:107], v[80:83], v[20:23]
	v_mfma_f32_16x16x32_bf16 v[12:15], v[104:107], v[192:195], v[12:15]
	v_mfma_f32_16x16x32_bf16 v[4:7], v[104:107], v[200:203], v[4:7]
	v_mfma_f32_16x16x32_bf16 v[28:31], v[120:123], v[68:71], v[28:31]
	v_mfma_f32_16x16x32_bf16 v[24:27], v[112:115], v[64:67], v[24:27]
	v_mfma_f32_16x16x32_bf16 v[20:23], v[120:123], v[84:87], v[20:23]
	v_mfma_f32_16x16x32_bf16 v[16:19], v[112:115], v[80:83], v[16:19]
	v_mfma_f32_16x16x32_bf16 v[12:15], v[120:123], v[196:199], v[12:15]
	v_mfma_f32_16x16x32_bf16 v[8:11], v[112:115], v[192:195], v[8:11]
	v_mfma_f32_16x16x32_bf16 v[4:7], v[120:123], v[204:207], v[4:7]
	v_mfma_f32_16x16x32_bf16 v[0:3], v[112:115], v[200:203], v[0:3]
	v_mfma_f32_16x16x32_bf16 v[164:167], v[220:223], v[68:71], v[24:27]
	v_mfma_f32_16x16x32_bf16 v[168:171], v[220:223], v[84:87], v[16:19]
	v_mfma_f32_16x16x32_bf16 v[172:175], v[220:223], v[196:199], v[8:11]
	v_mfma_f32_16x16x32_bf16 v[192:195], v[220:223], v[204:207], v[0:3]
	s_barrier

; #define LDA(dst, b, h) for (int m = 0; m < 4; ++m) { \
;     dst[m][0] = *reinterpret_cast<const bf16x8*>((char*)SA(b, h) + aoff0 + m * 2048); \
;     dst[m][1] = *reinterpret_cast<const bf16x8*>((char*)SA(b, h) + aoff1 + m * 2048); }
; #define LDB(dst, b, h) for (int n = 0; n < 2; ++n) { \
;     dst[n][0] = *reinterpret_cast<const bf16x8*>((char*)SB(b, h) + boff0 + n * 256); \
;     dst[n][1] = *reinterpret_cast<const bf16x8*>((char*)SB(b, h) + boff1 + n * 256); }
; #define MMA(ai, bj, At, Btf) do { __builtin_amdgcn_s_setprio(1); \
;     for (int m = 0; m < 4; ++m) for (int n = 0; n < 2; ++n) for (int k = 0; k < 2; ++k) \
;       acc[ai][bj][m][n] = __builtin_amdgcn_mfma_f32_16x16x32_bf16(Btf[n][k], At[m][k], acc[ai][bj][m][n], 0, 0, 0); \
;     __builtin_amdgcn_s_setprio(0); } while (0)
; #define WAIT_V(n) asm volatile("s_waitcnt vmcnt(" #n ")" ::: "memory")
; #define WAIT_L(n) asm volatile("s_waitcnt lgkmcnt(" #n ")" ::: "memory")
; #define BAR __builtin_amdgcn_s_barrier()
; template <int EPI> ...
;     ...
;   { LDB(B0, 1, 0); LDA(At, 1, 0); WAIT_V(2); BAR; WAIT_L(0); MMA(0, 0, At, B0); BAR;
	s_nop 1
	ds_read_b128 v[0:3], v156
	ds_read_b128 v[8:11], v156 offset:256
	ds_read_b128 v[16:19], v157
	ds_read_b128 v[24:27], v157 offset:256
	ds_read_b128 v[32:35], v149 offset:32768
	ds_read_b128 v[40:43], v149 offset:33792
	ds_read_b128 v[48:51], v149 offset:34816
	ds_read_b128 v[52:55], v149 offset:35840
	ds_read_b128 v[68:71], v149 offset:36864
	ds_read_b128 v[196:199], v149 offset:37888
	ds_read_b128 v[200:203], v149 offset:38912
	ds_read_b128 v[204:207], v149 offset:39936
	s_waitcnt vmcnt(2)
	s_waitcnt lgkmcnt(0)

; #define LDA(dst, b, h) for (int m = 0; m < 4; ++m) { \
;     dst[m][0] = *reinterpret_cast<const bf16x8*>((char*)SA(b, h) + aoff0 + m * 2048); \
;     dst[m][1] = *reinterpret_cast<const bf16x8*>((char*)SA(b, h) + aoff1 + m * 2048); }
; #define LDB(dst, b, h) for (int n = 0; n < 2; ++n) { \
;     dst[n][0] = *reinterpret_cast<const bf16x8*>((char*)SB(b, h) + boff0 + n * 256); \
;     dst[n][1] = *reinterpret_cast<const bf16x8*>((char*)SB(b, h) + boff1 + n * 256); }
; #define MMA(ai, bj, At, Btf) do { __builtin_amdgcn_s_setprio(1); \
;     for (int m = 0; m < 4; ++m) for (int n = 0; n < 2; ++n) for (int k = 0; k < 2; ++k) \
;       acc[ai][bj][m][n] = __builtin_amdgcn_mfma_f32_16x16x32_bf16(Btf[n][k], At[m][k], acc[ai][bj][m][n], 0, 0, 0); \
;     __builtin_amdgcn_s_setprio(0); } while (0)
; #define WAIT_V(n) asm volatile("s_waitcnt vmcnt(" #n ")" ::: "memory")
; #define WAIT_L(n) asm volatile("s_waitcnt lgkmcnt(" #n ")" ::: "memory")
; #define BAR __builtin_amdgcn_s_barrier()
; template <int EPI> ...
;     ...
;   { LDB(B0, 1, 0); LDA(At, 1, 0); WAIT_V(2); BAR; WAIT_L(0); MMA(0, 0, At, B0); BAR;
	s_barrier
	v_mfma_f32_16x16x32_bf16 v[64:67], v[0:3], v[32:35], v[124:127]
	v_mfma_f32_16x16x32_bf16 v[120:123], v[16:19], v[40:43], v[64:67]
	v_mfma_f32_16x16x32_bf16 v[64:67], v[8:11], v[32:35], v[208:211]
	v_mfma_f32_16x16x32_bf16 v[124:127], v[24:27], v[40:43], v[64:67]
	v_mfma_f32_16x16x32_bf16 v[64:67], v[0:3], v[48:51], v[116:119]
	v_mfma_f32_16x16x32_bf16 v[112:115], v[16:19], v[52:55], v[64:67]
	v_mfma_f32_16x16x32_bf16 v[64:67], v[8:11], v[48:51], v[212:215]
	v_mfma_f32_16x16x32_bf16 v[116:119], v[24:27], v[52:55], v[64:67]
	v_mfma_f32_16x16x32_bf16 v[64:67], v[0:3], v[68:71], v[108:111]
	v_mfma_f32_16x16x32_bf16 v[104:107], v[16:19], v[196:199], v[64:67]
	v_mfma_f32_16x16x32_bf16 v[64:67], v[8:11], v[68:71], v[216:219]
	v_mfma_f32_16x16x32_bf16 v[108:111], v[24:27], v[196:199], v[64:67]
	v_mfma_f32_16x16x32_bf16 v[64:67], v[0:3], v[200:203], v[100:103]
	v_mfma_f32_16x16x32_bf16 v[80:83], v[16:19], v[204:207], v[64:67]
	v_mfma_f32_16x16x32_bf16 v[64:67], v[8:11], v[200:203], v[96:99]
	v_mfma_f32_16x16x32_bf16 v[84:87], v[24:27], v[204:207], v[64:67]
	s_barrier

; #define LDB(dst, b, h) for (int n = 0; n < 2; ++n) { \
;     dst[n][0] = *reinterpret_cast<const bf16x8*>((char*)SB(b, h) + boff0 + n * 256); \
;     dst[n][1] = *reinterpret_cast<const bf16x8*>((char*)SB(b, h) + boff1 + n * 256); }
; #define MMA(ai, bj, At, Btf) do { __builtin_amdgcn_s_setprio(1); \
;     for (int m = 0; m < 4; ++m) for (int n = 0; n < 2; ++n) for (int k = 0; k < 2; ++k) \
;       acc[ai][bj][m][n] = __builtin_amdgcn_mfma_f32_16x16x32_bf16(Btf[n][k], At[m][k], acc[ai][bj][m][n], 0, 0, 0); \
;     __builtin_amdgcn_s_setprio(0); } while (0)
; #define WAIT_V(n) asm volatile("s_waitcnt vmcnt(" #n ")" ::: "memory")
; #define WAIT_L(n) asm volatile("s_waitcnt lgkmcnt(" #n ")" ::: "memory")
; #define BAR __builtin_amdgcn_s_barrier()
; template <int EPI> ...
;     ...
;     LDB(B1, 1, 1); WAIT_V(0); BAR; WAIT_L(0); MMA(0, 1, At, B1); BAR;
	ds_read_b128 v[208:211], v158
	ds_read_b128 v[212:215], v158 offset:256
	ds_read_b128 v[216:219], v159
	ds_read_b128 v[220:223], v159 offset:256
	s_waitcnt vmcnt(0)
	s_waitcnt lgkmcnt(0)

; #define LDB(dst, b, h) for (int n = 0; n < 2; ++n) { \
;     dst[n][0] = *reinterpret_cast<const bf16x8*>((char*)SB(b, h) + boff0 + n * 256); \
;     dst[n][1] = *reinterpret_cast<const bf16x8*>((char*)SB(b, h) + boff1 + n * 256); }
; #define MMA(ai, bj, At, Btf) do { __builtin_amdgcn_s_setprio(1); \
;     for (int m = 0; m < 4; ++m) for (int n = 0; n < 2; ++n) for (int k = 0; k < 2; ++k) \
;       acc[ai][bj][m][n] = __builtin_amdgcn_mfma_f32_16x16x32_bf16(Btf[n][k], At[m][k], acc[ai][bj][m][n], 0, 0, 0); \
;     __builtin_amdgcn_s_setprio(0); } while (0)
; #define WAIT_V(n) asm volatile("s_waitcnt vmcnt(" #n ")" ::: "memory")
; #define WAIT_L(n) asm volatile("s_waitcnt lgkmcnt(" #n ")" ::: "memory")
; #define BAR __builtin_amdgcn_s_barrier()
; template <int EPI> ...
;     ...
;     LDB(B1, 1, 1); WAIT_V(0); BAR; WAIT_L(0); MMA(0, 1, At, B1); BAR;
	s_barrier
	v_mfma_f32_16x16x32_bf16 v[64:67], v[208:211], v[32:35], v[92:95]
	v_mfma_f32_16x16x32_bf16 v[32:35], v[212:215], v[32:35], v[88:91]
	v_mfma_f32_16x16x32_bf16 v[100:103], v[220:223], v[40:43], v[32:35]
	v_mfma_f32_16x16x32_bf16 v[32:35], v[208:211], v[48:51], v[176:179]
	v_mfma_f32_16x16x32_bf16 v[88:91], v[216:219], v[52:55], v[32:35]
	v_mfma_f32_16x16x32_bf16 v[32:35], v[212:215], v[48:51], v[180:183]
	v_mfma_f32_16x16x32_bf16 v[92:95], v[220:223], v[52:55], v[32:35]
	v_mfma_f32_16x16x32_bf16 v[32:35], v[208:211], v[68:71], v[76:79]
	v_mfma_f32_16x16x32_bf16 v[96:99], v[216:219], v[40:43], v[64:67]
	v_mfma_f32_16x16x32_bf16 v[64:67], v[216:219], v[196:199], v[32:35]
	v_mfma_f32_16x16x32_bf16 v[32:35], v[212:215], v[68:71], v[72:75]
	v_mfma_f32_16x16x32_bf16 v[68:71], v[220:223], v[196:199], v[32:35]
	v_mfma_f32_16x16x32_bf16 v[32:35], v[208:211], v[200:203], v[184:187]
	v_mfma_f32_16x16x32_bf16 v[48:51], v[216:219], v[204:207], v[32:35]
	v_mfma_f32_16x16x32_bf16 v[32:35], v[212:215], v[200:203], v[188:191]
	v_mfma_f32_16x16x32_bf16 v[52:55], v[220:223], v[204:207], v[32:35]
	s_barrier

; #define LDA(dst, b, h) for (int m = 0; m < 4; ++m) { \
;     dst[m][0] = *reinterpret_cast<const bf16x8*>((char*)SA(b, h) + aoff0 + m * 2048); \
;     dst[m][1] = *reinterpret_cast<const bf16x8*>((char*)SA(b, h) + aoff1 + m * 2048); }
; #define MMA(ai, bj, At, Btf) do { __builtin_amdgcn_s_setprio(1); \
;     for (int m = 0; m < 4; ++m) for (int n = 0; n < 2; ++n) for (int k = 0; k < 2; ++k) \
;       acc[ai][bj][m][n] = __builtin_amdgcn_mfma_f32_16x16x32_bf16(Btf[n][k], At[m][k], acc[ai][bj][m][n], 0, 0, 0); \
;     __builtin_amdgcn_s_setprio(0); } while (0)
; #define WAIT_L(n) asm volatile("s_waitcnt lgkmcnt(" #n ")" ::: "memory")
; #define BAR __builtin_amdgcn_s_barrier()
; template <int EPI> ...
;     ...
;     LDA(At, 1, 1); BAR; WAIT_L(0); MMA(1, 0, At, B0); MMA(1, 1, At, B1); BAR; }
	ds_read_b128 v[176:179], v149 offset:49152
	ds_read_b128 v[180:183], v149 offset:50176
	ds_read_b128 v[184:187], v149 offset:51200
	ds_read_b128 v[188:191], v149 offset:52224
	ds_read_b128 v[196:199], v149 offset:53248
	ds_read_b128 v[200:203], v149 offset:54272
	ds_read_b128 v[204:207], v149 offset:55296
	ds_read_b128 v[236:239], v149 offset:56320
	s_waitcnt lgkmcnt(0)

; #define LDA(dst, b, h) for (int m = 0; m < 4; ++m) { \
;     dst[m][0] = *reinterpret_cast<const bf16x8*>((char*)SA(b, h) + aoff0 + m * 2048); \
;     dst[m][1] = *reinterpret_cast<const bf16x8*>((char*)SA(b, h) + aoff1 + m * 2048); }
; #define MMA(ai, bj, At, Btf) do { __builtin_amdgcn_s_setprio(1); \
;     for (int m = 0; m < 4; ++m) for (int n = 0; n < 2; ++n) for (int k = 0; k < 2; ++k) \
;       acc[ai][bj][m][n] = __builtin_amdgcn_mfma_f32_16x16x32_bf16(Btf[n][k], At[m][k], acc[ai][bj][m][n], 0, 0, 0); \
;     __builtin_amdgcn_s_setprio(0); } while (0)
; #define WAIT_L(n) asm volatile("s_waitcnt lgkmcnt(" #n ")" ::: "memory")
; #define BAR __builtin_amdgcn_s_barrier()
; template <int EPI> ...
;     ...
;     LDA(At, 1, 1); BAR; WAIT_L(0); MMA(1, 0, At, B0); MMA(1, 1, At, B1); BAR; }
	s_barrier
	v_mfma_f32_16x16x32_bf16 v[32:35], v[0:3], v[176:179], v[60:63]
	v_mfma_f32_16x16x32_bf16 v[72:75], v[16:19], v[180:183], v[32:35]
	v_mfma_f32_16x16x32_bf16 v[32:35], v[8:11], v[176:179], v[56:59]
	v_mfma_f32_16x16x32_bf16 v[76:79], v[24:27], v[180:183], v[32:35]
	v_mfma_f32_16x16x32_bf16 v[32:35], v[0:3], v[184:187], v[224:227]
	v_mfma_f32_16x16x32_bf16 v[56:59], v[16:19], v[188:191], v[32:35]
	v_mfma_f32_16x16x32_bf16 v[32:35], v[8:11], v[184:187], v[228:231]
	v_mfma_f32_16x16x32_bf16 v[60:63], v[24:27], v[188:191], v[32:35]
	v_mfma_f32_16x16x32_bf16 v[32:35], v[0:3], v[196:199], v[44:47]
	v_mfma_f32_16x16x32_bf16 v[40:43], v[16:19], v[200:203], v[32:35]
	v_mfma_f32_16x16x32_bf16 v[32:35], v[8:11], v[196:199], v[232:235]
	v_mfma_f32_16x16x32_bf16 v[0:3], v[0:3], v[204:207], v[36:39]
	v_mfma_f32_16x16x32_bf16 v[44:47], v[24:27], v[200:203], v[32:35]
	v_mfma_f32_16x16x32_bf16 v[32:35], v[16:19], v[236:239], v[0:3]
	v_mfma_f32_16x16x32_bf16 v[0:3], v[8:11], v[204:207], v[160:163]
	v_mfma_f32_16x16x32_bf16 v[36:39], v[24:27], v[236:239], v[0:3]
	v_mfma_f32_16x16x32_bf16 v[0:3], v[208:211], v[176:179], v[28:31]
	v_mfma_f32_16x16x32_bf16 v[24:27], v[216:219], v[180:183], v[0:3]
	v_mfma_f32_16x16x32_bf16 v[0:3], v[212:215], v[176:179], v[164:167]
	v_mfma_f32_16x16x32_bf16 v[28:31], v[220:223], v[180:183], v[0:3]
	v_mfma_f32_16x16x32_bf16 v[0:3], v[208:211], v[184:187], v[20:23]
	v_mfma_f32_16x16x32_bf16 v[16:19], v[216:219], v[188:191], v[0:3]
	v_mfma_f32_16x16x32_bf16 v[0:3], v[212:215], v[184:187], v[168:171]
	v_mfma_f32_16x16x32_bf16 v[20:23], v[220:223], v[188:191], v[0:3]
	v_mfma_f32_16x16x32_bf16 v[0:3], v[208:211], v[196:199], v[12:15]
	v_mfma_f32_16x16x32_bf16 v[8:11], v[216:219], v[200:203], v[0:3]
	v_mfma_f32_16x16x32_bf16 v[0:3], v[212:215], v[196:199], v[172:175]
	v_mfma_f32_16x16x32_bf16 v[12:15], v[220:223], v[200:203], v[0:3]
	v_mfma_f32_16x16x32_bf16 v[0:3], v[208:211], v[204:207], v[4:7]
	v_mfma_f32_16x16x32_bf16 v[4:7], v[212:215], v[204:207], v[192:195]
	v_mfma_f32_16x16x32_bf16 v[0:3], v[216:219], v[236:239], v[0:3]
	v_mfma_f32_16x16x32_bf16 v[4:7], v[220:223], v[236:239], v[4:7]
	s_barrier

; #define BAR __builtin_amdgcn_s_barrier()
; template <int EPI> ...
;     ...
;   if (wr == 0) BAR;
; template <int EPI>
; __device__ __forceinline__ void gemm_phase(const u16* A, const u16* Bt, int M, int N, int K, u16* out, int ldo,
;                                            const float* aux, int bid, int nblk, int wv) {
;     ...
;   for (int base = 0; base < ntile; base += nblk) {
;     int wgid;
;     if (base + nblk <= ntile && (nblk & 7) == 0) wgid = base + (bid & 7) * (nblk >> 3) + (bid >> 3);
;     else wgid = base + bid;
;     if (wgid >= ntile) break;
;     int nig = WGM * nN, gid = wgid / nig, fm = gid * WGM, gsz = min(nM - fm, WGM);
;     int pm = fm + ((wgid % nig) % gsz), pn = (wgid % nig) / gsz;
;     int brow = pm * BM, bcol = pn * BM;
;     gemm_tile<EPI>(A, Bt, K, brow, bcol, out, ldo, EPI == 1 ? pn * HALF : bcol, aux, tid);
	s_setprio 0
	s_and_saveexec_b64 s[64:65], s[2:3]
	s_cbranch_execz .LBB0_405
	s_barrier
	s_branch .LBB0_405

; #define STAGE(P, BASE, br, kt) do { const char* _gb = (const char*)(BASE) + ((size_t)(br) * K + (size_t)(kt) * BK) * 2; \
;     __builtin_amdgcn_global_load_lds((const unsigned*)(_gb + loff0), (unsigned*)((char*)(P) + tid * 16), 16, 0, 0); \
;     __builtin_amdgcn_global_load_lds((const unsigned*)(_gb + (size_t)K * 128 + loff0), (unsigned*)((char*)(P) + tid * 16 + 8192), 16, 0, 0); } while (0)
; #define BAR __builtin_amdgcn_s_barrier()
; template <int EPI> ...
;     ...
;   f32x4 acc[2][2][4][2] = {};
;   bf16x8 At[4][2], B0[2][2], B1[2][2];
;   int nt = K / BK;
;   const int aoff0 = lds_byte(wr * 64 + fr, fq * 8), aoff1 = lds_byte(wr * 64 + fr, 32 + fq * 8);
;   const int brw = wc * 32 + (fr >> 2) * 8 + (fr & 3);
;   const int boff0 = lds_byte(brw, fq * 8), boff1 = lds_byte(brw, 32 + fq * 8);
;   unsigned loff0;
;   { int _r, _c; stage_rc(tid * 16, _r, _c); loff0 = (unsigned)(_r * K + _c) * 2u; }
;   STAGE(SB(0, 0), Bt, bcol, 0); STAGE(SA(0, 0), A, brow, 0);
;   STAGE(SB(0, 1), Bt, bcol + HALF, 0); STAGE(SA(0, 1), A, brow + HALF, 0);
;   if (wr == 1) BAR;
; template <int EPI>
; __device__ __forceinline__ void gemm_phase(const u16* A, const u16* Bt, int M, int N, int K, u16* out, int ldo,
;                                            const float* aux, int bid, int nblk, int wv) {
;     ...
;   for (int base = 0; base < ntile; base += nblk) {
;     int wgid;
;     if (base + nblk <= ntile && (nblk & 7) == 0) wgid = base + (bid & 7) * (nblk >> 3) + (bid >> 3);
;     else wgid = base + bid;
;     if (wgid >= ntile) break;
;     int nig = WGM * nN, gid = wgid / nig, fm = gid * WGM, gsz = min(nM - fm, WGM);
;     int pm = fm + ((wgid % nig) % gsz), pn = (wgid % nig) / gsz;
;     int brow = pm * BM, bcol = pn * BM;
.LBB0_1014:
	s_mov_b32 s60, s74
	s_add_i32 s74, s74, s33
	s_cmpk_lt_i32 s74, 0x401
	s_cselect_b64 s[58:59], -1, 0
	s_and_b64 s[58:59], s[44:45], s[58:59]
	s_and_b64 s[58:59], s[58:59], exec
	s_cselect_b32 s58, s86, s91
	s_add_i32 s60, s58, s60
	s_cmpk_gt_i32 s60, 0x3ff
	s_mov_b64 s[58:59], -1
	s_cbranch_scc1 .LBB0_1013
	s_sub_i32 s60, 0x3ff, s60
	s_ashr_i32 s58, s60, 31
	s_lshr_b32 s58, s58, 26
	s_add_i32 s58, s60, s58
	s_and_b32 s59, s58, 0xffc0
	s_sub_i32 s59, s60, s59
	s_bfe_i32 s60, s59, 0x80000
	s_bfe_u32 s60, s60, 0x3000c
	s_add_i32 s60, s59, s60
	s_bfe_i32 s61, s60, 0x80000
	s_and_b32 s60, s60, 0xf8
	s_sub_i32 s59, s59, s60
	s_sext_i32_i8 s59, s59
	s_lshl_b32 s58, s58, 5
	s_sext_i32_i16 s61, s61
	s_and_b32 s58, s58, 0xfffff800
	s_lshl_b32 s59, s59, 8
	s_add_i32 s58, s59, s58
	s_lshl_b32 s59, s61, 5
	s_and_b32 s60, s59, 0xffffff00
	s_ashr_i32 s61, s60, 31
	s_lshl_b64 s[64:65], s[60:61], 12
	s_add_u32 s62, s70, s64
	s_addc_u32 s63, s71, s65
	v_readfirstlane_b32 s59, v135
	v_lshl_add_u64 v[0:1], s[62:63], 0, v[128:129]
	s_mov_b32 m0, s59
	v_readfirstlane_b32 s59, v136
	global_load_lds_dwordx4 v[0:1], off
	s_mov_b32 m0, s59
	s_ashr_i32 s59, s58, 31
	s_lshl_b64 s[66:67], s[58:59], 12
	s_add_u32 s62, s14, s66
	v_lshl_add_u64 v[2:3], v[0:1], 0, s[8:9]
	s_addc_u32 s63, s43, s67
	global_load_lds_dwordx4 v[2:3], off
	v_lshl_add_u64 v[2:3], s[62:63], 0, v[128:129]
	s_or_b32 s62, s60, 0x80
	s_ashr_i32 s63, s62, 31
	v_readfirstlane_b32 s59, v137
	s_lshl_b64 s[62:63], s[62:63], 12
	s_mov_b32 m0, s59
	v_readfirstlane_b32 s59, v138
	s_add_u32 s62, s70, s62
	global_load_lds_dwordx4 v[2:3], off
	v_lshl_add_u64 v[4:5], v[2:3], 0, s[8:9]
	s_mov_b32 m0, s59
	s_addc_u32 s63, s71, s63
	global_load_lds_dwordx4 v[4:5], off
	v_lshl_add_u64 v[4:5], s[62:63], 0, v[128:129]
	s_or_b32 s62, s58, 0x80
	s_ashr_i32 s63, s62, 31
	v_readfirstlane_b32 s59, v139
	s_lshl_b64 s[62:63], s[62:63], 12
	s_mov_b32 m0, s59
	v_readfirstlane_b32 s59, v140
	s_add_u32 s68, s14, s62
	global_load_lds_dwordx4 v[4:5], off
	v_lshl_add_u64 v[6:7], v[4:5], 0, s[8:9]
	s_mov_b32 m0, s59
	s_addc_u32 s69, s43, s63
	v_readfirstlane_b32 s59, v141
	global_load_lds_dwordx4 v[6:7], off
	v_lshl_add_u64 v[6:7], s[68:69], 0, v[128:129]
	s_mov_b32 m0, s59
	v_readfirstlane_b32 s59, v142
	global_load_lds_dwordx4 v[6:7], off
	v_lshl_add_u64 v[6:7], v[6:7], 0, s[8:9]
	s_mov_b32 m0, s59
	s_nop 0
	global_load_lds_dwordx4 v[6:7], off
	v_mov_b32_e32 v8, 0
	v_mov_b32_e32 v9, 0
	v_mov_b32_e32 v10, 0
	v_mov_b32_e32 v11, 0
	v_mov_b32_e32 v12, 0
	v_mov_b32_e32 v13, 0
	v_mov_b32_e32 v14, 0
	v_mov_b32_e32 v15, 0
	v_mov_b32_e32 v16, 0
	v_mov_b32_e32 v17, 0
	v_mov_b32_e32 v18, 0
	v_mov_b32_e32 v19, 0
	v_mov_b32_e32 v20, 0
	v_mov_b32_e32 v21, 0
	v_mov_b32_e32 v22, 0
	v_mov_b32_e32 v23, 0
	v_mov_b32_e32 v24, 0
	v_mov_b32_e32 v25, 0
	v_mov_b32_e32 v26, 0
	v_mov_b32_e32 v27, 0
	v_mov_b32_e32 v28, 0
	v_mov_b32_e32 v29, 0
	v_mov_b32_e32 v30, 0
	v_mov_b32_e32 v31, 0
	v_mov_b32_e32 v32, 0
	v_mov_b32_e32 v33, 0
	v_mov_b32_e32 v34, 0
	v_mov_b32_e32 v35, 0
	v_mov_b32_e32 v36, 0
	v_mov_b32_e32 v37, 0
	v_mov_b32_e32 v38, 0
	v_mov_b32_e32 v39, 0
	v_mov_b32_e32 v40, 0
	v_mov_b32_e32 v41, 0
	v_mov_b32_e32 v42, 0
	v_mov_b32_e32 v43, 0
	v_mov_b32_e32 v44, 0
	v_mov_b32_e32 v45, 0
	v_mov_b32_e32 v46, 0
	v_mov_b32_e32 v47, 0
	v_mov_b32_e32 v48, 0
	v_mov_b32_e32 v49, 0
	v_mov_b32_e32 v50, 0
	v_mov_b32_e32 v51, 0
	v_mov_b32_e32 v52, 0
	v_mov_b32_e32 v53, 0
	v_mov_b32_e32 v54, 0
	v_mov_b32_e32 v55, 0
	v_mov_b32_e32 v56, 0
	v_mov_b32_e32 v57, 0
	v_mov_b32_e32 v58, 0
	v_mov_b32_e32 v59, 0
	v_mov_b32_e32 v60, 0
	v_mov_b32_e32 v61, 0
	v_mov_b32_e32 v62, 0
	v_mov_b32_e32 v63, 0
	v_mov_b32_e32 v64, 0
	v_mov_b32_e32 v65, 0
	v_mov_b32_e32 v66, 0
	v_mov_b32_e32 v67, 0
	v_mov_b32_e32 v68, 0
	v_mov_b32_e32 v69, 0
	v_mov_b32_e32 v70, 0
	v_mov_b32_e32 v71, 0
	v_mov_b32_e32 v72, 0
	v_mov_b32_e32 v73, 0
	v_mov_b32_e32 v74, 0
	v_mov_b32_e32 v75, 0
	v_mov_b32_e32 v76, 0
	v_mov_b32_e32 v77, 0
	v_mov_b32_e32 v78, 0
	v_mov_b32_e32 v79, 0
	v_mov_b32_e32 v80, 0
	v_mov_b32_e32 v81, 0
	v_mov_b32_e32 v82, 0
	v_mov_b32_e32 v83, 0
	v_mov_b32_e32 v84, 0
	v_mov_b32_e32 v85, 0
	v_mov_b32_e32 v86, 0
	v_mov_b32_e32 v87, 0
	v_mov_b32_e32 v88, 0
	v_mov_b32_e32 v89, 0
	v_mov_b32_e32 v90, 0
	v_mov_b32_e32 v91, 0
	v_mov_b32_e32 v92, 0
	v_mov_b32_e32 v93, 0
	v_mov_b32_e32 v94, 0
	v_mov_b32_e32 v95, 0
	v_mov_b32_e32 v96, 0
	v_mov_b32_e32 v97, 0
	v_mov_b32_e32 v98, 0
	v_mov_b32_e32 v99, 0
	v_mov_b32_e32 v100, 0
	v_mov_b32_e32 v101, 0
	v_mov_b32_e32 v102, 0
	v_mov_b32_e32 v103, 0
	v_mov_b32_e32 v104, 0
	v_mov_b32_e32 v105, 0
	v_mov_b32_e32 v106, 0
	v_mov_b32_e32 v107, 0
	v_mov_b32_e32 v108, 0
	v_mov_b32_e32 v109, 0
	v_mov_b32_e32 v110, 0
	v_mov_b32_e32 v111, 0
	v_mov_b32_e32 v112, 0
	v_mov_b32_e32 v113, 0
	v_mov_b32_e32 v114, 0
	v_mov_b32_e32 v115, 0
	v_mov_b32_e32 v116, 0
	v_mov_b32_e32 v117, 0
	v_mov_b32_e32 v118, 0
	v_mov_b32_e32 v119, 0
	v_mov_b32_e32 v120, 0
	v_mov_b32_e32 v121, 0
	v_mov_b32_e32 v122, 0
	v_mov_b32_e32 v123, 0
	v_mov_b32_e32 v124, 0
	v_mov_b32_e32 v125, 0
	v_mov_b32_e32 v126, 0
	v_mov_b32_e32 v127, 0
	s_and_saveexec_b64 s[68:69], s[4:5]
	s_cbranch_execz .LBB0_1017
	s_setprio 1
	s_barrier

; #define STAGE(P, BASE, br, kt) do { const char* _gb = (const char*)(BASE) + ((size_t)(br) * K + (size_t)(kt) * BK) * 2; \
;     __builtin_amdgcn_global_load_lds((const unsigned*)(_gb + loff0), (unsigned*)((char*)(P) + tid * 16), 16, 0, 0); \
;     __builtin_amdgcn_global_load_lds((const unsigned*)(_gb + (size_t)K * 128 + loff0), (unsigned*)((char*)(P) + tid * 16 + 8192), 16, 0, 0); } while (0)
; #define LDA(dst, b, h) for (int m = 0; m < 4; ++m) { \
;     dst[m][0] = *reinterpret_cast<const bf16x8*>((char*)SA(b, h) + aoff0 + m * 2048); \
;     dst[m][1] = *reinterpret_cast<const bf16x8*>((char*)SA(b, h) + aoff1 + m * 2048); }
; #define LDB(dst, b, h) for (int n = 0; n < 2; ++n) { \
;     dst[n][0] = *reinterpret_cast<const bf16x8*>((char*)SB(b, h) + boff0 + n * 256); \
;     dst[n][1] = *reinterpret_cast<const bf16x8*>((char*)SB(b, h) + boff1 + n * 256); }
; #define MMA(ai, bj, At, Btf) do { __builtin_amdgcn_s_setprio(1); \
;     for (int m = 0; m < 4; ++m) for (int n = 0; n < 2; ++n) for (int k = 0; k < 2; ++k) \
;       acc[ai][bj][m][n] = __builtin_amdgcn_mfma_f32_16x16x32_bf16(Btf[n][k], At[m][k], acc[ai][bj][m][n], 0, 0, 0); \
;     __builtin_amdgcn_s_setprio(0); } while (0)
; #define WAIT_L(n) asm volatile("s_waitcnt lgkmcnt(" #n ")" ::: "memory")
; #define BAR __builtin_amdgcn_s_barrier()
; #define SCHED __builtin_amdgcn_sched_barrier(0)
; template <int EPI> ...
;     ...
;     LDB(B0, 0, 0); SCHED; LDA(At, 0, 0); STAGE(SA(1, 1), A, brow + HALF, t + 1);
;     WAIT_L(8); BAR; WAIT_L(0); MMA(0, 0, At, B0); BAR; SCHED;
;     LDB(B1, 0, 1); STAGE(SB(0, 0), Bt, bcol, t + 2);
.LBB0_1018:
	ds_read_b128 v[160:163], v152
	ds_read_b128 v[164:167], v152 offset:256
	ds_read_b128 v[168:171], v153
	ds_read_b128 v[172:175], v153 offset:256
	v_lshl_add_u64 v[224:225], s[66:67], 0, v[132:133]
	v_readfirstlane_b32 s68, v150
	v_lshl_add_u64 v[208:209], v[224:225], 0, s[16:17]
	s_mov_b32 m0, s68
	v_readfirstlane_b32 s68, v151
	ds_read_b128 v[176:179], v149
	ds_read_b128 v[180:183], v149 offset:1024
	ds_read_b128 v[184:187], v149 offset:2048
	ds_read_b128 v[188:191], v149 offset:3072
	ds_read_b128 v[192:195], v149 offset:4096
	ds_read_b128 v[196:199], v149 offset:5120
	ds_read_b128 v[200:203], v149 offset:6144
	ds_read_b128 v[204:207], v149 offset:7168
	global_load_lds_dwordx4 v[208:209], off
	v_lshl_add_u64 v[208:209], v[224:225], 0, s[18:19]
	s_mov_b32 m0, s68
	s_nop 0
	global_load_lds_dwordx4 v[208:209], off
	s_waitcnt lgkmcnt(8)
	v_readfirstlane_b32 s68, v148
	v_lshl_add_u64 v[246:247], v[226:227], 0, s[56:57]
	s_mov_b32 m0, s68
	s_nop 0
	global_load_lds_dwordx4 v[246:247], off
	ds_read_b128 v[208:211], v154
	ds_read_b128 v[212:215], v154 offset:256
	ds_read_b128 v[216:219], v155
	ds_read_b128 v[220:223], v155 offset:256
	s_waitcnt lgkmcnt(0)

; #define STAGE(P, BASE, br, kt) do { const char* _gb = (const char*)(BASE) + ((size_t)(br) * K + (size_t)(kt) * BK) * 2; \
;     __builtin_amdgcn_global_load_lds((const unsigned*)(_gb + loff0), (unsigned*)((char*)(P) + tid * 16), 16, 0, 0); \
;     __builtin_amdgcn_global_load_lds((const unsigned*)(_gb + (size_t)K * 128 + loff0), (unsigned*)((char*)(P) + tid * 16 + 8192), 16, 0, 0); } while (0)
; #define LDB(dst, b, h) for (int n = 0; n < 2; ++n) { \
;     dst[n][0] = *reinterpret_cast<const bf16x8*>((char*)SB(b, h) + boff0 + n * 256); \
;     dst[n][1] = *reinterpret_cast<const bf16x8*>((char*)SB(b, h) + boff1 + n * 256); }
; #define MMA(ai, bj, At, Btf) do { __builtin_amdgcn_s_setprio(1); \
;     for (int m = 0; m < 4; ++m) for (int n = 0; n < 2; ++n) for (int k = 0; k < 2; ++k) \
;       acc[ai][bj][m][n] = __builtin_amdgcn_mfma_f32_16x16x32_bf16(Btf[n][k], At[m][k], acc[ai][bj][m][n], 0, 0, 0); \
;     __builtin_amdgcn_s_setprio(0); } while (0)
; #define WAIT_L(n) asm volatile("s_waitcnt lgkmcnt(" #n ")" ::: "memory")
; #define BAR __builtin_amdgcn_s_barrier()
; #define SCHED __builtin_amdgcn_sched_barrier(0)
; template <int EPI> ...
;     ...
;     WAIT_L(8); BAR; WAIT_L(0); MMA(0, 0, At, B0); BAR; SCHED;
;     LDB(B1, 0, 1); STAGE(SB(0, 0), Bt, bcol, t + 2);
;     BAR; WAIT_L(0); MMA(0, 1, At, B1); BAR;
	s_barrier
	v_mfma_f32_16x16x32_bf16 v[124:127], v[160:163], v[176:179], v[124:127]
	v_mfma_f32_16x16x32_bf16 v[120:123], v[164:167], v[176:179], v[120:123]
	v_mfma_f32_16x16x32_bf16 v[116:119], v[160:163], v[184:187], v[116:119]
	v_mfma_f32_16x16x32_bf16 v[112:115], v[164:167], v[184:187], v[112:115]
	v_mfma_f32_16x16x32_bf16 v[108:111], v[160:163], v[192:195], v[108:111]
	v_mfma_f32_16x16x32_bf16 v[104:107], v[164:167], v[192:195], v[104:107]
	v_mfma_f32_16x16x32_bf16 v[100:103], v[160:163], v[200:203], v[100:103]
	v_mfma_f32_16x16x32_bf16 v[96:99], v[164:167], v[200:203], v[96:99]
	v_mfma_f32_16x16x32_bf16 v[124:127], v[168:171], v[180:183], v[124:127]
	v_mfma_f32_16x16x32_bf16 v[120:123], v[172:175], v[180:183], v[120:123]
	v_mfma_f32_16x16x32_bf16 v[116:119], v[168:171], v[188:191], v[116:119]
	v_mfma_f32_16x16x32_bf16 v[112:115], v[172:175], v[188:191], v[112:115]
	v_mfma_f32_16x16x32_bf16 v[108:111], v[168:171], v[196:199], v[108:111]
	v_mfma_f32_16x16x32_bf16 v[104:107], v[172:175], v[196:199], v[104:107]
	v_mfma_f32_16x16x32_bf16 v[100:103], v[168:171], v[204:207], v[100:103]
	v_mfma_f32_16x16x32_bf16 v[96:99], v[172:175], v[204:207], v[96:99]
	v_mfma_f32_16x16x32_bf16 v[92:95], v[208:211], v[176:179], v[92:95]
	v_mfma_f32_16x16x32_bf16 v[88:91], v[212:215], v[176:179], v[88:91]
	v_mfma_f32_16x16x32_bf16 v[84:87], v[208:211], v[184:187], v[84:87]
	v_mfma_f32_16x16x32_bf16 v[80:83], v[212:215], v[184:187], v[80:83]
	v_mfma_f32_16x16x32_bf16 v[76:79], v[208:211], v[192:195], v[76:79]
	v_mfma_f32_16x16x32_bf16 v[72:75], v[212:215], v[192:195], v[72:75]
	v_mfma_f32_16x16x32_bf16 v[68:71], v[208:211], v[200:203], v[68:71]
	v_mfma_f32_16x16x32_bf16 v[64:67], v[212:215], v[200:203], v[64:67]
	v_mfma_f32_16x16x32_bf16 v[92:95], v[216:219], v[180:183], v[92:95]
	v_mfma_f32_16x16x32_bf16 v[88:91], v[220:223], v[180:183], v[88:91]
	v_mfma_f32_16x16x32_bf16 v[84:87], v[216:219], v[188:191], v[84:87]
	v_mfma_f32_16x16x32_bf16 v[80:83], v[220:223], v[188:191], v[80:83]
	v_mfma_f32_16x16x32_bf16 v[76:79], v[216:219], v[196:199], v[76:79]
	v_mfma_f32_16x16x32_bf16 v[72:75], v[220:223], v[196:199], v[72:75]
	v_mfma_f32_16x16x32_bf16 v[68:71], v[216:219], v[204:207], v[68:71]
	v_mfma_f32_16x16x32_bf16 v[64:67], v[220:223], v[204:207], v[64:67]
	s_barrier

; #define STAGE(P, BASE, br, kt) do { const char* _gb = (const char*)(BASE) + ((size_t)(br) * K + (size_t)(kt) * BK) * 2; \
;     __builtin_amdgcn_global_load_lds((const unsigned*)(_gb + loff0), (unsigned*)((char*)(P) + tid * 16), 16, 0, 0); \
;     __builtin_amdgcn_global_load_lds((const unsigned*)(_gb + (size_t)K * 128 + loff0), (unsigned*)((char*)(P) + tid * 16 + 8192), 16, 0, 0); } while (0)
; #define LDA(dst, b, h) for (int m = 0; m < 4; ++m) { \
;     dst[m][0] = *reinterpret_cast<const bf16x8*>((char*)SA(b, h) + aoff0 + m * 2048); \
;     dst[m][1] = *reinterpret_cast<const bf16x8*>((char*)SA(b, h) + aoff1 + m * 2048); }
; #define LDB(dst, b, h) for (int n = 0; n < 2; ++n) { \
;     dst[n][0] = *reinterpret_cast<const bf16x8*>((char*)SB(b, h) + boff0 + n * 256); \
;     dst[n][1] = *reinterpret_cast<const bf16x8*>((char*)SB(b, h) + boff1 + n * 256); }
; #define MMA(ai, bj, At, Btf) do { __builtin_amdgcn_s_setprio(1); \
;     for (int m = 0; m < 4; ++m) for (int n = 0; n < 2; ++n) for (int k = 0; k < 2; ++k) \
;       acc[ai][bj][m][n] = __builtin_amdgcn_mfma_f32_16x16x32_bf16(Btf[n][k], At[m][k], acc[ai][bj][m][n], 0, 0, 0); \
;     __builtin_amdgcn_s_setprio(0); } while (0)
; #define WAIT_V(n) asm volatile("s_waitcnt vmcnt(" #n ")" ::: "memory")
; #define WAIT_L(n) asm volatile("s_waitcnt lgkmcnt(" #n ")" ::: "memory")
; #define BAR __builtin_amdgcn_s_barrier()
; #define SCHED __builtin_amdgcn_sched_barrier(0)
; template <int EPI> ...
;     ...
;     LDB(B1, 0, 1); STAGE(SB(0, 0), Bt, bcol, t + 2);
;     BAR; WAIT_L(0); MMA(0, 1, At, B1); BAR;
;     LDA(At, 0, 1); STAGE(SA(0, 0), A, brow, t + 2);
;     BAR; WAIT_L(0); MMA(1, 0, At, B0); BAR; SCHED;
;     STAGE(SB(0, 1), Bt, bcol + HALF, t + 2);
;     WAIT_V(6); BAR; MMA(1, 1, At, B1); BAR;
	v_lshl_add_u64 v[226:227], s[64:65], 0, v[132:133]
	v_readfirstlane_b32 s68, v135
	v_lshl_add_u64 v[228:229], v[226:227], 0, s[20:21]
	s_mov_b32 m0, s68
	v_readfirstlane_b32 s68, v136
	global_load_lds_dwordx4 v[228:229], off
	v_lshl_add_u64 v[228:229], v[226:227], 0, s[22:23]
	s_mov_b32 m0, s68
	s_nop 0
	global_load_lds_dwordx4 v[228:229], off
	v_readfirstlane_b32 s68, v137
	v_lshl_add_u64 v[228:229], v[224:225], 0, s[24:25]
	s_mov_b32 m0, s68
	v_readfirstlane_b32 s68, v138
	ds_read_b128 v[176:179], v149 offset:16384
	ds_read_b128 v[180:183], v149 offset:17408
	ds_read_b128 v[184:187], v149 offset:18432
	ds_read_b128 v[188:191], v149 offset:19456
	ds_read_b128 v[192:195], v149 offset:20480
	ds_read_b128 v[196:199], v149 offset:21504
	ds_read_b128 v[200:203], v149 offset:22528
	ds_read_b128 v[204:207], v149 offset:23552
	global_load_lds_dwordx4 v[228:229], off
	v_lshl_add_u64 v[228:229], v[224:225], 0, s[26:27]
	s_mov_b32 m0, s68
	s_nop 0
	global_load_lds_dwordx4 v[228:229], off
	v_readfirstlane_b32 s68, v139
	v_lshl_add_u64 v[246:247], v[226:227], 0, s[28:29]
	s_mov_b32 m0, s68
	v_readfirstlane_b32 s68, v140
	global_load_lds_dwordx4 v[246:247], off
	s_waitcnt vmcnt(5)
	s_waitcnt lgkmcnt(0)

; #define STAGE(P, BASE, br, kt) do { const char* _gb = (const char*)(BASE) + ((size_t)(br) * K + (size_t)(kt) * BK) * 2; \
;     __builtin_amdgcn_global_load_lds((const unsigned*)(_gb + loff0), (unsigned*)((char*)(P) + tid * 16), 16, 0, 0); \
;     __builtin_amdgcn_global_load_lds((const unsigned*)(_gb + (size_t)K * 128 + loff0), (unsigned*)((char*)(P) + tid * 16 + 8192), 16, 0, 0); } while (0)
; #define MMA(ai, bj, At, Btf) do { __builtin_amdgcn_s_setprio(1); \
;     for (int m = 0; m < 4; ++m) for (int n = 0; n < 2; ++n) for (int k = 0; k < 2; ++k) \
;       acc[ai][bj][m][n] = __builtin_amdgcn_mfma_f32_16x16x32_bf16(Btf[n][k], At[m][k], acc[ai][bj][m][n], 0, 0, 0); \
;     __builtin_amdgcn_s_setprio(0); } while (0)
; #define WAIT_V(n) asm volatile("s_waitcnt vmcnt(" #n ")" ::: "memory")
; #define WAIT_L(n) asm volatile("s_waitcnt lgkmcnt(" #n ")" ::: "memory")
; #define BAR __builtin_amdgcn_s_barrier()
; #define SCHED __builtin_amdgcn_sched_barrier(0)
; template <int EPI> ...
;     ...
;     BAR; WAIT_L(0); MMA(1, 0, At, B0); BAR; SCHED;
;     STAGE(SB(0, 1), Bt, bcol + HALF, t + 2);
;     WAIT_V(6); BAR; MMA(1, 1, At, B1); BAR;
	s_barrier
	v_mfma_f32_16x16x32_bf16 v[60:63], v[160:163], v[176:179], v[60:63]
	v_mfma_f32_16x16x32_bf16 v[56:59], v[164:167], v[176:179], v[56:59]
	v_mfma_f32_16x16x32_bf16 v[52:55], v[160:163], v[184:187], v[52:55]
	v_mfma_f32_16x16x32_bf16 v[48:51], v[164:167], v[184:187], v[48:51]
	v_mfma_f32_16x16x32_bf16 v[44:47], v[160:163], v[192:195], v[44:47]
	v_mfma_f32_16x16x32_bf16 v[40:43], v[164:167], v[192:195], v[40:43]
	v_mfma_f32_16x16x32_bf16 v[36:39], v[160:163], v[200:203], v[36:39]
	v_mfma_f32_16x16x32_bf16 v[32:35], v[164:167], v[200:203], v[32:35]
	v_mfma_f32_16x16x32_bf16 v[60:63], v[168:171], v[180:183], v[60:63]
	v_mfma_f32_16x16x32_bf16 v[56:59], v[172:175], v[180:183], v[56:59]
	v_mfma_f32_16x16x32_bf16 v[52:55], v[168:171], v[188:191], v[52:55]
	v_mfma_f32_16x16x32_bf16 v[48:51], v[172:175], v[188:191], v[48:51]
	v_mfma_f32_16x16x32_bf16 v[44:47], v[168:171], v[196:199], v[44:47]
	v_mfma_f32_16x16x32_bf16 v[40:43], v[172:175], v[196:199], v[40:43]
	v_mfma_f32_16x16x32_bf16 v[36:39], v[168:171], v[204:207], v[36:39]
	v_mfma_f32_16x16x32_bf16 v[32:35], v[172:175], v[204:207], v[32:35]
	v_mfma_f32_16x16x32_bf16 v[28:31], v[208:211], v[176:179], v[28:31]
	v_mfma_f32_16x16x32_bf16 v[24:27], v[212:215], v[176:179], v[24:27]
	v_mfma_f32_16x16x32_bf16 v[20:23], v[208:211], v[184:187], v[20:23]
	v_mfma_f32_16x16x32_bf16 v[16:19], v[212:215], v[184:187], v[16:19]
	v_mfma_f32_16x16x32_bf16 v[12:15], v[208:211], v[192:195], v[12:15]
	v_mfma_f32_16x16x32_bf16 v[8:11], v[212:215], v[192:195], v[8:11]
	v_mfma_f32_16x16x32_bf16 v[4:7], v[208:211], v[200:203], v[4:7]
	v_mfma_f32_16x16x32_bf16 v[0:3], v[212:215], v[200:203], v[0:3]
	v_mfma_f32_16x16x32_bf16 v[28:31], v[216:219], v[180:183], v[28:31]
	v_mfma_f32_16x16x32_bf16 v[24:27], v[220:223], v[180:183], v[24:27]
	v_mfma_f32_16x16x32_bf16 v[20:23], v[216:219], v[188:191], v[20:23]
	v_mfma_f32_16x16x32_bf16 v[16:19], v[220:223], v[188:191], v[16:19]
	v_mfma_f32_16x16x32_bf16 v[12:15], v[216:219], v[196:199], v[12:15]
	v_mfma_f32_16x16x32_bf16 v[8:11], v[220:223], v[196:199], v[8:11]
	v_mfma_f32_16x16x32_bf16 v[4:7], v[216:219], v[204:207], v[4:7]
	v_mfma_f32_16x16x32_bf16 v[0:3], v[220:223], v[204:207], v[0:3]
	s_barrier

; #define STAGE(P, BASE, br, kt) do { const char* _gb = (const char*)(BASE) + ((size_t)(br) * K + (size_t)(kt) * BK) * 2; \
;     __builtin_amdgcn_global_load_lds((const unsigned*)(_gb + loff0), (unsigned*)((char*)(P) + tid * 16), 16, 0, 0); \
;     __builtin_amdgcn_global_load_lds((const unsigned*)(_gb + (size_t)K * 128 + loff0), (unsigned*)((char*)(P) + tid * 16 + 8192), 16, 0, 0); } while (0)
; #define LDA(dst, b, h) for (int m = 0; m < 4; ++m) { \
;     dst[m][0] = *reinterpret_cast<const bf16x8*>((char*)SA(b, h) + aoff0 + m * 2048); \
;     dst[m][1] = *reinterpret_cast<const bf16x8*>((char*)SA(b, h) + aoff1 + m * 2048); }
; #define LDB(dst, b, h) for (int n = 0; n < 2; ++n) { \
;     dst[n][0] = *reinterpret_cast<const bf16x8*>((char*)SB(b, h) + boff0 + n * 256); \
;     dst[n][1] = *reinterpret_cast<const bf16x8*>((char*)SB(b, h) + boff1 + n * 256); }
; #define MMA(ai, bj, At, Btf) do { __builtin_amdgcn_s_setprio(1); \
;     for (int m = 0; m < 4; ++m) for (int n = 0; n < 2; ++n) for (int k = 0; k < 2; ++k) \
;       acc[ai][bj][m][n] = __builtin_amdgcn_mfma_f32_16x16x32_bf16(Btf[n][k], At[m][k], acc[ai][bj][m][n], 0, 0, 0); \
;     __builtin_amdgcn_s_setprio(0); } while (0)
; #define WAIT_L(n) asm volatile("s_waitcnt lgkmcnt(" #n ")" ::: "memory")
; #define BAR __builtin_amdgcn_s_barrier()
; #define SCHED __builtin_amdgcn_sched_barrier(0)
; template <int EPI> ...
;     ...
;     LDB(B0, 1, 0); SCHED; LDA(At, 1, 0); STAGE(SA(0, 1), A, brow + HALF, t + 2);
;     WAIT_L(8); BAR; WAIT_L(0); MMA(0, 0, At, B0); BAR; SCHED;
;     LDB(B1, 1, 1); STAGE(SB(1, 0), Bt, bcol, t + 3);
	ds_read_b128 v[160:163], v156
	ds_read_b128 v[164:167], v156 offset:256
	ds_read_b128 v[168:171], v157
	ds_read_b128 v[172:175], v157 offset:256
	v_readfirstlane_b32 s68, v141
	v_lshl_add_u64 v[208:209], v[224:225], 0, s[36:37]
	s_mov_b32 m0, s68
	v_readfirstlane_b32 s68, v142
	ds_read_b128 v[176:179], v149 offset:32768
	ds_read_b128 v[180:183], v149 offset:33792
	ds_read_b128 v[184:187], v149 offset:34816
	ds_read_b128 v[188:191], v149 offset:35840
	ds_read_b128 v[192:195], v149 offset:36864
	ds_read_b128 v[196:199], v149 offset:37888
	ds_read_b128 v[200:203], v149 offset:38912
	ds_read_b128 v[204:207], v149 offset:39936
	global_load_lds_dwordx4 v[208:209], off
	v_lshl_add_u64 v[208:209], v[224:225], 0, s[38:39]
	s_mov_b32 m0, s68
	s_nop 0
	global_load_lds_dwordx4 v[208:209], off
	s_waitcnt lgkmcnt(8)
	v_readfirstlane_b32 s68, v140
	v_lshl_add_u64 v[246:247], v[226:227], 0, s[30:31]
	s_mov_b32 m0, s68
	s_nop 0
	global_load_lds_dwordx4 v[246:247], off
	ds_read_b128 v[208:211], v158
	ds_read_b128 v[212:215], v158 offset:256
	ds_read_b128 v[216:219], v159
	ds_read_b128 v[220:223], v159 offset:256
	s_waitcnt lgkmcnt(0)

; #define STAGE(P, BASE, br, kt) do { const char* _gb = (const char*)(BASE) + ((size_t)(br) * K + (size_t)(kt) * BK) * 2; \
;     __builtin_amdgcn_global_load_lds((const unsigned*)(_gb + loff0), (unsigned*)((char*)(P) + tid * 16), 16, 0, 0); \
;     __builtin_amdgcn_global_load_lds((const unsigned*)(_gb + (size_t)K * 128 + loff0), (unsigned*)((char*)(P) + tid * 16 + 8192), 16, 0, 0); } while (0)
; #define LDB(dst, b, h) for (int n = 0; n < 2; ++n) { \
;     dst[n][0] = *reinterpret_cast<const bf16x8*>((char*)SB(b, h) + boff0 + n * 256); \
;     dst[n][1] = *reinterpret_cast<const bf16x8*>((char*)SB(b, h) + boff1 + n * 256); }
; #define MMA(ai, bj, At, Btf) do { __builtin_amdgcn_s_setprio(1); \
;     for (int m = 0; m < 4; ++m) for (int n = 0; n < 2; ++n) for (int k = 0; k < 2; ++k) \
;       acc[ai][bj][m][n] = __builtin_amdgcn_mfma_f32_16x16x32_bf16(Btf[n][k], At[m][k], acc[ai][bj][m][n], 0, 0, 0); \
;     __builtin_amdgcn_s_setprio(0); } while (0)
; #define WAIT_L(n) asm volatile("s_waitcnt lgkmcnt(" #n ")" ::: "memory")
; #define BAR __builtin_amdgcn_s_barrier()
; #define SCHED __builtin_amdgcn_sched_barrier(0)
; template <int EPI> ...
;     ...
;     WAIT_L(8); BAR; WAIT_L(0); MMA(0, 0, At, B0); BAR; SCHED;
;     LDB(B1, 1, 1); STAGE(SB(1, 0), Bt, bcol, t + 3);
;     BAR; WAIT_L(0); MMA(0, 1, At, B1); BAR;
	s_barrier
	v_mfma_f32_16x16x32_bf16 v[124:127], v[160:163], v[176:179], v[124:127]
	v_mfma_f32_16x16x32_bf16 v[120:123], v[164:167], v[176:179], v[120:123]
	v_mfma_f32_16x16x32_bf16 v[116:119], v[160:163], v[184:187], v[116:119]
	v_mfma_f32_16x16x32_bf16 v[112:115], v[164:167], v[184:187], v[112:115]
	v_mfma_f32_16x16x32_bf16 v[108:111], v[160:163], v[192:195], v[108:111]
	v_mfma_f32_16x16x32_bf16 v[104:107], v[164:167], v[192:195], v[104:107]
	v_mfma_f32_16x16x32_bf16 v[100:103], v[160:163], v[200:203], v[100:103]
	v_mfma_f32_16x16x32_bf16 v[96:99], v[164:167], v[200:203], v[96:99]
	v_mfma_f32_16x16x32_bf16 v[124:127], v[168:171], v[180:183], v[124:127]
	v_mfma_f32_16x16x32_bf16 v[120:123], v[172:175], v[180:183], v[120:123]
	v_mfma_f32_16x16x32_bf16 v[116:119], v[168:171], v[188:191], v[116:119]
	v_mfma_f32_16x16x32_bf16 v[112:115], v[172:175], v[188:191], v[112:115]
	v_mfma_f32_16x16x32_bf16 v[108:111], v[168:171], v[196:199], v[108:111]
	v_mfma_f32_16x16x32_bf16 v[104:107], v[172:175], v[196:199], v[104:107]
	v_mfma_f32_16x16x32_bf16 v[100:103], v[168:171], v[204:207], v[100:103]
	v_mfma_f32_16x16x32_bf16 v[96:99], v[172:175], v[204:207], v[96:99]
	v_mfma_f32_16x16x32_bf16 v[92:95], v[208:211], v[176:179], v[92:95]
	v_mfma_f32_16x16x32_bf16 v[88:91], v[212:215], v[176:179], v[88:91]
	v_mfma_f32_16x16x32_bf16 v[84:87], v[208:211], v[184:187], v[84:87]
	v_mfma_f32_16x16x32_bf16 v[80:83], v[212:215], v[184:187], v[80:83]
	v_mfma_f32_16x16x32_bf16 v[76:79], v[208:211], v[192:195], v[76:79]
	v_mfma_f32_16x16x32_bf16 v[72:75], v[212:215], v[192:195], v[72:75]
	v_mfma_f32_16x16x32_bf16 v[68:71], v[208:211], v[200:203], v[68:71]
	v_mfma_f32_16x16x32_bf16 v[64:67], v[212:215], v[200:203], v[64:67]
	v_mfma_f32_16x16x32_bf16 v[92:95], v[216:219], v[180:183], v[92:95]
	v_mfma_f32_16x16x32_bf16 v[88:91], v[220:223], v[180:183], v[88:91]
	v_mfma_f32_16x16x32_bf16 v[84:87], v[216:219], v[188:191], v[84:87]
	v_mfma_f32_16x16x32_bf16 v[80:83], v[220:223], v[188:191], v[80:83]
	v_mfma_f32_16x16x32_bf16 v[76:79], v[216:219], v[196:199], v[76:79]
	v_mfma_f32_16x16x32_bf16 v[72:75], v[220:223], v[196:199], v[72:75]
	v_mfma_f32_16x16x32_bf16 v[68:71], v[216:219], v[204:207], v[68:71]
	v_mfma_f32_16x16x32_bf16 v[64:67], v[220:223], v[204:207], v[64:67]
	s_barrier

; #define STAGE(P, BASE, br, kt) do { const char* _gb = (const char*)(BASE) + ((size_t)(br) * K + (size_t)(kt) * BK) * 2; \
;     __builtin_amdgcn_global_load_lds((const unsigned*)(_gb + loff0), (unsigned*)((char*)(P) + tid * 16), 16, 0, 0); \
;     __builtin_amdgcn_global_load_lds((const unsigned*)(_gb + (size_t)K * 128 + loff0), (unsigned*)((char*)(P) + tid * 16 + 8192), 16, 0, 0); } while (0)
; #define LDA(dst, b, h) for (int m = 0; m < 4; ++m) { \
;     dst[m][0] = *reinterpret_cast<const bf16x8*>((char*)SA(b, h) + aoff0 + m * 2048); \
;     dst[m][1] = *reinterpret_cast<const bf16x8*>((char*)SA(b, h) + aoff1 + m * 2048); }
; #define LDB(dst, b, h) for (int n = 0; n < 2; ++n) { \
;     dst[n][0] = *reinterpret_cast<const bf16x8*>((char*)SB(b, h) + boff0 + n * 256); \
;     dst[n][1] = *reinterpret_cast<const bf16x8*>((char*)SB(b, h) + boff1 + n * 256); }
; #define MMA(ai, bj, At, Btf) do { __builtin_amdgcn_s_setprio(1); \
;     for (int m = 0; m < 4; ++m) for (int n = 0; n < 2; ++n) for (int k = 0; k < 2; ++k) \
;       acc[ai][bj][m][n] = __builtin_amdgcn_mfma_f32_16x16x32_bf16(Btf[n][k], At[m][k], acc[ai][bj][m][n], 0, 0, 0); \
;     __builtin_amdgcn_s_setprio(0); } while (0)
; #define WAIT_V(n) asm volatile("s_waitcnt vmcnt(" #n ")" ::: "memory")
; #define WAIT_L(n) asm volatile("s_waitcnt lgkmcnt(" #n ")" ::: "memory")
; #define BAR __builtin_amdgcn_s_barrier()
; #define SCHED __builtin_amdgcn_sched_barrier(0)
; template <int EPI> ...
;     ...
;     LDB(B1, 1, 1); STAGE(SB(1, 0), Bt, bcol, t + 3);
;     BAR; WAIT_L(0); MMA(0, 1, At, B1); BAR;
;     LDA(At, 1, 1); STAGE(SA(1, 0), A, brow, t + 3);
;     BAR; WAIT_L(0); MMA(1, 0, At, B0); BAR; SCHED;
;     STAGE(SB(1, 1), Bt, bcol + HALF, t + 3);
;     WAIT_V(6); BAR; MMA(1, 1, At, B1); BAR;
	v_readfirstlane_b32 s68, v143
	v_lshl_add_u64 v[228:229], v[226:227], 0, s[46:47]
	s_mov_b32 m0, s68
	v_readfirstlane_b32 s68, v144
	global_load_lds_dwordx4 v[228:229], off
	v_lshl_add_u64 v[228:229], v[226:227], 0, s[48:49]
	s_mov_b32 m0, s68
	s_nop 0
	global_load_lds_dwordx4 v[228:229], off
	v_readfirstlane_b32 s68, v145
	v_lshl_add_u64 v[228:229], v[224:225], 0, s[50:51]
	s_mov_b32 m0, s68
	v_readfirstlane_b32 s68, v146
	ds_read_b128 v[176:179], v149 offset:49152
	ds_read_b128 v[180:183], v149 offset:50176
	ds_read_b128 v[184:187], v149 offset:51200
	ds_read_b128 v[188:191], v149 offset:52224
	ds_read_b128 v[192:195], v149 offset:53248
	ds_read_b128 v[196:199], v149 offset:54272
	ds_read_b128 v[200:203], v149 offset:55296
	ds_read_b128 v[204:207], v149 offset:56320
	global_load_lds_dwordx4 v[228:229], off
	v_lshl_add_u64 v[224:225], v[224:225], 0, s[52:53]
	s_mov_b32 m0, s68
	s_nop 0
	global_load_lds_dwordx4 v[224:225], off
	v_readfirstlane_b32 s68, v147
	v_lshl_add_u64 v[246:247], v[226:227], 0, s[54:55]
	s_mov_b32 m0, s68
	v_readfirstlane_b32 s68, v148
	global_load_lds_dwordx4 v[246:247], off
	s_waitcnt vmcnt(5)
	s_barrier
	s_waitcnt lgkmcnt(0)

; #define MMA(ai, bj, At, Btf) do { __builtin_amdgcn_s_setprio(1); \
;     for (int m = 0; m < 4; ++m) for (int n = 0; n < 2; ++n) for (int k = 0; k < 2; ++k) \
;       acc[ai][bj][m][n] = __builtin_amdgcn_mfma_f32_16x16x32_bf16(Btf[n][k], At[m][k], acc[ai][bj][m][n], 0, 0, 0); \
;     __builtin_amdgcn_s_setprio(0); } while (0)
; #define WAIT_L(n) asm volatile("s_waitcnt lgkmcnt(" #n ")" ::: "memory")
; #define BAR __builtin_amdgcn_s_barrier()
; #define SCHED __builtin_amdgcn_sched_barrier(0)
; template <int EPI> ...
;     ...
;     BAR; WAIT_L(0); MMA(1, 0, At, B0); BAR; SCHED;
	s_waitcnt lgkmcnt(0)
	v_mfma_f32_16x16x32_bf16 v[60:63], v[160:163], v[176:179], v[60:63]
	v_mfma_f32_16x16x32_bf16 v[56:59], v[164:167], v[176:179], v[56:59]
	v_mfma_f32_16x16x32_bf16 v[52:55], v[160:163], v[184:187], v[52:55]
	v_mfma_f32_16x16x32_bf16 v[48:51], v[164:167], v[184:187], v[48:51]
	v_mfma_f32_16x16x32_bf16 v[44:47], v[160:163], v[192:195], v[44:47]
	v_mfma_f32_16x16x32_bf16 v[40:43], v[164:167], v[192:195], v[40:43]
	v_mfma_f32_16x16x32_bf16 v[36:39], v[160:163], v[200:203], v[36:39]
	v_mfma_f32_16x16x32_bf16 v[32:35], v[164:167], v[200:203], v[32:35]
	v_mfma_f32_16x16x32_bf16 v[60:63], v[168:171], v[180:183], v[60:63]
	v_mfma_f32_16x16x32_bf16 v[56:59], v[172:175], v[180:183], v[56:59]
	v_mfma_f32_16x16x32_bf16 v[52:55], v[168:171], v[188:191], v[52:55]
	v_mfma_f32_16x16x32_bf16 v[48:51], v[172:175], v[188:191], v[48:51]
	v_mfma_f32_16x16x32_bf16 v[44:47], v[168:171], v[196:199], v[44:47]
	v_mfma_f32_16x16x32_bf16 v[40:43], v[172:175], v[196:199], v[40:43]
	v_mfma_f32_16x16x32_bf16 v[36:39], v[168:171], v[204:207], v[36:39]
	v_mfma_f32_16x16x32_bf16 v[32:35], v[172:175], v[204:207], v[32:35]


; #define MMA(ai, bj, At, Btf) do { __builtin_amdgcn_s_setprio(1); \
;     for (int m = 0; m < 4; ++m) for (int n = 0; n < 2; ++n) for (int k = 0; k < 2; ++k) \
;       acc[ai][bj][m][n] = __builtin_amdgcn_mfma_f32_16x16x32_bf16(Btf[n][k], At[m][k], acc[ai][bj][m][n], 0, 0, 0); \
;     __builtin_amdgcn_s_setprio(0); } while (0)
; #define WAIT_V(n) asm volatile("s_waitcnt vmcnt(" #n ")" ::: "memory")
; #define BAR __builtin_amdgcn_s_barrier()
; template <int EPI> ...
;     ...
;     WAIT_V(6); BAR; MMA(1, 1, At, B1); BAR;
	v_mfma_f32_16x16x32_bf16 v[28:31], v[208:211], v[176:179], v[28:31]
	v_mfma_f32_16x16x32_bf16 v[24:27], v[212:215], v[176:179], v[24:27]
	v_mfma_f32_16x16x32_bf16 v[20:23], v[208:211], v[184:187], v[20:23]
	v_mfma_f32_16x16x32_bf16 v[16:19], v[212:215], v[184:187], v[16:19]
	v_mfma_f32_16x16x32_bf16 v[12:15], v[208:211], v[192:195], v[12:15]
	v_mfma_f32_16x16x32_bf16 v[8:11], v[212:215], v[192:195], v[8:11]
	v_mfma_f32_16x16x32_bf16 v[4:7], v[208:211], v[200:203], v[4:7]
	v_mfma_f32_16x16x32_bf16 v[0:3], v[212:215], v[200:203], v[0:3]
	v_mfma_f32_16x16x32_bf16 v[28:31], v[216:219], v[180:183], v[28:31]
	v_mfma_f32_16x16x32_bf16 v[24:27], v[220:223], v[180:183], v[24:27]
	v_mfma_f32_16x16x32_bf16 v[20:23], v[216:219], v[188:191], v[20:23]
	v_mfma_f32_16x16x32_bf16 v[16:19], v[220:223], v[188:191], v[16:19]
	v_mfma_f32_16x16x32_bf16 v[12:15], v[216:219], v[196:199], v[12:15]
	v_mfma_f32_16x16x32_bf16 v[8:11], v[220:223], v[196:199], v[8:11]
	v_mfma_f32_16x16x32_bf16 v[4:7], v[216:219], v[204:207], v[4:7]
	v_mfma_f32_16x16x32_bf16 v[0:3], v[220:223], v[204:207], v[0:3]

; #define STAGE(P, BASE, br, kt) do { const char* _gb = (const char*)(BASE) + ((size_t)(br) * K + (size_t)(kt) * BK) * 2; \
;     __builtin_amdgcn_global_load_lds((const unsigned*)(_gb + loff0), (unsigned*)((char*)(P) + tid * 16), 16, 0, 0); \
;     __builtin_amdgcn_global_load_lds((const unsigned*)(_gb + (size_t)K * 128 + loff0), (unsigned*)((char*)(P) + tid * 16 + 8192), 16, 0, 0); } while (0)
; #define LDA(dst, b, h) for (int m = 0; m < 4; ++m) { \
;     dst[m][0] = *reinterpret_cast<const bf16x8*>((char*)SA(b, h) + aoff0 + m * 2048); \
;     dst[m][1] = *reinterpret_cast<const bf16x8*>((char*)SA(b, h) + aoff1 + m * 2048); }
; #define LDB(dst, b, h) for (int n = 0; n < 2; ++n) { \
;     dst[n][0] = *reinterpret_cast<const bf16x8*>((char*)SB(b, h) + boff0 + n * 256); \
;     dst[n][1] = *reinterpret_cast<const bf16x8*>((char*)SB(b, h) + boff1 + n * 256); }
; #define MMA(ai, bj, At, Btf) do { __builtin_amdgcn_s_setprio(1); \
;     for (int m = 0; m < 4; ++m) for (int n = 0; n < 2; ++n) for (int k = 0; k < 2; ++k) \
;       acc[ai][bj][m][n] = __builtin_amdgcn_mfma_f32_16x16x32_bf16(Btf[n][k], At[m][k], acc[ai][bj][m][n], 0, 0, 0); \
;     __builtin_amdgcn_s_setprio(0); } while (0)
; #define WAIT_V(n) asm volatile("s_waitcnt vmcnt(" #n ")" ::: "memory")
; #define WAIT_L(n) asm volatile("s_waitcnt lgkmcnt(" #n ")" ::: "memory")
; template <int EPI> ...
;     ...
;   for (int t = 0; t < nt - 2; t += 2) {
;     LDB(B0, 0, 0); SCHED; LDA(At, 0, 0); STAGE(SA(1, 1), A, brow + HALF, t + 1);
;     WAIT_L(8); BAR; WAIT_L(0); MMA(0, 0, At, B0); BAR; SCHED;
;     LDB(B1, 0, 1); STAGE(SB(0, 0), Bt, bcol, t + 2);
;     BAR; WAIT_L(0); MMA(0, 1, At, B1); BAR;
;     LDA(At, 0, 1); STAGE(SA(0, 0), A, brow, t + 2);
;     BAR; WAIT_L(0); MMA(1, 0, At, B0); BAR; SCHED;
;     STAGE(SB(0, 1), Bt, bcol + HALF, t + 2);
;     WAIT_V(6); BAR; MMA(1, 1, At, B1); BAR;
;     LDB(B0, 1, 0); SCHED; LDA(At, 1, 0); STAGE(SA(0, 1), A, brow + HALF, t + 2);
;     WAIT_L(8); BAR; WAIT_L(0); MMA(0, 0, At, B0); BAR; SCHED;
;     LDB(B1, 1, 1); STAGE(SB(1, 0), Bt, bcol, t + 3);
;     BAR; WAIT_L(0); MMA(0, 1, At, B1); BAR;
;     LDA(At, 1, 1); STAGE(SA(1, 0), A, brow, t + 3);
;     BAR; WAIT_L(0); MMA(1, 0, At, B0); BAR; SCHED;
;     STAGE(SB(1, 1), Bt, bcol + HALF, t + 3);
;     WAIT_V(6); BAR; MMA(1, 1, At, B1); BAR;
;   }
;   { LDB(B0, 0, 0); LDA(At, 0, 0); STAGE(SA(1, 1), A, brow + HALF, nt - 1);
	s_add_i32 s59, s59, 2
	s_add_u32 s64, s64, 0x100
	s_addc_u32 s65, s65, 0
	s_add_u32 s66, s66, 0x100
	s_addc_u32 s67, s67, 0
	s_cmp_lt_u32 s59, 28
	s_barrier
	s_cbranch_scc1 .LBB0_1018
	v_readfirstlane_b32 s68, v148
	v_lshl_add_u64 v[246:247], v[226:227], 0, s[56:57]
	s_mov_b32 m0, s68
	s_nop 0
	global_load_lds_dwordx4 v[246:247], off
	s_add_u32 s62, s72, s62
	s_addc_u32 s63, s73, s63
	v_readfirstlane_b32 s59, v150
	v_lshl_add_u64 v[208:209], s[62:63], 0, v[128:129]
	s_mov_b32 m0, s59
	v_readfirstlane_b32 s59, v151
	ds_read_b128 v[160:163], v152
	ds_read_b128 v[164:167], v152 offset:256
	ds_read_b128 v[168:171], v153
	ds_read_b128 v[172:175], v153 offset:256
	ds_read_b128 v[176:179], v149
	ds_read_b128 v[180:183], v149 offset:1024
	ds_read_b128 v[184:187], v149 offset:2048
	ds_read_b128 v[188:191], v149 offset:3072
	ds_read_b128 v[192:195], v149 offset:4096
	ds_read_b128 v[196:199], v149 offset:5120
	ds_read_b128 v[200:203], v149 offset:6144
	ds_read_b128 v[204:207], v149 offset:7168
	global_load_lds_dwordx4 v[208:209], off
	v_lshl_add_u64 v[208:209], v[208:209], 0, s[8:9]
	s_mov_b32 m0, s59
	s_nop 0
	global_load_lds_dwordx4 v[208:209], off
	s_waitcnt lgkmcnt(0)

; #define MMA(ai, bj, At, Btf) do { __builtin_amdgcn_s_setprio(1); \
;     for (int m = 0; m < 4; ++m) for (int n = 0; n < 2; ++n) for (int k = 0; k < 2; ++k) \
;       acc[ai][bj][m][n] = __builtin_amdgcn_mfma_f32_16x16x32_bf16(Btf[n][k], At[m][k], acc[ai][bj][m][n], 0, 0, 0); \
;     __builtin_amdgcn_s_setprio(0); } while (0)
; #define WAIT_L(n) asm volatile("s_waitcnt lgkmcnt(" #n ")" ::: "memory")
; #define BAR __builtin_amdgcn_s_barrier()
; template <int EPI> ...
;     ...
;     BAR; WAIT_L(0); MMA(0, 0, At, B0); BAR;
	s_barrier
	v_mfma_f32_16x16x32_bf16 v[124:127], v[160:163], v[176:179], v[124:127]
	v_mfma_f32_16x16x32_bf16 v[116:119], v[160:163], v[184:187], v[116:119]
	v_mfma_f32_16x16x32_bf16 v[108:111], v[160:163], v[192:195], v[108:111]
	v_mfma_f32_16x16x32_bf16 v[100:103], v[160:163], v[200:203], v[100:103]
	v_mfma_f32_16x16x32_bf16 v[96:99], v[164:167], v[200:203], v[96:99]
	v_mfma_f32_16x16x32_bf16 v[124:127], v[168:171], v[180:183], v[124:127]
	v_mfma_f32_16x16x32_bf16 v[120:123], v[164:167], v[176:179], v[120:123]
	v_mfma_f32_16x16x32_bf16 v[116:119], v[168:171], v[188:191], v[116:119]
	v_mfma_f32_16x16x32_bf16 v[112:115], v[164:167], v[184:187], v[112:115]
	v_mfma_f32_16x16x32_bf16 v[108:111], v[168:171], v[196:199], v[108:111]
	v_mfma_f32_16x16x32_bf16 v[104:107], v[164:167], v[192:195], v[104:107]
	v_mfma_f32_16x16x32_bf16 v[100:103], v[168:171], v[204:207], v[100:103]
	v_mfma_f32_16x16x32_bf16 v[96:99], v[172:175], v[204:207], v[96:99]
	v_mfma_f32_16x16x32_bf16 v[208:211], v[172:175], v[180:183], v[120:123]
	v_mfma_f32_16x16x32_bf16 v[212:215], v[172:175], v[188:191], v[112:115]
	v_mfma_f32_16x16x32_bf16 v[216:219], v[172:175], v[196:199], v[104:107]
	s_barrier

; #define LDB(dst, b, h) for (int n = 0; n < 2; ++n) { \
;     dst[n][0] = *reinterpret_cast<const bf16x8*>((char*)SB(b, h) + boff0 + n * 256); \
;     dst[n][1] = *reinterpret_cast<const bf16x8*>((char*)SB(b, h) + boff1 + n * 256); }
; #define MMA(ai, bj, At, Btf) do { __builtin_amdgcn_s_setprio(1); \
;     for (int m = 0; m < 4; ++m) for (int n = 0; n < 2; ++n) for (int k = 0; k < 2; ++k) \
;       acc[ai][bj][m][n] = __builtin_amdgcn_mfma_f32_16x16x32_bf16(Btf[n][k], At[m][k], acc[ai][bj][m][n], 0, 0, 0); \
;     __builtin_amdgcn_s_setprio(0); } while (0)
; #define WAIT_L(n) asm volatile("s_waitcnt lgkmcnt(" #n ")" ::: "memory")
; #define BAR __builtin_amdgcn_s_barrier()
; template <int EPI> ...
;     ...
;     LDB(B1, 0, 1); BAR; WAIT_L(0); MMA(0, 1, At, B1); BAR;
	s_nop 0
	ds_read_b128 v[104:107], v154
	ds_read_b128 v[112:115], v154 offset:256
	ds_read_b128 v[120:123], v155
	ds_read_b128 v[220:223], v155 offset:256
	s_waitcnt lgkmcnt(0)

; #define LDB(dst, b, h) for (int n = 0; n < 2; ++n) { \
;     dst[n][0] = *reinterpret_cast<const bf16x8*>((char*)SB(b, h) + boff0 + n * 256); \
;     dst[n][1] = *reinterpret_cast<const bf16x8*>((char*)SB(b, h) + boff1 + n * 256); }
; #define MMA(ai, bj, At, Btf) do { __builtin_amdgcn_s_setprio(1); \
;     for (int m = 0; m < 4; ++m) for (int n = 0; n < 2; ++n) for (int k = 0; k < 2; ++k) \
;       acc[ai][bj][m][n] = __builtin_amdgcn_mfma_f32_16x16x32_bf16(Btf[n][k], At[m][k], acc[ai][bj][m][n], 0, 0, 0); \
;     __builtin_amdgcn_s_setprio(0); } while (0)
; #define WAIT_L(n) asm volatile("s_waitcnt lgkmcnt(" #n ")" ::: "memory")
; #define BAR __builtin_amdgcn_s_barrier()
; template <int EPI> ...
;     ...
;     LDB(B1, 0, 1); BAR; WAIT_L(0); MMA(0, 1, At, B1); BAR;
	s_barrier
	v_mfma_f32_16x16x32_bf16 v[84:87], v[104:107], v[184:187], v[84:87]
	v_mfma_f32_16x16x32_bf16 v[76:79], v[104:107], v[192:195], v[76:79]
	v_mfma_f32_16x16x32_bf16 v[72:75], v[112:115], v[192:195], v[72:75]
	v_mfma_f32_16x16x32_bf16 v[92:95], v[104:107], v[176:179], v[92:95]
	v_mfma_f32_16x16x32_bf16 v[88:91], v[112:115], v[176:179], v[88:91]
	v_mfma_f32_16x16x32_bf16 v[84:87], v[120:123], v[188:191], v[84:87]
	v_mfma_f32_16x16x32_bf16 v[80:83], v[112:115], v[184:187], v[80:83]
	v_mfma_f32_16x16x32_bf16 v[76:79], v[120:123], v[196:199], v[76:79]
	v_mfma_f32_16x16x32_bf16 v[72:75], v[220:223], v[196:199], v[72:75]
	v_mfma_f32_16x16x32_bf16 v[68:71], v[104:107], v[200:203], v[68:71]
	v_mfma_f32_16x16x32_bf16 v[64:67], v[112:115], v[200:203], v[64:67]
	v_mfma_f32_16x16x32_bf16 v[224:227], v[120:123], v[180:183], v[92:95]
	v_mfma_f32_16x16x32_bf16 v[176:179], v[220:223], v[180:183], v[88:91]
	v_mfma_f32_16x16x32_bf16 v[180:183], v[220:223], v[188:191], v[80:83]
	v_mfma_f32_16x16x32_bf16 v[184:187], v[120:123], v[204:207], v[68:71]
	v_mfma_f32_16x16x32_bf16 v[188:191], v[220:223], v[204:207], v[64:67]
	s_barrier

; #define LDA(dst, b, h) for (int m = 0; m < 4; ++m) { \
;     dst[m][0] = *reinterpret_cast<const bf16x8*>((char*)SA(b, h) + aoff0 + m * 2048); \
;     dst[m][1] = *reinterpret_cast<const bf16x8*>((char*)SA(b, h) + aoff1 + m * 2048); }
; #define MMA(ai, bj, At, Btf) do { __builtin_amdgcn_s_setprio(1); \
;     for (int m = 0; m < 4; ++m) for (int n = 0; n < 2; ++n) for (int k = 0; k < 2; ++k) \
;       acc[ai][bj][m][n] = __builtin_amdgcn_mfma_f32_16x16x32_bf16(Btf[n][k], At[m][k], acc[ai][bj][m][n], 0, 0, 0); \
;     __builtin_amdgcn_s_setprio(0); } while (0)
; #define WAIT_V(n) asm volatile("s_waitcnt vmcnt(" #n ")" ::: "memory")
; #define WAIT_L(n) asm volatile("s_waitcnt lgkmcnt(" #n ")" ::: "memory")
; #define BAR __builtin_amdgcn_s_barrier()
; template <int EPI> ...
;     ...
;     LDA(At, 0, 1); WAIT_V(4); BAR; WAIT_L(0); MMA(1, 0, At, B0); MMA(1, 1, At, B1); BAR; }
	s_nop 0
	ds_read_b128 v[64:67], v149 offset:16384
	ds_read_b128 v[68:71], v149 offset:17408
	ds_read_b128 v[80:83], v149 offset:18432
	ds_read_b128 v[88:91], v149 offset:19456
	ds_read_b128 v[92:95], v149 offset:20480
	ds_read_b128 v[192:195], v149 offset:21504
	ds_read_b128 v[196:199], v149 offset:22528
	ds_read_b128 v[200:203], v149 offset:23552
	s_waitcnt vmcnt(4)
	s_waitcnt lgkmcnt(0)

; #define LDA(dst, b, h) for (int m = 0; m < 4; ++m) { \
;     dst[m][0] = *reinterpret_cast<const bf16x8*>((char*)SA(b, h) + aoff0 + m * 2048); \
;     dst[m][1] = *reinterpret_cast<const bf16x8*>((char*)SA(b, h) + aoff1 + m * 2048); }
; #define MMA(ai, bj, At, Btf) do { __builtin_amdgcn_s_setprio(1); \
;     for (int m = 0; m < 4; ++m) for (int n = 0; n < 2; ++n) for (int k = 0; k < 2; ++k) \
;       acc[ai][bj][m][n] = __builtin_amdgcn_mfma_f32_16x16x32_bf16(Btf[n][k], At[m][k], acc[ai][bj][m][n], 0, 0, 0); \
;     __builtin_amdgcn_s_setprio(0); } while (0)
; #define WAIT_V(n) asm volatile("s_waitcnt vmcnt(" #n ")" ::: "memory")
; #define WAIT_L(n) asm volatile("s_waitcnt lgkmcnt(" #n ")" ::: "memory")
; #define BAR __builtin_amdgcn_s_barrier()
; template <int EPI> ...
;     ...
;     LDA(At, 0, 1); WAIT_V(4); BAR; WAIT_L(0); MMA(1, 0, At, B0); MMA(1, 1, At, B1); BAR; }
	s_barrier
	v_mfma_f32_16x16x32_bf16 v[52:55], v[160:163], v[80:83], v[52:55]
	v_mfma_f32_16x16x32_bf16 v[44:47], v[160:163], v[92:95], v[44:47]
	v_mfma_f32_16x16x32_bf16 v[36:39], v[160:163], v[196:199], v[36:39]
	v_mfma_f32_16x16x32_bf16 v[60:63], v[160:163], v[64:67], v[60:63]
	v_mfma_f32_16x16x32_bf16 v[56:59], v[164:167], v[64:67], v[56:59]
	v_mfma_f32_16x16x32_bf16 v[52:55], v[168:171], v[88:91], v[52:55]
	v_mfma_f32_16x16x32_bf16 v[48:51], v[164:167], v[80:83], v[48:51]
	v_mfma_f32_16x16x32_bf16 v[44:47], v[168:171], v[192:195], v[44:47]
	v_mfma_f32_16x16x32_bf16 v[40:43], v[164:167], v[92:95], v[40:43]
	v_mfma_f32_16x16x32_bf16 v[36:39], v[168:171], v[200:203], v[36:39]
	v_mfma_f32_16x16x32_bf16 v[32:35], v[164:167], v[196:199], v[32:35]
	v_mfma_f32_16x16x32_bf16 v[204:207], v[168:171], v[68:71], v[60:63]
	v_mfma_f32_16x16x32_bf16 v[228:231], v[172:175], v[68:71], v[56:59]
	v_mfma_f32_16x16x32_bf16 v[232:235], v[172:175], v[88:91], v[48:51]
	v_mfma_f32_16x16x32_bf16 v[236:239], v[172:175], v[192:195], v[40:43]
	v_mfma_f32_16x16x32_bf16 v[160:163], v[172:175], v[200:203], v[32:35]
	v_mfma_f32_16x16x32_bf16 v[28:31], v[104:107], v[64:67], v[28:31]
	v_mfma_f32_16x16x32_bf16 v[20:23], v[104:107], v[80:83], v[20:23]
	v_mfma_f32_16x16x32_bf16 v[12:15], v[104:107], v[92:95], v[12:15]
	v_mfma_f32_16x16x32_bf16 v[4:7], v[104:107], v[196:199], v[4:7]
	v_mfma_f32_16x16x32_bf16 v[28:31], v[120:123], v[68:71], v[28:31]
	v_mfma_f32_16x16x32_bf16 v[24:27], v[112:115], v[64:67], v[24:27]
	v_mfma_f32_16x16x32_bf16 v[20:23], v[120:123], v[88:91], v[20:23]
	v_mfma_f32_16x16x32_bf16 v[16:19], v[112:115], v[80:83], v[16:19]
	v_mfma_f32_16x16x32_bf16 v[12:15], v[120:123], v[192:195], v[12:15]
	v_mfma_f32_16x16x32_bf16 v[8:11], v[112:115], v[92:95], v[8:11]
	v_mfma_f32_16x16x32_bf16 v[4:7], v[120:123], v[200:203], v[4:7]
	v_mfma_f32_16x16x32_bf16 v[0:3], v[112:115], v[196:199], v[0:3]
	v_mfma_f32_16x16x32_bf16 v[164:167], v[220:223], v[68:71], v[24:27]
	v_mfma_f32_16x16x32_bf16 v[168:171], v[220:223], v[88:91], v[16:19]
	v_mfma_f32_16x16x32_bf16 v[172:175], v[220:223], v[192:195], v[8:11]
	v_mfma_f32_16x16x32_bf16 v[192:195], v[220:223], v[200:203], v[0:3]
	s_barrier

; #define LDA(dst, b, h) for (int m = 0; m < 4; ++m) { \
;     dst[m][0] = *reinterpret_cast<const bf16x8*>((char*)SA(b, h) + aoff0 + m * 2048); \
;     dst[m][1] = *reinterpret_cast<const bf16x8*>((char*)SA(b, h) + aoff1 + m * 2048); }
; #define LDB(dst, b, h) for (int n = 0; n < 2; ++n) { \
;     dst[n][0] = *reinterpret_cast<const bf16x8*>((char*)SB(b, h) + boff0 + n * 256); \
;     dst[n][1] = *reinterpret_cast<const bf16x8*>((char*)SB(b, h) + boff1 + n * 256); }
; #define MMA(ai, bj, At, Btf) do { __builtin_amdgcn_s_setprio(1); \
;     for (int m = 0; m < 4; ++m) for (int n = 0; n < 2; ++n) for (int k = 0; k < 2; ++k) \
;       acc[ai][bj][m][n] = __builtin_amdgcn_mfma_f32_16x16x32_bf16(Btf[n][k], At[m][k], acc[ai][bj][m][n], 0, 0, 0); \
;     __builtin_amdgcn_s_setprio(0); } while (0)
; #define WAIT_V(n) asm volatile("s_waitcnt vmcnt(" #n ")" ::: "memory")
; #define WAIT_L(n) asm volatile("s_waitcnt lgkmcnt(" #n ")" ::: "memory")
; #define BAR __builtin_amdgcn_s_barrier()
; template <int EPI> ...
;     ...
;   { LDB(B0, 1, 0); LDA(At, 1, 0); WAIT_V(2); BAR; WAIT_L(0); MMA(0, 0, At, B0); BAR;
	s_nop 1
	ds_read_b128 v[0:3], v156
	ds_read_b128 v[8:11], v156 offset:256
	ds_read_b128 v[16:19], v157
	ds_read_b128 v[24:27], v157 offset:256
	ds_read_b128 v[32:35], v149 offset:32768
	ds_read_b128 v[40:43], v149 offset:33792
	ds_read_b128 v[48:51], v149 offset:34816
	ds_read_b128 v[56:59], v149 offset:35840
	ds_read_b128 v[60:63], v149 offset:36864
	ds_read_b128 v[68:71], v149 offset:37888
	ds_read_b128 v[196:199], v149 offset:38912
	ds_read_b128 v[200:203], v149 offset:39936
	s_waitcnt vmcnt(2)
	s_waitcnt lgkmcnt(0)

; #define LDA(dst, b, h) for (int m = 0; m < 4; ++m) { \
;     dst[m][0] = *reinterpret_cast<const bf16x8*>((char*)SA(b, h) + aoff0 + m * 2048); \
;     dst[m][1] = *reinterpret_cast<const bf16x8*>((char*)SA(b, h) + aoff1 + m * 2048); }
; #define LDB(dst, b, h) for (int n = 0; n < 2; ++n) { \
;     dst[n][0] = *reinterpret_cast<const bf16x8*>((char*)SB(b, h) + boff0 + n * 256); \
;     dst[n][1] = *reinterpret_cast<const bf16x8*>((char*)SB(b, h) + boff1 + n * 256); }
; #define MMA(ai, bj, At, Btf) do { __builtin_amdgcn_s_setprio(1); \
;     for (int m = 0; m < 4; ++m) for (int n = 0; n < 2; ++n) for (int k = 0; k < 2; ++k) \
;       acc[ai][bj][m][n] = __builtin_amdgcn_mfma_f32_16x16x32_bf16(Btf[n][k], At[m][k], acc[ai][bj][m][n], 0, 0, 0); \
;     __builtin_amdgcn_s_setprio(0); } while (0)
; #define WAIT_V(n) asm volatile("s_waitcnt vmcnt(" #n ")" ::: "memory")
; #define WAIT_L(n) asm volatile("s_waitcnt lgkmcnt(" #n ")" ::: "memory")
; #define BAR __builtin_amdgcn_s_barrier()
; template <int EPI> ...
;     ...
;   { LDB(B0, 1, 0); LDA(At, 1, 0); WAIT_V(2); BAR; WAIT_L(0); MMA(0, 0, At, B0); BAR;
	s_barrier
	v_mfma_f32_16x16x32_bf16 v[64:67], v[0:3], v[32:35], v[124:127]
	v_mfma_f32_16x16x32_bf16 v[120:123], v[16:19], v[40:43], v[64:67]
	v_mfma_f32_16x16x32_bf16 v[64:67], v[8:11], v[32:35], v[208:211]
	v_mfma_f32_16x16x32_bf16 v[124:127], v[24:27], v[40:43], v[64:67]
	v_mfma_f32_16x16x32_bf16 v[64:67], v[0:3], v[48:51], v[116:119]
	v_mfma_f32_16x16x32_bf16 v[112:115], v[16:19], v[56:59], v[64:67]
	v_mfma_f32_16x16x32_bf16 v[64:67], v[8:11], v[48:51], v[212:215]
	v_mfma_f32_16x16x32_bf16 v[116:119], v[24:27], v[56:59], v[64:67]
	v_mfma_f32_16x16x32_bf16 v[64:67], v[0:3], v[60:63], v[108:111]
	v_mfma_f32_16x16x32_bf16 v[104:107], v[16:19], v[68:71], v[64:67]
	v_mfma_f32_16x16x32_bf16 v[64:67], v[8:11], v[60:63], v[216:219]
	v_mfma_f32_16x16x32_bf16 v[108:111], v[24:27], v[68:71], v[64:67]
	v_mfma_f32_16x16x32_bf16 v[64:67], v[0:3], v[196:199], v[100:103]
	v_mfma_f32_16x16x32_bf16 v[88:91], v[16:19], v[200:203], v[64:67]
	v_mfma_f32_16x16x32_bf16 v[64:67], v[8:11], v[196:199], v[96:99]
	v_mfma_f32_16x16x32_bf16 v[92:95], v[24:27], v[200:203], v[64:67]
	s_barrier

; #define LDB(dst, b, h) for (int n = 0; n < 2; ++n) { \
;     dst[n][0] = *reinterpret_cast<const bf16x8*>((char*)SB(b, h) + boff0 + n * 256); \
;     dst[n][1] = *reinterpret_cast<const bf16x8*>((char*)SB(b, h) + boff1 + n * 256); }
; #define MMA(ai, bj, At, Btf) do { __builtin_amdgcn_s_setprio(1); \
;     for (int m = 0; m < 4; ++m) for (int n = 0; n < 2; ++n) for (int k = 0; k < 2; ++k) \
;       acc[ai][bj][m][n] = __builtin_amdgcn_mfma_f32_16x16x32_bf16(Btf[n][k], At[m][k], acc[ai][bj][m][n], 0, 0, 0); \
;     __builtin_amdgcn_s_setprio(0); } while (0)
; #define WAIT_V(n) asm volatile("s_waitcnt vmcnt(" #n ")" ::: "memory")
; #define WAIT_L(n) asm volatile("s_waitcnt lgkmcnt(" #n ")" ::: "memory")
; #define BAR __builtin_amdgcn_s_barrier()
; template <int EPI> ...
;     ...
;     LDB(B1, 1, 1); WAIT_V(0); BAR; WAIT_L(0); MMA(0, 1, At, B1); BAR;
	ds_read_b128 v[208:211], v158
	ds_read_b128 v[212:215], v158 offset:256
	ds_read_b128 v[216:219], v159
	ds_read_b128 v[220:223], v159 offset:256
	s_waitcnt vmcnt(0)
	s_waitcnt lgkmcnt(0)

; #define LDB(dst, b, h) for (int n = 0; n < 2; ++n) { \
;     dst[n][0] = *reinterpret_cast<const bf16x8*>((char*)SB(b, h) + boff0 + n * 256); \
;     dst[n][1] = *reinterpret_cast<const bf16x8*>((char*)SB(b, h) + boff1 + n * 256); }
; #define MMA(ai, bj, At, Btf) do { __builtin_amdgcn_s_setprio(1); \
;     for (int m = 0; m < 4; ++m) for (int n = 0; n < 2; ++n) for (int k = 0; k < 2; ++k) \
;       acc[ai][bj][m][n] = __builtin_amdgcn_mfma_f32_16x16x32_bf16(Btf[n][k], At[m][k], acc[ai][bj][m][n], 0, 0, 0); \
;     __builtin_amdgcn_s_setprio(0); } while (0)
; #define WAIT_V(n) asm volatile("s_waitcnt vmcnt(" #n ")" ::: "memory")
; #define WAIT_L(n) asm volatile("s_waitcnt lgkmcnt(" #n ")" ::: "memory")
; #define BAR __builtin_amdgcn_s_barrier()
; template <int EPI> ...
;     ...
;     LDB(B1, 1, 1); WAIT_V(0); BAR; WAIT_L(0); MMA(0, 1, At, B1); BAR;
	s_barrier
	v_mfma_f32_16x16x32_bf16 v[64:67], v[208:211], v[32:35], v[224:227]
	v_mfma_f32_16x16x32_bf16 v[32:35], v[212:215], v[32:35], v[176:179]
	v_mfma_f32_16x16x32_bf16 v[100:103], v[220:223], v[40:43], v[32:35]
	v_mfma_f32_16x16x32_bf16 v[32:35], v[208:211], v[48:51], v[84:87]
	v_mfma_f32_16x16x32_bf16 v[80:83], v[216:219], v[56:59], v[32:35]
	v_mfma_f32_16x16x32_bf16 v[32:35], v[212:215], v[48:51], v[180:183]
	v_mfma_f32_16x16x32_bf16 v[84:87], v[220:223], v[56:59], v[32:35]
	v_mfma_f32_16x16x32_bf16 v[32:35], v[208:211], v[60:63], v[76:79]
	v_mfma_f32_16x16x32_bf16 v[96:99], v[216:219], v[40:43], v[64:67]
	v_mfma_f32_16x16x32_bf16 v[64:67], v[216:219], v[68:71], v[32:35]
	v_mfma_f32_16x16x32_bf16 v[32:35], v[212:215], v[60:63], v[72:75]
	v_mfma_f32_16x16x32_bf16 v[68:71], v[220:223], v[68:71], v[32:35]
	v_mfma_f32_16x16x32_bf16 v[32:35], v[208:211], v[196:199], v[184:187]
	v_mfma_f32_16x16x32_bf16 v[56:59], v[216:219], v[200:203], v[32:35]
	v_mfma_f32_16x16x32_bf16 v[32:35], v[212:215], v[196:199], v[188:191]
	v_mfma_f32_16x16x32_bf16 v[60:63], v[220:223], v[200:203], v[32:35]
	s_barrier

; #define LDA(dst, b, h) for (int m = 0; m < 4; ++m) { \
;     dst[m][0] = *reinterpret_cast<const bf16x8*>((char*)SA(b, h) + aoff0 + m * 2048); \
;     dst[m][1] = *reinterpret_cast<const bf16x8*>((char*)SA(b, h) + aoff1 + m * 2048); }
; #define MMA(ai, bj, At, Btf) do { __builtin_amdgcn_s_setprio(1); \
;     for (int m = 0; m < 4; ++m) for (int n = 0; n < 2; ++n) for (int k = 0; k < 2; ++k) \
;       acc[ai][bj][m][n] = __builtin_amdgcn_mfma_f32_16x16x32_bf16(Btf[n][k], At[m][k], acc[ai][bj][m][n], 0, 0, 0); \
;     __builtin_amdgcn_s_setprio(0); } while (0)
; #define WAIT_L(n) asm volatile("s_waitcnt lgkmcnt(" #n ")" ::: "memory")
; #define BAR __builtin_amdgcn_s_barrier()
; template <int EPI> ...
;     ...
;     LDA(At, 1, 1); BAR; WAIT_L(0); MMA(1, 0, At, B0); MMA(1, 1, At, B1); BAR; }
	ds_read_b128 v[176:179], v149 offset:49152
	ds_read_b128 v[180:183], v149 offset:50176
	ds_read_b128 v[184:187], v149 offset:51200
	ds_read_b128 v[188:191], v149 offset:52224
	ds_read_b128 v[196:199], v149 offset:53248
	ds_read_b128 v[200:203], v149 offset:54272
	ds_read_b128 v[224:227], v149 offset:55296
	ds_read_b128 v[240:243], v149 offset:56320
	s_waitcnt lgkmcnt(0)

; #define LDA(dst, b, h) for (int m = 0; m < 4; ++m) { \
;     dst[m][0] = *reinterpret_cast<const bf16x8*>((char*)SA(b, h) + aoff0 + m * 2048); \
;     dst[m][1] = *reinterpret_cast<const bf16x8*>((char*)SA(b, h) + aoff1 + m * 2048); }
; #define MMA(ai, bj, At, Btf) do { __builtin_amdgcn_s_setprio(1); \
;     for (int m = 0; m < 4; ++m) for (int n = 0; n < 2; ++n) for (int k = 0; k < 2; ++k) \
;       acc[ai][bj][m][n] = __builtin_amdgcn_mfma_f32_16x16x32_bf16(Btf[n][k], At[m][k], acc[ai][bj][m][n], 0, 0, 0); \
;     __builtin_amdgcn_s_setprio(0); } while (0)
; #define WAIT_L(n) asm volatile("s_waitcnt lgkmcnt(" #n ")" ::: "memory")
; #define BAR __builtin_amdgcn_s_barrier()
; template <int EPI> ...
;     ...
;     LDA(At, 1, 1); BAR; WAIT_L(0); MMA(1, 0, At, B0); MMA(1, 1, At, B1); BAR; }
	s_barrier
	v_mfma_f32_16x16x32_bf16 v[32:35], v[0:3], v[176:179], v[204:207]
	v_mfma_f32_16x16x32_bf16 v[72:75], v[16:19], v[180:183], v[32:35]
	v_mfma_f32_16x16x32_bf16 v[32:35], v[8:11], v[176:179], v[228:231]
	v_mfma_f32_16x16x32_bf16 v[76:79], v[24:27], v[180:183], v[32:35]
	v_mfma_f32_16x16x32_bf16 v[32:35], v[0:3], v[184:187], v[52:55]
	v_mfma_f32_16x16x32_bf16 v[48:51], v[16:19], v[188:191], v[32:35]
	v_mfma_f32_16x16x32_bf16 v[32:35], v[8:11], v[184:187], v[232:235]
	v_mfma_f32_16x16x32_bf16 v[52:55], v[24:27], v[188:191], v[32:35]
	v_mfma_f32_16x16x32_bf16 v[32:35], v[0:3], v[196:199], v[44:47]
	v_mfma_f32_16x16x32_bf16 v[40:43], v[16:19], v[200:203], v[32:35]
	v_mfma_f32_16x16x32_bf16 v[32:35], v[8:11], v[196:199], v[236:239]
	v_mfma_f32_16x16x32_bf16 v[0:3], v[0:3], v[224:227], v[36:39]
	v_mfma_f32_16x16x32_bf16 v[44:47], v[24:27], v[200:203], v[32:35]
	v_mfma_f32_16x16x32_bf16 v[32:35], v[16:19], v[240:243], v[0:3]
	v_mfma_f32_16x16x32_bf16 v[0:3], v[8:11], v[224:227], v[160:163]
	v_mfma_f32_16x16x32_bf16 v[36:39], v[24:27], v[240:243], v[0:3]
	v_mfma_f32_16x16x32_bf16 v[0:3], v[208:211], v[176:179], v[28:31]
	v_mfma_f32_16x16x32_bf16 v[24:27], v[216:219], v[180:183], v[0:3]
	v_mfma_f32_16x16x32_bf16 v[0:3], v[212:215], v[176:179], v[164:167]
	v_mfma_f32_16x16x32_bf16 v[28:31], v[220:223], v[180:183], v[0:3]
	v_mfma_f32_16x16x32_bf16 v[0:3], v[208:211], v[184:187], v[20:23]
	v_mfma_f32_16x16x32_bf16 v[16:19], v[216:219], v[188:191], v[0:3]
	v_mfma_f32_16x16x32_bf16 v[0:3], v[212:215], v[184:187], v[168:171]
	v_mfma_f32_16x16x32_bf16 v[20:23], v[220:223], v[188:191], v[0:3]
	v_mfma_f32_16x16x32_bf16 v[0:3], v[208:211], v[196:199], v[12:15]
	v_mfma_f32_16x16x32_bf16 v[8:11], v[216:219], v[200:203], v[0:3]
	v_mfma_f32_16x16x32_bf16 v[0:3], v[212:215], v[196:199], v[172:175]
	v_mfma_f32_16x16x32_bf16 v[12:15], v[220:223], v[200:203], v[0:3]
	v_mfma_f32_16x16x32_bf16 v[0:3], v[208:211], v[224:227], v[4:7]
	v_mfma_f32_16x16x32_bf16 v[4:7], v[212:215], v[224:227], v[192:195]
	v_mfma_f32_16x16x32_bf16 v[0:3], v[216:219], v[240:243], v[0:3]
	v_mfma_f32_16x16x32_bf16 v[4:7], v[220:223], v[240:243], v[4:7]
	s_barrier

; #define BAR __builtin_amdgcn_s_barrier()
; template <int EPI> ...
;     ...
;   if (wr == 0) BAR;
; template <int EPI>
; __device__ __forceinline__ void gemm_phase(const u16* A, const u16* Bt, int M, int N, int K, u16* out, int ldo,
;                                            const float* aux, int bid, int nblk, int wv) {
;     ...
;   for (int base = 0; base < ntile; base += nblk) {
;     int wgid;
;     if (base + nblk <= ntile && (nblk & 7) == 0) wgid = base + (bid & 7) * (nblk >> 3) + (bid >> 3);
;     else wgid = base + bid;
;     if (wgid >= ntile) break;
;     int nig = WGM * nN, gid = wgid / nig, fm = gid * WGM, gsz = min(nM - fm, WGM);
;     int pm = fm + ((wgid % nig) % gsz), pn = (wgid % nig) / gsz;
;     int brow = pm * BM, bcol = pn * BM;
;     gemm_tile<EPI>(A, Bt, K, brow, bcol, out, ldo, EPI == 1 ? pn * HALF : bcol, aux, tid);
	s_setprio 0
	s_and_saveexec_b64 s[62:63], s[2:3]
	s_cbranch_execz .LBB0_1012
	s_barrier
	s_branch .LBB0_1012

; #define STAGE(P, BASE, br, kt) do { const char* _gb = (const char*)(BASE) + ((size_t)(br) * K + (size_t)(kt) * BK) * 2; \
;     __builtin_amdgcn_global_load_lds((const unsigned*)(_gb + loff0), (unsigned*)((char*)(P) + tid * 16), 16, 0, 0); \
;     __builtin_amdgcn_global_load_lds((const unsigned*)(_gb + (size_t)K * 128 + loff0), (unsigned*)((char*)(P) + tid * 16 + 8192), 16, 0, 0); } while (0)
; #define BAR __builtin_amdgcn_s_barrier()
; template <int EPI> ...
;     ...
;   f32x4 acc[2][2][4][2] = {};
;   bf16x8 At[4][2], B0[2][2], B1[2][2];
;   int nt = K / BK;
;   const int aoff0 = lds_byte(wr * 64 + fr, fq * 8), aoff1 = lds_byte(wr * 64 + fr, 32 + fq * 8);
;   const int brw = wc * 32 + (fr >> 2) * 8 + (fr & 3);
;   const int boff0 = lds_byte(brw, fq * 8), boff1 = lds_byte(brw, 32 + fq * 8);
;   unsigned loff0;
;   { int _r, _c; stage_rc(tid * 16, _r, _c); loff0 = (unsigned)(_r * K + _c) * 2u; }
;   STAGE(SB(0, 0), Bt, bcol, 0); STAGE(SA(0, 0), A, brow, 0);
;   STAGE(SB(0, 1), Bt, bcol + HALF, 0); STAGE(SA(0, 1), A, brow + HALF, 0);
;   if (wr == 1) BAR;
; template <int EPI>
; __device__ __forceinline__ void gemm_phase(const u16* A, const u16* Bt, int M, int N, int K, u16* out, int ldo,
;                                            const float* aux, int bid, int nblk, int wv) {
;     ...
;     int nig = WGM * nN, gid = wgid / nig, fm = gid * WGM, gsz = min(nM - fm, WGM);
;     int pm = fm + ((wgid % nig) % gsz), pn = (wgid % nig) / gsz;
;     int brow = pm * BM, bcol = pn * BM;
.LBB0_1101:
	s_mov_b32 s66, s74
	s_add_i32 s74, s74, s33
	s_cmpk_lt_i32 s74, 0x1601
	s_cselect_b64 s[64:65], -1, 0
	s_and_b64 s[64:65], s[44:45], s[64:65]
	s_and_b64 s[64:65], s[64:65], exec
	s_cselect_b32 s64, s86, s91
	s_add_i32 s66, s64, s66
	s_cmpk_gt_i32 s66, 0x15ff
	s_mov_b64 s[64:65], -1
	s_cbranch_scc1 .LBB0_1100
	s_mul_hi_i32 s64, s66, 0x2e8ba2e9
	s_lshr_b32 s65, s64, 31
	s_ashr_i32 s64, s64, 6
	s_add_i32 s64, s64, s65
	s_mul_i32 s65, s64, 0x160
	s_sub_i32 s65, s66, s65
	s_sext_i32_i16 s66, s65
	s_bfe_u32 s66, s66, 0x3001c
	s_add_i32 s66, s65, s66
	s_sext_i32_i16 s67, s66
	s_and_b32 s66, s66, 0xfff8
	s_sub_i32 s65, s65, s66
	s_ashr_i32 s76, s67, 3
	s_sext_i32_i16 s65, s65
	s_lshl_b32 s70, s76, 8
	s_lshl_b32 s64, s64, 11
	s_lshl_b32 s65, s65, 8
	s_ashr_i32 s71, s70, 31
	s_add_i32 s64, s65, s64
	s_lshl_b64 s[68:69], s[70:71], 12
	s_add_u32 s66, s72, s68
	s_addc_u32 s67, s73, s69
	v_readfirstlane_b32 s65, v136
	v_lshl_add_u64 v[0:1], s[66:67], 0, v[128:129]
	s_mov_b32 m0, s65
	v_readfirstlane_b32 s65, v137
	global_load_lds_dwordx4 v[0:1], off
	s_mov_b32 m0, s65
	s_ashr_i32 s65, s64, 31
	s_lshl_b64 s[66:67], s[64:65], 12
	s_add_u32 s78, s14, s66
	s_addc_u32 s79, s43, s67
	s_bitset1_b32 s70, 7
	s_ashr_i32 s71, s70, 31
	v_lshl_add_u64 v[2:3], v[0:1], 0, s[10:11]
	v_readfirstlane_b32 s65, v138
	s_lshl_b64 s[70:71], s[70:71], 12
	global_load_lds_dwordx4 v[2:3], off
	v_lshl_add_u64 v[2:3], s[78:79], 0, v[128:129]
	s_mov_b32 m0, s65
	v_readfirstlane_b32 s65, v139
	s_add_u32 s70, s72, s70
	global_load_lds_dwordx4 v[2:3], off
	v_lshl_add_u64 v[4:5], v[2:3], 0, s[10:11]
	s_mov_b32 m0, s65
	s_addc_u32 s71, s73, s71
	global_load_lds_dwordx4 v[4:5], off
	v_lshl_add_u64 v[4:5], s[70:71], 0, v[128:129]
	s_or_b32 s70, s64, 0x80
	s_ashr_i32 s71, s70, 31
	v_readfirstlane_b32 s65, v140
	s_lshl_b64 s[70:71], s[70:71], 12
	s_mov_b32 m0, s65
	v_readfirstlane_b32 s65, v141
	s_add_u32 s70, s14, s70
	global_load_lds_dwordx4 v[4:5], off
	v_lshl_add_u64 v[6:7], v[4:5], 0, s[10:11]
	s_mov_b32 m0, s65
	s_addc_u32 s71, s43, s71
	v_readfirstlane_b32 s65, v142
	global_load_lds_dwordx4 v[6:7], off
	v_lshl_add_u64 v[132:133], s[70:71], 0, v[128:129]
	s_mov_b32 m0, s65
	v_readfirstlane_b32 s65, v143
	global_load_lds_dwordx4 v[132:133], off
	v_lshl_add_u64 v[6:7], v[132:133], 0, s[10:11]
	s_mov_b32 m0, s65
	s_nop 0
	global_load_lds_dwordx4 v[6:7], off
	v_mov_b32_e32 v8, 0
	v_mov_b32_e32 v9, 0
	v_mov_b32_e32 v10, 0
	v_mov_b32_e32 v11, 0
	v_mov_b32_e32 v12, 0
	v_mov_b32_e32 v13, 0
	v_mov_b32_e32 v14, 0
	v_mov_b32_e32 v15, 0
	v_mov_b32_e32 v16, 0
	v_mov_b32_e32 v17, 0
	v_mov_b32_e32 v18, 0
	v_mov_b32_e32 v19, 0
	v_mov_b32_e32 v20, 0
	v_mov_b32_e32 v21, 0
	v_mov_b32_e32 v22, 0
	v_mov_b32_e32 v23, 0
	v_mov_b32_e32 v24, 0
	v_mov_b32_e32 v25, 0
	v_mov_b32_e32 v26, 0
	v_mov_b32_e32 v27, 0
	v_mov_b32_e32 v28, 0
	v_mov_b32_e32 v29, 0
	v_mov_b32_e32 v30, 0
	v_mov_b32_e32 v31, 0
	v_mov_b32_e32 v32, 0
	v_mov_b32_e32 v33, 0
	v_mov_b32_e32 v34, 0
	v_mov_b32_e32 v35, 0
	v_mov_b32_e32 v36, 0
	v_mov_b32_e32 v37, 0
	v_mov_b32_e32 v38, 0
	v_mov_b32_e32 v39, 0
	v_mov_b32_e32 v40, 0
	v_mov_b32_e32 v41, 0
	v_mov_b32_e32 v42, 0
	v_mov_b32_e32 v43, 0
	v_mov_b32_e32 v44, 0
	v_mov_b32_e32 v45, 0
	v_mov_b32_e32 v46, 0
	v_mov_b32_e32 v47, 0
	v_mov_b32_e32 v48, 0
	v_mov_b32_e32 v49, 0
	v_mov_b32_e32 v50, 0
	v_mov_b32_e32 v51, 0
	v_mov_b32_e32 v52, 0
	v_mov_b32_e32 v53, 0
	v_mov_b32_e32 v54, 0
	v_mov_b32_e32 v55, 0
	v_mov_b32_e32 v56, 0
	v_mov_b32_e32 v57, 0
	v_mov_b32_e32 v58, 0
	v_mov_b32_e32 v59, 0
	v_mov_b32_e32 v60, 0
	v_mov_b32_e32 v61, 0
	v_mov_b32_e32 v62, 0
	v_mov_b32_e32 v63, 0
	v_mov_b32_e32 v64, 0
	v_mov_b32_e32 v65, 0
	v_mov_b32_e32 v66, 0
	v_mov_b32_e32 v67, 0
	v_mov_b32_e32 v68, 0
	v_mov_b32_e32 v69, 0
	v_mov_b32_e32 v70, 0
	v_mov_b32_e32 v71, 0
	v_mov_b32_e32 v72, 0
	v_mov_b32_e32 v73, 0
	v_mov_b32_e32 v74, 0
	v_mov_b32_e32 v75, 0
	v_mov_b32_e32 v76, 0
	v_mov_b32_e32 v77, 0
	v_mov_b32_e32 v78, 0
	v_mov_b32_e32 v79, 0
	v_mov_b32_e32 v80, 0
	v_mov_b32_e32 v81, 0
	v_mov_b32_e32 v82, 0
	v_mov_b32_e32 v83, 0
	v_mov_b32_e32 v84, 0
	v_mov_b32_e32 v85, 0
	v_mov_b32_e32 v86, 0
	v_mov_b32_e32 v87, 0
	v_mov_b32_e32 v88, 0
	v_mov_b32_e32 v89, 0
	v_mov_b32_e32 v90, 0
	v_mov_b32_e32 v91, 0
	v_mov_b32_e32 v92, 0
	v_mov_b32_e32 v93, 0
	v_mov_b32_e32 v94, 0
	v_mov_b32_e32 v95, 0
	v_mov_b32_e32 v96, 0
	v_mov_b32_e32 v97, 0
	v_mov_b32_e32 v98, 0
	v_mov_b32_e32 v99, 0
	v_mov_b32_e32 v100, 0
	v_mov_b32_e32 v101, 0
	v_mov_b32_e32 v102, 0
	v_mov_b32_e32 v103, 0
	v_mov_b32_e32 v104, 0
	v_mov_b32_e32 v105, 0
	v_mov_b32_e32 v106, 0
	v_mov_b32_e32 v107, 0
	v_mov_b32_e32 v108, 0
	v_mov_b32_e32 v109, 0
	v_mov_b32_e32 v110, 0
	v_mov_b32_e32 v111, 0
	v_mov_b32_e32 v112, 0
	v_mov_b32_e32 v113, 0
	v_mov_b32_e32 v114, 0
	v_mov_b32_e32 v115, 0
	v_mov_b32_e32 v116, 0
	v_mov_b32_e32 v117, 0
	v_mov_b32_e32 v118, 0
	v_mov_b32_e32 v119, 0
	v_mov_b32_e32 v120, 0
	v_mov_b32_e32 v121, 0
	v_mov_b32_e32 v122, 0
	v_mov_b32_e32 v123, 0
	v_mov_b32_e32 v124, 0
	v_mov_b32_e32 v125, 0
	v_mov_b32_e32 v126, 0
	v_mov_b32_e32 v127, 0
	s_and_saveexec_b64 s[70:71], s[4:5]
	s_cbranch_execz .LBB0_1104
	s_setprio 1
	s_barrier

; #define STAGE(P, BASE, br, kt) do { const char* _gb = (const char*)(BASE) + ((size_t)(br) * K + (size_t)(kt) * BK) * 2; \
;     __builtin_amdgcn_global_load_lds((const unsigned*)(_gb + loff0), (unsigned*)((char*)(P) + tid * 16), 16, 0, 0); \
;     __builtin_amdgcn_global_load_lds((const unsigned*)(_gb + (size_t)K * 128 + loff0), (unsigned*)((char*)(P) + tid * 16 + 8192), 16, 0, 0); } while (0)
; #define LDA(dst, b, h) for (int m = 0; m < 4; ++m) { \
;     dst[m][0] = *reinterpret_cast<const bf16x8*>((char*)SA(b, h) + aoff0 + m * 2048); \
;     dst[m][1] = *reinterpret_cast<const bf16x8*>((char*)SA(b, h) + aoff1 + m * 2048); }
; #define LDB(dst, b, h) for (int n = 0; n < 2; ++n) { \
;     dst[n][0] = *reinterpret_cast<const bf16x8*>((char*)SB(b, h) + boff0 + n * 256); \
;     dst[n][1] = *reinterpret_cast<const bf16x8*>((char*)SB(b, h) + boff1 + n * 256); }
; #define MMA(ai, bj, At, Btf) do { __builtin_amdgcn_s_setprio(1); \
;     for (int m = 0; m < 4; ++m) for (int n = 0; n < 2; ++n) for (int k = 0; k < 2; ++k) \
;       acc[ai][bj][m][n] = __builtin_amdgcn_mfma_f32_16x16x32_bf16(Btf[n][k], At[m][k], acc[ai][bj][m][n], 0, 0, 0); \
;     __builtin_amdgcn_s_setprio(0); } while (0)
; #define WAIT_L(n) asm volatile("s_waitcnt lgkmcnt(" #n ")" ::: "memory")
; #define BAR __builtin_amdgcn_s_barrier()
; #define SCHED __builtin_amdgcn_sched_barrier(0)
; template <int EPI> ...
;     ...
;     LDB(B0, 0, 0); SCHED; LDA(At, 0, 0); STAGE(SA(1, 1), A, brow + HALF, t + 1);
;     WAIT_L(8); BAR; WAIT_L(0); MMA(0, 0, At, B0); BAR; SCHED;
;     LDB(B1, 0, 1); STAGE(SB(0, 0), Bt, bcol, t + 2);
.LBB0_1105:
	ds_read_b128 v[162:165], v153
	ds_read_b128 v[166:169], v153 offset:256
	ds_read_b128 v[170:173], v154
	ds_read_b128 v[174:177], v154 offset:256
	v_lshl_add_u64 v[226:227], s[66:67], 0, v[130:131]
	v_readfirstlane_b32 s70, v151
	v_lshl_add_u64 v[210:211], v[226:227], 0, s[18:19]
	s_mov_b32 m0, s70
	v_readfirstlane_b32 s70, v152
	ds_read_b128 v[178:181], v150
	ds_read_b128 v[182:185], v150 offset:1024
	ds_read_b128 v[186:189], v150 offset:2048
	ds_read_b128 v[190:193], v150 offset:3072
	ds_read_b128 v[194:197], v150 offset:4096
	ds_read_b128 v[198:201], v150 offset:5120
	ds_read_b128 v[202:205], v150 offset:6144
	ds_read_b128 v[206:209], v150 offset:7168
	global_load_lds_dwordx4 v[210:211], off
	v_lshl_add_u64 v[210:211], v[226:227], 0, s[20:21]
	s_mov_b32 m0, s70
	s_nop 0
	global_load_lds_dwordx4 v[210:211], off
	s_waitcnt lgkmcnt(8)
	v_readfirstlane_b32 s70, v149
	v_lshl_add_u64 v[246:247], v[228:229], 0, s[58:59]
	s_mov_b32 m0, s70
	s_nop 0
	global_load_lds_dwordx4 v[246:247], off
	ds_read_b128 v[210:213], v155
	ds_read_b128 v[214:217], v155 offset:256
	ds_read_b128 v[218:221], v156
	ds_read_b128 v[222:225], v156 offset:256
	s_waitcnt lgkmcnt(0)

; #define STAGE(P, BASE, br, kt) do { const char* _gb = (const char*)(BASE) + ((size_t)(br) * K + (size_t)(kt) * BK) * 2; \
;     __builtin_amdgcn_global_load_lds((const unsigned*)(_gb + loff0), (unsigned*)((char*)(P) + tid * 16), 16, 0, 0); \
;     __builtin_amdgcn_global_load_lds((const unsigned*)(_gb + (size_t)K * 128 + loff0), (unsigned*)((char*)(P) + tid * 16 + 8192), 16, 0, 0); } while (0)
; #define LDB(dst, b, h) for (int n = 0; n < 2; ++n) { \
;     dst[n][0] = *reinterpret_cast<const bf16x8*>((char*)SB(b, h) + boff0 + n * 256); \
;     dst[n][1] = *reinterpret_cast<const bf16x8*>((char*)SB(b, h) + boff1 + n * 256); }
; #define MMA(ai, bj, At, Btf) do { __builtin_amdgcn_s_setprio(1); \
;     for (int m = 0; m < 4; ++m) for (int n = 0; n < 2; ++n) for (int k = 0; k < 2; ++k) \
;       acc[ai][bj][m][n] = __builtin_amdgcn_mfma_f32_16x16x32_bf16(Btf[n][k], At[m][k], acc[ai][bj][m][n], 0, 0, 0); \
;     __builtin_amdgcn_s_setprio(0); } while (0)
; #define WAIT_L(n) asm volatile("s_waitcnt lgkmcnt(" #n ")" ::: "memory")
; #define BAR __builtin_amdgcn_s_barrier()
; #define SCHED __builtin_amdgcn_sched_barrier(0)
; template <int EPI> ...
;     ...
;     WAIT_L(8); BAR; WAIT_L(0); MMA(0, 0, At, B0); BAR; SCHED;
;     LDB(B1, 0, 1); STAGE(SB(0, 0), Bt, bcol, t + 2);
;     BAR; WAIT_L(0); MMA(0, 1, At, B1); BAR;
	s_barrier
	v_mfma_f32_16x16x32_bf16 v[124:127], v[162:165], v[178:181], v[124:127]
	v_mfma_f32_16x16x32_bf16 v[120:123], v[166:169], v[178:181], v[120:123]
	v_mfma_f32_16x16x32_bf16 v[116:119], v[162:165], v[186:189], v[116:119]
	v_mfma_f32_16x16x32_bf16 v[112:115], v[166:169], v[186:189], v[112:115]
	v_mfma_f32_16x16x32_bf16 v[108:111], v[162:165], v[194:197], v[108:111]
	v_mfma_f32_16x16x32_bf16 v[104:107], v[166:169], v[194:197], v[104:107]
	v_mfma_f32_16x16x32_bf16 v[100:103], v[162:165], v[202:205], v[100:103]
	v_mfma_f32_16x16x32_bf16 v[96:99], v[166:169], v[202:205], v[96:99]
	v_mfma_f32_16x16x32_bf16 v[124:127], v[170:173], v[182:185], v[124:127]
	v_mfma_f32_16x16x32_bf16 v[120:123], v[174:177], v[182:185], v[120:123]
	v_mfma_f32_16x16x32_bf16 v[116:119], v[170:173], v[190:193], v[116:119]
	v_mfma_f32_16x16x32_bf16 v[112:115], v[174:177], v[190:193], v[112:115]
	v_mfma_f32_16x16x32_bf16 v[108:111], v[170:173], v[198:201], v[108:111]
	v_mfma_f32_16x16x32_bf16 v[104:107], v[174:177], v[198:201], v[104:107]
	v_mfma_f32_16x16x32_bf16 v[100:103], v[170:173], v[206:209], v[100:103]
	v_mfma_f32_16x16x32_bf16 v[96:99], v[174:177], v[206:209], v[96:99]
	v_mfma_f32_16x16x32_bf16 v[92:95], v[210:213], v[178:181], v[92:95]
	v_mfma_f32_16x16x32_bf16 v[88:91], v[214:217], v[178:181], v[88:91]
	v_mfma_f32_16x16x32_bf16 v[84:87], v[210:213], v[186:189], v[84:87]
	v_mfma_f32_16x16x32_bf16 v[80:83], v[214:217], v[186:189], v[80:83]
	v_mfma_f32_16x16x32_bf16 v[76:79], v[210:213], v[194:197], v[76:79]
	v_mfma_f32_16x16x32_bf16 v[72:75], v[214:217], v[194:197], v[72:75]
	v_mfma_f32_16x16x32_bf16 v[68:71], v[210:213], v[202:205], v[68:71]
	v_mfma_f32_16x16x32_bf16 v[64:67], v[214:217], v[202:205], v[64:67]
	v_mfma_f32_16x16x32_bf16 v[92:95], v[218:221], v[182:185], v[92:95]
	v_mfma_f32_16x16x32_bf16 v[88:91], v[222:225], v[182:185], v[88:91]
	v_mfma_f32_16x16x32_bf16 v[84:87], v[218:221], v[190:193], v[84:87]
	v_mfma_f32_16x16x32_bf16 v[80:83], v[222:225], v[190:193], v[80:83]
	v_mfma_f32_16x16x32_bf16 v[76:79], v[218:221], v[198:201], v[76:79]
	v_mfma_f32_16x16x32_bf16 v[72:75], v[222:225], v[198:201], v[72:75]
	v_mfma_f32_16x16x32_bf16 v[68:71], v[218:221], v[206:209], v[68:71]
	v_mfma_f32_16x16x32_bf16 v[64:67], v[222:225], v[206:209], v[64:67]
	s_barrier

; #define STAGE(P, BASE, br, kt) do { const char* _gb = (const char*)(BASE) + ((size_t)(br) * K + (size_t)(kt) * BK) * 2; \
;     __builtin_amdgcn_global_load_lds((const unsigned*)(_gb + loff0), (unsigned*)((char*)(P) + tid * 16), 16, 0, 0); \
;     __builtin_amdgcn_global_load_lds((const unsigned*)(_gb + (size_t)K * 128 + loff0), (unsigned*)((char*)(P) + tid * 16 + 8192), 16, 0, 0); } while (0)
; #define LDA(dst, b, h) for (int m = 0; m < 4; ++m) { \
;     dst[m][0] = *reinterpret_cast<const bf16x8*>((char*)SA(b, h) + aoff0 + m * 2048); \
;     dst[m][1] = *reinterpret_cast<const bf16x8*>((char*)SA(b, h) + aoff1 + m * 2048); }
; #define LDB(dst, b, h) for (int n = 0; n < 2; ++n) { \
;     dst[n][0] = *reinterpret_cast<const bf16x8*>((char*)SB(b, h) + boff0 + n * 256); \
;     dst[n][1] = *reinterpret_cast<const bf16x8*>((char*)SB(b, h) + boff1 + n * 256); }
; #define MMA(ai, bj, At, Btf) do { __builtin_amdgcn_s_setprio(1); \
;     for (int m = 0; m < 4; ++m) for (int n = 0; n < 2; ++n) for (int k = 0; k < 2; ++k) \
;       acc[ai][bj][m][n] = __builtin_amdgcn_mfma_f32_16x16x32_bf16(Btf[n][k], At[m][k], acc[ai][bj][m][n], 0, 0, 0); \
;     __builtin_amdgcn_s_setprio(0); } while (0)
; #define WAIT_V(n) asm volatile("s_waitcnt vmcnt(" #n ")" ::: "memory")
; #define WAIT_L(n) asm volatile("s_waitcnt lgkmcnt(" #n ")" ::: "memory")
; #define BAR __builtin_amdgcn_s_barrier()
; #define SCHED __builtin_amdgcn_sched_barrier(0)
; template <int EPI> ...
;     ...
;     LDB(B1, 0, 1); STAGE(SB(0, 0), Bt, bcol, t + 2);
;     BAR; WAIT_L(0); MMA(0, 1, At, B1); BAR;
;     LDA(At, 0, 1); STAGE(SA(0, 0), A, brow, t + 2);
;     BAR; WAIT_L(0); MMA(1, 0, At, B0); BAR; SCHED;
;     STAGE(SB(0, 1), Bt, bcol + HALF, t + 2);
;     WAIT_V(6); BAR; MMA(1, 1, At, B1); BAR;
	v_lshl_add_u64 v[228:229], s[68:69], 0, v[130:131]
	v_readfirstlane_b32 s70, v136
	v_lshl_add_u64 v[230:231], v[228:229], 0, s[22:23]
	s_mov_b32 m0, s70
	v_readfirstlane_b32 s70, v137
	global_load_lds_dwordx4 v[230:231], off
	v_lshl_add_u64 v[230:231], v[228:229], 0, s[24:25]
	s_mov_b32 m0, s70
	s_nop 0
	global_load_lds_dwordx4 v[230:231], off
	v_readfirstlane_b32 s70, v138
	v_lshl_add_u64 v[230:231], v[226:227], 0, s[26:27]
	s_mov_b32 m0, s70
	v_readfirstlane_b32 s70, v139
	ds_read_b128 v[178:181], v150 offset:16384
	ds_read_b128 v[182:185], v150 offset:17408
	ds_read_b128 v[186:189], v150 offset:18432
	ds_read_b128 v[190:193], v150 offset:19456
	ds_read_b128 v[194:197], v150 offset:20480
	ds_read_b128 v[198:201], v150 offset:21504
	ds_read_b128 v[202:205], v150 offset:22528
	ds_read_b128 v[206:209], v150 offset:23552
	global_load_lds_dwordx4 v[230:231], off
	v_lshl_add_u64 v[230:231], v[226:227], 0, s[28:29]
	s_mov_b32 m0, s70
	s_nop 0
	global_load_lds_dwordx4 v[230:231], off
	v_readfirstlane_b32 s70, v140
	v_lshl_add_u64 v[246:247], v[228:229], 0, s[30:31]
	s_mov_b32 m0, s70
	v_readfirstlane_b32 s70, v141
	global_load_lds_dwordx4 v[246:247], off
	s_waitcnt vmcnt(5)
	s_waitcnt lgkmcnt(0)

; #define STAGE(P, BASE, br, kt) do { const char* _gb = (const char*)(BASE) + ((size_t)(br) * K + (size_t)(kt) * BK) * 2; \
;     __builtin_amdgcn_global_load_lds((const unsigned*)(_gb + loff0), (unsigned*)((char*)(P) + tid * 16), 16, 0, 0); \
;     __builtin_amdgcn_global_load_lds((const unsigned*)(_gb + (size_t)K * 128 + loff0), (unsigned*)((char*)(P) + tid * 16 + 8192), 16, 0, 0); } while (0)
; #define MMA(ai, bj, At, Btf) do { __builtin_amdgcn_s_setprio(1); \
;     for (int m = 0; m < 4; ++m) for (int n = 0; n < 2; ++n) for (int k = 0; k < 2; ++k) \
;       acc[ai][bj][m][n] = __builtin_amdgcn_mfma_f32_16x16x32_bf16(Btf[n][k], At[m][k], acc[ai][bj][m][n], 0, 0, 0); \
;     __builtin_amdgcn_s_setprio(0); } while (0)
; #define WAIT_V(n) asm volatile("s_waitcnt vmcnt(" #n ")" ::: "memory")
; #define WAIT_L(n) asm volatile("s_waitcnt lgkmcnt(" #n ")" ::: "memory")
; #define BAR __builtin_amdgcn_s_barrier()
; #define SCHED __builtin_amdgcn_sched_barrier(0)
; template <int EPI> ...
;     ...
;     BAR; WAIT_L(0); MMA(1, 0, At, B0); BAR; SCHED;
;     STAGE(SB(0, 1), Bt, bcol + HALF, t + 2);
;     WAIT_V(6); BAR; MMA(1, 1, At, B1); BAR;
	s_barrier
	v_mfma_f32_16x16x32_bf16 v[60:63], v[162:165], v[178:181], v[60:63]
	v_mfma_f32_16x16x32_bf16 v[56:59], v[166:169], v[178:181], v[56:59]
	v_mfma_f32_16x16x32_bf16 v[52:55], v[162:165], v[186:189], v[52:55]
	v_mfma_f32_16x16x32_bf16 v[48:51], v[166:169], v[186:189], v[48:51]
	v_mfma_f32_16x16x32_bf16 v[44:47], v[162:165], v[194:197], v[44:47]
	v_mfma_f32_16x16x32_bf16 v[40:43], v[166:169], v[194:197], v[40:43]
	v_mfma_f32_16x16x32_bf16 v[36:39], v[162:165], v[202:205], v[36:39]
	v_mfma_f32_16x16x32_bf16 v[32:35], v[166:169], v[202:205], v[32:35]
	v_mfma_f32_16x16x32_bf16 v[60:63], v[170:173], v[182:185], v[60:63]
	v_mfma_f32_16x16x32_bf16 v[56:59], v[174:177], v[182:185], v[56:59]
	v_mfma_f32_16x16x32_bf16 v[52:55], v[170:173], v[190:193], v[52:55]
	v_mfma_f32_16x16x32_bf16 v[48:51], v[174:177], v[190:193], v[48:51]
	v_mfma_f32_16x16x32_bf16 v[44:47], v[170:173], v[198:201], v[44:47]
	v_mfma_f32_16x16x32_bf16 v[40:43], v[174:177], v[198:201], v[40:43]
	v_mfma_f32_16x16x32_bf16 v[36:39], v[170:173], v[206:209], v[36:39]
	v_mfma_f32_16x16x32_bf16 v[32:35], v[174:177], v[206:209], v[32:35]
	v_mfma_f32_16x16x32_bf16 v[28:31], v[210:213], v[178:181], v[28:31]
	v_mfma_f32_16x16x32_bf16 v[24:27], v[214:217], v[178:181], v[24:27]
	v_mfma_f32_16x16x32_bf16 v[20:23], v[210:213], v[186:189], v[20:23]
	v_mfma_f32_16x16x32_bf16 v[16:19], v[214:217], v[186:189], v[16:19]
	v_mfma_f32_16x16x32_bf16 v[12:15], v[210:213], v[194:197], v[12:15]
	v_mfma_f32_16x16x32_bf16 v[8:11], v[214:217], v[194:197], v[8:11]
	v_mfma_f32_16x16x32_bf16 v[4:7], v[210:213], v[202:205], v[4:7]
	v_mfma_f32_16x16x32_bf16 v[0:3], v[214:217], v[202:205], v[0:3]
	v_mfma_f32_16x16x32_bf16 v[28:31], v[218:221], v[182:185], v[28:31]
	v_mfma_f32_16x16x32_bf16 v[24:27], v[222:225], v[182:185], v[24:27]
	v_mfma_f32_16x16x32_bf16 v[20:23], v[218:221], v[190:193], v[20:23]
	v_mfma_f32_16x16x32_bf16 v[16:19], v[222:225], v[190:193], v[16:19]
	v_mfma_f32_16x16x32_bf16 v[12:15], v[218:221], v[198:201], v[12:15]
	v_mfma_f32_16x16x32_bf16 v[8:11], v[222:225], v[198:201], v[8:11]
	v_mfma_f32_16x16x32_bf16 v[4:7], v[218:221], v[206:209], v[4:7]
	v_mfma_f32_16x16x32_bf16 v[0:3], v[222:225], v[206:209], v[0:3]
	s_barrier

; #define STAGE(P, BASE, br, kt) do { const char* _gb = (const char*)(BASE) + ((size_t)(br) * K + (size_t)(kt) * BK) * 2; \
;     __builtin_amdgcn_global_load_lds((const unsigned*)(_gb + loff0), (unsigned*)((char*)(P) + tid * 16), 16, 0, 0); \
;     __builtin_amdgcn_global_load_lds((const unsigned*)(_gb + (size_t)K * 128 + loff0), (unsigned*)((char*)(P) + tid * 16 + 8192), 16, 0, 0); } while (0)
; #define LDA(dst, b, h) for (int m = 0; m < 4; ++m) { \
;     dst[m][0] = *reinterpret_cast<const bf16x8*>((char*)SA(b, h) + aoff0 + m * 2048); \
;     dst[m][1] = *reinterpret_cast<const bf16x8*>((char*)SA(b, h) + aoff1 + m * 2048); }
; #define LDB(dst, b, h) for (int n = 0; n < 2; ++n) { \
;     dst[n][0] = *reinterpret_cast<const bf16x8*>((char*)SB(b, h) + boff0 + n * 256); \
;     dst[n][1] = *reinterpret_cast<const bf16x8*>((char*)SB(b, h) + boff1 + n * 256); }
; #define MMA(ai, bj, At, Btf) do { __builtin_amdgcn_s_setprio(1); \
;     for (int m = 0; m < 4; ++m) for (int n = 0; n < 2; ++n) for (int k = 0; k < 2; ++k) \
;       acc[ai][bj][m][n] = __builtin_amdgcn_mfma_f32_16x16x32_bf16(Btf[n][k], At[m][k], acc[ai][bj][m][n], 0, 0, 0); \
;     __builtin_amdgcn_s_setprio(0); } while (0)
; #define WAIT_L(n) asm volatile("s_waitcnt lgkmcnt(" #n ")" ::: "memory")
; #define BAR __builtin_amdgcn_s_barrier()
; #define SCHED __builtin_amdgcn_sched_barrier(0)
; template <int EPI> ...
;     ...
;     LDB(B0, 1, 0); SCHED; LDA(At, 1, 0); STAGE(SA(0, 1), A, brow + HALF, t + 2);
;     WAIT_L(8); BAR; WAIT_L(0); MMA(0, 0, At, B0); BAR; SCHED;
;     LDB(B1, 1, 1); STAGE(SB(1, 0), Bt, bcol, t + 3);
	ds_read_b128 v[162:165], v157
	ds_read_b128 v[166:169], v157 offset:256
	ds_read_b128 v[170:173], v158
	ds_read_b128 v[174:177], v158 offset:256
	v_readfirstlane_b32 s70, v142
	v_lshl_add_u64 v[210:211], v[226:227], 0, s[38:39]
	s_mov_b32 m0, s70
	v_readfirstlane_b32 s70, v143
	ds_read_b128 v[178:181], v150 offset:32768
	ds_read_b128 v[182:185], v150 offset:33792
	ds_read_b128 v[186:189], v150 offset:34816
	ds_read_b128 v[190:193], v150 offset:35840
	ds_read_b128 v[194:197], v150 offset:36864
	ds_read_b128 v[198:201], v150 offset:37888
	ds_read_b128 v[202:205], v150 offset:38912
	ds_read_b128 v[206:209], v150 offset:39936
	global_load_lds_dwordx4 v[210:211], off
	v_lshl_add_u64 v[210:211], v[226:227], 0, s[46:47]
	s_mov_b32 m0, s70
	s_nop 0
	global_load_lds_dwordx4 v[210:211], off
	s_waitcnt lgkmcnt(8)
	v_readfirstlane_b32 s70, v141
	v_lshl_add_u64 v[246:247], v[228:229], 0, s[36:37]
	s_mov_b32 m0, s70
	s_nop 0
	global_load_lds_dwordx4 v[246:247], off
	ds_read_b128 v[210:213], v159
	ds_read_b128 v[214:217], v159 offset:256
	ds_read_b128 v[218:221], v160
	ds_read_b128 v[222:225], v160 offset:256
	s_waitcnt lgkmcnt(0)

; #define STAGE(P, BASE, br, kt) do { const char* _gb = (const char*)(BASE) + ((size_t)(br) * K + (size_t)(kt) * BK) * 2; \
;     __builtin_amdgcn_global_load_lds((const unsigned*)(_gb + loff0), (unsigned*)((char*)(P) + tid * 16), 16, 0, 0); \
;     __builtin_amdgcn_global_load_lds((const unsigned*)(_gb + (size_t)K * 128 + loff0), (unsigned*)((char*)(P) + tid * 16 + 8192), 16, 0, 0); } while (0)
; #define LDB(dst, b, h) for (int n = 0; n < 2; ++n) { \
;     dst[n][0] = *reinterpret_cast<const bf16x8*>((char*)SB(b, h) + boff0 + n * 256); \
;     dst[n][1] = *reinterpret_cast<const bf16x8*>((char*)SB(b, h) + boff1 + n * 256); }
; #define MMA(ai, bj, At, Btf) do { __builtin_amdgcn_s_setprio(1); \
;     for (int m = 0; m < 4; ++m) for (int n = 0; n < 2; ++n) for (int k = 0; k < 2; ++k) \
;       acc[ai][bj][m][n] = __builtin_amdgcn_mfma_f32_16x16x32_bf16(Btf[n][k], At[m][k], acc[ai][bj][m][n], 0, 0, 0); \
;     __builtin_amdgcn_s_setprio(0); } while (0)
; #define WAIT_L(n) asm volatile("s_waitcnt lgkmcnt(" #n ")" ::: "memory")
; #define BAR __builtin_amdgcn_s_barrier()
; #define SCHED __builtin_amdgcn_sched_barrier(0)
; template <int EPI> ...
;     ...
;     WAIT_L(8); BAR; WAIT_L(0); MMA(0, 0, At, B0); BAR; SCHED;
;     LDB(B1, 1, 1); STAGE(SB(1, 0), Bt, bcol, t + 3);
;     BAR; WAIT_L(0); MMA(0, 1, At, B1); BAR;
	s_barrier
	v_mfma_f32_16x16x32_bf16 v[124:127], v[162:165], v[178:181], v[124:127]
	v_mfma_f32_16x16x32_bf16 v[120:123], v[166:169], v[178:181], v[120:123]
	v_mfma_f32_16x16x32_bf16 v[116:119], v[162:165], v[186:189], v[116:119]
	v_mfma_f32_16x16x32_bf16 v[112:115], v[166:169], v[186:189], v[112:115]
	v_mfma_f32_16x16x32_bf16 v[108:111], v[162:165], v[194:197], v[108:111]
	v_mfma_f32_16x16x32_bf16 v[104:107], v[166:169], v[194:197], v[104:107]
	v_mfma_f32_16x16x32_bf16 v[100:103], v[162:165], v[202:205], v[100:103]
	v_mfma_f32_16x16x32_bf16 v[96:99], v[166:169], v[202:205], v[96:99]
	v_mfma_f32_16x16x32_bf16 v[124:127], v[170:173], v[182:185], v[124:127]
	v_mfma_f32_16x16x32_bf16 v[120:123], v[174:177], v[182:185], v[120:123]
	v_mfma_f32_16x16x32_bf16 v[116:119], v[170:173], v[190:193], v[116:119]
	v_mfma_f32_16x16x32_bf16 v[112:115], v[174:177], v[190:193], v[112:115]
	v_mfma_f32_16x16x32_bf16 v[108:111], v[170:173], v[198:201], v[108:111]
	v_mfma_f32_16x16x32_bf16 v[104:107], v[174:177], v[198:201], v[104:107]
	v_mfma_f32_16x16x32_bf16 v[100:103], v[170:173], v[206:209], v[100:103]
	v_mfma_f32_16x16x32_bf16 v[96:99], v[174:177], v[206:209], v[96:99]
	v_mfma_f32_16x16x32_bf16 v[92:95], v[210:213], v[178:181], v[92:95]
	v_mfma_f32_16x16x32_bf16 v[88:91], v[214:217], v[178:181], v[88:91]
	v_mfma_f32_16x16x32_bf16 v[84:87], v[210:213], v[186:189], v[84:87]
	v_mfma_f32_16x16x32_bf16 v[80:83], v[214:217], v[186:189], v[80:83]
	v_mfma_f32_16x16x32_bf16 v[76:79], v[210:213], v[194:197], v[76:79]
	v_mfma_f32_16x16x32_bf16 v[72:75], v[214:217], v[194:197], v[72:75]
	v_mfma_f32_16x16x32_bf16 v[68:71], v[210:213], v[202:205], v[68:71]
	v_mfma_f32_16x16x32_bf16 v[64:67], v[214:217], v[202:205], v[64:67]
	v_mfma_f32_16x16x32_bf16 v[92:95], v[218:221], v[182:185], v[92:95]
	v_mfma_f32_16x16x32_bf16 v[88:91], v[222:225], v[182:185], v[88:91]
	v_mfma_f32_16x16x32_bf16 v[84:87], v[218:221], v[190:193], v[84:87]
	v_mfma_f32_16x16x32_bf16 v[80:83], v[222:225], v[190:193], v[80:83]
	v_mfma_f32_16x16x32_bf16 v[76:79], v[218:221], v[198:201], v[76:79]
	v_mfma_f32_16x16x32_bf16 v[72:75], v[222:225], v[198:201], v[72:75]
	v_mfma_f32_16x16x32_bf16 v[68:71], v[218:221], v[206:209], v[68:71]
	v_mfma_f32_16x16x32_bf16 v[64:67], v[222:225], v[206:209], v[64:67]
	s_barrier

; #define STAGE(P, BASE, br, kt) do { const char* _gb = (const char*)(BASE) + ((size_t)(br) * K + (size_t)(kt) * BK) * 2; \
;     __builtin_amdgcn_global_load_lds((const unsigned*)(_gb + loff0), (unsigned*)((char*)(P) + tid * 16), 16, 0, 0); \
;     __builtin_amdgcn_global_load_lds((const unsigned*)(_gb + (size_t)K * 128 + loff0), (unsigned*)((char*)(P) + tid * 16 + 8192), 16, 0, 0); } while (0)
; #define LDA(dst, b, h) for (int m = 0; m < 4; ++m) { \
;     dst[m][0] = *reinterpret_cast<const bf16x8*>((char*)SA(b, h) + aoff0 + m * 2048); \
;     dst[m][1] = *reinterpret_cast<const bf16x8*>((char*)SA(b, h) + aoff1 + m * 2048); }
; #define LDB(dst, b, h) for (int n = 0; n < 2; ++n) { \
;     dst[n][0] = *reinterpret_cast<const bf16x8*>((char*)SB(b, h) + boff0 + n * 256); \
;     dst[n][1] = *reinterpret_cast<const bf16x8*>((char*)SB(b, h) + boff1 + n * 256); }
; #define MMA(ai, bj, At, Btf) do { __builtin_amdgcn_s_setprio(1); \
;     for (int m = 0; m < 4; ++m) for (int n = 0; n < 2; ++n) for (int k = 0; k < 2; ++k) \
;       acc[ai][bj][m][n] = __builtin_amdgcn_mfma_f32_16x16x32_bf16(Btf[n][k], At[m][k], acc[ai][bj][m][n], 0, 0, 0); \
;     __builtin_amdgcn_s_setprio(0); } while (0)
; #define WAIT_V(n) asm volatile("s_waitcnt vmcnt(" #n ")" ::: "memory")
; #define WAIT_L(n) asm volatile("s_waitcnt lgkmcnt(" #n ")" ::: "memory")
; #define BAR __builtin_amdgcn_s_barrier()
; #define SCHED __builtin_amdgcn_sched_barrier(0)
; template <int EPI> ...
;     ...
;     LDB(B1, 1, 1); STAGE(SB(1, 0), Bt, bcol, t + 3);
;     BAR; WAIT_L(0); MMA(0, 1, At, B1); BAR;
;     LDA(At, 1, 1); STAGE(SA(1, 0), A, brow, t + 3);
;     BAR; WAIT_L(0); MMA(1, 0, At, B0); BAR; SCHED;
;     STAGE(SB(1, 1), Bt, bcol + HALF, t + 3);
;     WAIT_V(6); BAR; MMA(1, 1, At, B1); BAR;
	v_readfirstlane_b32 s70, v144
	v_lshl_add_u64 v[230:231], v[228:229], 0, s[48:49]
	s_mov_b32 m0, s70
	v_readfirstlane_b32 s70, v145
	global_load_lds_dwordx4 v[230:231], off
	v_lshl_add_u64 v[230:231], v[228:229], 0, s[50:51]
	s_mov_b32 m0, s70
	s_nop 0
	global_load_lds_dwordx4 v[230:231], off
	v_readfirstlane_b32 s70, v146
	v_lshl_add_u64 v[230:231], v[226:227], 0, s[52:53]
	s_mov_b32 m0, s70
	v_readfirstlane_b32 s70, v147
	ds_read_b128 v[178:181], v150 offset:49152
	ds_read_b128 v[182:185], v150 offset:50176
	ds_read_b128 v[186:189], v150 offset:51200
	ds_read_b128 v[190:193], v150 offset:52224
	ds_read_b128 v[194:197], v150 offset:53248
	ds_read_b128 v[198:201], v150 offset:54272
	ds_read_b128 v[202:205], v150 offset:55296
	ds_read_b128 v[206:209], v150 offset:56320
	global_load_lds_dwordx4 v[230:231], off
	v_lshl_add_u64 v[226:227], v[226:227], 0, s[54:55]
	s_mov_b32 m0, s70
	s_nop 0
	global_load_lds_dwordx4 v[226:227], off
	v_readfirstlane_b32 s70, v148
	v_lshl_add_u64 v[246:247], v[228:229], 0, s[56:57]
	s_mov_b32 m0, s70
	v_readfirstlane_b32 s70, v149
	global_load_lds_dwordx4 v[246:247], off
	s_waitcnt vmcnt(5)
	s_barrier
	s_waitcnt lgkmcnt(0)

; #define MMA(ai, bj, At, Btf) do { __builtin_amdgcn_s_setprio(1); \
;     for (int m = 0; m < 4; ++m) for (int n = 0; n < 2; ++n) for (int k = 0; k < 2; ++k) \
;       acc[ai][bj][m][n] = __builtin_amdgcn_mfma_f32_16x16x32_bf16(Btf[n][k], At[m][k], acc[ai][bj][m][n], 0, 0, 0); \
;     __builtin_amdgcn_s_setprio(0); } while (0)
; #define WAIT_L(n) asm volatile("s_waitcnt lgkmcnt(" #n ")" ::: "memory")
; #define BAR __builtin_amdgcn_s_barrier()
; #define SCHED __builtin_amdgcn_sched_barrier(0)
; template <int EPI> ...
;     ...
;     BAR; WAIT_L(0); MMA(1, 0, At, B0); BAR; SCHED;
	s_waitcnt lgkmcnt(0)
	v_mfma_f32_16x16x32_bf16 v[60:63], v[162:165], v[178:181], v[60:63]
	v_mfma_f32_16x16x32_bf16 v[56:59], v[166:169], v[178:181], v[56:59]
	v_mfma_f32_16x16x32_bf16 v[52:55], v[162:165], v[186:189], v[52:55]
	v_mfma_f32_16x16x32_bf16 v[48:51], v[166:169], v[186:189], v[48:51]
	v_mfma_f32_16x16x32_bf16 v[44:47], v[162:165], v[194:197], v[44:47]
	v_mfma_f32_16x16x32_bf16 v[40:43], v[166:169], v[194:197], v[40:43]
	v_mfma_f32_16x16x32_bf16 v[36:39], v[162:165], v[202:205], v[36:39]
	v_mfma_f32_16x16x32_bf16 v[32:35], v[166:169], v[202:205], v[32:35]
	v_mfma_f32_16x16x32_bf16 v[60:63], v[170:173], v[182:185], v[60:63]
	v_mfma_f32_16x16x32_bf16 v[56:59], v[174:177], v[182:185], v[56:59]
	v_mfma_f32_16x16x32_bf16 v[52:55], v[170:173], v[190:193], v[52:55]
	v_mfma_f32_16x16x32_bf16 v[48:51], v[174:177], v[190:193], v[48:51]
	v_mfma_f32_16x16x32_bf16 v[44:47], v[170:173], v[198:201], v[44:47]
	v_mfma_f32_16x16x32_bf16 v[40:43], v[174:177], v[198:201], v[40:43]
	v_mfma_f32_16x16x32_bf16 v[36:39], v[170:173], v[206:209], v[36:39]
	v_mfma_f32_16x16x32_bf16 v[32:35], v[174:177], v[206:209], v[32:35]


; #define MMA(ai, bj, At, Btf) do { __builtin_amdgcn_s_setprio(1); \
;     for (int m = 0; m < 4; ++m) for (int n = 0; n < 2; ++n) for (int k = 0; k < 2; ++k) \
;       acc[ai][bj][m][n] = __builtin_amdgcn_mfma_f32_16x16x32_bf16(Btf[n][k], At[m][k], acc[ai][bj][m][n], 0, 0, 0); \
;     __builtin_amdgcn_s_setprio(0); } while (0)
; #define WAIT_V(n) asm volatile("s_waitcnt vmcnt(" #n ")" ::: "memory")
; #define BAR __builtin_amdgcn_s_barrier()
; template <int EPI> ...
;     ...
;     WAIT_V(6); BAR; MMA(1, 1, At, B1); BAR;
	v_mfma_f32_16x16x32_bf16 v[28:31], v[210:213], v[178:181], v[28:31]
	v_mfma_f32_16x16x32_bf16 v[24:27], v[214:217], v[178:181], v[24:27]
	v_mfma_f32_16x16x32_bf16 v[20:23], v[210:213], v[186:189], v[20:23]
	v_mfma_f32_16x16x32_bf16 v[16:19], v[214:217], v[186:189], v[16:19]
	v_mfma_f32_16x16x32_bf16 v[12:15], v[210:213], v[194:197], v[12:15]
	v_mfma_f32_16x16x32_bf16 v[8:11], v[214:217], v[194:197], v[8:11]
	v_mfma_f32_16x16x32_bf16 v[4:7], v[210:213], v[202:205], v[4:7]
	v_mfma_f32_16x16x32_bf16 v[0:3], v[214:217], v[202:205], v[0:3]
	v_mfma_f32_16x16x32_bf16 v[28:31], v[218:221], v[182:185], v[28:31]
	v_mfma_f32_16x16x32_bf16 v[24:27], v[222:225], v[182:185], v[24:27]
	v_mfma_f32_16x16x32_bf16 v[20:23], v[218:221], v[190:193], v[20:23]
	v_mfma_f32_16x16x32_bf16 v[16:19], v[222:225], v[190:193], v[16:19]
	v_mfma_f32_16x16x32_bf16 v[12:15], v[218:221], v[198:201], v[12:15]
	v_mfma_f32_16x16x32_bf16 v[8:11], v[222:225], v[198:201], v[8:11]
	v_mfma_f32_16x16x32_bf16 v[4:7], v[218:221], v[206:209], v[4:7]
	v_mfma_f32_16x16x32_bf16 v[0:3], v[222:225], v[206:209], v[0:3]

; #define STAGE(P, BASE, br, kt) do { const char* _gb = (const char*)(BASE) + ((size_t)(br) * K + (size_t)(kt) * BK) * 2; \
;     __builtin_amdgcn_global_load_lds((const unsigned*)(_gb + loff0), (unsigned*)((char*)(P) + tid * 16), 16, 0, 0); \
;     __builtin_amdgcn_global_load_lds((const unsigned*)(_gb + (size_t)K * 128 + loff0), (unsigned*)((char*)(P) + tid * 16 + 8192), 16, 0, 0); } while (0)
; #define LDA(dst, b, h) for (int m = 0; m < 4; ++m) { \
;     dst[m][0] = *reinterpret_cast<const bf16x8*>((char*)SA(b, h) + aoff0 + m * 2048); \
;     dst[m][1] = *reinterpret_cast<const bf16x8*>((char*)SA(b, h) + aoff1 + m * 2048); }
; #define LDB(dst, b, h) for (int n = 0; n < 2; ++n) { \
;     dst[n][0] = *reinterpret_cast<const bf16x8*>((char*)SB(b, h) + boff0 + n * 256); \
;     dst[n][1] = *reinterpret_cast<const bf16x8*>((char*)SB(b, h) + boff1 + n * 256); }
; #define MMA(ai, bj, At, Btf) do { __builtin_amdgcn_s_setprio(1); \
;     for (int m = 0; m < 4; ++m) for (int n = 0; n < 2; ++n) for (int k = 0; k < 2; ++k) \
;       acc[ai][bj][m][n] = __builtin_amdgcn_mfma_f32_16x16x32_bf16(Btf[n][k], At[m][k], acc[ai][bj][m][n], 0, 0, 0); \
;     __builtin_amdgcn_s_setprio(0); } while (0)
; #define WAIT_V(n) asm volatile("s_waitcnt vmcnt(" #n ")" ::: "memory")
; #define WAIT_L(n) asm volatile("s_waitcnt lgkmcnt(" #n ")" ::: "memory")
; template <int EPI> ...
;     ...
;   for (int t = 0; t < nt - 2; t += 2) {
;     LDB(B0, 0, 0); SCHED; LDA(At, 0, 0); STAGE(SA(1, 1), A, brow + HALF, t + 1);
;     WAIT_L(8); BAR; WAIT_L(0); MMA(0, 0, At, B0); BAR; SCHED;
;     LDB(B1, 0, 1); STAGE(SB(0, 0), Bt, bcol, t + 2);
;     BAR; WAIT_L(0); MMA(0, 1, At, B1); BAR;
;     LDA(At, 0, 1); STAGE(SA(0, 0), A, brow, t + 2);
;     BAR; WAIT_L(0); MMA(1, 0, At, B0); BAR; SCHED;
;     STAGE(SB(0, 1), Bt, bcol + HALF, t + 2);
;     WAIT_V(6); BAR; MMA(1, 1, At, B1); BAR;
;     LDB(B0, 1, 0); SCHED; LDA(At, 1, 0); STAGE(SA(0, 1), A, brow + HALF, t + 2);
;     WAIT_L(8); BAR; WAIT_L(0); MMA(0, 0, At, B0); BAR; SCHED;
;     LDB(B1, 1, 1); STAGE(SB(1, 0), Bt, bcol, t + 3);
;     BAR; WAIT_L(0); MMA(0, 1, At, B1); BAR;
;     LDA(At, 1, 1); STAGE(SA(1, 0), A, brow, t + 3);
;     BAR; WAIT_L(0); MMA(1, 0, At, B0); BAR; SCHED;
;     STAGE(SB(1, 1), Bt, bcol + HALF, t + 3);
;     WAIT_V(6); BAR; MMA(1, 1, At, B1); BAR;
;   }
;   { LDB(B0, 0, 0); LDA(At, 0, 0); STAGE(SA(1, 1), A, brow + HALF, nt - 1);
	s_add_i32 s65, s65, 2
	s_add_u32 s66, s66, 0x100
	s_addc_u32 s67, s67, 0
	s_add_u32 s68, s68, 0x100
	s_addc_u32 s69, s69, 0
	s_cmp_lt_u32 s65, 28
	s_barrier
	s_cbranch_scc1 .LBB0_1105
	v_readfirstlane_b32 s70, v149
	v_lshl_add_u64 v[246:247], v[228:229], 0, s[58:59]
	s_mov_b32 m0, s70
	s_nop 0
	global_load_lds_dwordx4 v[246:247], off
	v_readfirstlane_b32 s65, v151
	v_lshl_add_u64 v[210:211], v[132:133], 0, s[60:61]
	s_mov_b32 m0, s65
	v_readfirstlane_b32 s65, v152
	ds_read_b128 v[162:165], v153
	ds_read_b128 v[166:169], v153 offset:256
	ds_read_b128 v[170:173], v154
	ds_read_b128 v[174:177], v154 offset:256
	ds_read_b128 v[178:181], v150
	ds_read_b128 v[182:185], v150 offset:1024
	ds_read_b128 v[186:189], v150 offset:2048
	ds_read_b128 v[190:193], v150 offset:3072
	ds_read_b128 v[194:197], v150 offset:4096
	ds_read_b128 v[198:201], v150 offset:5120
	ds_read_b128 v[202:205], v150 offset:6144
	ds_read_b128 v[206:209], v150 offset:7168
	global_load_lds_dwordx4 v[210:211], off
	v_lshl_add_u64 v[132:133], v[132:133], 0, s[62:63]
	s_mov_b32 m0, s65
	s_nop 0
	global_load_lds_dwordx4 v[132:133], off
	s_waitcnt lgkmcnt(0)

; #define MMA(ai, bj, At, Btf) do { __builtin_amdgcn_s_setprio(1); \
;     for (int m = 0; m < 4; ++m) for (int n = 0; n < 2; ++n) for (int k = 0; k < 2; ++k) \
;       acc[ai][bj][m][n] = __builtin_amdgcn_mfma_f32_16x16x32_bf16(Btf[n][k], At[m][k], acc[ai][bj][m][n], 0, 0, 0); \
;     __builtin_amdgcn_s_setprio(0); } while (0)
; #define WAIT_L(n) asm volatile("s_waitcnt lgkmcnt(" #n ")" ::: "memory")
; #define BAR __builtin_amdgcn_s_barrier()
; template <int EPI> ...
;     ...
;     BAR; WAIT_L(0); MMA(0, 0, At, B0); BAR;
	s_barrier
	v_mfma_f32_16x16x32_bf16 v[124:127], v[162:165], v[178:181], v[124:127]
	v_mfma_f32_16x16x32_bf16 v[116:119], v[162:165], v[186:189], v[116:119]
	v_mfma_f32_16x16x32_bf16 v[108:111], v[162:165], v[194:197], v[108:111]
	v_mfma_f32_16x16x32_bf16 v[100:103], v[162:165], v[202:205], v[100:103]
	v_mfma_f32_16x16x32_bf16 v[124:127], v[170:173], v[182:185], v[124:127]
	v_mfma_f32_16x16x32_bf16 v[120:123], v[166:169], v[178:181], v[120:123]
	v_mfma_f32_16x16x32_bf16 v[116:119], v[170:173], v[190:193], v[116:119]
	v_mfma_f32_16x16x32_bf16 v[112:115], v[166:169], v[186:189], v[112:115]
	v_mfma_f32_16x16x32_bf16 v[108:111], v[170:173], v[198:201], v[108:111]
	v_mfma_f32_16x16x32_bf16 v[104:107], v[166:169], v[194:197], v[104:107]
	v_mfma_f32_16x16x32_bf16 v[100:103], v[170:173], v[206:209], v[100:103]
	v_mfma_f32_16x16x32_bf16 v[96:99], v[166:169], v[202:205], v[96:99]
	v_mfma_f32_16x16x32_bf16 v[210:213], v[174:177], v[182:185], v[120:123]
	v_mfma_f32_16x16x32_bf16 v[214:217], v[174:177], v[190:193], v[112:115]
	v_mfma_f32_16x16x32_bf16 v[218:221], v[174:177], v[198:201], v[104:107]
	v_mfma_f32_16x16x32_bf16 v[222:225], v[174:177], v[206:209], v[96:99]
	s_barrier

; #define LDB(dst, b, h) for (int n = 0; n < 2; ++n) { \
;     dst[n][0] = *reinterpret_cast<const bf16x8*>((char*)SB(b, h) + boff0 + n * 256); \
;     dst[n][1] = *reinterpret_cast<const bf16x8*>((char*)SB(b, h) + boff1 + n * 256); }
; #define MMA(ai, bj, At, Btf) do { __builtin_amdgcn_s_setprio(1); \
;     for (int m = 0; m < 4; ++m) for (int n = 0; n < 2; ++n) for (int k = 0; k < 2; ++k) \
;       acc[ai][bj][m][n] = __builtin_amdgcn_mfma_f32_16x16x32_bf16(Btf[n][k], At[m][k], acc[ai][bj][m][n], 0, 0, 0); \
;     __builtin_amdgcn_s_setprio(0); } while (0)
; #define WAIT_L(n) asm volatile("s_waitcnt lgkmcnt(" #n ")" ::: "memory")
; #define BAR __builtin_amdgcn_s_barrier()
; template <int EPI> ...
;     ...
;     LDB(B1, 0, 1); BAR; WAIT_L(0); MMA(0, 1, At, B1); BAR;
	s_nop 1
	ds_read_b128 v[96:99], v155
	ds_read_b128 v[104:107], v155 offset:256
	ds_read_b128 v[112:115], v156
	ds_read_b128 v[120:123], v156 offset:256
	s_waitcnt lgkmcnt(0)

; #define LDB(dst, b, h) for (int n = 0; n < 2; ++n) { \
;     dst[n][0] = *reinterpret_cast<const bf16x8*>((char*)SB(b, h) + boff0 + n * 256); \
;     dst[n][1] = *reinterpret_cast<const bf16x8*>((char*)SB(b, h) + boff1 + n * 256); }
; #define MMA(ai, bj, At, Btf) do { __builtin_amdgcn_s_setprio(1); \
;     for (int m = 0; m < 4; ++m) for (int n = 0; n < 2; ++n) for (int k = 0; k < 2; ++k) \
;       acc[ai][bj][m][n] = __builtin_amdgcn_mfma_f32_16x16x32_bf16(Btf[n][k], At[m][k], acc[ai][bj][m][n], 0, 0, 0); \
;     __builtin_amdgcn_s_setprio(0); } while (0)
; #define WAIT_L(n) asm volatile("s_waitcnt lgkmcnt(" #n ")" ::: "memory")
; #define BAR __builtin_amdgcn_s_barrier()
; template <int EPI> ...
;     ...
;     LDB(B1, 0, 1); BAR; WAIT_L(0); MMA(0, 1, At, B1); BAR;
	s_barrier
	v_mfma_f32_16x16x32_bf16 v[92:95], v[96:99], v[178:181], v[92:95]
	v_mfma_f32_16x16x32_bf16 v[84:87], v[96:99], v[186:189], v[84:87]
	v_mfma_f32_16x16x32_bf16 v[76:79], v[96:99], v[194:197], v[76:79]
	v_mfma_f32_16x16x32_bf16 v[68:71], v[96:99], v[202:205], v[68:71]
	v_mfma_f32_16x16x32_bf16 v[92:95], v[112:115], v[182:185], v[92:95]
	v_mfma_f32_16x16x32_bf16 v[88:91], v[104:107], v[178:181], v[88:91]
	v_mfma_f32_16x16x32_bf16 v[84:87], v[112:115], v[190:193], v[84:87]
	v_mfma_f32_16x16x32_bf16 v[80:83], v[104:107], v[186:189], v[80:83]
	v_mfma_f32_16x16x32_bf16 v[76:79], v[112:115], v[198:201], v[76:79]
	v_mfma_f32_16x16x32_bf16 v[72:75], v[104:107], v[194:197], v[72:75]
	v_mfma_f32_16x16x32_bf16 v[68:71], v[112:115], v[206:209], v[68:71]
	v_mfma_f32_16x16x32_bf16 v[64:67], v[104:107], v[202:205], v[64:67]
	v_mfma_f32_16x16x32_bf16 v[178:181], v[120:123], v[182:185], v[88:91]
	v_mfma_f32_16x16x32_bf16 v[182:185], v[120:123], v[190:193], v[80:83]
	v_mfma_f32_16x16x32_bf16 v[186:189], v[120:123], v[198:201], v[72:75]
	v_mfma_f32_16x16x32_bf16 v[190:193], v[120:123], v[206:209], v[64:67]
	s_barrier

; #define LDA(dst, b, h) for (int m = 0; m < 4; ++m) { \
;     dst[m][0] = *reinterpret_cast<const bf16x8*>((char*)SA(b, h) + aoff0 + m * 2048); \
;     dst[m][1] = *reinterpret_cast<const bf16x8*>((char*)SA(b, h) + aoff1 + m * 2048); }
; #define MMA(ai, bj, At, Btf) do { __builtin_amdgcn_s_setprio(1); \
;     for (int m = 0; m < 4; ++m) for (int n = 0; n < 2; ++n) for (int k = 0; k < 2; ++k) \
;       acc[ai][bj][m][n] = __builtin_amdgcn_mfma_f32_16x16x32_bf16(Btf[n][k], At[m][k], acc[ai][bj][m][n], 0, 0, 0); \
;     __builtin_amdgcn_s_setprio(0); } while (0)
; #define WAIT_V(n) asm volatile("s_waitcnt vmcnt(" #n ")" ::: "memory")
; #define WAIT_L(n) asm volatile("s_waitcnt lgkmcnt(" #n ")" ::: "memory")
; #define BAR __builtin_amdgcn_s_barrier()
; template <int EPI> ...
;     ...
;     LDA(At, 0, 1); WAIT_V(4); BAR; WAIT_L(0); MMA(1, 0, At, B0); MMA(1, 1, At, B1); BAR; }
	s_nop 1
	ds_read_b128 v[64:67], v150 offset:16384
	ds_read_b128 v[72:75], v150 offset:17408
	ds_read_b128 v[80:83], v150 offset:18432
	ds_read_b128 v[88:91], v150 offset:19456
	ds_read_b128 v[194:197], v150 offset:20480
	ds_read_b128 v[198:201], v150 offset:21504
	ds_read_b128 v[202:205], v150 offset:22528
	ds_read_b128 v[206:209], v150 offset:23552
	s_waitcnt vmcnt(4)
	s_waitcnt lgkmcnt(0)

; #define LDA(dst, b, h) for (int m = 0; m < 4; ++m) { \
;     dst[m][0] = *reinterpret_cast<const bf16x8*>((char*)SA(b, h) + aoff0 + m * 2048); \
;     dst[m][1] = *reinterpret_cast<const bf16x8*>((char*)SA(b, h) + aoff1 + m * 2048); }
; #define MMA(ai, bj, At, Btf) do { __builtin_amdgcn_s_setprio(1); \
;     for (int m = 0; m < 4; ++m) for (int n = 0; n < 2; ++n) for (int k = 0; k < 2; ++k) \
;       acc[ai][bj][m][n] = __builtin_amdgcn_mfma_f32_16x16x32_bf16(Btf[n][k], At[m][k], acc[ai][bj][m][n], 0, 0, 0); \
;     __builtin_amdgcn_s_setprio(0); } while (0)
; #define WAIT_V(n) asm volatile("s_waitcnt vmcnt(" #n ")" ::: "memory")
; #define WAIT_L(n) asm volatile("s_waitcnt lgkmcnt(" #n ")" ::: "memory")
; #define BAR __builtin_amdgcn_s_barrier()
; template <int EPI> ...
;     ...
;     LDA(At, 0, 1); WAIT_V(4); BAR; WAIT_L(0); MMA(1, 0, At, B0); MMA(1, 1, At, B1); BAR; }
	s_barrier
	v_mfma_f32_16x16x32_bf16 v[60:63], v[162:165], v[64:67], v[60:63]
	v_mfma_f32_16x16x32_bf16 v[56:59], v[166:169], v[64:67], v[56:59]
	v_mfma_f32_16x16x32_bf16 v[52:55], v[162:165], v[80:83], v[52:55]
	v_mfma_f32_16x16x32_bf16 v[40:43], v[166:169], v[194:197], v[40:43]
	v_mfma_f32_16x16x32_bf16 v[36:39], v[162:165], v[202:205], v[36:39]
	v_mfma_f32_16x16x32_bf16 v[60:63], v[170:173], v[72:75], v[60:63]
	v_mfma_f32_16x16x32_bf16 v[56:59], v[174:177], v[72:75], v[56:59]
	v_mfma_f32_16x16x32_bf16 v[52:55], v[170:173], v[88:91], v[52:55]
	v_mfma_f32_16x16x32_bf16 v[48:51], v[166:169], v[80:83], v[48:51]
	v_mfma_f32_16x16x32_bf16 v[44:47], v[162:165], v[194:197], v[44:47]
	v_mfma_f32_16x16x32_bf16 v[40:43], v[174:177], v[198:201], v[40:43]
	v_mfma_f32_16x16x32_bf16 v[36:39], v[170:173], v[206:209], v[36:39]
	v_mfma_f32_16x16x32_bf16 v[32:35], v[166:169], v[202:205], v[32:35]
	v_mfma_f32_16x16x32_bf16 v[226:229], v[174:177], v[88:91], v[48:51]
	v_mfma_f32_16x16x32_bf16 v[230:233], v[170:173], v[198:201], v[44:47]
	v_mfma_f32_16x16x32_bf16 v[162:165], v[174:177], v[206:209], v[32:35]
	v_mfma_f32_16x16x32_bf16 v[24:27], v[104:107], v[64:67], v[24:27]
	v_mfma_f32_16x16x32_bf16 v[20:23], v[96:99], v[80:83], v[20:23]
	v_mfma_f32_16x16x32_bf16 v[8:11], v[104:107], v[194:197], v[8:11]
	v_mfma_f32_16x16x32_bf16 v[4:7], v[96:99], v[202:205], v[4:7]
	v_mfma_f32_16x16x32_bf16 v[28:31], v[96:99], v[64:67], v[28:31]
	v_mfma_f32_16x16x32_bf16 v[24:27], v[120:123], v[72:75], v[24:27]
	v_mfma_f32_16x16x32_bf16 v[20:23], v[112:115], v[88:91], v[20:23]
	v_mfma_f32_16x16x32_bf16 v[16:19], v[104:107], v[80:83], v[16:19]
	v_mfma_f32_16x16x32_bf16 v[12:15], v[96:99], v[194:197], v[12:15]
	v_mfma_f32_16x16x32_bf16 v[8:11], v[120:123], v[198:201], v[8:11]
	v_mfma_f32_16x16x32_bf16 v[4:7], v[112:115], v[206:209], v[4:7]
	v_mfma_f32_16x16x32_bf16 v[0:3], v[104:107], v[202:205], v[0:3]
	v_mfma_f32_16x16x32_bf16 v[166:169], v[112:115], v[72:75], v[28:31]
	v_mfma_f32_16x16x32_bf16 v[170:173], v[120:123], v[88:91], v[16:19]
	v_mfma_f32_16x16x32_bf16 v[174:177], v[112:115], v[198:201], v[12:15]
	v_mfma_f32_16x16x32_bf16 v[194:197], v[120:123], v[206:209], v[0:3]
	s_barrier

; #define LDA(dst, b, h) for (int m = 0; m < 4; ++m) { \
;     dst[m][0] = *reinterpret_cast<const bf16x8*>((char*)SA(b, h) + aoff0 + m * 2048); \
;     dst[m][1] = *reinterpret_cast<const bf16x8*>((char*)SA(b, h) + aoff1 + m * 2048); }
; #define LDB(dst, b, h) for (int n = 0; n < 2; ++n) { \
;     dst[n][0] = *reinterpret_cast<const bf16x8*>((char*)SB(b, h) + boff0 + n * 256); \
;     dst[n][1] = *reinterpret_cast<const bf16x8*>((char*)SB(b, h) + boff1 + n * 256); }
; #define MMA(ai, bj, At, Btf) do { __builtin_amdgcn_s_setprio(1); \
;     for (int m = 0; m < 4; ++m) for (int n = 0; n < 2; ++n) for (int k = 0; k < 2; ++k) \
;       acc[ai][bj][m][n] = __builtin_amdgcn_mfma_f32_16x16x32_bf16(Btf[n][k], At[m][k], acc[ai][bj][m][n], 0, 0, 0); \
;     __builtin_amdgcn_s_setprio(0); } while (0)
; #define WAIT_V(n) asm volatile("s_waitcnt vmcnt(" #n ")" ::: "memory")
; #define WAIT_L(n) asm volatile("s_waitcnt lgkmcnt(" #n ")" ::: "memory")
; #define BAR __builtin_amdgcn_s_barrier()
; template <int EPI> ...
;     ...
;   { LDB(B0, 1, 0); LDA(At, 1, 0); WAIT_V(2); BAR; WAIT_L(0); MMA(0, 0, At, B0); BAR;
	s_nop 1
	ds_read_b128 v[0:3], v157
	ds_read_b128 v[198:201], v157 offset:256
	ds_read_b128 v[12:15], v158
	ds_read_b128 v[202:205], v158 offset:256
	ds_read_b128 v[16:19], v150 offset:32768
	ds_read_b128 v[28:31], v150 offset:33792
	ds_read_b128 v[32:35], v150 offset:34816
	ds_read_b128 v[44:47], v150 offset:35840
	ds_read_b128 v[48:51], v150 offset:36864
	ds_read_b128 v[206:209], v150 offset:37888
	ds_read_b128 v[234:237], v150 offset:38912
	ds_read_b128 v[238:241], v150 offset:39936
	s_waitcnt vmcnt(2)
	s_waitcnt lgkmcnt(0)

; #define LDA(dst, b, h) for (int m = 0; m < 4; ++m) { \
;     dst[m][0] = *reinterpret_cast<const bf16x8*>((char*)SA(b, h) + aoff0 + m * 2048); \
;     dst[m][1] = *reinterpret_cast<const bf16x8*>((char*)SA(b, h) + aoff1 + m * 2048); }
; #define LDB(dst, b, h) for (int n = 0; n < 2; ++n) { \
;     dst[n][0] = *reinterpret_cast<const bf16x8*>((char*)SB(b, h) + boff0 + n * 256); \
;     dst[n][1] = *reinterpret_cast<const bf16x8*>((char*)SB(b, h) + boff1 + n * 256); }
; #define MMA(ai, bj, At, Btf) do { __builtin_amdgcn_s_setprio(1); \
;     for (int m = 0; m < 4; ++m) for (int n = 0; n < 2; ++n) for (int k = 0; k < 2; ++k) \
;       acc[ai][bj][m][n] = __builtin_amdgcn_mfma_f32_16x16x32_bf16(Btf[n][k], At[m][k], acc[ai][bj][m][n], 0, 0, 0); \
;     __builtin_amdgcn_s_setprio(0); } while (0)
; #define WAIT_V(n) asm volatile("s_waitcnt vmcnt(" #n ")" ::: "memory")
; #define WAIT_L(n) asm volatile("s_waitcnt lgkmcnt(" #n ")" ::: "memory")
; #define BAR __builtin_amdgcn_s_barrier()
; template <int EPI> ...
;     ...
;   { LDB(B0, 1, 0); LDA(At, 1, 0); WAIT_V(2); BAR; WAIT_L(0); MMA(0, 0, At, B0); BAR;
	s_barrier
	v_mfma_f32_16x16x32_bf16 v[64:67], v[0:3], v[16:19], v[124:127]
	v_mfma_f32_16x16x32_bf16 v[120:123], v[12:15], v[28:31], v[64:67]
	v_mfma_f32_16x16x32_bf16 v[64:67], v[198:201], v[16:19], v[210:213]
	v_mfma_f32_16x16x32_bf16 v[112:115], v[202:205], v[28:31], v[64:67]
	v_mfma_f32_16x16x32_bf16 v[64:67], v[0:3], v[32:35], v[116:119]
	v_mfma_f32_16x16x32_bf16 v[104:107], v[12:15], v[44:47], v[64:67]
	v_mfma_f32_16x16x32_bf16 v[64:67], v[198:201], v[32:35], v[214:217]
	v_mfma_f32_16x16x32_bf16 v[96:99], v[202:205], v[44:47], v[64:67]
	v_mfma_f32_16x16x32_bf16 v[64:67], v[0:3], v[48:51], v[108:111]
	v_mfma_f32_16x16x32_bf16 v[88:91], v[12:15], v[206:209], v[64:67]
	v_mfma_f32_16x16x32_bf16 v[64:67], v[198:201], v[48:51], v[218:221]
	v_mfma_f32_16x16x32_bf16 v[80:83], v[202:205], v[206:209], v[64:67]
	v_mfma_f32_16x16x32_bf16 v[64:67], v[0:3], v[234:237], v[100:103]
	v_mfma_f32_16x16x32_bf16 v[72:75], v[12:15], v[238:241], v[64:67]
	v_mfma_f32_16x16x32_bf16 v[64:67], v[198:201], v[234:237], v[222:225]
	v_mfma_f32_16x16x32_bf16 v[64:67], v[202:205], v[238:241], v[64:67]
	s_barrier

; #define LDB(dst, b, h) for (int n = 0; n < 2; ++n) { \
;     dst[n][0] = *reinterpret_cast<const bf16x8*>((char*)SB(b, h) + boff0 + n * 256); \
;     dst[n][1] = *reinterpret_cast<const bf16x8*>((char*)SB(b, h) + boff1 + n * 256); }
; #define MMA(ai, bj, At, Btf) do { __builtin_amdgcn_s_setprio(1); \
;     for (int m = 0; m < 4; ++m) for (int n = 0; n < 2; ++n) for (int k = 0; k < 2; ++k) \
;       acc[ai][bj][m][n] = __builtin_amdgcn_mfma_f32_16x16x32_bf16(Btf[n][k], At[m][k], acc[ai][bj][m][n], 0, 0, 0); \
;     __builtin_amdgcn_s_setprio(0); } while (0)
; #define WAIT_V(n) asm volatile("s_waitcnt vmcnt(" #n ")" ::: "memory")
; #define WAIT_L(n) asm volatile("s_waitcnt lgkmcnt(" #n ")" ::: "memory")
; #define BAR __builtin_amdgcn_s_barrier()
; template <int EPI> ...
;     ...
;     LDB(B1, 1, 1); WAIT_V(0); BAR; WAIT_L(0); MMA(0, 1, At, B1); BAR;
	ds_read_b128 v[210:213], v159
	ds_read_b128 v[214:217], v159 offset:256
	ds_read_b128 v[218:221], v160
	ds_read_b128 v[222:225], v160 offset:256
	s_waitcnt vmcnt(0)
	s_waitcnt lgkmcnt(0)

; #define LDB(dst, b, h) for (int n = 0; n < 2; ++n) { \
;     dst[n][0] = *reinterpret_cast<const bf16x8*>((char*)SB(b, h) + boff0 + n * 256); \
;     dst[n][1] = *reinterpret_cast<const bf16x8*>((char*)SB(b, h) + boff1 + n * 256); }
; #define MMA(ai, bj, At, Btf) do { __builtin_amdgcn_s_setprio(1); \
;     for (int m = 0; m < 4; ++m) for (int n = 0; n < 2; ++n) for (int k = 0; k < 2; ++k) \
;       acc[ai][bj][m][n] = __builtin_amdgcn_mfma_f32_16x16x32_bf16(Btf[n][k], At[m][k], acc[ai][bj][m][n], 0, 0, 0); \
;     __builtin_amdgcn_s_setprio(0); } while (0)
; #define WAIT_V(n) asm volatile("s_waitcnt vmcnt(" #n ")" ::: "memory")
; #define WAIT_L(n) asm volatile("s_waitcnt lgkmcnt(" #n ")" ::: "memory")
; #define BAR __builtin_amdgcn_s_barrier()
; template <int EPI> ...
;     ...
;     LDB(B1, 1, 1); WAIT_V(0); BAR; WAIT_L(0); MMA(0, 1, At, B1); BAR;
	s_barrier
	v_mfma_f32_16x16x32_bf16 v[92:95], v[210:213], v[16:19], v[92:95]
	v_mfma_f32_16x16x32_bf16 v[16:19], v[214:217], v[16:19], v[178:181]
	v_mfma_f32_16x16x32_bf16 v[116:119], v[222:225], v[28:31], v[16:19]
	v_mfma_f32_16x16x32_bf16 v[16:19], v[210:213], v[32:35], v[84:87]
	v_mfma_f32_16x16x32_bf16 v[108:111], v[218:221], v[44:47], v[16:19]
	v_mfma_f32_16x16x32_bf16 v[16:19], v[214:217], v[32:35], v[182:185]
	v_mfma_f32_16x16x32_bf16 v[100:103], v[222:225], v[44:47], v[16:19]
	v_mfma_f32_16x16x32_bf16 v[16:19], v[210:213], v[48:51], v[76:79]
	v_mfma_f32_16x16x32_bf16 v[124:127], v[218:221], v[28:31], v[92:95]
	v_mfma_f32_16x16x32_bf16 v[92:95], v[218:221], v[206:209], v[16:19]
	v_mfma_f32_16x16x32_bf16 v[16:19], v[214:217], v[48:51], v[186:189]
	v_mfma_f32_16x16x32_bf16 v[84:87], v[222:225], v[206:209], v[16:19]
	v_mfma_f32_16x16x32_bf16 v[16:19], v[210:213], v[234:237], v[68:71]
	v_mfma_f32_16x16x32_bf16 v[76:79], v[218:221], v[238:241], v[16:19]
	v_mfma_f32_16x16x32_bf16 v[16:19], v[214:217], v[234:237], v[190:193]
	v_mfma_f32_16x16x32_bf16 v[68:71], v[222:225], v[238:241], v[16:19]
	s_barrier

; #define LDA(dst, b, h) for (int m = 0; m < 4; ++m) { \
;     dst[m][0] = *reinterpret_cast<const bf16x8*>((char*)SA(b, h) + aoff0 + m * 2048); \
;     dst[m][1] = *reinterpret_cast<const bf16x8*>((char*)SA(b, h) + aoff1 + m * 2048); }
; #define MMA(ai, bj, At, Btf) do { __builtin_amdgcn_s_setprio(1); \
;     for (int m = 0; m < 4; ++m) for (int n = 0; n < 2; ++n) for (int k = 0; k < 2; ++k) \
;       acc[ai][bj][m][n] = __builtin_amdgcn_mfma_f32_16x16x32_bf16(Btf[n][k], At[m][k], acc[ai][bj][m][n], 0, 0, 0); \
;     __builtin_amdgcn_s_setprio(0); } while (0)
; #define WAIT_L(n) asm volatile("s_waitcnt lgkmcnt(" #n ")" ::: "memory")
; #define BAR __builtin_amdgcn_s_barrier()
; template <int EPI> ...
;     ...
;     LDA(At, 1, 1); BAR; WAIT_L(0); MMA(1, 0, At, B0); MMA(1, 1, At, B1); BAR; }
	ds_read_b128 v[178:181], v150 offset:49152
	ds_read_b128 v[182:185], v150 offset:50176
	ds_read_b128 v[186:189], v150 offset:51200
	ds_read_b128 v[190:193], v150 offset:52224
	ds_read_b128 v[206:209], v150 offset:53248
	ds_read_b128 v[234:237], v150 offset:54272
	ds_read_b128 v[238:241], v150 offset:55296
	ds_read_b128 v[242:245], v150 offset:56320
	s_waitcnt lgkmcnt(0)

; #define LDA(dst, b, h) for (int m = 0; m < 4; ++m) { \
;     dst[m][0] = *reinterpret_cast<const bf16x8*>((char*)SA(b, h) + aoff0 + m * 2048); \
;     dst[m][1] = *reinterpret_cast<const bf16x8*>((char*)SA(b, h) + aoff1 + m * 2048); }
; #define MMA(ai, bj, At, Btf) do { __builtin_amdgcn_s_setprio(1); \
;     for (int m = 0; m < 4; ++m) for (int n = 0; n < 2; ++n) for (int k = 0; k < 2; ++k) \
;       acc[ai][bj][m][n] = __builtin_amdgcn_mfma_f32_16x16x32_bf16(Btf[n][k], At[m][k], acc[ai][bj][m][n], 0, 0, 0); \
;     __builtin_amdgcn_s_setprio(0); } while (0)
; #define WAIT_L(n) asm volatile("s_waitcnt lgkmcnt(" #n ")" ::: "memory")
; #define BAR __builtin_amdgcn_s_barrier()
; template <int EPI> ...
;     ...
;     LDA(At, 1, 1); BAR; WAIT_L(0); MMA(1, 0, At, B0); MMA(1, 1, At, B1); BAR; }
	s_barrier
	v_mfma_f32_16x16x32_bf16 v[16:19], v[0:3], v[178:181], v[60:63]
	v_mfma_f32_16x16x32_bf16 v[60:63], v[12:15], v[182:185], v[16:19]
	v_mfma_f32_16x16x32_bf16 v[16:19], v[198:201], v[178:181], v[56:59]
	v_mfma_f32_16x16x32_bf16 v[48:51], v[202:205], v[182:185], v[16:19]
	v_mfma_f32_16x16x32_bf16 v[16:19], v[0:3], v[186:189], v[52:55]
	v_mfma_f32_16x16x32_bf16 v[44:47], v[12:15], v[190:193], v[16:19]
	v_mfma_f32_16x16x32_bf16 v[16:19], v[198:201], v[186:189], v[226:229]
	v_mfma_f32_16x16x32_bf16 v[32:35], v[202:205], v[190:193], v[16:19]
	v_mfma_f32_16x16x32_bf16 v[16:19], v[0:3], v[206:209], v[230:233]
	v_mfma_f32_16x16x32_bf16 v[0:3], v[0:3], v[238:241], v[36:39]
	v_mfma_f32_16x16x32_bf16 v[28:31], v[12:15], v[234:237], v[16:19]
	v_mfma_f32_16x16x32_bf16 v[16:19], v[198:201], v[206:209], v[40:43]
	v_mfma_f32_16x16x32_bf16 v[12:15], v[12:15], v[242:245], v[0:3]
	v_mfma_f32_16x16x32_bf16 v[0:3], v[198:201], v[238:241], v[162:165]
	v_mfma_f32_16x16x32_bf16 v[16:19], v[202:205], v[234:237], v[16:19]
	v_mfma_f32_16x16x32_bf16 v[0:3], v[202:205], v[242:245], v[0:3]
	v_mfma_f32_16x16x32_bf16 v[20:23], v[210:213], v[186:189], v[20:23]
	v_mfma_f32_16x16x32_bf16 v[36:39], v[210:213], v[178:181], v[166:169]
	v_mfma_f32_16x16x32_bf16 v[40:43], v[218:221], v[190:193], v[20:23]
	v_mfma_f32_16x16x32_bf16 v[20:23], v[214:217], v[186:189], v[170:173]
	v_mfma_f32_16x16x32_bf16 v[56:59], v[218:221], v[182:185], v[36:39]
	v_mfma_f32_16x16x32_bf16 v[24:27], v[214:217], v[178:181], v[24:27]
	v_mfma_f32_16x16x32_bf16 v[36:39], v[222:225], v[190:193], v[20:23]
	v_mfma_f32_16x16x32_bf16 v[20:23], v[210:213], v[206:209], v[174:177]
	v_mfma_f32_16x16x32_bf16 v[8:11], v[214:217], v[206:209], v[8:11]
	v_mfma_f32_16x16x32_bf16 v[4:7], v[210:213], v[238:241], v[4:7]
	v_mfma_f32_16x16x32_bf16 v[52:55], v[222:225], v[182:185], v[24:27]
	v_mfma_f32_16x16x32_bf16 v[24:27], v[218:221], v[234:237], v[20:23]
	v_mfma_f32_16x16x32_bf16 v[20:23], v[222:225], v[234:237], v[8:11]
	v_mfma_f32_16x16x32_bf16 v[8:11], v[218:221], v[242:245], v[4:7]
	v_mfma_f32_16x16x32_bf16 v[4:7], v[214:217], v[238:241], v[194:197]
	v_mfma_f32_16x16x32_bf16 v[4:7], v[222:225], v[242:245], v[4:7]
	s_barrier

; #define BAR __builtin_amdgcn_s_barrier()
; template <int EPI> ...
;     ...
;   if (wr == 0) BAR;
; template <int EPI>
; __device__ __forceinline__ void gemm_phase(const u16* A, const u16* Bt, int M, int N, int K, u16* out, int ldo,
;                                            const float* aux, int bid, int nblk, int wv) {
;     ...
;   for (int base = 0; base < ntile; base += nblk) {
;     int wgid;
;     if (base + nblk <= ntile && (nblk & 7) == 0) wgid = base + (bid & 7) * (nblk >> 3) + (bid >> 3);
;     else wgid = base + bid;
;     if (wgid >= ntile) break;
;     int nig = WGM * nN, gid = wgid / nig, fm = gid * WGM, gsz = min(nM - fm, WGM);
;     int pm = fm + ((wgid % nig) % gsz), pn = (wgid % nig) / gsz;
;     int brow = pm * BM, bcol = pn * BM;
;     gemm_tile<EPI>(A, Bt, K, brow, bcol, out, ldo, EPI == 1 ? pn * HALF : bcol, aux, tid);
	s_setprio 0
	s_and_saveexec_b64 s[66:67], s[2:3]
	s_cbranch_execz .LBB0_1099
	s_barrier
	s_branch .LBB0_1099

; #define STAGE(P, BASE, br, kt) do { const char* _gb = (const char*)(BASE) + ((size_t)(br) * K + (size_t)(kt) * BK) * 2; \
;     __builtin_amdgcn_global_load_lds((const unsigned*)(_gb + loff0), (unsigned*)((char*)(P) + tid * 16), 16, 0, 0); \
;     __builtin_amdgcn_global_load_lds((const unsigned*)(_gb + (size_t)K * 128 + loff0), (unsigned*)((char*)(P) + tid * 16 + 8192), 16, 0, 0); } while (0)
; #define BAR __builtin_amdgcn_s_barrier()
; template <int EPI> ...
;     ...
;   f32x4 acc[2][2][4][2] = {};
;   bf16x8 At[4][2], B0[2][2], B1[2][2];
;   int nt = K / BK;
;   const int aoff0 = lds_byte(wr * 64 + fr, fq * 8), aoff1 = lds_byte(wr * 64 + fr, 32 + fq * 8);
;   const int brw = wc * 32 + (fr >> 2) * 8 + (fr & 3);
;   const int boff0 = lds_byte(brw, fq * 8), boff1 = lds_byte(brw, 32 + fq * 8);
;   unsigned loff0;
;   { int _r, _c; stage_rc(tid * 16, _r, _c); loff0 = (unsigned)(_r * K + _c) * 2u; }
;   STAGE(SB(0, 0), Bt, bcol, 0); STAGE(SA(0, 0), A, brow, 0);
;   STAGE(SB(0, 1), Bt, bcol + HALF, 0); STAGE(SA(0, 1), A, brow + HALF, 0);
;   if (wr == 1) BAR;
; template <int EPI>
; __device__ __forceinline__ void gemm_phase(const u16* A, const u16* Bt, int M, int N, int K, u16* out, int ldo,
;                                            const float* aux, int bid, int nblk, int wv) {
;     ...
;   for (int base = 0; base < ntile; base += nblk) {
;     int wgid;
;     if (base + nblk <= ntile && (nblk & 7) == 0) wgid = base + (bid & 7) * (nblk >> 3) + (bid >> 3);
;     else wgid = base + bid;
;     if (wgid >= ntile) break;
;     int nig = WGM * nN, gid = wgid / nig, fm = gid * WGM, gsz = min(nM - fm, WGM);
;     int pm = fm + ((wgid % nig) % gsz), pn = (wgid % nig) / gsz;
;     int brow = pm * BM, bcol = pn * BM;
.LBB0_1148:
	s_mov_b32 s60, s70
	s_add_i32 s70, s70, s33
	s_cmpk_lt_i32 s70, 0x401
	s_cselect_b64 s[58:59], -1, 0
	s_and_b64 s[58:59], s[44:45], s[58:59]
	s_and_b64 s[58:59], s[58:59], exec
	s_cselect_b32 s58, s86, s91
	s_add_i32 s60, s58, s60
	s_cmpk_gt_i32 s60, 0x3ff
	s_mov_b64 s[58:59], -1
	s_cbranch_scc1 .LBB0_1147
	s_sub_i32 s60, 0x3ff, s60
	s_ashr_i32 s58, s60, 31
	s_lshr_b32 s58, s58, 26
	s_add_i32 s58, s60, s58
	s_and_b32 s59, s58, 0xffc0
	s_sub_i32 s59, s60, s59
	s_bfe_i32 s60, s59, 0x80000
	s_bfe_u32 s60, s60, 0x3000c
	s_add_i32 s60, s59, s60
	s_bfe_i32 s61, s60, 0x80000
	s_and_b32 s60, s60, 0xf8
	s_sub_i32 s59, s59, s60
	s_sext_i32_i16 s61, s61
	s_sext_i32_i8 s59, s59
	s_lshl_b32 s58, s58, 5
	s_ashr_i32 s62, s61, 3
	s_and_b32 s58, s58, 0xfffff800
	s_lshl_b32 s71, s59, 8
	s_add_i32 s71, s71, s58
	s_lshl_b32 s58, s62, 8
	s_mul_i32 s64, s62, 0x2c0000
	s_mul_hi_i32 s65, s58, 0x2c00
	s_add_u32 s60, s66, s64
	s_addc_u32 s61, s67, s65
	v_readfirstlane_b32 s59, v135
	s_mul_i32 s75, s71, 0x2c00
	v_lshl_add_u64 v[0:1], s[60:61], 0, v[128:129]
	s_mov_b32 m0, s59
	v_readfirstlane_b32 s59, v136
	s_mul_hi_i32 s74, s71, 0x2c00
	s_add_u32 s60, s14, s75
	global_load_lds_dwordx4 v[0:1], off
	v_lshl_add_u64 v[2:3], v[0:1], 0, s[8:9]
	s_mov_b32 m0, s59
	s_addc_u32 s61, s43, s74
	global_load_lds_dwordx4 v[2:3], off
	v_lshl_add_u64 v[2:3], s[60:61], 0, v[128:129]
	s_mul_i32 s60, s62, 0x160000
	v_readfirstlane_b32 s59, v137
	s_ashr_i32 s61, s60, 31
	s_mov_b32 m0, s59
	v_readfirstlane_b32 s59, v138
	s_lshl_b64 s[60:61], s[60:61], 1
	global_load_lds_dwordx4 v[2:3], off
	s_mov_b32 m0, s59
	s_add_u32 s59, s66, s60
	s_addc_u32 s63, s67, s61
	s_add_u32 s62, s59, 0x160000
	v_lshl_add_u64 v[4:5], v[2:3], 0, s[8:9]
	s_addc_u32 s63, s63, 0
	v_readfirstlane_b32 s59, v139
	global_load_lds_dwordx4 v[4:5], off
	v_lshl_add_u64 v[4:5], s[62:63], 0, v[128:129]
	s_mov_b32 m0, s59
	v_readfirstlane_b32 s59, v140
	global_load_lds_dwordx4 v[4:5], off
	s_mov_b32 m0, s59
	s_or_b32 s59, s71, 0x80
	s_mul_i32 s73, s59, 0x2c00
	s_mul_hi_i32 s72, s59, 0x2c00
	s_add_u32 s62, s14, s73
	v_lshl_add_u64 v[6:7], v[4:5], 0, s[8:9]
	s_addc_u32 s63, s43, s72
	v_readfirstlane_b32 s59, v141
	global_load_lds_dwordx4 v[6:7], off
	v_lshl_add_u64 v[6:7], s[62:63], 0, v[128:129]
	s_mov_b32 m0, s59
	v_readfirstlane_b32 s59, v142
	global_load_lds_dwordx4 v[6:7], off
	v_lshl_add_u64 v[6:7], v[6:7], 0, s[8:9]
	s_mov_b32 m0, s59
	s_nop 0
	global_load_lds_dwordx4 v[6:7], off
	v_mov_b32_e32 v8, 0
	v_mov_b32_e32 v9, 0
	v_mov_b32_e32 v10, 0
	v_mov_b32_e32 v11, 0
	v_mov_b32_e32 v12, 0
	v_mov_b32_e32 v13, 0
	v_mov_b32_e32 v14, 0
	v_mov_b32_e32 v15, 0
	v_mov_b32_e32 v16, 0
	v_mov_b32_e32 v17, 0
	v_mov_b32_e32 v18, 0
	v_mov_b32_e32 v19, 0
	v_mov_b32_e32 v20, 0
	v_mov_b32_e32 v21, 0
	v_mov_b32_e32 v22, 0
	v_mov_b32_e32 v23, 0
	v_mov_b32_e32 v24, 0
	v_mov_b32_e32 v25, 0
	v_mov_b32_e32 v26, 0
	v_mov_b32_e32 v27, 0
	v_mov_b32_e32 v28, 0
	v_mov_b32_e32 v29, 0
	v_mov_b32_e32 v30, 0
	v_mov_b32_e32 v31, 0
	v_mov_b32_e32 v32, 0
	v_mov_b32_e32 v33, 0
	v_mov_b32_e32 v34, 0
	v_mov_b32_e32 v35, 0
	v_mov_b32_e32 v36, 0
	v_mov_b32_e32 v37, 0
	v_mov_b32_e32 v38, 0
	v_mov_b32_e32 v39, 0
	v_mov_b32_e32 v40, 0
	v_mov_b32_e32 v41, 0
	v_mov_b32_e32 v42, 0
	v_mov_b32_e32 v43, 0
	v_mov_b32_e32 v44, 0
	v_mov_b32_e32 v45, 0
	v_mov_b32_e32 v46, 0
	v_mov_b32_e32 v47, 0
	v_mov_b32_e32 v48, 0
	v_mov_b32_e32 v49, 0
	v_mov_b32_e32 v50, 0
	v_mov_b32_e32 v51, 0
	v_mov_b32_e32 v52, 0
	v_mov_b32_e32 v53, 0
	v_mov_b32_e32 v54, 0
	v_mov_b32_e32 v55, 0
	v_mov_b32_e32 v56, 0
	v_mov_b32_e32 v57, 0
	v_mov_b32_e32 v58, 0
	v_mov_b32_e32 v59, 0
	v_mov_b32_e32 v60, 0
	v_mov_b32_e32 v61, 0
	v_mov_b32_e32 v62, 0
	v_mov_b32_e32 v63, 0
	v_mov_b32_e32 v64, 0
	v_mov_b32_e32 v65, 0
	v_mov_b32_e32 v66, 0
	v_mov_b32_e32 v67, 0
	v_mov_b32_e32 v68, 0
	v_mov_b32_e32 v69, 0
	v_mov_b32_e32 v70, 0
	v_mov_b32_e32 v71, 0
	v_mov_b32_e32 v72, 0
	v_mov_b32_e32 v73, 0
	v_mov_b32_e32 v74, 0
	v_mov_b32_e32 v75, 0
	v_mov_b32_e32 v76, 0
	v_mov_b32_e32 v77, 0
	v_mov_b32_e32 v78, 0
	v_mov_b32_e32 v79, 0
	v_mov_b32_e32 v80, 0
	v_mov_b32_e32 v81, 0
	v_mov_b32_e32 v82, 0
	v_mov_b32_e32 v83, 0
	v_mov_b32_e32 v84, 0
	v_mov_b32_e32 v85, 0
	v_mov_b32_e32 v86, 0
	v_mov_b32_e32 v87, 0
	v_mov_b32_e32 v88, 0
	v_mov_b32_e32 v89, 0
	v_mov_b32_e32 v90, 0
	v_mov_b32_e32 v91, 0
	v_mov_b32_e32 v92, 0
	v_mov_b32_e32 v93, 0
	v_mov_b32_e32 v94, 0
	v_mov_b32_e32 v95, 0
	v_mov_b32_e32 v96, 0
	v_mov_b32_e32 v97, 0
	v_mov_b32_e32 v98, 0
	v_mov_b32_e32 v99, 0
	v_mov_b32_e32 v100, 0
	v_mov_b32_e32 v101, 0
	v_mov_b32_e32 v102, 0
	v_mov_b32_e32 v103, 0
	v_mov_b32_e32 v104, 0
	v_mov_b32_e32 v105, 0
	v_mov_b32_e32 v106, 0
	v_mov_b32_e32 v107, 0
	v_mov_b32_e32 v108, 0
	v_mov_b32_e32 v109, 0
	v_mov_b32_e32 v110, 0
	v_mov_b32_e32 v111, 0
	v_mov_b32_e32 v112, 0
	v_mov_b32_e32 v113, 0
	v_mov_b32_e32 v114, 0
	v_mov_b32_e32 v115, 0
	v_mov_b32_e32 v116, 0
	v_mov_b32_e32 v117, 0
	v_mov_b32_e32 v118, 0
	v_mov_b32_e32 v119, 0
	v_mov_b32_e32 v120, 0
	v_mov_b32_e32 v121, 0
	v_mov_b32_e32 v122, 0
	v_mov_b32_e32 v123, 0
	v_mov_b32_e32 v124, 0
	v_mov_b32_e32 v125, 0
	v_mov_b32_e32 v126, 0
	v_mov_b32_e32 v127, 0
	s_and_saveexec_b64 s[62:63], s[4:5]
	s_cbranch_execz .LBB0_1151
	s_setprio 1
	s_barrier

; #define STAGE(P, BASE, br, kt) do { const char* _gb = (const char*)(BASE) + ((size_t)(br) * K + (size_t)(kt) * BK) * 2; \
;     __builtin_amdgcn_global_load_lds((const unsigned*)(_gb + loff0), (unsigned*)((char*)(P) + tid * 16), 16, 0, 0); \
;     __builtin_amdgcn_global_load_lds((const unsigned*)(_gb + (size_t)K * 128 + loff0), (unsigned*)((char*)(P) + tid * 16 + 8192), 16, 0, 0); } while (0)
; #define LDA(dst, b, h) for (int m = 0; m < 4; ++m) { \
;     dst[m][0] = *reinterpret_cast<const bf16x8*>((char*)SA(b, h) + aoff0 + m * 2048); \
;     dst[m][1] = *reinterpret_cast<const bf16x8*>((char*)SA(b, h) + aoff1 + m * 2048); }
; #define LDB(dst, b, h) for (int n = 0; n < 2; ++n) { \
;     dst[n][0] = *reinterpret_cast<const bf16x8*>((char*)SB(b, h) + boff0 + n * 256); \
;     dst[n][1] = *reinterpret_cast<const bf16x8*>((char*)SB(b, h) + boff1 + n * 256); }
; #define MMA(ai, bj, At, Btf) do { __builtin_amdgcn_s_setprio(1); \
;     for (int m = 0; m < 4; ++m) for (int n = 0; n < 2; ++n) for (int k = 0; k < 2; ++k) \
;       acc[ai][bj][m][n] = __builtin_amdgcn_mfma_f32_16x16x32_bf16(Btf[n][k], At[m][k], acc[ai][bj][m][n], 0, 0, 0); \
;     __builtin_amdgcn_s_setprio(0); } while (0)
; #define WAIT_L(n) asm volatile("s_waitcnt lgkmcnt(" #n ")" ::: "memory")
; #define BAR __builtin_amdgcn_s_barrier()
; #define SCHED __builtin_amdgcn_sched_barrier(0)
; template <int EPI> ...
;     ...
;     LDB(B0, 0, 0); SCHED; LDA(At, 0, 0); STAGE(SA(1, 1), A, brow + HALF, t + 1);
;     WAIT_L(8); BAR; WAIT_L(0); MMA(0, 0, At, B0); BAR; SCHED;
;     LDB(B1, 0, 1); STAGE(SB(0, 0), Bt, bcol, t + 2);
.LBB0_1152:
	ds_read_b128 v[160:163], v152
	ds_read_b128 v[164:167], v152 offset:256
	ds_read_b128 v[168:171], v153
	ds_read_b128 v[172:175], v153 offset:256
	v_lshl_add_u64 v[224:225], s[62:63], 0, v[132:133]
	v_readfirstlane_b32 s75, v150
	v_lshl_add_u64 v[208:209], v[224:225], 0, s[16:17]
	s_mov_b32 m0, s75
	v_readfirstlane_b32 s75, v151
	ds_read_b128 v[176:179], v149
	ds_read_b128 v[180:183], v149 offset:1024
	ds_read_b128 v[184:187], v149 offset:2048
	ds_read_b128 v[188:191], v149 offset:3072
	ds_read_b128 v[192:195], v149 offset:4096
	ds_read_b128 v[196:199], v149 offset:5120
	ds_read_b128 v[200:203], v149 offset:6144
	ds_read_b128 v[204:207], v149 offset:7168
	global_load_lds_dwordx4 v[208:209], off
	v_lshl_add_u64 v[208:209], v[224:225], 0, s[18:19]
	s_mov_b32 m0, s75
	s_nop 0
	global_load_lds_dwordx4 v[208:209], off
	s_waitcnt lgkmcnt(8)
	v_readfirstlane_b32 s75, v148
	v_lshl_add_u64 v[246:247], v[228:229], 0, s[56:57]
	s_mov_b32 m0, s75
	s_nop 0
	global_load_lds_dwordx4 v[246:247], off
	ds_read_b128 v[208:211], v154
	ds_read_b128 v[212:215], v154 offset:256
	ds_read_b128 v[216:219], v155
	ds_read_b128 v[220:223], v155 offset:256
	s_waitcnt lgkmcnt(0)

; #define STAGE(P, BASE, br, kt) do { const char* _gb = (const char*)(BASE) + ((size_t)(br) * K + (size_t)(kt) * BK) * 2; \
;     __builtin_amdgcn_global_load_lds((const unsigned*)(_gb + loff0), (unsigned*)((char*)(P) + tid * 16), 16, 0, 0); \
;     __builtin_amdgcn_global_load_lds((const unsigned*)(_gb + (size_t)K * 128 + loff0), (unsigned*)((char*)(P) + tid * 16 + 8192), 16, 0, 0); } while (0)
; #define LDB(dst, b, h) for (int n = 0; n < 2; ++n) { \
;     dst[n][0] = *reinterpret_cast<const bf16x8*>((char*)SB(b, h) + boff0 + n * 256); \
;     dst[n][1] = *reinterpret_cast<const bf16x8*>((char*)SB(b, h) + boff1 + n * 256); }
; #define MMA(ai, bj, At, Btf) do { __builtin_amdgcn_s_setprio(1); \
;     for (int m = 0; m < 4; ++m) for (int n = 0; n < 2; ++n) for (int k = 0; k < 2; ++k) \
;       acc[ai][bj][m][n] = __builtin_amdgcn_mfma_f32_16x16x32_bf16(Btf[n][k], At[m][k], acc[ai][bj][m][n], 0, 0, 0); \
;     __builtin_amdgcn_s_setprio(0); } while (0)
; #define WAIT_L(n) asm volatile("s_waitcnt lgkmcnt(" #n ")" ::: "memory")
; #define BAR __builtin_amdgcn_s_barrier()
; #define SCHED __builtin_amdgcn_sched_barrier(0)
; template <int EPI> ...
;     ...
;     WAIT_L(8); BAR; WAIT_L(0); MMA(0, 0, At, B0); BAR; SCHED;
;     LDB(B1, 0, 1); STAGE(SB(0, 0), Bt, bcol, t + 2);
;     BAR; WAIT_L(0); MMA(0, 1, At, B1); BAR;
	s_barrier
	v_mfma_f32_16x16x32_bf16 v[124:127], v[160:163], v[176:179], v[124:127]
	v_mfma_f32_16x16x32_bf16 v[120:123], v[164:167], v[176:179], v[120:123]
	v_mfma_f32_16x16x32_bf16 v[116:119], v[160:163], v[184:187], v[116:119]
	v_mfma_f32_16x16x32_bf16 v[112:115], v[164:167], v[184:187], v[112:115]
	v_mfma_f32_16x16x32_bf16 v[108:111], v[160:163], v[192:195], v[108:111]
	v_mfma_f32_16x16x32_bf16 v[104:107], v[164:167], v[192:195], v[104:107]
	v_mfma_f32_16x16x32_bf16 v[100:103], v[160:163], v[200:203], v[100:103]
	v_mfma_f32_16x16x32_bf16 v[96:99], v[164:167], v[200:203], v[96:99]
	v_mfma_f32_16x16x32_bf16 v[124:127], v[168:171], v[180:183], v[124:127]
	v_mfma_f32_16x16x32_bf16 v[120:123], v[172:175], v[180:183], v[120:123]
	v_mfma_f32_16x16x32_bf16 v[116:119], v[168:171], v[188:191], v[116:119]
	v_mfma_f32_16x16x32_bf16 v[112:115], v[172:175], v[188:191], v[112:115]
	v_mfma_f32_16x16x32_bf16 v[108:111], v[168:171], v[196:199], v[108:111]
	v_mfma_f32_16x16x32_bf16 v[104:107], v[172:175], v[196:199], v[104:107]
	v_mfma_f32_16x16x32_bf16 v[100:103], v[168:171], v[204:207], v[100:103]
	v_mfma_f32_16x16x32_bf16 v[96:99], v[172:175], v[204:207], v[96:99]
	v_mfma_f32_16x16x32_bf16 v[92:95], v[208:211], v[176:179], v[92:95]
	v_mfma_f32_16x16x32_bf16 v[88:91], v[212:215], v[176:179], v[88:91]
	v_mfma_f32_16x16x32_bf16 v[84:87], v[208:211], v[184:187], v[84:87]
	v_mfma_f32_16x16x32_bf16 v[80:83], v[212:215], v[184:187], v[80:83]
	v_mfma_f32_16x16x32_bf16 v[76:79], v[208:211], v[192:195], v[76:79]
	v_mfma_f32_16x16x32_bf16 v[72:75], v[212:215], v[192:195], v[72:75]
	v_mfma_f32_16x16x32_bf16 v[68:71], v[208:211], v[200:203], v[68:71]
	v_mfma_f32_16x16x32_bf16 v[64:67], v[212:215], v[200:203], v[64:67]
	v_mfma_f32_16x16x32_bf16 v[92:95], v[216:219], v[180:183], v[92:95]
	v_mfma_f32_16x16x32_bf16 v[88:91], v[220:223], v[180:183], v[88:91]
	v_mfma_f32_16x16x32_bf16 v[84:87], v[216:219], v[188:191], v[84:87]
	v_mfma_f32_16x16x32_bf16 v[80:83], v[220:223], v[188:191], v[80:83]
	v_mfma_f32_16x16x32_bf16 v[76:79], v[216:219], v[196:199], v[76:79]
	v_mfma_f32_16x16x32_bf16 v[72:75], v[220:223], v[196:199], v[72:75]
	v_mfma_f32_16x16x32_bf16 v[68:71], v[216:219], v[204:207], v[68:71]
	v_mfma_f32_16x16x32_bf16 v[64:67], v[220:223], v[204:207], v[64:67]
	s_barrier

; #define STAGE(P, BASE, br, kt) do { const char* _gb = (const char*)(BASE) + ((size_t)(br) * K + (size_t)(kt) * BK) * 2; \
;     __builtin_amdgcn_global_load_lds((const unsigned*)(_gb + loff0), (unsigned*)((char*)(P) + tid * 16), 16, 0, 0); \
;     __builtin_amdgcn_global_load_lds((const unsigned*)(_gb + (size_t)K * 128 + loff0), (unsigned*)((char*)(P) + tid * 16 + 8192), 16, 0, 0); } while (0)
; #define LDA(dst, b, h) for (int m = 0; m < 4; ++m) { \
;     dst[m][0] = *reinterpret_cast<const bf16x8*>((char*)SA(b, h) + aoff0 + m * 2048); \
;     dst[m][1] = *reinterpret_cast<const bf16x8*>((char*)SA(b, h) + aoff1 + m * 2048); }
; #define MMA(ai, bj, At, Btf) do { __builtin_amdgcn_s_setprio(1); \
;     for (int m = 0; m < 4; ++m) for (int n = 0; n < 2; ++n) for (int k = 0; k < 2; ++k) \
;       acc[ai][bj][m][n] = __builtin_amdgcn_mfma_f32_16x16x32_bf16(Btf[n][k], At[m][k], acc[ai][bj][m][n], 0, 0, 0); \
;     __builtin_amdgcn_s_setprio(0); } while (0)
; #define WAIT_V(n) asm volatile("s_waitcnt vmcnt(" #n ")" ::: "memory")
; #define WAIT_L(n) asm volatile("s_waitcnt lgkmcnt(" #n ")" ::: "memory")
; #define BAR __builtin_amdgcn_s_barrier()
; #define SCHED __builtin_amdgcn_sched_barrier(0)
; template <int EPI> ...
;     ...
;     LDA(At, 0, 1); STAGE(SA(0, 0), A, brow, t + 2);
;     BAR; WAIT_L(0); MMA(1, 0, At, B0); BAR; SCHED;
;     STAGE(SB(0, 1), Bt, bcol + HALF, t + 2);
;     WAIT_V(6); BAR; MMA(1, 1, At, B1); BAR;
	v_lshl_add_u64 v[226:227], s[64:65], 0, v[132:133]
	v_readfirstlane_b32 s75, v135
	v_lshl_add_u64 v[228:229], v[226:227], 0, s[20:21]
	s_mov_b32 m0, s75
	v_readfirstlane_b32 s75, v136
	global_load_lds_dwordx4 v[228:229], off
	v_lshl_add_u64 v[228:229], v[226:227], 0, s[22:23]
	s_mov_b32 m0, s75
	s_nop 0
	global_load_lds_dwordx4 v[228:229], off
	v_readfirstlane_b32 s75, v137
	v_lshl_add_u64 v[228:229], v[224:225], 0, s[24:25]
	s_mov_b32 m0, s75
	v_readfirstlane_b32 s75, v138
	ds_read_b128 v[176:179], v149 offset:16384
	ds_read_b128 v[180:183], v149 offset:17408
	ds_read_b128 v[184:187], v149 offset:18432
	ds_read_b128 v[188:191], v149 offset:19456
	ds_read_b128 v[192:195], v149 offset:20480
	ds_read_b128 v[196:199], v149 offset:21504
	ds_read_b128 v[200:203], v149 offset:22528
	ds_read_b128 v[204:207], v149 offset:23552
	global_load_lds_dwordx4 v[228:229], off
	v_lshl_add_u64 v[228:229], v[224:225], 0, s[26:27]
	s_mov_b32 m0, s75
	s_nop 0
	global_load_lds_dwordx4 v[228:229], off
	v_lshl_add_u64 v[228:229], s[60:61], 0, v[132:133]
	v_readfirstlane_b32 s75, v139
	v_lshl_add_u64 v[246:247], v[228:229], 0, s[28:29]
	s_mov_b32 m0, s75
	v_readfirstlane_b32 s75, v140
	global_load_lds_dwordx4 v[246:247], off
	s_waitcnt vmcnt(5)
	s_waitcnt lgkmcnt(0)

; #define STAGE(P, BASE, br, kt) do { const char* _gb = (const char*)(BASE) + ((size_t)(br) * K + (size_t)(kt) * BK) * 2; \
;     __builtin_amdgcn_global_load_lds((const unsigned*)(_gb + loff0), (unsigned*)((char*)(P) + tid * 16), 16, 0, 0); \
;     __builtin_amdgcn_global_load_lds((const unsigned*)(_gb + (size_t)K * 128 + loff0), (unsigned*)((char*)(P) + tid * 16 + 8192), 16, 0, 0); } while (0)
; #define MMA(ai, bj, At, Btf) do { __builtin_amdgcn_s_setprio(1); \
;     for (int m = 0; m < 4; ++m) for (int n = 0; n < 2; ++n) for (int k = 0; k < 2; ++k) \
;       acc[ai][bj][m][n] = __builtin_amdgcn_mfma_f32_16x16x32_bf16(Btf[n][k], At[m][k], acc[ai][bj][m][n], 0, 0, 0); \
;     __builtin_amdgcn_s_setprio(0); } while (0)
; #define WAIT_V(n) asm volatile("s_waitcnt vmcnt(" #n ")" ::: "memory")
; #define WAIT_L(n) asm volatile("s_waitcnt lgkmcnt(" #n ")" ::: "memory")
; #define BAR __builtin_amdgcn_s_barrier()
; #define SCHED __builtin_amdgcn_sched_barrier(0)
; template <int EPI> ...
;     ...
;     BAR; WAIT_L(0); MMA(1, 0, At, B0); BAR; SCHED;
;     STAGE(SB(0, 1), Bt, bcol + HALF, t + 2);
;     WAIT_V(6); BAR; MMA(1, 1, At, B1); BAR;
	s_barrier
	v_mfma_f32_16x16x32_bf16 v[60:63], v[160:163], v[176:179], v[60:63]
	v_mfma_f32_16x16x32_bf16 v[56:59], v[164:167], v[176:179], v[56:59]
	v_mfma_f32_16x16x32_bf16 v[52:55], v[160:163], v[184:187], v[52:55]
	v_mfma_f32_16x16x32_bf16 v[48:51], v[164:167], v[184:187], v[48:51]
	v_mfma_f32_16x16x32_bf16 v[44:47], v[160:163], v[192:195], v[44:47]
	v_mfma_f32_16x16x32_bf16 v[40:43], v[164:167], v[192:195], v[40:43]
	v_mfma_f32_16x16x32_bf16 v[36:39], v[160:163], v[200:203], v[36:39]
	v_mfma_f32_16x16x32_bf16 v[32:35], v[164:167], v[200:203], v[32:35]
	v_mfma_f32_16x16x32_bf16 v[60:63], v[168:171], v[180:183], v[60:63]
	v_mfma_f32_16x16x32_bf16 v[56:59], v[172:175], v[180:183], v[56:59]
	v_mfma_f32_16x16x32_bf16 v[52:55], v[168:171], v[188:191], v[52:55]
	v_mfma_f32_16x16x32_bf16 v[48:51], v[172:175], v[188:191], v[48:51]
	v_mfma_f32_16x16x32_bf16 v[44:47], v[168:171], v[196:199], v[44:47]
	v_mfma_f32_16x16x32_bf16 v[40:43], v[172:175], v[196:199], v[40:43]
	v_mfma_f32_16x16x32_bf16 v[36:39], v[168:171], v[204:207], v[36:39]
	v_mfma_f32_16x16x32_bf16 v[32:35], v[172:175], v[204:207], v[32:35]
	v_mfma_f32_16x16x32_bf16 v[28:31], v[208:211], v[176:179], v[28:31]
	v_mfma_f32_16x16x32_bf16 v[24:27], v[212:215], v[176:179], v[24:27]
	v_mfma_f32_16x16x32_bf16 v[20:23], v[208:211], v[184:187], v[20:23]
	v_mfma_f32_16x16x32_bf16 v[16:19], v[212:215], v[184:187], v[16:19]
	v_mfma_f32_16x16x32_bf16 v[12:15], v[208:211], v[192:195], v[12:15]
	v_mfma_f32_16x16x32_bf16 v[8:11], v[212:215], v[192:195], v[8:11]
	v_mfma_f32_16x16x32_bf16 v[4:7], v[208:211], v[200:203], v[4:7]
	v_mfma_f32_16x16x32_bf16 v[0:3], v[212:215], v[200:203], v[0:3]
	v_mfma_f32_16x16x32_bf16 v[28:31], v[216:219], v[180:183], v[28:31]
	v_mfma_f32_16x16x32_bf16 v[24:27], v[220:223], v[180:183], v[24:27]
	v_mfma_f32_16x16x32_bf16 v[20:23], v[216:219], v[188:191], v[20:23]
	v_mfma_f32_16x16x32_bf16 v[16:19], v[220:223], v[188:191], v[16:19]
	v_mfma_f32_16x16x32_bf16 v[12:15], v[216:219], v[196:199], v[12:15]
	v_mfma_f32_16x16x32_bf16 v[8:11], v[220:223], v[196:199], v[8:11]
	v_mfma_f32_16x16x32_bf16 v[4:7], v[216:219], v[204:207], v[4:7]
	v_mfma_f32_16x16x32_bf16 v[0:3], v[220:223], v[204:207], v[0:3]
	s_barrier

; #define STAGE(P, BASE, br, kt) do { const char* _gb = (const char*)(BASE) + ((size_t)(br) * K + (size_t)(kt) * BK) * 2; \
;     __builtin_amdgcn_global_load_lds((const unsigned*)(_gb + loff0), (unsigned*)((char*)(P) + tid * 16), 16, 0, 0); \
;     __builtin_amdgcn_global_load_lds((const unsigned*)(_gb + (size_t)K * 128 + loff0), (unsigned*)((char*)(P) + tid * 16 + 8192), 16, 0, 0); } while (0)
; #define LDA(dst, b, h) for (int m = 0; m < 4; ++m) { \
;     dst[m][0] = *reinterpret_cast<const bf16x8*>((char*)SA(b, h) + aoff0 + m * 2048); \
;     dst[m][1] = *reinterpret_cast<const bf16x8*>((char*)SA(b, h) + aoff1 + m * 2048); }
; #define LDB(dst, b, h) for (int n = 0; n < 2; ++n) { \
;     dst[n][0] = *reinterpret_cast<const bf16x8*>((char*)SB(b, h) + boff0 + n * 256); \
;     dst[n][1] = *reinterpret_cast<const bf16x8*>((char*)SB(b, h) + boff1 + n * 256); }
; #define MMA(ai, bj, At, Btf) do { __builtin_amdgcn_s_setprio(1); \
;     for (int m = 0; m < 4; ++m) for (int n = 0; n < 2; ++n) for (int k = 0; k < 2; ++k) \
;       acc[ai][bj][m][n] = __builtin_amdgcn_mfma_f32_16x16x32_bf16(Btf[n][k], At[m][k], acc[ai][bj][m][n], 0, 0, 0); \
;     __builtin_amdgcn_s_setprio(0); } while (0)
; #define WAIT_L(n) asm volatile("s_waitcnt lgkmcnt(" #n ")" ::: "memory")
; #define BAR __builtin_amdgcn_s_barrier()
; #define SCHED __builtin_amdgcn_sched_barrier(0)
; template <int EPI> ...
;     ...
;     LDB(B0, 1, 0); SCHED; LDA(At, 1, 0); STAGE(SA(0, 1), A, brow + HALF, t + 2);
;     WAIT_L(8); BAR; WAIT_L(0); MMA(0, 0, At, B0); BAR; SCHED;
;     LDB(B1, 1, 1); STAGE(SB(1, 0), Bt, bcol, t + 3);
	ds_read_b128 v[160:163], v156
	ds_read_b128 v[164:167], v156 offset:256
	ds_read_b128 v[168:171], v157
	ds_read_b128 v[172:175], v157 offset:256
	v_readfirstlane_b32 s75, v141
	v_lshl_add_u64 v[208:209], v[224:225], 0, s[36:37]
	s_mov_b32 m0, s75
	v_readfirstlane_b32 s75, v142
	ds_read_b128 v[176:179], v149 offset:32768
	ds_read_b128 v[180:183], v149 offset:33792
	ds_read_b128 v[184:187], v149 offset:34816
	ds_read_b128 v[188:191], v149 offset:35840
	ds_read_b128 v[192:195], v149 offset:36864
	ds_read_b128 v[196:199], v149 offset:37888
	ds_read_b128 v[200:203], v149 offset:38912
	ds_read_b128 v[204:207], v149 offset:39936
	global_load_lds_dwordx4 v[208:209], off
	v_lshl_add_u64 v[208:209], v[224:225], 0, s[38:39]
	s_mov_b32 m0, s75
	s_nop 0
	global_load_lds_dwordx4 v[208:209], off
	s_waitcnt lgkmcnt(8)
	v_readfirstlane_b32 s75, v140
	v_lshl_add_u64 v[246:247], v[228:229], 0, s[30:31]
	s_mov_b32 m0, s75
	s_nop 0
	global_load_lds_dwordx4 v[246:247], off
	ds_read_b128 v[208:211], v158
	ds_read_b128 v[212:215], v158 offset:256
	ds_read_b128 v[216:219], v159
	ds_read_b128 v[220:223], v159 offset:256
	s_waitcnt lgkmcnt(0)

; #define STAGE(P, BASE, br, kt) do { const char* _gb = (const char*)(BASE) + ((size_t)(br) * K + (size_t)(kt) * BK) * 2; \
;     __builtin_amdgcn_global_load_lds((const unsigned*)(_gb + loff0), (unsigned*)((char*)(P) + tid * 16), 16, 0, 0); \
;     __builtin_amdgcn_global_load_lds((const unsigned*)(_gb + (size_t)K * 128 + loff0), (unsigned*)((char*)(P) + tid * 16 + 8192), 16, 0, 0); } while (0)
; #define LDB(dst, b, h) for (int n = 0; n < 2; ++n) { \
;     dst[n][0] = *reinterpret_cast<const bf16x8*>((char*)SB(b, h) + boff0 + n * 256); \
;     dst[n][1] = *reinterpret_cast<const bf16x8*>((char*)SB(b, h) + boff1 + n * 256); }
; #define MMA(ai, bj, At, Btf) do { __builtin_amdgcn_s_setprio(1); \
;     for (int m = 0; m < 4; ++m) for (int n = 0; n < 2; ++n) for (int k = 0; k < 2; ++k) \
;       acc[ai][bj][m][n] = __builtin_amdgcn_mfma_f32_16x16x32_bf16(Btf[n][k], At[m][k], acc[ai][bj][m][n], 0, 0, 0); \
;     __builtin_amdgcn_s_setprio(0); } while (0)
; #define WAIT_L(n) asm volatile("s_waitcnt lgkmcnt(" #n ")" ::: "memory")
; #define BAR __builtin_amdgcn_s_barrier()
; #define SCHED __builtin_amdgcn_sched_barrier(0)
; template <int EPI> ...
;     ...
;     WAIT_L(8); BAR; WAIT_L(0); MMA(0, 0, At, B0); BAR; SCHED;
;     LDB(B1, 1, 1); STAGE(SB(1, 0), Bt, bcol, t + 3);
;     BAR; WAIT_L(0); MMA(0, 1, At, B1); BAR;
	s_barrier
	v_mfma_f32_16x16x32_bf16 v[124:127], v[160:163], v[176:179], v[124:127]
	v_mfma_f32_16x16x32_bf16 v[120:123], v[164:167], v[176:179], v[120:123]
	v_mfma_f32_16x16x32_bf16 v[116:119], v[160:163], v[184:187], v[116:119]
	v_mfma_f32_16x16x32_bf16 v[112:115], v[164:167], v[184:187], v[112:115]
	v_mfma_f32_16x16x32_bf16 v[108:111], v[160:163], v[192:195], v[108:111]
	v_mfma_f32_16x16x32_bf16 v[104:107], v[164:167], v[192:195], v[104:107]
	v_mfma_f32_16x16x32_bf16 v[100:103], v[160:163], v[200:203], v[100:103]
	v_mfma_f32_16x16x32_bf16 v[96:99], v[164:167], v[200:203], v[96:99]
	v_mfma_f32_16x16x32_bf16 v[124:127], v[168:171], v[180:183], v[124:127]
	v_mfma_f32_16x16x32_bf16 v[120:123], v[172:175], v[180:183], v[120:123]
	v_mfma_f32_16x16x32_bf16 v[116:119], v[168:171], v[188:191], v[116:119]
	v_mfma_f32_16x16x32_bf16 v[112:115], v[172:175], v[188:191], v[112:115]
	v_mfma_f32_16x16x32_bf16 v[108:111], v[168:171], v[196:199], v[108:111]
	v_mfma_f32_16x16x32_bf16 v[104:107], v[172:175], v[196:199], v[104:107]
	v_mfma_f32_16x16x32_bf16 v[100:103], v[168:171], v[204:207], v[100:103]
	v_mfma_f32_16x16x32_bf16 v[96:99], v[172:175], v[204:207], v[96:99]
	v_mfma_f32_16x16x32_bf16 v[92:95], v[208:211], v[176:179], v[92:95]
	v_mfma_f32_16x16x32_bf16 v[88:91], v[212:215], v[176:179], v[88:91]
	v_mfma_f32_16x16x32_bf16 v[84:87], v[208:211], v[184:187], v[84:87]
	v_mfma_f32_16x16x32_bf16 v[80:83], v[212:215], v[184:187], v[80:83]
	v_mfma_f32_16x16x32_bf16 v[76:79], v[208:211], v[192:195], v[76:79]
	v_mfma_f32_16x16x32_bf16 v[72:75], v[212:215], v[192:195], v[72:75]
	v_mfma_f32_16x16x32_bf16 v[68:71], v[208:211], v[200:203], v[68:71]
	v_mfma_f32_16x16x32_bf16 v[64:67], v[212:215], v[200:203], v[64:67]
	v_mfma_f32_16x16x32_bf16 v[92:95], v[216:219], v[180:183], v[92:95]
	v_mfma_f32_16x16x32_bf16 v[88:91], v[220:223], v[180:183], v[88:91]
	v_mfma_f32_16x16x32_bf16 v[84:87], v[216:219], v[188:191], v[84:87]
	v_mfma_f32_16x16x32_bf16 v[80:83], v[220:223], v[188:191], v[80:83]
	v_mfma_f32_16x16x32_bf16 v[76:79], v[216:219], v[196:199], v[76:79]
	v_mfma_f32_16x16x32_bf16 v[72:75], v[220:223], v[196:199], v[72:75]
	v_mfma_f32_16x16x32_bf16 v[68:71], v[216:219], v[204:207], v[68:71]
	v_mfma_f32_16x16x32_bf16 v[64:67], v[220:223], v[204:207], v[64:67]
	s_barrier

; #define STAGE(P, BASE, br, kt) do { const char* _gb = (const char*)(BASE) + ((size_t)(br) * K + (size_t)(kt) * BK) * 2; \
;     __builtin_amdgcn_global_load_lds((const unsigned*)(_gb + loff0), (unsigned*)((char*)(P) + tid * 16), 16, 0, 0); \
;     __builtin_amdgcn_global_load_lds((const unsigned*)(_gb + (size_t)K * 128 + loff0), (unsigned*)((char*)(P) + tid * 16 + 8192), 16, 0, 0); } while (0)
; #define LDA(dst, b, h) for (int m = 0; m < 4; ++m) { \
;     dst[m][0] = *reinterpret_cast<const bf16x8*>((char*)SA(b, h) + aoff0 + m * 2048); \
;     dst[m][1] = *reinterpret_cast<const bf16x8*>((char*)SA(b, h) + aoff1 + m * 2048); }
; #define MMA(ai, bj, At, Btf) do { __builtin_amdgcn_s_setprio(1); \
;     for (int m = 0; m < 4; ++m) for (int n = 0; n < 2; ++n) for (int k = 0; k < 2; ++k) \
;       acc[ai][bj][m][n] = __builtin_amdgcn_mfma_f32_16x16x32_bf16(Btf[n][k], At[m][k], acc[ai][bj][m][n], 0, 0, 0); \
;     __builtin_amdgcn_s_setprio(0); } while (0)
; #define WAIT_V(n) asm volatile("s_waitcnt vmcnt(" #n ")" ::: "memory")
; #define WAIT_L(n) asm volatile("s_waitcnt lgkmcnt(" #n ")" ::: "memory")
; #define BAR __builtin_amdgcn_s_barrier()
; #define SCHED __builtin_amdgcn_sched_barrier(0)
; template <int EPI> ...
;     ...
;     LDA(At, 1, 1); STAGE(SA(1, 0), A, brow, t + 3);
;     BAR; WAIT_L(0); MMA(1, 0, At, B0); BAR; SCHED;
;     STAGE(SB(1, 1), Bt, bcol + HALF, t + 3);
;     WAIT_V(6); BAR; MMA(1, 1, At, B1); BAR;
	v_readfirstlane_b32 s75, v143
	v_lshl_add_u64 v[230:231], v[226:227], 0, s[46:47]
	s_mov_b32 m0, s75
	v_readfirstlane_b32 s75, v144
	global_load_lds_dwordx4 v[230:231], off
	v_lshl_add_u64 v[226:227], v[226:227], 0, s[48:49]
	s_mov_b32 m0, s75
	s_nop 0
	global_load_lds_dwordx4 v[226:227], off
	v_readfirstlane_b32 s75, v145
	v_lshl_add_u64 v[226:227], v[224:225], 0, s[50:51]
	s_mov_b32 m0, s75
	v_readfirstlane_b32 s75, v146
	ds_read_b128 v[176:179], v149 offset:49152
	ds_read_b128 v[180:183], v149 offset:50176
	ds_read_b128 v[184:187], v149 offset:51200
	ds_read_b128 v[188:191], v149 offset:52224
	ds_read_b128 v[192:195], v149 offset:53248
	ds_read_b128 v[196:199], v149 offset:54272
	ds_read_b128 v[200:203], v149 offset:55296
	ds_read_b128 v[204:207], v149 offset:56320
	global_load_lds_dwordx4 v[226:227], off
	v_lshl_add_u64 v[224:225], v[224:225], 0, s[52:53]
	s_mov_b32 m0, s75
	s_nop 0
	global_load_lds_dwordx4 v[224:225], off
	v_readfirstlane_b32 s75, v147
	v_lshl_add_u64 v[246:247], v[228:229], 0, s[54:55]
	s_mov_b32 m0, s75
	v_readfirstlane_b32 s75, v148
	global_load_lds_dwordx4 v[246:247], off
	s_waitcnt vmcnt(5)
	s_barrier
	s_waitcnt lgkmcnt(0)

; #define STAGE(P, BASE, br, kt) do { const char* _gb = (const char*)(BASE) + ((size_t)(br) * K + (size_t)(kt) * BK) * 2; \
;     __builtin_amdgcn_global_load_lds((const unsigned*)(_gb + loff0), (unsigned*)((char*)(P) + tid * 16), 16, 0, 0); \
;     __builtin_amdgcn_global_load_lds((const unsigned*)(_gb + (size_t)K * 128 + loff0), (unsigned*)((char*)(P) + tid * 16 + 8192), 16, 0, 0); } while (0)
; #define MMA(ai, bj, At, Btf) do { __builtin_amdgcn_s_setprio(1); \
;     for (int m = 0; m < 4; ++m) for (int n = 0; n < 2; ++n) for (int k = 0; k < 2; ++k) \
;       acc[ai][bj][m][n] = __builtin_amdgcn_mfma_f32_16x16x32_bf16(Btf[n][k], At[m][k], acc[ai][bj][m][n], 0, 0, 0); \
;     __builtin_amdgcn_s_setprio(0); } while (0)
; #define WAIT_V(n) asm volatile("s_waitcnt vmcnt(" #n ")" ::: "memory")
; #define WAIT_L(n) asm volatile("s_waitcnt lgkmcnt(" #n ")" ::: "memory")
; #define BAR __builtin_amdgcn_s_barrier()
; #define SCHED __builtin_amdgcn_sched_barrier(0)
; template <int EPI> ...
;     ...
;     BAR; WAIT_L(0); MMA(1, 0, At, B0); BAR; SCHED;
;     STAGE(SB(1, 1), Bt, bcol + HALF, t + 3);
;     WAIT_V(6); BAR; MMA(1, 1, At, B1); BAR;
	s_waitcnt lgkmcnt(0)
	v_mfma_f32_16x16x32_bf16 v[60:63], v[160:163], v[176:179], v[60:63]
	v_mfma_f32_16x16x32_bf16 v[56:59], v[164:167], v[176:179], v[56:59]
	v_mfma_f32_16x16x32_bf16 v[52:55], v[160:163], v[184:187], v[52:55]
	v_mfma_f32_16x16x32_bf16 v[48:51], v[164:167], v[184:187], v[48:51]
	v_mfma_f32_16x16x32_bf16 v[44:47], v[160:163], v[192:195], v[44:47]
	v_mfma_f32_16x16x32_bf16 v[40:43], v[164:167], v[192:195], v[40:43]
	v_mfma_f32_16x16x32_bf16 v[36:39], v[160:163], v[200:203], v[36:39]
	v_mfma_f32_16x16x32_bf16 v[32:35], v[164:167], v[200:203], v[32:35]
	v_mfma_f32_16x16x32_bf16 v[60:63], v[168:171], v[180:183], v[60:63]
	v_mfma_f32_16x16x32_bf16 v[56:59], v[172:175], v[180:183], v[56:59]
	v_mfma_f32_16x16x32_bf16 v[52:55], v[168:171], v[188:191], v[52:55]
	v_mfma_f32_16x16x32_bf16 v[48:51], v[172:175], v[188:191], v[48:51]
	v_mfma_f32_16x16x32_bf16 v[44:47], v[168:171], v[196:199], v[44:47]
	v_mfma_f32_16x16x32_bf16 v[40:43], v[172:175], v[196:199], v[40:43]
	v_mfma_f32_16x16x32_bf16 v[36:39], v[168:171], v[204:207], v[36:39]
	v_mfma_f32_16x16x32_bf16 v[32:35], v[172:175], v[204:207], v[32:35]


; #define MMA(ai, bj, At, Btf) do { __builtin_amdgcn_s_setprio(1); \
;     for (int m = 0; m < 4; ++m) for (int n = 0; n < 2; ++n) for (int k = 0; k < 2; ++k) \
;       acc[ai][bj][m][n] = __builtin_amdgcn_mfma_f32_16x16x32_bf16(Btf[n][k], At[m][k], acc[ai][bj][m][n], 0, 0, 0); \
;     __builtin_amdgcn_s_setprio(0); } while (0)
; #define WAIT_V(n) asm volatile("s_waitcnt vmcnt(" #n ")" ::: "memory")
; #define BAR __builtin_amdgcn_s_barrier()
; template <int EPI> ...
;     ...
;     WAIT_V(6); BAR; MMA(1, 1, At, B1); BAR;
	v_mfma_f32_16x16x32_bf16 v[28:31], v[208:211], v[176:179], v[28:31]
	v_mfma_f32_16x16x32_bf16 v[24:27], v[212:215], v[176:179], v[24:27]
	v_mfma_f32_16x16x32_bf16 v[20:23], v[208:211], v[184:187], v[20:23]
	v_mfma_f32_16x16x32_bf16 v[16:19], v[212:215], v[184:187], v[16:19]
	v_mfma_f32_16x16x32_bf16 v[12:15], v[208:211], v[192:195], v[12:15]
	v_mfma_f32_16x16x32_bf16 v[8:11], v[212:215], v[192:195], v[8:11]
	v_mfma_f32_16x16x32_bf16 v[4:7], v[208:211], v[200:203], v[4:7]
	v_mfma_f32_16x16x32_bf16 v[0:3], v[212:215], v[200:203], v[0:3]
	v_mfma_f32_16x16x32_bf16 v[28:31], v[216:219], v[180:183], v[28:31]
	v_mfma_f32_16x16x32_bf16 v[24:27], v[220:223], v[180:183], v[24:27]
	v_mfma_f32_16x16x32_bf16 v[20:23], v[216:219], v[188:191], v[20:23]
	v_mfma_f32_16x16x32_bf16 v[16:19], v[220:223], v[188:191], v[16:19]
	v_mfma_f32_16x16x32_bf16 v[12:15], v[216:219], v[196:199], v[12:15]
	v_mfma_f32_16x16x32_bf16 v[8:11], v[220:223], v[196:199], v[8:11]
	v_mfma_f32_16x16x32_bf16 v[4:7], v[216:219], v[204:207], v[4:7]
	v_mfma_f32_16x16x32_bf16 v[0:3], v[220:223], v[204:207], v[0:3]

; #define STAGE(P, BASE, br, kt) do { const char* _gb = (const char*)(BASE) + ((size_t)(br) * K + (size_t)(kt) * BK) * 2; \
;     __builtin_amdgcn_global_load_lds((const unsigned*)(_gb + loff0), (unsigned*)((char*)(P) + tid * 16), 16, 0, 0); \
;     __builtin_amdgcn_global_load_lds((const unsigned*)(_gb + (size_t)K * 128 + loff0), (unsigned*)((char*)(P) + tid * 16 + 8192), 16, 0, 0); } while (0)
; #define LDA(dst, b, h) for (int m = 0; m < 4; ++m) { \
;     dst[m][0] = *reinterpret_cast<const bf16x8*>((char*)SA(b, h) + aoff0 + m * 2048); \
;     dst[m][1] = *reinterpret_cast<const bf16x8*>((char*)SA(b, h) + aoff1 + m * 2048); }
; #define LDB(dst, b, h) for (int n = 0; n < 2; ++n) { \
;     dst[n][0] = *reinterpret_cast<const bf16x8*>((char*)SB(b, h) + boff0 + n * 256); \
;     dst[n][1] = *reinterpret_cast<const bf16x8*>((char*)SB(b, h) + boff1 + n * 256); }
; #define MMA(ai, bj, At, Btf) do { __builtin_amdgcn_s_setprio(1); \
;     for (int m = 0; m < 4; ++m) for (int n = 0; n < 2; ++n) for (int k = 0; k < 2; ++k) \
;       acc[ai][bj][m][n] = __builtin_amdgcn_mfma_f32_16x16x32_bf16(Btf[n][k], At[m][k], acc[ai][bj][m][n], 0, 0, 0); \
;     __builtin_amdgcn_s_setprio(0); } while (0)
; #define WAIT_V(n) asm volatile("s_waitcnt vmcnt(" #n ")" ::: "memory")
; #define BAR __builtin_amdgcn_s_barrier()
; template <int EPI> ...
;     ...
;   for (int t = 0; t < nt - 2; t += 2) {
;     ...
;     WAIT_V(6); BAR; MMA(1, 1, At, B1); BAR;
;   }
;   { LDB(B0, 0, 0); LDA(At, 0, 0); STAGE(SA(1, 1), A, brow + HALF, nt - 1);
	s_add_i32 s74, s74, 2
	s_add_u32 s60, s60, 0x100
	s_addc_u32 s61, s61, 0
	s_add_u32 s62, s62, 0x100
	s_addc_u32 s63, s63, 0
	s_add_u32 s64, s64, 0x100
	s_addc_u32 s65, s65, 0
	s_cmpk_lt_u32 s74, 0x54
	s_barrier
	s_cbranch_scc1 .LBB0_1152
	v_readfirstlane_b32 s75, v148
	v_lshl_add_u64 v[246:247], v[228:229], 0, s[56:57]
	s_mov_b32 m0, s75
	s_nop 0
	global_load_lds_dwordx4 v[246:247], off
	s_add_u32 s60, s68, s73
	s_addc_u32 s61, s69, s72
	v_lshl_add_u64 v[208:209], s[60:61], 0, v[128:129]
	v_readfirstlane_b32 s60, v150
	s_mov_b32 m0, s60
	v_readfirstlane_b32 s60, v151
	ds_read_b128 v[160:163], v152
	ds_read_b128 v[164:167], v152 offset:256
	ds_read_b128 v[168:171], v153
	ds_read_b128 v[172:175], v153 offset:256
	ds_read_b128 v[176:179], v149
	ds_read_b128 v[180:183], v149 offset:1024
	ds_read_b128 v[184:187], v149 offset:2048
	ds_read_b128 v[188:191], v149 offset:3072
	ds_read_b128 v[192:195], v149 offset:4096
	ds_read_b128 v[196:199], v149 offset:5120
	ds_read_b128 v[200:203], v149 offset:6144
	ds_read_b128 v[204:207], v149 offset:7168
	global_load_lds_dwordx4 v[208:209], off
	v_lshl_add_u64 v[208:209], v[208:209], 0, s[8:9]
	s_mov_b32 m0, s60
	s_nop 0
	global_load_lds_dwordx4 v[208:209], off
	s_waitcnt lgkmcnt(0)

; #define STAGE(P, BASE, br, kt) do { const char* _gb = (const char*)(BASE) + ((size_t)(br) * K + (size_t)(kt) * BK) * 2; \
;     __builtin_amdgcn_global_load_lds((const unsigned*)(_gb + loff0), (unsigned*)((char*)(P) + tid * 16), 16, 0, 0); \
;     __builtin_amdgcn_global_load_lds((const unsigned*)(_gb + (size_t)K * 128 + loff0), (unsigned*)((char*)(P) + tid * 16 + 8192), 16, 0, 0); } while (0)
; #define LDA(dst, b, h) for (int m = 0; m < 4; ++m) { \
;     dst[m][0] = *reinterpret_cast<const bf16x8*>((char*)SA(b, h) + aoff0 + m * 2048); \
;     dst[m][1] = *reinterpret_cast<const bf16x8*>((char*)SA(b, h) + aoff1 + m * 2048); }
; #define LDB(dst, b, h) for (int n = 0; n < 2; ++n) { \
;     dst[n][0] = *reinterpret_cast<const bf16x8*>((char*)SB(b, h) + boff0 + n * 256); \
;     dst[n][1] = *reinterpret_cast<const bf16x8*>((char*)SB(b, h) + boff1 + n * 256); }
; #define MMA(ai, bj, At, Btf) do { __builtin_amdgcn_s_setprio(1); \
;     for (int m = 0; m < 4; ++m) for (int n = 0; n < 2; ++n) for (int k = 0; k < 2; ++k) \
;       acc[ai][bj][m][n] = __builtin_amdgcn_mfma_f32_16x16x32_bf16(Btf[n][k], At[m][k], acc[ai][bj][m][n], 0, 0, 0); \
;     __builtin_amdgcn_s_setprio(0); } while (0)
; #define WAIT_L(n) asm volatile("s_waitcnt lgkmcnt(" #n ")" ::: "memory")
; #define BAR __builtin_amdgcn_s_barrier()
; template <int EPI> ...
;     ...
;   { LDB(B0, 0, 0); LDA(At, 0, 0); STAGE(SA(1, 1), A, brow + HALF, nt - 1);
;     BAR; WAIT_L(0); MMA(0, 0, At, B0); BAR;
	s_barrier
	v_mfma_f32_16x16x32_bf16 v[124:127], v[160:163], v[176:179], v[124:127]
	v_mfma_f32_16x16x32_bf16 v[116:119], v[160:163], v[184:187], v[116:119]
	v_mfma_f32_16x16x32_bf16 v[108:111], v[160:163], v[192:195], v[108:111]
	v_mfma_f32_16x16x32_bf16 v[100:103], v[160:163], v[200:203], v[100:103]
	v_mfma_f32_16x16x32_bf16 v[96:99], v[164:167], v[200:203], v[96:99]
	v_mfma_f32_16x16x32_bf16 v[124:127], v[168:171], v[180:183], v[124:127]
	v_mfma_f32_16x16x32_bf16 v[120:123], v[164:167], v[176:179], v[120:123]
	v_mfma_f32_16x16x32_bf16 v[116:119], v[168:171], v[188:191], v[116:119]
	v_mfma_f32_16x16x32_bf16 v[112:115], v[164:167], v[184:187], v[112:115]
	v_mfma_f32_16x16x32_bf16 v[108:111], v[168:171], v[196:199], v[108:111]
	v_mfma_f32_16x16x32_bf16 v[104:107], v[164:167], v[192:195], v[104:107]
	v_mfma_f32_16x16x32_bf16 v[100:103], v[168:171], v[204:207], v[100:103]
	v_mfma_f32_16x16x32_bf16 v[96:99], v[172:175], v[204:207], v[96:99]
	v_mfma_f32_16x16x32_bf16 v[208:211], v[172:175], v[180:183], v[120:123]
	v_mfma_f32_16x16x32_bf16 v[212:215], v[172:175], v[188:191], v[112:115]
	v_mfma_f32_16x16x32_bf16 v[216:219], v[172:175], v[196:199], v[104:107]
	s_barrier

; #define LDB(dst, b, h) for (int n = 0; n < 2; ++n) { \
;     dst[n][0] = *reinterpret_cast<const bf16x8*>((char*)SB(b, h) + boff0 + n * 256); \
;     dst[n][1] = *reinterpret_cast<const bf16x8*>((char*)SB(b, h) + boff1 + n * 256); }
; #define MMA(ai, bj, At, Btf) do { __builtin_amdgcn_s_setprio(1); \
;     for (int m = 0; m < 4; ++m) for (int n = 0; n < 2; ++n) for (int k = 0; k < 2; ++k) \
;       acc[ai][bj][m][n] = __builtin_amdgcn_mfma_f32_16x16x32_bf16(Btf[n][k], At[m][k], acc[ai][bj][m][n], 0, 0, 0); \
;     __builtin_amdgcn_s_setprio(0); } while (0)
; #define WAIT_L(n) asm volatile("s_waitcnt lgkmcnt(" #n ")" ::: "memory")
; #define BAR __builtin_amdgcn_s_barrier()
; template <int EPI> ...
;     ...
;     LDB(B1, 0, 1); BAR; WAIT_L(0); MMA(0, 1, At, B1); BAR;
	s_nop 0
	ds_read_b128 v[104:107], v154
	ds_read_b128 v[112:115], v154 offset:256
	ds_read_b128 v[120:123], v155
	ds_read_b128 v[220:223], v155 offset:256
	s_waitcnt lgkmcnt(0)

; #define LDB(dst, b, h) for (int n = 0; n < 2; ++n) { \
;     dst[n][0] = *reinterpret_cast<const bf16x8*>((char*)SB(b, h) + boff0 + n * 256); \
;     dst[n][1] = *reinterpret_cast<const bf16x8*>((char*)SB(b, h) + boff1 + n * 256); }
; #define MMA(ai, bj, At, Btf) do { __builtin_amdgcn_s_setprio(1); \
;     for (int m = 0; m < 4; ++m) for (int n = 0; n < 2; ++n) for (int k = 0; k < 2; ++k) \
;       acc[ai][bj][m][n] = __builtin_amdgcn_mfma_f32_16x16x32_bf16(Btf[n][k], At[m][k], acc[ai][bj][m][n], 0, 0, 0); \
;     __builtin_amdgcn_s_setprio(0); } while (0)
; #define WAIT_L(n) asm volatile("s_waitcnt lgkmcnt(" #n ")" ::: "memory")
; #define BAR __builtin_amdgcn_s_barrier()
; template <int EPI> ...
;     ...
;     LDB(B1, 0, 1); BAR; WAIT_L(0); MMA(0, 1, At, B1); BAR;
	s_barrier
	v_mfma_f32_16x16x32_bf16 v[84:87], v[104:107], v[184:187], v[84:87]
	v_mfma_f32_16x16x32_bf16 v[76:79], v[104:107], v[192:195], v[76:79]
	v_mfma_f32_16x16x32_bf16 v[72:75], v[112:115], v[192:195], v[72:75]
	v_mfma_f32_16x16x32_bf16 v[92:95], v[104:107], v[176:179], v[92:95]
	v_mfma_f32_16x16x32_bf16 v[88:91], v[112:115], v[176:179], v[88:91]
	v_mfma_f32_16x16x32_bf16 v[84:87], v[120:123], v[188:191], v[84:87]
	v_mfma_f32_16x16x32_bf16 v[80:83], v[112:115], v[184:187], v[80:83]
	v_mfma_f32_16x16x32_bf16 v[76:79], v[120:123], v[196:199], v[76:79]
	v_mfma_f32_16x16x32_bf16 v[72:75], v[220:223], v[196:199], v[72:75]
	v_mfma_f32_16x16x32_bf16 v[68:71], v[104:107], v[200:203], v[68:71]
	v_mfma_f32_16x16x32_bf16 v[64:67], v[112:115], v[200:203], v[64:67]
	v_mfma_f32_16x16x32_bf16 v[224:227], v[120:123], v[180:183], v[92:95]
	v_mfma_f32_16x16x32_bf16 v[176:179], v[220:223], v[180:183], v[88:91]
	v_mfma_f32_16x16x32_bf16 v[180:183], v[220:223], v[188:191], v[80:83]
	v_mfma_f32_16x16x32_bf16 v[184:187], v[120:123], v[204:207], v[68:71]
	v_mfma_f32_16x16x32_bf16 v[188:191], v[220:223], v[204:207], v[64:67]
	s_barrier

; #define LDA(dst, b, h) for (int m = 0; m < 4; ++m) { \
;     dst[m][0] = *reinterpret_cast<const bf16x8*>((char*)SA(b, h) + aoff0 + m * 2048); \
;     dst[m][1] = *reinterpret_cast<const bf16x8*>((char*)SA(b, h) + aoff1 + m * 2048); }
; #define MMA(ai, bj, At, Btf) do { __builtin_amdgcn_s_setprio(1); \
;     for (int m = 0; m < 4; ++m) for (int n = 0; n < 2; ++n) for (int k = 0; k < 2; ++k) \
;       acc[ai][bj][m][n] = __builtin_amdgcn_mfma_f32_16x16x32_bf16(Btf[n][k], At[m][k], acc[ai][bj][m][n], 0, 0, 0); \
;     __builtin_amdgcn_s_setprio(0); } while (0)
; #define WAIT_V(n) asm volatile("s_waitcnt vmcnt(" #n ")" ::: "memory")
; #define WAIT_L(n) asm volatile("s_waitcnt lgkmcnt(" #n ")" ::: "memory")
; #define BAR __builtin_amdgcn_s_barrier()
; template <int EPI> ...
;     ...
;     LDA(At, 0, 1); WAIT_V(4); BAR; WAIT_L(0); MMA(1, 0, At, B0); MMA(1, 1, At, B1); BAR; }
	s_nop 0
	ds_read_b128 v[64:67], v149 offset:16384
	ds_read_b128 v[68:71], v149 offset:17408
	ds_read_b128 v[80:83], v149 offset:18432
	ds_read_b128 v[88:91], v149 offset:19456
	ds_read_b128 v[92:95], v149 offset:20480
	ds_read_b128 v[192:195], v149 offset:21504
	ds_read_b128 v[196:199], v149 offset:22528
	ds_read_b128 v[200:203], v149 offset:23552
	s_waitcnt vmcnt(4)
	s_waitcnt lgkmcnt(0)

; #define LDA(dst, b, h) for (int m = 0; m < 4; ++m) { \
;     dst[m][0] = *reinterpret_cast<const bf16x8*>((char*)SA(b, h) + aoff0 + m * 2048); \
;     dst[m][1] = *reinterpret_cast<const bf16x8*>((char*)SA(b, h) + aoff1 + m * 2048); }
; #define MMA(ai, bj, At, Btf) do { __builtin_amdgcn_s_setprio(1); \
;     for (int m = 0; m < 4; ++m) for (int n = 0; n < 2; ++n) for (int k = 0; k < 2; ++k) \
;       acc[ai][bj][m][n] = __builtin_amdgcn_mfma_f32_16x16x32_bf16(Btf[n][k], At[m][k], acc[ai][bj][m][n], 0, 0, 0); \
;     __builtin_amdgcn_s_setprio(0); } while (0)
; #define WAIT_V(n) asm volatile("s_waitcnt vmcnt(" #n ")" ::: "memory")
; #define WAIT_L(n) asm volatile("s_waitcnt lgkmcnt(" #n ")" ::: "memory")
; #define BAR __builtin_amdgcn_s_barrier()
; template <int EPI> ...
;     ...
;     LDA(At, 0, 1); WAIT_V(4); BAR; WAIT_L(0); MMA(1, 0, At, B0); MMA(1, 1, At, B1); BAR; }
	s_barrier
	v_mfma_f32_16x16x32_bf16 v[52:55], v[160:163], v[80:83], v[52:55]
	v_mfma_f32_16x16x32_bf16 v[44:47], v[160:163], v[92:95], v[44:47]
	v_mfma_f32_16x16x32_bf16 v[36:39], v[160:163], v[196:199], v[36:39]
	v_mfma_f32_16x16x32_bf16 v[60:63], v[160:163], v[64:67], v[60:63]
	v_mfma_f32_16x16x32_bf16 v[56:59], v[164:167], v[64:67], v[56:59]
	v_mfma_f32_16x16x32_bf16 v[52:55], v[168:171], v[88:91], v[52:55]
	v_mfma_f32_16x16x32_bf16 v[48:51], v[164:167], v[80:83], v[48:51]
	v_mfma_f32_16x16x32_bf16 v[44:47], v[168:171], v[192:195], v[44:47]
	v_mfma_f32_16x16x32_bf16 v[40:43], v[164:167], v[92:95], v[40:43]
	v_mfma_f32_16x16x32_bf16 v[36:39], v[168:171], v[200:203], v[36:39]
	v_mfma_f32_16x16x32_bf16 v[32:35], v[164:167], v[196:199], v[32:35]
	v_mfma_f32_16x16x32_bf16 v[204:207], v[168:171], v[68:71], v[60:63]
	v_mfma_f32_16x16x32_bf16 v[228:231], v[172:175], v[68:71], v[56:59]
	v_mfma_f32_16x16x32_bf16 v[232:235], v[172:175], v[88:91], v[48:51]
	v_mfma_f32_16x16x32_bf16 v[236:239], v[172:175], v[192:195], v[40:43]
	v_mfma_f32_16x16x32_bf16 v[160:163], v[172:175], v[200:203], v[32:35]
	v_mfma_f32_16x16x32_bf16 v[28:31], v[104:107], v[64:67], v[28:31]
	v_mfma_f32_16x16x32_bf16 v[20:23], v[104:107], v[80:83], v[20:23]
	v_mfma_f32_16x16x32_bf16 v[12:15], v[104:107], v[92:95], v[12:15]
	v_mfma_f32_16x16x32_bf16 v[4:7], v[104:107], v[196:199], v[4:7]
	v_mfma_f32_16x16x32_bf16 v[28:31], v[120:123], v[68:71], v[28:31]
	v_mfma_f32_16x16x32_bf16 v[24:27], v[112:115], v[64:67], v[24:27]
	v_mfma_f32_16x16x32_bf16 v[20:23], v[120:123], v[88:91], v[20:23]
	v_mfma_f32_16x16x32_bf16 v[16:19], v[112:115], v[80:83], v[16:19]
	v_mfma_f32_16x16x32_bf16 v[12:15], v[120:123], v[192:195], v[12:15]
	v_mfma_f32_16x16x32_bf16 v[8:11], v[112:115], v[92:95], v[8:11]
	v_mfma_f32_16x16x32_bf16 v[4:7], v[120:123], v[200:203], v[4:7]
	v_mfma_f32_16x16x32_bf16 v[0:3], v[112:115], v[196:199], v[0:3]
	v_mfma_f32_16x16x32_bf16 v[164:167], v[220:223], v[68:71], v[24:27]
	v_mfma_f32_16x16x32_bf16 v[168:171], v[220:223], v[88:91], v[16:19]
	v_mfma_f32_16x16x32_bf16 v[172:175], v[220:223], v[192:195], v[8:11]
	v_mfma_f32_16x16x32_bf16 v[192:195], v[220:223], v[200:203], v[0:3]
	s_barrier

; #define LDA(dst, b, h) for (int m = 0; m < 4; ++m) { \
;     dst[m][0] = *reinterpret_cast<const bf16x8*>((char*)SA(b, h) + aoff0 + m * 2048); \
;     dst[m][1] = *reinterpret_cast<const bf16x8*>((char*)SA(b, h) + aoff1 + m * 2048); }
; #define LDB(dst, b, h) for (int n = 0; n < 2; ++n) { \
;     dst[n][0] = *reinterpret_cast<const bf16x8*>((char*)SB(b, h) + boff0 + n * 256); \
;     dst[n][1] = *reinterpret_cast<const bf16x8*>((char*)SB(b, h) + boff1 + n * 256); }
; #define MMA(ai, bj, At, Btf) do { __builtin_amdgcn_s_setprio(1); \
;     for (int m = 0; m < 4; ++m) for (int n = 0; n < 2; ++n) for (int k = 0; k < 2; ++k) \
;       acc[ai][bj][m][n] = __builtin_amdgcn_mfma_f32_16x16x32_bf16(Btf[n][k], At[m][k], acc[ai][bj][m][n], 0, 0, 0); \
;     __builtin_amdgcn_s_setprio(0); } while (0)
; #define WAIT_V(n) asm volatile("s_waitcnt vmcnt(" #n ")" ::: "memory")
; #define WAIT_L(n) asm volatile("s_waitcnt lgkmcnt(" #n ")" ::: "memory")
; #define BAR __builtin_amdgcn_s_barrier()
; template <int EPI> ...
;     ...
;   { LDB(B0, 1, 0); LDA(At, 1, 0); WAIT_V(2); BAR; WAIT_L(0); MMA(0, 0, At, B0); BAR;
	s_nop 1
	ds_read_b128 v[0:3], v156
	ds_read_b128 v[8:11], v156 offset:256
	ds_read_b128 v[16:19], v157
	ds_read_b128 v[24:27], v157 offset:256
	ds_read_b128 v[32:35], v149 offset:32768
	ds_read_b128 v[40:43], v149 offset:33792
	ds_read_b128 v[48:51], v149 offset:34816
	ds_read_b128 v[56:59], v149 offset:35840
	ds_read_b128 v[60:63], v149 offset:36864
	ds_read_b128 v[68:71], v149 offset:37888
	ds_read_b128 v[196:199], v149 offset:38912
	ds_read_b128 v[200:203], v149 offset:39936
	s_waitcnt vmcnt(2)
	s_waitcnt lgkmcnt(0)

; #define LDA(dst, b, h) for (int m = 0; m < 4; ++m) { \
;     dst[m][0] = *reinterpret_cast<const bf16x8*>((char*)SA(b, h) + aoff0 + m * 2048); \
;     dst[m][1] = *reinterpret_cast<const bf16x8*>((char*)SA(b, h) + aoff1 + m * 2048); }
; #define LDB(dst, b, h) for (int n = 0; n < 2; ++n) { \
;     dst[n][0] = *reinterpret_cast<const bf16x8*>((char*)SB(b, h) + boff0 + n * 256); \
;     dst[n][1] = *reinterpret_cast<const bf16x8*>((char*)SB(b, h) + boff1 + n * 256); }
; #define MMA(ai, bj, At, Btf) do { __builtin_amdgcn_s_setprio(1); \
;     for (int m = 0; m < 4; ++m) for (int n = 0; n < 2; ++n) for (int k = 0; k < 2; ++k) \
;       acc[ai][bj][m][n] = __builtin_amdgcn_mfma_f32_16x16x32_bf16(Btf[n][k], At[m][k], acc[ai][bj][m][n], 0, 0, 0); \
;     __builtin_amdgcn_s_setprio(0); } while (0)
; #define WAIT_V(n) asm volatile("s_waitcnt vmcnt(" #n ")" ::: "memory")
; #define WAIT_L(n) asm volatile("s_waitcnt lgkmcnt(" #n ")" ::: "memory")
; #define BAR __builtin_amdgcn_s_barrier()
; template <int EPI> ...
;     ...
;   { LDB(B0, 1, 0); LDA(At, 1, 0); WAIT_V(2); BAR; WAIT_L(0); MMA(0, 0, At, B0); BAR;
	s_barrier
	v_mfma_f32_16x16x32_bf16 v[64:67], v[0:3], v[32:35], v[124:127]
	v_mfma_f32_16x16x32_bf16 v[120:123], v[16:19], v[40:43], v[64:67]
	v_mfma_f32_16x16x32_bf16 v[64:67], v[8:11], v[32:35], v[208:211]
	v_mfma_f32_16x16x32_bf16 v[124:127], v[24:27], v[40:43], v[64:67]
	v_mfma_f32_16x16x32_bf16 v[64:67], v[0:3], v[48:51], v[116:119]
	v_mfma_f32_16x16x32_bf16 v[112:115], v[16:19], v[56:59], v[64:67]
	v_mfma_f32_16x16x32_bf16 v[64:67], v[8:11], v[48:51], v[212:215]
	v_mfma_f32_16x16x32_bf16 v[116:119], v[24:27], v[56:59], v[64:67]
	v_mfma_f32_16x16x32_bf16 v[64:67], v[0:3], v[60:63], v[108:111]
	v_mfma_f32_16x16x32_bf16 v[104:107], v[16:19], v[68:71], v[64:67]
	v_mfma_f32_16x16x32_bf16 v[64:67], v[8:11], v[60:63], v[216:219]
	v_mfma_f32_16x16x32_bf16 v[108:111], v[24:27], v[68:71], v[64:67]
	v_mfma_f32_16x16x32_bf16 v[64:67], v[0:3], v[196:199], v[100:103]
	v_mfma_f32_16x16x32_bf16 v[88:91], v[16:19], v[200:203], v[64:67]
	v_mfma_f32_16x16x32_bf16 v[64:67], v[8:11], v[196:199], v[96:99]
	v_mfma_f32_16x16x32_bf16 v[92:95], v[24:27], v[200:203], v[64:67]
	s_barrier

; #define LDB(dst, b, h) for (int n = 0; n < 2; ++n) { \
;     dst[n][0] = *reinterpret_cast<const bf16x8*>((char*)SB(b, h) + boff0 + n * 256); \
;     dst[n][1] = *reinterpret_cast<const bf16x8*>((char*)SB(b, h) + boff1 + n * 256); }
; #define MMA(ai, bj, At, Btf) do { __builtin_amdgcn_s_setprio(1); \
;     for (int m = 0; m < 4; ++m) for (int n = 0; n < 2; ++n) for (int k = 0; k < 2; ++k) \
;       acc[ai][bj][m][n] = __builtin_amdgcn_mfma_f32_16x16x32_bf16(Btf[n][k], At[m][k], acc[ai][bj][m][n], 0, 0, 0); \
;     __builtin_amdgcn_s_setprio(0); } while (0)
; #define WAIT_V(n) asm volatile("s_waitcnt vmcnt(" #n ")" ::: "memory")
; #define WAIT_L(n) asm volatile("s_waitcnt lgkmcnt(" #n ")" ::: "memory")
; #define BAR __builtin_amdgcn_s_barrier()
; template <int EPI> ...
;     ...
;     LDB(B1, 1, 1); WAIT_V(0); BAR; WAIT_L(0); MMA(0, 1, At, B1); BAR;
	ds_read_b128 v[208:211], v158
	ds_read_b128 v[212:215], v158 offset:256
	ds_read_b128 v[216:219], v159
	ds_read_b128 v[220:223], v159 offset:256
	s_waitcnt vmcnt(0)
	s_waitcnt lgkmcnt(0)

; #define LDB(dst, b, h) for (int n = 0; n < 2; ++n) { \
;     dst[n][0] = *reinterpret_cast<const bf16x8*>((char*)SB(b, h) + boff0 + n * 256); \
;     dst[n][1] = *reinterpret_cast<const bf16x8*>((char*)SB(b, h) + boff1 + n * 256); }
; #define MMA(ai, bj, At, Btf) do { __builtin_amdgcn_s_setprio(1); \
;     for (int m = 0; m < 4; ++m) for (int n = 0; n < 2; ++n) for (int k = 0; k < 2; ++k) \
;       acc[ai][bj][m][n] = __builtin_amdgcn_mfma_f32_16x16x32_bf16(Btf[n][k], At[m][k], acc[ai][bj][m][n], 0, 0, 0); \
;     __builtin_amdgcn_s_setprio(0); } while (0)
; #define WAIT_V(n) asm volatile("s_waitcnt vmcnt(" #n ")" ::: "memory")
; #define WAIT_L(n) asm volatile("s_waitcnt lgkmcnt(" #n ")" ::: "memory")
; #define BAR __builtin_amdgcn_s_barrier()
; template <int EPI> ...
;     ...
;     LDB(B1, 1, 1); WAIT_V(0); BAR; WAIT_L(0); MMA(0, 1, At, B1); BAR;
	s_barrier
	v_mfma_f32_16x16x32_bf16 v[64:67], v[208:211], v[32:35], v[224:227]
	v_mfma_f32_16x16x32_bf16 v[32:35], v[212:215], v[32:35], v[176:179]
	v_mfma_f32_16x16x32_bf16 v[100:103], v[220:223], v[40:43], v[32:35]
	v_mfma_f32_16x16x32_bf16 v[32:35], v[208:211], v[48:51], v[84:87]
	v_mfma_f32_16x16x32_bf16 v[80:83], v[216:219], v[56:59], v[32:35]
	v_mfma_f32_16x16x32_bf16 v[32:35], v[212:215], v[48:51], v[180:183]
	v_mfma_f32_16x16x32_bf16 v[84:87], v[220:223], v[56:59], v[32:35]
	v_mfma_f32_16x16x32_bf16 v[32:35], v[208:211], v[60:63], v[76:79]
	v_mfma_f32_16x16x32_bf16 v[96:99], v[216:219], v[40:43], v[64:67]
	v_mfma_f32_16x16x32_bf16 v[64:67], v[216:219], v[68:71], v[32:35]
	v_mfma_f32_16x16x32_bf16 v[32:35], v[212:215], v[60:63], v[72:75]
	v_mfma_f32_16x16x32_bf16 v[68:71], v[220:223], v[68:71], v[32:35]
	v_mfma_f32_16x16x32_bf16 v[32:35], v[208:211], v[196:199], v[184:187]
	v_mfma_f32_16x16x32_bf16 v[56:59], v[216:219], v[200:203], v[32:35]
	v_mfma_f32_16x16x32_bf16 v[32:35], v[212:215], v[196:199], v[188:191]
	v_mfma_f32_16x16x32_bf16 v[60:63], v[220:223], v[200:203], v[32:35]
	s_barrier

; #define LDA(dst, b, h) for (int m = 0; m < 4; ++m) { \
;     dst[m][0] = *reinterpret_cast<const bf16x8*>((char*)SA(b, h) + aoff0 + m * 2048); \
;     dst[m][1] = *reinterpret_cast<const bf16x8*>((char*)SA(b, h) + aoff1 + m * 2048); }
; #define MMA(ai, bj, At, Btf) do { __builtin_amdgcn_s_setprio(1); \
;     for (int m = 0; m < 4; ++m) for (int n = 0; n < 2; ++n) for (int k = 0; k < 2; ++k) \
;       acc[ai][bj][m][n] = __builtin_amdgcn_mfma_f32_16x16x32_bf16(Btf[n][k], At[m][k], acc[ai][bj][m][n], 0, 0, 0); \
;     __builtin_amdgcn_s_setprio(0); } while (0)
; #define WAIT_L(n) asm volatile("s_waitcnt lgkmcnt(" #n ")" ::: "memory")
; #define BAR __builtin_amdgcn_s_barrier()
; template <int EPI> ...
;     ...
;     LDA(At, 1, 1); BAR; WAIT_L(0); MMA(1, 0, At, B0); MMA(1, 1, At, B1); BAR; }
	ds_read_b128 v[176:179], v149 offset:49152
	ds_read_b128 v[180:183], v149 offset:50176
	ds_read_b128 v[184:187], v149 offset:51200
	ds_read_b128 v[188:191], v149 offset:52224
	ds_read_b128 v[196:199], v149 offset:53248
	ds_read_b128 v[200:203], v149 offset:54272
	ds_read_b128 v[224:227], v149 offset:55296
	ds_read_b128 v[240:243], v149 offset:56320
	s_waitcnt lgkmcnt(0)

; #define LDA(dst, b, h) for (int m = 0; m < 4; ++m) { \
;     dst[m][0] = *reinterpret_cast<const bf16x8*>((char*)SA(b, h) + aoff0 + m * 2048); \
;     dst[m][1] = *reinterpret_cast<const bf16x8*>((char*)SA(b, h) + aoff1 + m * 2048); }
; #define MMA(ai, bj, At, Btf) do { __builtin_amdgcn_s_setprio(1); \
;     for (int m = 0; m < 4; ++m) for (int n = 0; n < 2; ++n) for (int k = 0; k < 2; ++k) \
;       acc[ai][bj][m][n] = __builtin_amdgcn_mfma_f32_16x16x32_bf16(Btf[n][k], At[m][k], acc[ai][bj][m][n], 0, 0, 0); \
;     __builtin_amdgcn_s_setprio(0); } while (0)
; #define WAIT_L(n) asm volatile("s_waitcnt lgkmcnt(" #n ")" ::: "memory")
; #define BAR __builtin_amdgcn_s_barrier()
; template <int EPI> ...
;     ...
;     LDA(At, 1, 1); BAR; WAIT_L(0); MMA(1, 0, At, B0); MMA(1, 1, At, B1); BAR; }
	s_barrier
	v_mfma_f32_16x16x32_bf16 v[32:35], v[0:3], v[176:179], v[204:207]
	v_mfma_f32_16x16x32_bf16 v[72:75], v[16:19], v[180:183], v[32:35]
	v_mfma_f32_16x16x32_bf16 v[32:35], v[8:11], v[176:179], v[228:231]
	v_mfma_f32_16x16x32_bf16 v[76:79], v[24:27], v[180:183], v[32:35]
	v_mfma_f32_16x16x32_bf16 v[32:35], v[0:3], v[184:187], v[52:55]
	v_mfma_f32_16x16x32_bf16 v[48:51], v[16:19], v[188:191], v[32:35]
	v_mfma_f32_16x16x32_bf16 v[32:35], v[8:11], v[184:187], v[232:235]
	v_mfma_f32_16x16x32_bf16 v[52:55], v[24:27], v[188:191], v[32:35]
	v_mfma_f32_16x16x32_bf16 v[32:35], v[0:3], v[196:199], v[44:47]
	v_mfma_f32_16x16x32_bf16 v[40:43], v[16:19], v[200:203], v[32:35]
	v_mfma_f32_16x16x32_bf16 v[32:35], v[8:11], v[196:199], v[236:239]
	v_mfma_f32_16x16x32_bf16 v[0:3], v[0:3], v[224:227], v[36:39]
	v_mfma_f32_16x16x32_bf16 v[44:47], v[24:27], v[200:203], v[32:35]
	v_mfma_f32_16x16x32_bf16 v[32:35], v[16:19], v[240:243], v[0:3]
	v_mfma_f32_16x16x32_bf16 v[0:3], v[8:11], v[224:227], v[160:163]
	v_mfma_f32_16x16x32_bf16 v[36:39], v[24:27], v[240:243], v[0:3]
	v_mfma_f32_16x16x32_bf16 v[0:3], v[208:211], v[176:179], v[28:31]
	v_mfma_f32_16x16x32_bf16 v[24:27], v[216:219], v[180:183], v[0:3]
	v_mfma_f32_16x16x32_bf16 v[0:3], v[212:215], v[176:179], v[164:167]
	v_mfma_f32_16x16x32_bf16 v[28:31], v[220:223], v[180:183], v[0:3]
	v_mfma_f32_16x16x32_bf16 v[0:3], v[208:211], v[184:187], v[20:23]
	v_mfma_f32_16x16x32_bf16 v[16:19], v[216:219], v[188:191], v[0:3]
	v_mfma_f32_16x16x32_bf16 v[0:3], v[212:215], v[184:187], v[168:171]
	v_mfma_f32_16x16x32_bf16 v[20:23], v[220:223], v[188:191], v[0:3]
	v_mfma_f32_16x16x32_bf16 v[0:3], v[208:211], v[196:199], v[12:15]
	v_mfma_f32_16x16x32_bf16 v[8:11], v[216:219], v[200:203], v[0:3]
	v_mfma_f32_16x16x32_bf16 v[0:3], v[212:215], v[196:199], v[172:175]
	v_mfma_f32_16x16x32_bf16 v[12:15], v[220:223], v[200:203], v[0:3]
	v_mfma_f32_16x16x32_bf16 v[0:3], v[208:211], v[224:227], v[4:7]
	v_mfma_f32_16x16x32_bf16 v[4:7], v[212:215], v[224:227], v[192:195]
	v_mfma_f32_16x16x32_bf16 v[0:3], v[216:219], v[240:243], v[0:3]
	v_mfma_f32_16x16x32_bf16 v[4:7], v[220:223], v[240:243], v[4:7]
	s_barrier

; #define LDA(dst, b, h) for (int m = 0; m < 4; ++m) { \
;     dst[m][0] = *reinterpret_cast<const bf16x8*>((char*)SA(b, h) + aoff0 + m * 2048); \
;     dst[m][1] = *reinterpret_cast<const bf16x8*>((char*)SA(b, h) + aoff1 + m * 2048); }
; #define MMA(ai, bj, At, Btf) do { __builtin_amdgcn_s_setprio(1); \
;     for (int m = 0; m < 4; ++m) for (int n = 0; n < 2; ++n) for (int k = 0; k < 2; ++k) \
;       acc[ai][bj][m][n] = __builtin_amdgcn_mfma_f32_16x16x32_bf16(Btf[n][k], At[m][k], acc[ai][bj][m][n], 0, 0, 0); \
;     __builtin_amdgcn_s_setprio(0); } while (0)
; #define WAIT_L(n) asm volatile("s_waitcnt lgkmcnt(" #n ")" ::: "memory")
; #define BAR __builtin_amdgcn_s_barrier()
; template <int EPI> ...
;     ...
;     LDA(At, 1, 1); BAR; WAIT_L(0); MMA(1, 0, At, B0); MMA(1, 1, At, B1); BAR; }
;   if (wr == 0) BAR;
; template <int EPI>
; __device__ __forceinline__ void gemm_phase(const u16* A, const u16* Bt, int M, int N, int K, u16* out, int ldo,
;                                            const float* aux, int bid, int nblk, int wv) {
;     ...
;   for (int base = 0; base < ntile; base += nblk) {
;     int wgid;
;     if (base + nblk <= ntile && (nblk & 7) == 0) wgid = base + (bid & 7) * (nblk >> 3) + (bid >> 3);
;     else wgid = base + bid;
;     if (wgid >= ntile) break;
;     int nig = WGM * nN, gid = wgid / nig, fm = gid * WGM, gsz = min(nM - fm, WGM);
;     int pm = fm + ((wgid % nig) % gsz), pn = (wgid % nig) / gsz;
;     int brow = pm * BM, bcol = pn * BM;
;     gemm_tile<EPI>(A, Bt, K, brow, bcol, out, ldo, EPI == 1 ? pn * HALF : bcol, aux, tid);
	s_setprio 0
	s_and_saveexec_b64 s[60:61], s[2:3]
	s_cbranch_execz .LBB0_1146
	s_barrier
	s_branch .LBB0_1146
